# v27 + remaining K-loop stage loads also in saddr form (+0x80 bases formed by SALU); no v_lshl_add_u64 left in most K-loops
# baseline (speedup 1.0000x reference)
; #define PG8_STAGE(bufoff, gbase, voff) do { _Pragma("unroll") for (int _i = 0; _i < 2; ++_i) \
;         __builtin_amdgcn_global_load_lds((const unsigned*)((const char*)(gbase) + (voff)[_i]), (LAS unsigned*)(lds + (bufoff) + ldsw + _i * 8192), 16, 0, 0); } while (0)
; #define PG8_LDA(dst, b, h) do { _Pragma("unroll") for (int m = 0; m < 4; ++m) _Pragma("unroll") for (int k = 0; k < 2; ++k) dst[m][k] = *(const LAS bf16x8*)(lds + PG8_SA(b, h) + aoff + m * 2048 + k * 1024); } while (0)
; #define PG8_LDB(dst, b, h) do { _Pragma("unroll") for (int n = 0; n < 2; ++n) _Pragma("unroll") for (int k = 0; k < 2; ++k) dst[n][k] = *(const LAS bf16x8*)(lds + PG8_SB(b, h) + boff + n * 2048 + k * 1024); } while (0)
; #define PG8_MMA(ai, bj, At, Bt) do { __builtin_amdgcn_s_setprio(1); _Pragma("unroll") for (int m = 0; m < 4; ++m) _Pragma("unroll") for (int n = 0; n < 2; ++n) _Pragma("unroll") for (int k = 0; k < 2; ++k) \
;         acc[ai][bj][m][n] = __builtin_amdgcn_mfma_f32_16x16x32_bf16(Bt[n][k], At[m][k], acc[ai][bj][m][n], 0, 0, 0); __builtin_amdgcn_s_setprio(0); } while (0)
; #define PG8_WAIT_V(n) asm volatile("s_waitcnt vmcnt(" #n ")" ::: "memory")
; #define PG8_WAIT_L(n) asm volatile("s_waitcnt lgkmcnt(" #n ")" ::: "memory")
; #define PG8_BAR __builtin_amdgcn_s_barrier()
; template <class Epi, class Sched, bool ALIGN_EPI = false, bool SP2 = false>
; __device__ __forceinline__ void gemm_phase(LAS unsigned char* lds, const Gemm g, const Sched& S, const Epi& E) {
;     ...
;             const bool last = (t == nt - 2);
;             const char* a1 = cA + (size_t)(t + 1) * kstep;
;             const char* a2 = last ? nA : cA + (size_t)(t + 2) * kstep; const char* b2 = last ? nB : cB + (size_t)(t + 2) * kstep;
;             const char* a3 = a2 + kstep; const char* b3 = b2 + kstep;
;             if (last && has_next) S.a_ready(nxt);
;             if constexpr (SP2) {
;             PG8_LDB(B0, 0, 0); PG8_LDB(B1, 0, 1); PG8_SCHED; PG8_LDA(At, 0, 0); PG8_STAGE(PG8_SA(1, 1), a1 + hstep, voffA);
;             PG8_WAIT_V(8); PG8_WAIT_L(0); PG8_BAR; PG8_MMA(0, 0, At, B0); PG8_MMA(0, 1, At, B1); PG8_BAR; PG8_SCHED;
;             PG8_LDA(At, 0, 1); PG8_STAGE(PG8_SB(0, 0), b2, voffB); PG8_STAGE(PG8_SB(0, 1), b2 + hstepB, voffB); PG8_STAGE(PG8_SA(0, 0), a2, voffA);
;             PG8_WAIT_V(8); PG8_WAIT_L(0); PG8_BAR; PG8_MMA(1, 0, At, B0); PG8_MMA(1, 1, At, B1); PG8_BAR; PG8_SCHED;
.Lprio_188:
	ds_read_b128 v[66:69], v174
	ds_read_b128 v[70:73], v174 offset:1024
	ds_read_b128 v[74:77], v174 offset:2048
	ds_read_b128 v[78:81], v174 offset:3072
	ds_read_b128 v[162:165], v175
	ds_read_b128 v[182:185], v175 offset:1024
	ds_read_b128 v[186:189], v175 offset:2048
	ds_read_b128 v[190:193], v175 offset:3072
	s_add_u32 s20, s16, 0xfff80080
	s_addc_u32 s21, s17, -1
	s_cmp_eq_u32 s19, 28
	s_cselect_b32 s53, s3, s21
	s_cselect_b32 s52, s12, s20
	s_cselect_b32 s51, s13, s18
	s_cselect_b32 s50, s14, s15
	s_add_i32 m0, s33, 0xc000
	ds_read_b128 v[194:197], v176
	ds_read_b128 v[198:201], v176 offset:1024
	ds_read_b128 v[202:205], v176 offset:2048
	ds_read_b128 v[206:209], v176 offset:3072
	ds_read_b128 v[210:213], v176 offset:4096
	ds_read_b128 v[214:217], v176 offset:5120
	ds_read_b128 v[218:221], v176 offset:6144
	ds_read_b128 v[222:225], v176 offset:7168
	global_load_lds_dwordx4 v154, s[16:17]
	s_add_i32 m0, s33, 0xe000
	s_nop 0
	global_load_lds_dwordx4 v156, s[16:17]
	s_waitcnt lgkmcnt(0)
	s_barrier
	s_waitcnt lgkmcnt(0)
	v_mfma_f32_16x16x32_bf16 v[142:145], v[66:69], v[194:197], 0
	v_mfma_f32_16x16x32_bf16 v[138:141], v[74:77], v[194:197], 0
	v_mfma_f32_16x16x32_bf16 v[126:129], v[66:69], v[202:205], 0
	v_mfma_f32_16x16x32_bf16 v[122:125], v[74:77], v[202:205], 0
	v_mfma_f32_16x16x32_bf16 v[110:113], v[66:69], v[210:213], 0
	v_mfma_f32_16x16x32_bf16 v[106:109], v[74:77], v[210:213], 0
	v_mfma_f32_16x16x32_bf16 v[94:97], v[66:69], v[218:221], 0
	v_mfma_f32_16x16x32_bf16 v[90:93], v[74:77], v[218:221], 0
	v_mfma_f32_16x16x32_bf16 v[142:145], v[70:73], v[198:201], v[142:145]
	v_mfma_f32_16x16x32_bf16 v[138:141], v[78:81], v[198:201], v[138:141]
	v_mfma_f32_16x16x32_bf16 v[126:129], v[70:73], v[206:209], v[126:129]
	v_mfma_f32_16x16x32_bf16 v[122:125], v[78:81], v[206:209], v[122:125]
	v_mfma_f32_16x16x32_bf16 v[110:113], v[70:73], v[214:217], v[110:113]
	v_mfma_f32_16x16x32_bf16 v[106:109], v[78:81], v[214:217], v[106:109]
	v_mfma_f32_16x16x32_bf16 v[94:97], v[70:73], v[222:225], v[94:97]
	v_mfma_f32_16x16x32_bf16 v[90:93], v[78:81], v[222:225], v[90:93]
	v_mfma_f32_16x16x32_bf16 v[134:137], v[162:165], v[194:197], 0
	v_mfma_f32_16x16x32_bf16 v[130:133], v[186:189], v[194:197], 0
	v_mfma_f32_16x16x32_bf16 v[118:121], v[162:165], v[202:205], 0
	v_mfma_f32_16x16x32_bf16 v[114:117], v[186:189], v[202:205], 0
	v_mfma_f32_16x16x32_bf16 v[102:105], v[162:165], v[210:213], 0
	v_mfma_f32_16x16x32_bf16 v[98:101], v[186:189], v[210:213], 0
	v_mfma_f32_16x16x32_bf16 v[86:89], v[162:165], v[218:221], 0
	v_mfma_f32_16x16x32_bf16 v[82:85], v[186:189], v[218:221], 0
	v_mfma_f32_16x16x32_bf16 v[134:137], v[182:185], v[198:201], v[134:137]
	v_mfma_f32_16x16x32_bf16 v[130:133], v[190:193], v[198:201], v[130:133]
	v_mfma_f32_16x16x32_bf16 v[118:121], v[182:185], v[206:209], v[118:121]
	v_mfma_f32_16x16x32_bf16 v[114:117], v[190:193], v[206:209], v[114:117]
	v_mfma_f32_16x16x32_bf16 v[102:105], v[182:185], v[214:217], v[102:105]
	v_mfma_f32_16x16x32_bf16 v[98:101], v[190:193], v[214:217], v[98:101]
	v_mfma_f32_16x16x32_bf16 v[86:89], v[182:185], v[222:225], v[86:89]
	v_mfma_f32_16x16x32_bf16 v[82:85], v[190:193], v[222:225], v[82:85]
	s_barrier
	s_add_i32 s20, s57, s27
	s_mov_b32 m0, s20
	ds_read_b128 v[194:197], v176 offset:16384
	ds_read_b128 v[198:201], v176 offset:17408
	ds_read_b128 v[202:205], v176 offset:18432
	ds_read_b128 v[206:209], v176 offset:19456
	ds_read_b128 v[210:213], v176 offset:20480
	ds_read_b128 v[214:217], v176 offset:21504
	ds_read_b128 v[218:221], v176 offset:22528
	ds_read_b128 v[222:225], v176 offset:23552
	global_load_lds_dwordx4 v150, s[50:51]
	s_add_i32 m0, s20, 0x2000
	s_add_u32 s20, s50, 0x80000
	s_addc_u32 s21, s51, 0
	s_add_i32 s22, s58, s27
	global_load_lds_dwordx4 v146, s[50:51]
	s_mov_b32 m0, s22
	global_load_lds_dwordx4 v150, s[20:21]
	s_add_i32 m0, s22, 0x2000
	s_nop 0
	global_load_lds_dwordx4 v146, s[20:21]
	s_mov_b32 m0, s33
	s_nop 0
	global_load_lds_dwordx4 v152, s[52:53]
	s_mov_b32 m0, s34
	s_nop 0
	global_load_lds_dwordx4 v148, s[52:53]
	s_waitcnt lgkmcnt(0)
	s_barrier
	s_waitcnt lgkmcnt(0)
	v_mfma_f32_16x16x32_bf16 v[62:65], v[66:69], v[194:197], 0
	v_mfma_f32_16x16x32_bf16 v[58:61], v[74:77], v[194:197], 0
	v_mfma_f32_16x16x32_bf16 v[46:49], v[66:69], v[202:205], 0
	v_mfma_f32_16x16x32_bf16 v[42:45], v[74:77], v[202:205], 0
	v_mfma_f32_16x16x32_bf16 v[30:33], v[66:69], v[210:213], 0
	v_mfma_f32_16x16x32_bf16 v[26:29], v[74:77], v[210:213], 0
	v_mfma_f32_16x16x32_bf16 v[14:17], v[66:69], v[218:221], 0
	v_mfma_f32_16x16x32_bf16 v[10:13], v[74:77], v[218:221], 0
	v_mfma_f32_16x16x32_bf16 v[62:65], v[70:73], v[198:201], v[62:65]
	v_mfma_f32_16x16x32_bf16 v[58:61], v[78:81], v[198:201], v[58:61]
	v_mfma_f32_16x16x32_bf16 v[46:49], v[70:73], v[206:209], v[46:49]
	v_mfma_f32_16x16x32_bf16 v[42:45], v[78:81], v[206:209], v[42:45]
	v_mfma_f32_16x16x32_bf16 v[30:33], v[70:73], v[214:217], v[30:33]
	v_mfma_f32_16x16x32_bf16 v[26:29], v[78:81], v[214:217], v[26:29]
	v_mfma_f32_16x16x32_bf16 v[14:17], v[70:73], v[222:225], v[14:17]
	v_mfma_f32_16x16x32_bf16 v[10:13], v[78:81], v[222:225], v[10:13]
	v_mfma_f32_16x16x32_bf16 v[54:57], v[162:165], v[194:197], 0
	v_mfma_f32_16x16x32_bf16 v[50:53], v[186:189], v[194:197], 0
	v_mfma_f32_16x16x32_bf16 v[38:41], v[162:165], v[202:205], 0
	v_mfma_f32_16x16x32_bf16 v[34:37], v[186:189], v[202:205], 0
	v_mfma_f32_16x16x32_bf16 v[22:25], v[162:165], v[210:213], 0
	v_mfma_f32_16x16x32_bf16 v[18:21], v[186:189], v[210:213], 0
	v_mfma_f32_16x16x32_bf16 v[6:9], v[162:165], v[218:221], 0
	v_mfma_f32_16x16x32_bf16 v[2:5], v[186:189], v[218:221], 0
	v_mfma_f32_16x16x32_bf16 v[54:57], v[182:185], v[198:201], v[54:57]
	v_mfma_f32_16x16x32_bf16 v[50:53], v[190:193], v[198:201], v[50:53]
	v_mfma_f32_16x16x32_bf16 v[38:41], v[182:185], v[206:209], v[38:41]
	v_mfma_f32_16x16x32_bf16 v[34:37], v[190:193], v[206:209], v[34:37]
	v_mfma_f32_16x16x32_bf16 v[22:25], v[182:185], v[214:217], v[22:25]
	v_mfma_f32_16x16x32_bf16 v[18:21], v[190:193], v[214:217], v[18:21]
	v_mfma_f32_16x16x32_bf16 v[6:9], v[182:185], v[222:225], v[6:9]
	v_mfma_f32_16x16x32_bf16 v[2:5], v[190:193], v[222:225], v[2:5]
	s_barrier
; #define PG8_STAGE(bufoff, gbase, voff) do { _Pragma("unroll") for (int _i = 0; _i < 2; ++_i) \
;         __builtin_amdgcn_global_load_lds((const unsigned*)((const char*)(gbase) + (voff)[_i]), (LAS unsigned*)(lds + (bufoff) + ldsw + _i * 8192), 16, 0, 0); } while (0)
; #define PG8_LDA(dst, b, h) do { _Pragma("unroll") for (int m = 0; m < 4; ++m) _Pragma("unroll") for (int k = 0; k < 2; ++k) dst[m][k] = *(const LAS bf16x8*)(lds + PG8_SA(b, h) + aoff + m * 2048 + k * 1024); } while (0)
; #define PG8_LDB(dst, b, h) do { _Pragma("unroll") for (int n = 0; n < 2; ++n) _Pragma("unroll") for (int k = 0; k < 2; ++k) dst[n][k] = *(const LAS bf16x8*)(lds + PG8_SB(b, h) + boff + n * 2048 + k * 1024); } while (0)
; #define PG8_MMA(ai, bj, At, Bt) do { __builtin_amdgcn_s_setprio(1); _Pragma("unroll") for (int m = 0; m < 4; ++m) _Pragma("unroll") for (int n = 0; n < 2; ++n) _Pragma("unroll") for (int k = 0; k < 2; ++k) \
;         acc[ai][bj][m][n] = __builtin_amdgcn_mfma_f32_16x16x32_bf16(Bt[n][k], At[m][k], acc[ai][bj][m][n], 0, 0, 0); __builtin_amdgcn_s_setprio(0); } while (0)
; #define PG8_WAIT_V(n) asm volatile("s_waitcnt vmcnt(" #n ")" ::: "memory")
; #define PG8_WAIT_L(n) asm volatile("s_waitcnt lgkmcnt(" #n ")" ::: "memory")
; #define PG8_BAR __builtin_amdgcn_s_barrier()
; #define PG8_SCHED __builtin_amdgcn_sched_barrier(0)
; template <class Epi, class Sched, bool ALIGN_EPI = false, bool SP2 = false>
; __device__ __forceinline__ void gemm_phase(LAS unsigned char* lds, const Gemm g, const Sched& S, const Epi& E) {
;     ...
;             PG8_LDB(B0, 1, 0); PG8_LDB(B1, 1, 1); PG8_SCHED; PG8_LDA(At, 1, 0); PG8_STAGE(PG8_SA(0, 1), a2 + hstep, voffA);
;             PG8_WAIT_V(8); PG8_WAIT_L(0); PG8_BAR; PG8_MMA(0, 0, At, B0); PG8_MMA(0, 1, At, B1); PG8_BAR; PG8_SCHED;
;             PG8_LDA(At, 1, 1); PG8_STAGE(PG8_SB(1, 0), b3, voffB); PG8_STAGE(PG8_SB(1, 1), b3 + hstepB, voffB); PG8_STAGE(PG8_SA(1, 0), a3, voffA);
;             PG8_WAIT_V(8); PG8_WAIT_L(0); PG8_BAR; PG8_MMA(1, 0, At, B0); PG8_MMA(1, 1, At, B1); PG8_BAR; PG8_SCHED;
	s_add_i32 s22, 0, 0x18000
	s_add_i32 s23, 0, 0x1c000
	v_add_u32_e32 v78, s22, v170
	v_add_u32_e32 v168, s23, v170
	ds_read_b128 v[66:69], v78
	ds_read_b128 v[70:73], v78 offset:1024
	ds_read_b128 v[74:77], v78 offset:2048
	ds_read_b128 v[78:81], v78 offset:3072
	ds_read_b128 v[162:165], v168
	ds_read_b128 v[182:185], v168 offset:1024
	ds_read_b128 v[186:189], v168 offset:2048
	ds_read_b128 v[190:193], v168 offset:3072
	s_add_u32 s20, s52, 0x80000
	s_addc_u32 s21, s53, 0
	s_mov_b32 m0, s35
	ds_read_b128 v[194:197], v176 offset:32768
	ds_read_b128 v[198:201], v176 offset:33792
	ds_read_b128 v[202:205], v176 offset:34816
	ds_read_b128 v[206:209], v176 offset:35840
	ds_read_b128 v[210:213], v176 offset:36864
	ds_read_b128 v[214:217], v176 offset:37888
	ds_read_b128 v[218:221], v176 offset:38912
	ds_read_b128 v[222:225], v176 offset:39936
	global_load_lds_dwordx4 v152, s[20:21]
	s_mov_b32 m0, s36
	s_nop 0
	global_load_lds_dwordx4 v148, s[20:21]
	s_waitcnt vmcnt(8)
	s_waitcnt lgkmcnt(0)
	s_barrier
	s_waitcnt lgkmcnt(0)
	v_mfma_f32_16x16x32_bf16 v[142:145], v[66:69], v[194:197], v[142:145]
	v_mfma_f32_16x16x32_bf16 v[138:141], v[74:77], v[194:197], v[138:141]
	v_mfma_f32_16x16x32_bf16 v[126:129], v[66:69], v[202:205], v[126:129]
	v_mfma_f32_16x16x32_bf16 v[122:125], v[74:77], v[202:205], v[122:125]
	v_mfma_f32_16x16x32_bf16 v[110:113], v[66:69], v[210:213], v[110:113]
	v_mfma_f32_16x16x32_bf16 v[106:109], v[74:77], v[210:213], v[106:109]
	v_mfma_f32_16x16x32_bf16 v[94:97], v[66:69], v[218:221], v[94:97]
	v_mfma_f32_16x16x32_bf16 v[90:93], v[74:77], v[218:221], v[90:93]
	v_mfma_f32_16x16x32_bf16 v[142:145], v[70:73], v[198:201], v[142:145]
	v_mfma_f32_16x16x32_bf16 v[138:141], v[78:81], v[198:201], v[138:141]
	v_mfma_f32_16x16x32_bf16 v[126:129], v[70:73], v[206:209], v[126:129]
	v_mfma_f32_16x16x32_bf16 v[122:125], v[78:81], v[206:209], v[122:125]
	v_mfma_f32_16x16x32_bf16 v[110:113], v[70:73], v[214:217], v[110:113]
	v_mfma_f32_16x16x32_bf16 v[106:109], v[78:81], v[214:217], v[106:109]
	v_mfma_f32_16x16x32_bf16 v[94:97], v[70:73], v[222:225], v[94:97]
	v_mfma_f32_16x16x32_bf16 v[90:93], v[78:81], v[222:225], v[90:93]
	v_mfma_f32_16x16x32_bf16 v[134:137], v[162:165], v[194:197], v[134:137]
	v_mfma_f32_16x16x32_bf16 v[130:133], v[186:189], v[194:197], v[130:133]
	v_mfma_f32_16x16x32_bf16 v[118:121], v[162:165], v[202:205], v[118:121]
	v_mfma_f32_16x16x32_bf16 v[114:117], v[186:189], v[202:205], v[114:117]
	v_mfma_f32_16x16x32_bf16 v[102:105], v[162:165], v[210:213], v[102:105]
	v_mfma_f32_16x16x32_bf16 v[98:101], v[186:189], v[210:213], v[98:101]
	v_mfma_f32_16x16x32_bf16 v[86:89], v[162:165], v[218:221], v[86:89]
	v_mfma_f32_16x16x32_bf16 v[82:85], v[186:189], v[218:221], v[82:85]
	v_mfma_f32_16x16x32_bf16 v[134:137], v[182:185], v[198:201], v[134:137]
	v_mfma_f32_16x16x32_bf16 v[130:133], v[190:193], v[198:201], v[130:133]
	v_mfma_f32_16x16x32_bf16 v[118:121], v[182:185], v[206:209], v[118:121]
	v_mfma_f32_16x16x32_bf16 v[114:117], v[190:193], v[206:209], v[114:117]
	v_mfma_f32_16x16x32_bf16 v[102:105], v[182:185], v[214:217], v[102:105]
	v_mfma_f32_16x16x32_bf16 v[98:101], v[190:193], v[214:217], v[98:101]
	v_mfma_f32_16x16x32_bf16 v[86:89], v[182:185], v[222:225], v[86:89]
	v_mfma_f32_16x16x32_bf16 v[82:85], v[190:193], v[222:225], v[82:85]
	s_barrier
	s_add_u32 s98, s50, 0x80
	s_addc_u32 s99, s51, 0
	s_add_u32 s100, s52, 0x80
	s_addc_u32 s101, s53, 0
	s_add_i32 s20, s22, s27
	s_mov_b32 m0, s20
	ds_read_b128 v[194:197], v176 offset:49152
	ds_read_b128 v[198:201], v176 offset:50176
	ds_read_b128 v[202:205], v176 offset:51200
	ds_read_b128 v[206:209], v176 offset:52224
	ds_read_b128 v[210:213], v176 offset:53248
	ds_read_b128 v[214:217], v176 offset:54272
	ds_read_b128 v[218:221], v176 offset:55296
	ds_read_b128 v[222:225], v176 offset:56320
	global_load_lds_dwordx4 v150, s[98:99]
	s_add_i32 m0, s20, 0x2000
	s_add_u32 s20, s50, 0x80080
	s_addc_u32 s21, s51, 0
	s_add_i32 s22, s23, s27
	global_load_lds_dwordx4 v146, s[98:99]
	s_mov_b32 m0, s22
	s_nop 0
	global_load_lds_dwordx4 v150, s[20:21]
	s_add_i32 m0, s22, 0x2000
	s_nop 0
	global_load_lds_dwordx4 v146, s[20:21]
	s_mov_b32 m0, s55
	s_nop 0
	global_load_lds_dwordx4 v152, s[100:101]
	s_mov_b32 m0, s56
	s_nop 0
	global_load_lds_dwordx4 v148, s[100:101]
	s_waitcnt vmcnt(8)
	s_waitcnt lgkmcnt(0)
	s_barrier
	s_waitcnt lgkmcnt(0)
	v_mfma_f32_16x16x32_bf16 v[62:65], v[66:69], v[194:197], v[62:65]
	v_mfma_f32_16x16x32_bf16 v[58:61], v[74:77], v[194:197], v[58:61]
	v_mfma_f32_16x16x32_bf16 v[46:49], v[66:69], v[202:205], v[46:49]
	v_mfma_f32_16x16x32_bf16 v[42:45], v[74:77], v[202:205], v[42:45]
	v_mfma_f32_16x16x32_bf16 v[30:33], v[66:69], v[210:213], v[30:33]
	v_mfma_f32_16x16x32_bf16 v[26:29], v[74:77], v[210:213], v[26:29]
	v_mfma_f32_16x16x32_bf16 v[14:17], v[66:69], v[218:221], v[14:17]
	v_mfma_f32_16x16x32_bf16 v[10:13], v[74:77], v[218:221], v[10:13]
	v_mfma_f32_16x16x32_bf16 v[62:65], v[70:73], v[198:201], v[62:65]
	v_mfma_f32_16x16x32_bf16 v[58:61], v[78:81], v[198:201], v[58:61]
	v_mfma_f32_16x16x32_bf16 v[46:49], v[70:73], v[206:209], v[46:49]
	v_mfma_f32_16x16x32_bf16 v[42:45], v[78:81], v[206:209], v[42:45]
	v_mfma_f32_16x16x32_bf16 v[30:33], v[70:73], v[214:217], v[30:33]
	v_mfma_f32_16x16x32_bf16 v[26:29], v[78:81], v[214:217], v[26:29]
	v_mfma_f32_16x16x32_bf16 v[14:17], v[70:73], v[222:225], v[14:17]
	v_mfma_f32_16x16x32_bf16 v[10:13], v[78:81], v[222:225], v[10:13]
	v_mfma_f32_16x16x32_bf16 v[54:57], v[162:165], v[194:197], v[54:57]
	v_mfma_f32_16x16x32_bf16 v[50:53], v[186:189], v[194:197], v[50:53]
	v_mfma_f32_16x16x32_bf16 v[38:41], v[162:165], v[202:205], v[38:41]
	v_mfma_f32_16x16x32_bf16 v[34:37], v[186:189], v[202:205], v[34:37]
	v_mfma_f32_16x16x32_bf16 v[22:25], v[162:165], v[210:213], v[22:25]
	v_mfma_f32_16x16x32_bf16 v[18:21], v[186:189], v[210:213], v[18:21]
	v_mfma_f32_16x16x32_bf16 v[6:9], v[162:165], v[218:221], v[6:9]
	v_mfma_f32_16x16x32_bf16 v[2:5], v[186:189], v[218:221], v[2:5]
	v_mfma_f32_16x16x32_bf16 v[54:57], v[182:185], v[198:201], v[54:57]
	v_mfma_f32_16x16x32_bf16 v[50:53], v[190:193], v[198:201], v[50:53]
	v_mfma_f32_16x16x32_bf16 v[38:41], v[182:185], v[206:209], v[38:41]
	v_mfma_f32_16x16x32_bf16 v[34:37], v[190:193], v[206:209], v[34:37]
	v_mfma_f32_16x16x32_bf16 v[22:25], v[182:185], v[214:217], v[22:25]
	v_mfma_f32_16x16x32_bf16 v[18:21], v[190:193], v[214:217], v[18:21]
	v_mfma_f32_16x16x32_bf16 v[6:9], v[182:185], v[222:225], v[6:9]
	v_mfma_f32_16x16x32_bf16 v[2:5], v[190:193], v[222:225], v[2:5]
	s_barrier
	s_add_i32 s19, s19, 2
	s_add_u32 s16, s16, 0x100
	s_addc_u32 s17, s17, 0
	s_add_u32 s15, s15, 0x100
	s_addc_u32 s18, s18, 0
	s_cmp_gt_u32 s19, 29
; #define PG8_STAGE(bufoff, gbase, voff) do { _Pragma("unroll") for (int _i = 0; _i < 2; ++_i) \
;         __builtin_amdgcn_global_load_lds((const unsigned*)((const char*)(gbase) + (voff)[_i]), (LAS unsigned*)(lds + (bufoff) + ldsw + _i * 8192), 16, 0, 0); } while (0)
; #define PG8_LDA(dst, b, h) do { _Pragma("unroll") for (int m = 0; m < 4; ++m) _Pragma("unroll") for (int k = 0; k < 2; ++k) dst[m][k] = *(const LAS bf16x8*)(lds + PG8_SA(b, h) + aoff + m * 2048 + k * 1024); } while (0)
; #define PG8_LDB(dst, b, h) do { _Pragma("unroll") for (int n = 0; n < 2; ++n) _Pragma("unroll") for (int k = 0; k < 2; ++k) dst[n][k] = *(const LAS bf16x8*)(lds + PG8_SB(b, h) + boff + n * 2048 + k * 1024); } while (0)
; #define PG8_MMA(ai, bj, At, Bt) do { __builtin_amdgcn_s_setprio(1); _Pragma("unroll") for (int m = 0; m < 4; ++m) _Pragma("unroll") for (int n = 0; n < 2; ++n) _Pragma("unroll") for (int k = 0; k < 2; ++k) \
;         acc[ai][bj][m][n] = __builtin_amdgcn_mfma_f32_16x16x32_bf16(Bt[n][k], At[m][k], acc[ai][bj][m][n], 0, 0, 0); __builtin_amdgcn_s_setprio(0); } while (0)
; #define PG8_WAIT_V(n) asm volatile("s_waitcnt vmcnt(" #n ")" ::: "memory")
; #define PG8_WAIT_L(n) asm volatile("s_waitcnt lgkmcnt(" #n ")" ::: "memory")
; #define PG8_BAR __builtin_amdgcn_s_barrier()
; template <class Epi, class Sched, bool ALIGN_EPI = false, bool SP2 = false>
; __device__ __forceinline__ void gemm_phase(LAS unsigned char* lds, const Gemm g, const Sched& S, const Epi& E) {
;     ...
;             const bool last = (t == nt - 2);
;             const char* a1 = cA + (size_t)(t + 1) * kstep;
;             const char* a2 = last ? nA : cA + (size_t)(t + 2) * kstep; const char* b2 = last ? nB : cB + (size_t)(t + 2) * kstep;
;             const char* a3 = a2 + kstep; const char* b3 = b2 + kstep;
;             if (last && has_next) S.a_ready(nxt);
;             if constexpr (SP2) {
;             PG8_LDB(B0, 0, 0); PG8_LDB(B1, 0, 1); PG8_SCHED; PG8_LDA(At, 0, 0); PG8_STAGE(PG8_SA(1, 1), a1 + hstep, voffA);
;             PG8_WAIT_V(8); PG8_WAIT_L(0); PG8_BAR; PG8_MMA(0, 0, At, B0); PG8_MMA(0, 1, At, B1); PG8_BAR; PG8_SCHED;
;             PG8_LDA(At, 0, 1); PG8_STAGE(PG8_SB(0, 0), b2, voffB); PG8_STAGE(PG8_SB(0, 1), b2 + hstepB, voffB); PG8_STAGE(PG8_SA(0, 0), a2, voffA);
;             PG8_WAIT_V(8); PG8_WAIT_L(0); PG8_BAR; PG8_MMA(1, 0, At, B0); PG8_MMA(1, 1, At, B1); PG8_BAR; PG8_SCHED;
.LBB0_188:
	ds_read_b128 v[66:69], v174
	ds_read_b128 v[70:73], v174 offset:1024
	ds_read_b128 v[74:77], v174 offset:2048
	ds_read_b128 v[78:81], v174 offset:3072
	ds_read_b128 v[162:165], v175
	ds_read_b128 v[182:185], v175 offset:1024
	ds_read_b128 v[186:189], v175 offset:2048
	ds_read_b128 v[190:193], v175 offset:3072
	s_add_u32 s20, s16, 0xfff80080
	s_addc_u32 s21, s17, -1
	s_cmp_eq_u32 s19, 28
	s_cselect_b32 s53, s3, s21
	s_cselect_b32 s52, s12, s20
	s_cselect_b32 s51, s13, s18
	s_cselect_b32 s50, s14, s15
	s_add_i32 m0, s33, 0xc000
	ds_read_b128 v[194:197], v176
	ds_read_b128 v[198:201], v176 offset:1024
	ds_read_b128 v[202:205], v176 offset:2048
	ds_read_b128 v[206:209], v176 offset:3072
	ds_read_b128 v[210:213], v176 offset:4096
	ds_read_b128 v[214:217], v176 offset:5120
	ds_read_b128 v[218:221], v176 offset:6144
	ds_read_b128 v[222:225], v176 offset:7168
	global_load_lds_dwordx4 v154, s[16:17]
	s_add_i32 m0, s33, 0xe000
	s_nop 0
	global_load_lds_dwordx4 v156, s[16:17]
	s_waitcnt vmcnt(8)
	s_waitcnt lgkmcnt(0)
	s_barrier
	s_waitcnt lgkmcnt(0)
	v_mfma_f32_16x16x32_bf16 v[142:145], v[66:69], v[194:197], v[142:145]
	v_mfma_f32_16x16x32_bf16 v[138:141], v[74:77], v[194:197], v[138:141]
	v_mfma_f32_16x16x32_bf16 v[126:129], v[66:69], v[202:205], v[126:129]
	v_mfma_f32_16x16x32_bf16 v[122:125], v[74:77], v[202:205], v[122:125]
	v_mfma_f32_16x16x32_bf16 v[110:113], v[66:69], v[210:213], v[110:113]
	v_mfma_f32_16x16x32_bf16 v[106:109], v[74:77], v[210:213], v[106:109]
	v_mfma_f32_16x16x32_bf16 v[94:97], v[66:69], v[218:221], v[94:97]
	v_mfma_f32_16x16x32_bf16 v[90:93], v[74:77], v[218:221], v[90:93]
	v_mfma_f32_16x16x32_bf16 v[142:145], v[70:73], v[198:201], v[142:145]
	v_mfma_f32_16x16x32_bf16 v[138:141], v[78:81], v[198:201], v[138:141]
	v_mfma_f32_16x16x32_bf16 v[126:129], v[70:73], v[206:209], v[126:129]
	v_mfma_f32_16x16x32_bf16 v[122:125], v[78:81], v[206:209], v[122:125]
	v_mfma_f32_16x16x32_bf16 v[110:113], v[70:73], v[214:217], v[110:113]
	v_mfma_f32_16x16x32_bf16 v[106:109], v[78:81], v[214:217], v[106:109]
	v_mfma_f32_16x16x32_bf16 v[94:97], v[70:73], v[222:225], v[94:97]
	v_mfma_f32_16x16x32_bf16 v[90:93], v[78:81], v[222:225], v[90:93]
	v_mfma_f32_16x16x32_bf16 v[134:137], v[162:165], v[194:197], v[134:137]
	v_mfma_f32_16x16x32_bf16 v[130:133], v[186:189], v[194:197], v[130:133]
	v_mfma_f32_16x16x32_bf16 v[118:121], v[162:165], v[202:205], v[118:121]
	v_mfma_f32_16x16x32_bf16 v[114:117], v[186:189], v[202:205], v[114:117]
	v_mfma_f32_16x16x32_bf16 v[102:105], v[162:165], v[210:213], v[102:105]
	v_mfma_f32_16x16x32_bf16 v[98:101], v[186:189], v[210:213], v[98:101]
	v_mfma_f32_16x16x32_bf16 v[86:89], v[162:165], v[218:221], v[86:89]
	v_mfma_f32_16x16x32_bf16 v[82:85], v[186:189], v[218:221], v[82:85]
	v_mfma_f32_16x16x32_bf16 v[134:137], v[182:185], v[198:201], v[134:137]
	v_mfma_f32_16x16x32_bf16 v[130:133], v[190:193], v[198:201], v[130:133]
	v_mfma_f32_16x16x32_bf16 v[118:121], v[182:185], v[206:209], v[118:121]
	v_mfma_f32_16x16x32_bf16 v[114:117], v[190:193], v[206:209], v[114:117]
	v_mfma_f32_16x16x32_bf16 v[102:105], v[182:185], v[214:217], v[102:105]
	v_mfma_f32_16x16x32_bf16 v[98:101], v[190:193], v[214:217], v[98:101]
	v_mfma_f32_16x16x32_bf16 v[86:89], v[182:185], v[222:225], v[86:89]
	v_mfma_f32_16x16x32_bf16 v[82:85], v[190:193], v[222:225], v[82:85]
	s_barrier
	s_add_i32 s20, s57, s27
	s_mov_b32 m0, s20
	ds_read_b128 v[194:197], v176 offset:16384
	ds_read_b128 v[198:201], v176 offset:17408
	ds_read_b128 v[202:205], v176 offset:18432
	ds_read_b128 v[206:209], v176 offset:19456
	ds_read_b128 v[210:213], v176 offset:20480
	ds_read_b128 v[214:217], v176 offset:21504
	ds_read_b128 v[218:221], v176 offset:22528
	ds_read_b128 v[222:225], v176 offset:23552
	global_load_lds_dwordx4 v150, s[50:51]
	s_add_i32 m0, s20, 0x2000
	s_add_u32 s20, s50, 0x80000
	s_addc_u32 s21, s51, 0
	s_add_i32 s22, s58, s27
	global_load_lds_dwordx4 v146, s[50:51]
	s_mov_b32 m0, s22
	global_load_lds_dwordx4 v150, s[20:21]
	s_add_i32 m0, s22, 0x2000
	s_nop 0
	global_load_lds_dwordx4 v146, s[20:21]
	s_mov_b32 m0, s33
	s_nop 0
	global_load_lds_dwordx4 v152, s[52:53]
	s_mov_b32 m0, s34
	s_nop 0
	global_load_lds_dwordx4 v148, s[52:53]
	s_waitcnt vmcnt(8)
	s_waitcnt lgkmcnt(0)
	s_barrier
	s_waitcnt lgkmcnt(0)
	v_mfma_f32_16x16x32_bf16 v[62:65], v[66:69], v[194:197], v[62:65]
	v_mfma_f32_16x16x32_bf16 v[58:61], v[74:77], v[194:197], v[58:61]
	v_mfma_f32_16x16x32_bf16 v[46:49], v[66:69], v[202:205], v[46:49]
	v_mfma_f32_16x16x32_bf16 v[42:45], v[74:77], v[202:205], v[42:45]
	v_mfma_f32_16x16x32_bf16 v[30:33], v[66:69], v[210:213], v[30:33]
	v_mfma_f32_16x16x32_bf16 v[26:29], v[74:77], v[210:213], v[26:29]
	v_mfma_f32_16x16x32_bf16 v[14:17], v[66:69], v[218:221], v[14:17]
	v_mfma_f32_16x16x32_bf16 v[10:13], v[74:77], v[218:221], v[10:13]
	v_mfma_f32_16x16x32_bf16 v[62:65], v[70:73], v[198:201], v[62:65]
	v_mfma_f32_16x16x32_bf16 v[58:61], v[78:81], v[198:201], v[58:61]
	v_mfma_f32_16x16x32_bf16 v[46:49], v[70:73], v[206:209], v[46:49]
	v_mfma_f32_16x16x32_bf16 v[42:45], v[78:81], v[206:209], v[42:45]
	v_mfma_f32_16x16x32_bf16 v[30:33], v[70:73], v[214:217], v[30:33]
	v_mfma_f32_16x16x32_bf16 v[26:29], v[78:81], v[214:217], v[26:29]
	v_mfma_f32_16x16x32_bf16 v[14:17], v[70:73], v[222:225], v[14:17]
	v_mfma_f32_16x16x32_bf16 v[10:13], v[78:81], v[222:225], v[10:13]
	v_mfma_f32_16x16x32_bf16 v[54:57], v[162:165], v[194:197], v[54:57]
	v_mfma_f32_16x16x32_bf16 v[50:53], v[186:189], v[194:197], v[50:53]
	v_mfma_f32_16x16x32_bf16 v[38:41], v[162:165], v[202:205], v[38:41]
	v_mfma_f32_16x16x32_bf16 v[34:37], v[186:189], v[202:205], v[34:37]
	v_mfma_f32_16x16x32_bf16 v[22:25], v[162:165], v[210:213], v[22:25]
	v_mfma_f32_16x16x32_bf16 v[18:21], v[186:189], v[210:213], v[18:21]
	v_mfma_f32_16x16x32_bf16 v[6:9], v[162:165], v[218:221], v[6:9]
	v_mfma_f32_16x16x32_bf16 v[2:5], v[186:189], v[218:221], v[2:5]
	v_mfma_f32_16x16x32_bf16 v[54:57], v[182:185], v[198:201], v[54:57]
	v_mfma_f32_16x16x32_bf16 v[50:53], v[190:193], v[198:201], v[50:53]
	v_mfma_f32_16x16x32_bf16 v[38:41], v[182:185], v[206:209], v[38:41]
	v_mfma_f32_16x16x32_bf16 v[34:37], v[190:193], v[206:209], v[34:37]
	v_mfma_f32_16x16x32_bf16 v[22:25], v[182:185], v[214:217], v[22:25]
	v_mfma_f32_16x16x32_bf16 v[18:21], v[190:193], v[214:217], v[18:21]
	v_mfma_f32_16x16x32_bf16 v[6:9], v[182:185], v[222:225], v[6:9]
	v_mfma_f32_16x16x32_bf16 v[2:5], v[190:193], v[222:225], v[2:5]
	s_barrier
; #define PG8_STAGE(bufoff, gbase, voff) do { _Pragma("unroll") for (int _i = 0; _i < 2; ++_i) \
;         __builtin_amdgcn_global_load_lds((const unsigned*)((const char*)(gbase) + (voff)[_i]), (LAS unsigned*)(lds + (bufoff) + ldsw + _i * 8192), 16, 0, 0); } while (0)
; #define PG8_LDA(dst, b, h) do { _Pragma("unroll") for (int m = 0; m < 4; ++m) _Pragma("unroll") for (int k = 0; k < 2; ++k) dst[m][k] = *(const LAS bf16x8*)(lds + PG8_SA(b, h) + aoff + m * 2048 + k * 1024); } while (0)
; #define PG8_LDB(dst, b, h) do { _Pragma("unroll") for (int n = 0; n < 2; ++n) _Pragma("unroll") for (int k = 0; k < 2; ++k) dst[n][k] = *(const LAS bf16x8*)(lds + PG8_SB(b, h) + boff + n * 2048 + k * 1024); } while (0)
; #define PG8_MMA(ai, bj, At, Bt) do { __builtin_amdgcn_s_setprio(1); _Pragma("unroll") for (int m = 0; m < 4; ++m) _Pragma("unroll") for (int n = 0; n < 2; ++n) _Pragma("unroll") for (int k = 0; k < 2; ++k) \
;         acc[ai][bj][m][n] = __builtin_amdgcn_mfma_f32_16x16x32_bf16(Bt[n][k], At[m][k], acc[ai][bj][m][n], 0, 0, 0); __builtin_amdgcn_s_setprio(0); } while (0)
; #define PG8_WAIT_V(n) asm volatile("s_waitcnt vmcnt(" #n ")" ::: "memory")
; #define PG8_WAIT_L(n) asm volatile("s_waitcnt lgkmcnt(" #n ")" ::: "memory")
; #define PG8_BAR __builtin_amdgcn_s_barrier()
; #define PG8_SCHED __builtin_amdgcn_sched_barrier(0)
; template <class Epi, class Sched, bool ALIGN_EPI = false, bool SP2 = false>
; __device__ __forceinline__ void gemm_phase(LAS unsigned char* lds, const Gemm g, const Sched& S, const Epi& E) {
;     ...
;             PG8_LDB(B0, 1, 0); PG8_LDB(B1, 1, 1); PG8_SCHED; PG8_LDA(At, 1, 0); PG8_STAGE(PG8_SA(0, 1), a2 + hstep, voffA);
;             PG8_WAIT_V(8); PG8_WAIT_L(0); PG8_BAR; PG8_MMA(0, 0, At, B0); PG8_MMA(0, 1, At, B1); PG8_BAR; PG8_SCHED;
;             PG8_LDA(At, 1, 1); PG8_STAGE(PG8_SB(1, 0), b3, voffB); PG8_STAGE(PG8_SB(1, 1), b3 + hstepB, voffB); PG8_STAGE(PG8_SA(1, 0), a3, voffA);
;             PG8_WAIT_V(8); PG8_WAIT_L(0); PG8_BAR; PG8_MMA(1, 0, At, B0); PG8_MMA(1, 1, At, B1); PG8_BAR; PG8_SCHED;
	s_add_i32 s22, 0, 0x18000
	s_add_i32 s23, 0, 0x1c000
	v_add_u32_e32 v78, s22, v170
	v_add_u32_e32 v168, s23, v170
	ds_read_b128 v[66:69], v78
	ds_read_b128 v[70:73], v78 offset:1024
	ds_read_b128 v[74:77], v78 offset:2048
	ds_read_b128 v[78:81], v78 offset:3072
	ds_read_b128 v[162:165], v168
	ds_read_b128 v[182:185], v168 offset:1024
	ds_read_b128 v[186:189], v168 offset:2048
	ds_read_b128 v[190:193], v168 offset:3072
	s_add_u32 s20, s52, 0x80000
	s_addc_u32 s21, s53, 0
	s_mov_b32 m0, s35
	ds_read_b128 v[194:197], v176 offset:32768
	ds_read_b128 v[198:201], v176 offset:33792
	ds_read_b128 v[202:205], v176 offset:34816
	ds_read_b128 v[206:209], v176 offset:35840
	ds_read_b128 v[210:213], v176 offset:36864
	ds_read_b128 v[214:217], v176 offset:37888
	ds_read_b128 v[218:221], v176 offset:38912
	ds_read_b128 v[222:225], v176 offset:39936
	global_load_lds_dwordx4 v152, s[20:21]
	s_mov_b32 m0, s36
	s_nop 0
	global_load_lds_dwordx4 v148, s[20:21]
	s_waitcnt vmcnt(8)
	s_waitcnt lgkmcnt(0)
	s_barrier
	s_waitcnt lgkmcnt(0)
	v_mfma_f32_16x16x32_bf16 v[142:145], v[66:69], v[194:197], v[142:145]
	v_mfma_f32_16x16x32_bf16 v[138:141], v[74:77], v[194:197], v[138:141]
	v_mfma_f32_16x16x32_bf16 v[126:129], v[66:69], v[202:205], v[126:129]
	v_mfma_f32_16x16x32_bf16 v[122:125], v[74:77], v[202:205], v[122:125]
	v_mfma_f32_16x16x32_bf16 v[110:113], v[66:69], v[210:213], v[110:113]
	v_mfma_f32_16x16x32_bf16 v[106:109], v[74:77], v[210:213], v[106:109]
	v_mfma_f32_16x16x32_bf16 v[94:97], v[66:69], v[218:221], v[94:97]
	v_mfma_f32_16x16x32_bf16 v[90:93], v[74:77], v[218:221], v[90:93]
	v_mfma_f32_16x16x32_bf16 v[142:145], v[70:73], v[198:201], v[142:145]
	v_mfma_f32_16x16x32_bf16 v[138:141], v[78:81], v[198:201], v[138:141]
	v_mfma_f32_16x16x32_bf16 v[126:129], v[70:73], v[206:209], v[126:129]
	v_mfma_f32_16x16x32_bf16 v[122:125], v[78:81], v[206:209], v[122:125]
	v_mfma_f32_16x16x32_bf16 v[110:113], v[70:73], v[214:217], v[110:113]
	v_mfma_f32_16x16x32_bf16 v[106:109], v[78:81], v[214:217], v[106:109]
	v_mfma_f32_16x16x32_bf16 v[94:97], v[70:73], v[222:225], v[94:97]
	v_mfma_f32_16x16x32_bf16 v[90:93], v[78:81], v[222:225], v[90:93]
	v_mfma_f32_16x16x32_bf16 v[134:137], v[162:165], v[194:197], v[134:137]
	v_mfma_f32_16x16x32_bf16 v[130:133], v[186:189], v[194:197], v[130:133]
	v_mfma_f32_16x16x32_bf16 v[118:121], v[162:165], v[202:205], v[118:121]
	v_mfma_f32_16x16x32_bf16 v[114:117], v[186:189], v[202:205], v[114:117]
	v_mfma_f32_16x16x32_bf16 v[102:105], v[162:165], v[210:213], v[102:105]
	v_mfma_f32_16x16x32_bf16 v[98:101], v[186:189], v[210:213], v[98:101]
	v_mfma_f32_16x16x32_bf16 v[86:89], v[162:165], v[218:221], v[86:89]
	v_mfma_f32_16x16x32_bf16 v[82:85], v[186:189], v[218:221], v[82:85]
	v_mfma_f32_16x16x32_bf16 v[134:137], v[182:185], v[198:201], v[134:137]
	v_mfma_f32_16x16x32_bf16 v[130:133], v[190:193], v[198:201], v[130:133]
	v_mfma_f32_16x16x32_bf16 v[118:121], v[182:185], v[206:209], v[118:121]
	v_mfma_f32_16x16x32_bf16 v[114:117], v[190:193], v[206:209], v[114:117]
	v_mfma_f32_16x16x32_bf16 v[102:105], v[182:185], v[214:217], v[102:105]
	v_mfma_f32_16x16x32_bf16 v[98:101], v[190:193], v[214:217], v[98:101]
	v_mfma_f32_16x16x32_bf16 v[86:89], v[182:185], v[222:225], v[86:89]
	v_mfma_f32_16x16x32_bf16 v[82:85], v[190:193], v[222:225], v[82:85]
	s_barrier
	s_add_u32 s98, s50, 0x80
	s_addc_u32 s99, s51, 0
	s_add_u32 s100, s52, 0x80
	s_addc_u32 s101, s53, 0
	s_add_i32 s20, s22, s27
	s_mov_b32 m0, s20
	ds_read_b128 v[194:197], v176 offset:49152
	ds_read_b128 v[198:201], v176 offset:50176
	ds_read_b128 v[202:205], v176 offset:51200
	ds_read_b128 v[206:209], v176 offset:52224
	ds_read_b128 v[210:213], v176 offset:53248
	ds_read_b128 v[214:217], v176 offset:54272
	ds_read_b128 v[218:221], v176 offset:55296
	ds_read_b128 v[222:225], v176 offset:56320
	global_load_lds_dwordx4 v150, s[98:99]
	s_add_i32 m0, s20, 0x2000
	s_add_u32 s20, s50, 0x80080
	s_addc_u32 s21, s51, 0
	s_add_i32 s22, s23, s27
	global_load_lds_dwordx4 v146, s[98:99]
	s_mov_b32 m0, s22
	s_nop 0
	global_load_lds_dwordx4 v150, s[20:21]
	s_add_i32 m0, s22, 0x2000
	s_nop 0
	global_load_lds_dwordx4 v146, s[20:21]
	s_mov_b32 m0, s55
	s_nop 0
	global_load_lds_dwordx4 v152, s[100:101]
	s_mov_b32 m0, s56
	s_nop 0
	global_load_lds_dwordx4 v148, s[100:101]
	s_waitcnt vmcnt(8)
	s_waitcnt lgkmcnt(0)
	s_barrier
	s_waitcnt lgkmcnt(0)
	v_mfma_f32_16x16x32_bf16 v[62:65], v[66:69], v[194:197], v[62:65]
	v_mfma_f32_16x16x32_bf16 v[58:61], v[74:77], v[194:197], v[58:61]
	v_mfma_f32_16x16x32_bf16 v[46:49], v[66:69], v[202:205], v[46:49]
	v_mfma_f32_16x16x32_bf16 v[42:45], v[74:77], v[202:205], v[42:45]
	v_mfma_f32_16x16x32_bf16 v[30:33], v[66:69], v[210:213], v[30:33]
	v_mfma_f32_16x16x32_bf16 v[26:29], v[74:77], v[210:213], v[26:29]
	v_mfma_f32_16x16x32_bf16 v[14:17], v[66:69], v[218:221], v[14:17]
	v_mfma_f32_16x16x32_bf16 v[10:13], v[74:77], v[218:221], v[10:13]
	v_mfma_f32_16x16x32_bf16 v[62:65], v[70:73], v[198:201], v[62:65]
	v_mfma_f32_16x16x32_bf16 v[58:61], v[78:81], v[198:201], v[58:61]
	v_mfma_f32_16x16x32_bf16 v[46:49], v[70:73], v[206:209], v[46:49]
	v_mfma_f32_16x16x32_bf16 v[42:45], v[78:81], v[206:209], v[42:45]
	v_mfma_f32_16x16x32_bf16 v[30:33], v[70:73], v[214:217], v[30:33]
	v_mfma_f32_16x16x32_bf16 v[26:29], v[78:81], v[214:217], v[26:29]
	v_mfma_f32_16x16x32_bf16 v[14:17], v[70:73], v[222:225], v[14:17]
	v_mfma_f32_16x16x32_bf16 v[10:13], v[78:81], v[222:225], v[10:13]
	v_mfma_f32_16x16x32_bf16 v[54:57], v[162:165], v[194:197], v[54:57]
	v_mfma_f32_16x16x32_bf16 v[50:53], v[186:189], v[194:197], v[50:53]
	v_mfma_f32_16x16x32_bf16 v[38:41], v[162:165], v[202:205], v[38:41]
	v_mfma_f32_16x16x32_bf16 v[34:37], v[186:189], v[202:205], v[34:37]
	v_mfma_f32_16x16x32_bf16 v[22:25], v[162:165], v[210:213], v[22:25]
	v_mfma_f32_16x16x32_bf16 v[18:21], v[186:189], v[210:213], v[18:21]
	v_mfma_f32_16x16x32_bf16 v[6:9], v[162:165], v[218:221], v[6:9]
	v_mfma_f32_16x16x32_bf16 v[2:5], v[186:189], v[218:221], v[2:5]
	v_mfma_f32_16x16x32_bf16 v[54:57], v[182:185], v[198:201], v[54:57]
	v_mfma_f32_16x16x32_bf16 v[50:53], v[190:193], v[198:201], v[50:53]
	v_mfma_f32_16x16x32_bf16 v[38:41], v[182:185], v[206:209], v[38:41]
	v_mfma_f32_16x16x32_bf16 v[34:37], v[190:193], v[206:209], v[34:37]
	v_mfma_f32_16x16x32_bf16 v[22:25], v[182:185], v[214:217], v[22:25]
	v_mfma_f32_16x16x32_bf16 v[18:21], v[190:193], v[214:217], v[18:21]
	v_mfma_f32_16x16x32_bf16 v[6:9], v[182:185], v[222:225], v[6:9]
	v_mfma_f32_16x16x32_bf16 v[2:5], v[190:193], v[222:225], v[2:5]
	s_barrier
	s_add_i32 s19, s19, 2
	s_add_u32 s16, s16, 0x100
	s_addc_u32 s17, s17, 0
	s_add_u32 s15, s15, 0x100
	s_addc_u32 s18, s18, 0
	s_cmp_gt_u32 s19, 29
	s_cbranch_scc0 .LBB0_188
	s_setprio 0
	s_and_b64 vcc, exec, s[40:41]
	s_cbranch_vccz .LBB0_191
	s_barrier

; #define PG8_STAGE(bufoff, gbase, voff) do { _Pragma("unroll") for (int _i = 0; _i < 2; ++_i) \
;         __builtin_amdgcn_global_load_lds((const unsigned*)((const char*)(gbase) + (voff)[_i]), (LAS unsigned*)(lds + (bufoff) + ldsw + _i * 8192), 16, 0, 0); } while (0)
; #define PG8_LDA(dst, b, h) do { _Pragma("unroll") for (int m = 0; m < 4; ++m) _Pragma("unroll") for (int k = 0; k < 2; ++k) dst[m][k] = *(const LAS bf16x8*)(lds + PG8_SA(b, h) + aoff + m * 2048 + k * 1024); } while (0)
; #define PG8_LDB(dst, b, h) do { _Pragma("unroll") for (int n = 0; n < 2; ++n) _Pragma("unroll") for (int k = 0; k < 2; ++k) dst[n][k] = *(const LAS bf16x8*)(lds + PG8_SB(b, h) + boff + n * 2048 + k * 1024); } while (0)
; #define PG8_MMA(ai, bj, At, Bt) do { __builtin_amdgcn_s_setprio(1); _Pragma("unroll") for (int m = 0; m < 4; ++m) _Pragma("unroll") for (int n = 0; n < 2; ++n) _Pragma("unroll") for (int k = 0; k < 2; ++k) \
;         acc[ai][bj][m][n] = __builtin_amdgcn_mfma_f32_16x16x32_bf16(Bt[n][k], At[m][k], acc[ai][bj][m][n], 0, 0, 0); __builtin_amdgcn_s_setprio(0); } while (0)
; #define PG8_WAIT_V(n) asm volatile("s_waitcnt vmcnt(" #n ")" ::: "memory")
; #define PG8_WAIT_L(n) asm volatile("s_waitcnt lgkmcnt(" #n ")" ::: "memory")
; #define PG8_BAR __builtin_amdgcn_s_barrier()
; template <class Epi, class Sched, bool ALIGN_EPI = false, bool SP2 = false>
; __device__ __forceinline__ void gemm_phase(LAS unsigned char* lds, const Gemm g, const Sched& S, const Epi& E) {
;     ...
;             const bool last = (t == nt - 2);
;             const char* a1 = cA + (size_t)(t + 1) * kstep;
;             const char* a2 = last ? nA : cA + (size_t)(t + 2) * kstep; const char* b2 = last ? nB : cB + (size_t)(t + 2) * kstep;
;             const char* a3 = a2 + kstep; const char* b3 = b2 + kstep;
;             if (last && has_next) S.a_ready(nxt);
;             if constexpr (SP2) {
;             PG8_LDB(B0, 0, 0); PG8_LDB(B1, 0, 1); PG8_SCHED; PG8_LDA(At, 0, 0); PG8_STAGE(PG8_SA(1, 1), a1 + hstep, voffA);
;             PG8_WAIT_V(8); PG8_WAIT_L(0); PG8_BAR; PG8_MMA(0, 0, At, B0); PG8_MMA(0, 1, At, B1); PG8_BAR; PG8_SCHED;
;             PG8_LDA(At, 0, 1); PG8_STAGE(PG8_SB(0, 0), b2, voffB); PG8_STAGE(PG8_SB(0, 1), b2 + hstepB, voffB); PG8_STAGE(PG8_SA(0, 0), a2, voffA);
;             PG8_WAIT_V(8); PG8_WAIT_L(0); PG8_BAR; PG8_MMA(1, 0, At, B0); PG8_MMA(1, 1, At, B1); PG8_BAR; PG8_SCHED;
.Lprio_317:
	ds_read_b128 v[130:133], v196
	ds_read_b128 v[134:137], v196 offset:1024
	ds_read_b128 v[138:141], v196 offset:2048
	ds_read_b128 v[142:145], v196 offset:3072
	ds_read_b128 v[166:169], v197
	ds_read_b128 v[170:173], v197 offset:1024
	ds_read_b128 v[174:177], v197 offset:2048
	ds_read_b128 v[178:181], v197 offset:3072
	s_add_u32 s54, s16, 0x100
	s_addc_u32 s55, s17, 0
	s_cmpk_eq_i32 s13, 0x54
	s_cselect_b32 s59, s3, s55
	s_cselect_b32 s58, s2, s54
	s_cselect_b32 s57, s53, s12
	s_cselect_b32 s56, s52, s5
	v_lshl_add_u64 v[190:191], s[16:17], 0, v[158:159]
	s_add_i32 m0, s29, 0xc000
	ds_read_b128 v[182:185], v198
	ds_read_b128 v[186:189], v198 offset:1024
	ds_read_b128 v[202:205], v198 offset:2048
	ds_read_b128 v[206:209], v198 offset:3072
	ds_read_b128 v[210:213], v198 offset:4096
	ds_read_b128 v[214:217], v198 offset:5120
	ds_read_b128 v[218:221], v198 offset:6144
	ds_read_b128 v[222:225], v198 offset:7168
	global_load_lds_dwordx4 v[190:191], off
	v_lshl_add_u64 v[190:191], s[16:17], 0, v[160:161]
	s_add_i32 m0, s29, 0xe000
	s_nop 0
	global_load_lds_dwordx4 v[190:191], off
	s_waitcnt lgkmcnt(0)
	s_barrier
	s_waitcnt lgkmcnt(0)
	v_mfma_f32_16x16x32_bf16 v[126:129], v[130:133], v[182:185], 0
	v_mfma_f32_16x16x32_bf16 v[122:125], v[138:141], v[182:185], 0
	v_mfma_f32_16x16x32_bf16 v[110:113], v[130:133], v[202:205], 0
	v_mfma_f32_16x16x32_bf16 v[106:109], v[138:141], v[202:205], 0
	v_mfma_f32_16x16x32_bf16 v[94:97], v[130:133], v[210:213], 0
	v_mfma_f32_16x16x32_bf16 v[90:93], v[138:141], v[210:213], 0
	v_mfma_f32_16x16x32_bf16 v[78:81], v[130:133], v[218:221], 0
	v_mfma_f32_16x16x32_bf16 v[74:77], v[138:141], v[218:221], 0
	v_mfma_f32_16x16x32_bf16 v[126:129], v[134:137], v[186:189], v[126:129]
	v_mfma_f32_16x16x32_bf16 v[122:125], v[142:145], v[186:189], v[122:125]
	v_mfma_f32_16x16x32_bf16 v[110:113], v[134:137], v[206:209], v[110:113]
	v_mfma_f32_16x16x32_bf16 v[106:109], v[142:145], v[206:209], v[106:109]
	v_mfma_f32_16x16x32_bf16 v[94:97], v[134:137], v[214:217], v[94:97]
	v_mfma_f32_16x16x32_bf16 v[90:93], v[142:145], v[214:217], v[90:93]
	v_mfma_f32_16x16x32_bf16 v[78:81], v[134:137], v[222:225], v[78:81]
	v_mfma_f32_16x16x32_bf16 v[74:77], v[142:145], v[222:225], v[74:77]
	v_mfma_f32_16x16x32_bf16 v[118:121], v[166:169], v[182:185], 0
	v_mfma_f32_16x16x32_bf16 v[114:117], v[174:177], v[182:185], 0
	v_mfma_f32_16x16x32_bf16 v[102:105], v[166:169], v[202:205], 0
	v_mfma_f32_16x16x32_bf16 v[98:101], v[174:177], v[202:205], 0
	v_mfma_f32_16x16x32_bf16 v[86:89], v[166:169], v[210:213], 0
	v_mfma_f32_16x16x32_bf16 v[82:85], v[174:177], v[210:213], 0
	v_mfma_f32_16x16x32_bf16 v[70:73], v[166:169], v[218:221], 0
	v_mfma_f32_16x16x32_bf16 v[66:69], v[174:177], v[218:221], 0
	v_mfma_f32_16x16x32_bf16 v[118:121], v[170:173], v[186:189], v[118:121]
	v_mfma_f32_16x16x32_bf16 v[114:117], v[178:181], v[186:189], v[114:117]
	v_mfma_f32_16x16x32_bf16 v[102:105], v[170:173], v[206:209], v[102:105]
	v_mfma_f32_16x16x32_bf16 v[98:101], v[178:181], v[206:209], v[98:101]
	v_mfma_f32_16x16x32_bf16 v[86:89], v[170:173], v[214:217], v[86:89]
	v_mfma_f32_16x16x32_bf16 v[82:85], v[178:181], v[214:217], v[82:85]
	v_mfma_f32_16x16x32_bf16 v[70:73], v[170:173], v[222:225], v[70:73]
	v_mfma_f32_16x16x32_bf16 v[66:69], v[178:181], v[222:225], v[66:69]
	s_barrier
	s_add_i32 s14, s64, s28
	s_mov_b32 m0, s14
	ds_read_b128 v[182:185], v198 offset:16384
	ds_read_b128 v[186:189], v198 offset:17408
	ds_read_b128 v[202:205], v198 offset:18432
	ds_read_b128 v[206:209], v198 offset:19456
	ds_read_b128 v[210:213], v198 offset:20480
	ds_read_b128 v[214:217], v198 offset:21504
	ds_read_b128 v[218:221], v198 offset:22528
	ds_read_b128 v[222:225], v198 offset:23552
	global_load_lds_dwordx4 v148, s[56:57]
	s_add_i32 m0, s14, 0x2000
	s_add_u32 s14, s56, 0x58000
	s_addc_u32 s15, s57, 0
	s_add_i32 s16, s65, s28
	global_load_lds_dwordx4 v152, s[56:57]
	s_mov_b32 m0, s16
	global_load_lds_dwordx4 v148, s[14:15]
	s_add_i32 m0, s16, 0x2000
	s_nop 0
	global_load_lds_dwordx4 v152, s[14:15]
	s_mov_b32 m0, s29
	s_nop 0
	global_load_lds_dwordx4 v146, s[58:59]
	s_mov_b32 m0, s30
	s_nop 0
	global_load_lds_dwordx4 v150, s[58:59]
	s_waitcnt lgkmcnt(0)
	s_barrier
	s_waitcnt lgkmcnt(0)
	v_mfma_f32_16x16x32_bf16 v[62:65], v[130:133], v[182:185], 0
	v_mfma_f32_16x16x32_bf16 v[58:61], v[138:141], v[182:185], 0
	v_mfma_f32_16x16x32_bf16 v[46:49], v[130:133], v[202:205], 0
	v_mfma_f32_16x16x32_bf16 v[42:45], v[138:141], v[202:205], 0
	v_mfma_f32_16x16x32_bf16 v[30:33], v[130:133], v[210:213], 0
	v_mfma_f32_16x16x32_bf16 v[26:29], v[138:141], v[210:213], 0
	v_mfma_f32_16x16x32_bf16 v[14:17], v[130:133], v[218:221], 0
	v_mfma_f32_16x16x32_bf16 v[10:13], v[138:141], v[218:221], 0
	v_mfma_f32_16x16x32_bf16 v[62:65], v[134:137], v[186:189], v[62:65]
	v_mfma_f32_16x16x32_bf16 v[58:61], v[142:145], v[186:189], v[58:61]
	v_mfma_f32_16x16x32_bf16 v[46:49], v[134:137], v[206:209], v[46:49]
	v_mfma_f32_16x16x32_bf16 v[42:45], v[142:145], v[206:209], v[42:45]
	v_mfma_f32_16x16x32_bf16 v[30:33], v[134:137], v[214:217], v[30:33]
	v_mfma_f32_16x16x32_bf16 v[26:29], v[142:145], v[214:217], v[26:29]
	v_mfma_f32_16x16x32_bf16 v[14:17], v[134:137], v[222:225], v[14:17]
	v_mfma_f32_16x16x32_bf16 v[10:13], v[142:145], v[222:225], v[10:13]
	v_mfma_f32_16x16x32_bf16 v[54:57], v[166:169], v[182:185], 0
	v_mfma_f32_16x16x32_bf16 v[50:53], v[174:177], v[182:185], 0
	v_mfma_f32_16x16x32_bf16 v[38:41], v[166:169], v[202:205], 0
	v_mfma_f32_16x16x32_bf16 v[34:37], v[174:177], v[202:205], 0
	v_mfma_f32_16x16x32_bf16 v[22:25], v[166:169], v[210:213], 0
	v_mfma_f32_16x16x32_bf16 v[18:21], v[174:177], v[210:213], 0
	v_mfma_f32_16x16x32_bf16 v[6:9], v[166:169], v[218:221], 0
	v_mfma_f32_16x16x32_bf16 v[2:5], v[174:177], v[218:221], 0
	v_mfma_f32_16x16x32_bf16 v[54:57], v[170:173], v[186:189], v[54:57]
	v_mfma_f32_16x16x32_bf16 v[50:53], v[178:181], v[186:189], v[50:53]
	v_mfma_f32_16x16x32_bf16 v[38:41], v[170:173], v[206:209], v[38:41]
	v_mfma_f32_16x16x32_bf16 v[34:37], v[178:181], v[206:209], v[34:37]
	v_mfma_f32_16x16x32_bf16 v[22:25], v[170:173], v[214:217], v[22:25]
	v_mfma_f32_16x16x32_bf16 v[18:21], v[178:181], v[214:217], v[18:21]
	v_mfma_f32_16x16x32_bf16 v[6:9], v[170:173], v[222:225], v[6:9]
	v_mfma_f32_16x16x32_bf16 v[2:5], v[178:181], v[222:225], v[2:5]
	s_barrier
; #define PG8_STAGE(bufoff, gbase, voff) do { _Pragma("unroll") for (int _i = 0; _i < 2; ++_i) \
;         __builtin_amdgcn_global_load_lds((const unsigned*)((const char*)(gbase) + (voff)[_i]), (LAS unsigned*)(lds + (bufoff) + ldsw + _i * 8192), 16, 0, 0); } while (0)
; #define PG8_LDA(dst, b, h) do { _Pragma("unroll") for (int m = 0; m < 4; ++m) _Pragma("unroll") for (int k = 0; k < 2; ++k) dst[m][k] = *(const LAS bf16x8*)(lds + PG8_SA(b, h) + aoff + m * 2048 + k * 1024); } while (0)
; #define PG8_LDB(dst, b, h) do { _Pragma("unroll") for (int n = 0; n < 2; ++n) _Pragma("unroll") for (int k = 0; k < 2; ++k) dst[n][k] = *(const LAS bf16x8*)(lds + PG8_SB(b, h) + boff + n * 2048 + k * 1024); } while (0)
; #define PG8_MMA(ai, bj, At, Bt) do { __builtin_amdgcn_s_setprio(1); _Pragma("unroll") for (int m = 0; m < 4; ++m) _Pragma("unroll") for (int n = 0; n < 2; ++n) _Pragma("unroll") for (int k = 0; k < 2; ++k) \
;         acc[ai][bj][m][n] = __builtin_amdgcn_mfma_f32_16x16x32_bf16(Bt[n][k], At[m][k], acc[ai][bj][m][n], 0, 0, 0); __builtin_amdgcn_s_setprio(0); } while (0)
; #define PG8_WAIT_V(n) asm volatile("s_waitcnt vmcnt(" #n ")" ::: "memory")
; #define PG8_WAIT_L(n) asm volatile("s_waitcnt lgkmcnt(" #n ")" ::: "memory")
; #define PG8_BAR __builtin_amdgcn_s_barrier()
; #define PG8_SCHED __builtin_amdgcn_sched_barrier(0)
; template <class Epi, class Sched, bool ALIGN_EPI = false, bool SP2 = false>
; __device__ __forceinline__ void gemm_phase(LAS unsigned char* lds, const Gemm g, const Sched& S, const Epi& E) {
;     ...
;             PG8_LDB(B0, 1, 0); PG8_LDB(B1, 1, 1); PG8_SCHED; PG8_LDA(At, 1, 0); PG8_STAGE(PG8_SA(0, 1), a2 + hstep, voffA);
;             PG8_WAIT_V(8); PG8_WAIT_L(0); PG8_BAR; PG8_MMA(0, 0, At, B0); PG8_MMA(0, 1, At, B1); PG8_BAR; PG8_SCHED;
;             PG8_LDA(At, 1, 1); PG8_STAGE(PG8_SB(1, 0), b3, voffB); PG8_STAGE(PG8_SB(1, 1), b3 + hstepB, voffB); PG8_STAGE(PG8_SA(1, 0), a3, voffA);
;             PG8_WAIT_V(8); PG8_WAIT_L(0); PG8_BAR; PG8_MMA(1, 0, At, B0); PG8_MMA(1, 1, At, B1); PG8_BAR; PG8_SCHED;
	s_add_i32 s16, 0, 0x18000
	s_add_i32 s17, 0, 0x1c000
	v_add_u32_e32 v142, s16, v1
	v_add_u32_e32 v154, s17, v1
	ds_read_b128 v[130:133], v142
	ds_read_b128 v[134:137], v142 offset:1024
	ds_read_b128 v[138:141], v142 offset:2048
	ds_read_b128 v[142:145], v142 offset:3072
	ds_read_b128 v[166:169], v154
	ds_read_b128 v[170:173], v154 offset:1024
	ds_read_b128 v[174:177], v154 offset:2048
	ds_read_b128 v[178:181], v154 offset:3072
	s_add_u32 s14, s58, 0x160000
	s_addc_u32 s15, s59, 0
	s_mov_b32 m0, s31
	ds_read_b128 v[182:185], v198 offset:32768
	ds_read_b128 v[186:189], v198 offset:33792
	ds_read_b128 v[202:205], v198 offset:34816
	ds_read_b128 v[206:209], v198 offset:35840
	ds_read_b128 v[210:213], v198 offset:36864
	ds_read_b128 v[214:217], v198 offset:37888
	ds_read_b128 v[218:221], v198 offset:38912
	ds_read_b128 v[222:225], v198 offset:39936
	global_load_lds_dwordx4 v146, s[14:15]
	s_mov_b32 m0, s33
	s_nop 0
	global_load_lds_dwordx4 v150, s[14:15]
	s_waitcnt vmcnt(8)
	s_waitcnt lgkmcnt(0)
	s_barrier
	s_waitcnt lgkmcnt(0)
	v_mfma_f32_16x16x32_bf16 v[126:129], v[130:133], v[182:185], v[126:129]
	v_mfma_f32_16x16x32_bf16 v[122:125], v[138:141], v[182:185], v[122:125]
	v_mfma_f32_16x16x32_bf16 v[110:113], v[130:133], v[202:205], v[110:113]
	v_mfma_f32_16x16x32_bf16 v[106:109], v[138:141], v[202:205], v[106:109]
	v_mfma_f32_16x16x32_bf16 v[94:97], v[130:133], v[210:213], v[94:97]
	v_mfma_f32_16x16x32_bf16 v[90:93], v[138:141], v[210:213], v[90:93]
	v_mfma_f32_16x16x32_bf16 v[78:81], v[130:133], v[218:221], v[78:81]
	v_mfma_f32_16x16x32_bf16 v[74:77], v[138:141], v[218:221], v[74:77]
	v_mfma_f32_16x16x32_bf16 v[126:129], v[134:137], v[186:189], v[126:129]
	v_mfma_f32_16x16x32_bf16 v[122:125], v[142:145], v[186:189], v[122:125]
	v_mfma_f32_16x16x32_bf16 v[110:113], v[134:137], v[206:209], v[110:113]
	v_mfma_f32_16x16x32_bf16 v[106:109], v[142:145], v[206:209], v[106:109]
	v_mfma_f32_16x16x32_bf16 v[94:97], v[134:137], v[214:217], v[94:97]
	v_mfma_f32_16x16x32_bf16 v[90:93], v[142:145], v[214:217], v[90:93]
	v_mfma_f32_16x16x32_bf16 v[78:81], v[134:137], v[222:225], v[78:81]
	v_mfma_f32_16x16x32_bf16 v[74:77], v[142:145], v[222:225], v[74:77]
	v_mfma_f32_16x16x32_bf16 v[118:121], v[166:169], v[182:185], v[118:121]
	v_mfma_f32_16x16x32_bf16 v[114:117], v[174:177], v[182:185], v[114:117]
	v_mfma_f32_16x16x32_bf16 v[102:105], v[166:169], v[202:205], v[102:105]
	v_mfma_f32_16x16x32_bf16 v[98:101], v[174:177], v[202:205], v[98:101]
	v_mfma_f32_16x16x32_bf16 v[86:89], v[166:169], v[210:213], v[86:89]
	v_mfma_f32_16x16x32_bf16 v[82:85], v[174:177], v[210:213], v[82:85]
	v_mfma_f32_16x16x32_bf16 v[70:73], v[166:169], v[218:221], v[70:73]
	v_mfma_f32_16x16x32_bf16 v[66:69], v[174:177], v[218:221], v[66:69]
	v_mfma_f32_16x16x32_bf16 v[118:121], v[170:173], v[186:189], v[118:121]
	v_mfma_f32_16x16x32_bf16 v[114:117], v[178:181], v[186:189], v[114:117]
	v_mfma_f32_16x16x32_bf16 v[102:105], v[170:173], v[206:209], v[102:105]
	v_mfma_f32_16x16x32_bf16 v[98:101], v[178:181], v[206:209], v[98:101]
	v_mfma_f32_16x16x32_bf16 v[86:89], v[170:173], v[214:217], v[86:89]
	v_mfma_f32_16x16x32_bf16 v[82:85], v[178:181], v[214:217], v[82:85]
	v_mfma_f32_16x16x32_bf16 v[70:73], v[170:173], v[222:225], v[70:73]
	v_mfma_f32_16x16x32_bf16 v[66:69], v[178:181], v[222:225], v[66:69]
	s_barrier
	s_add_u32 s98, s56, 0x80
	s_addc_u32 s99, s57, 0
	s_add_u32 s100, s58, 0x80
	s_addc_u32 s101, s59, 0
	s_add_i32 s14, s16, s28
	s_mov_b32 m0, s14
	ds_read_b128 v[182:185], v198 offset:49152
	ds_read_b128 v[186:189], v198 offset:50176
	ds_read_b128 v[202:205], v198 offset:51200
	ds_read_b128 v[206:209], v198 offset:52224
	ds_read_b128 v[210:213], v198 offset:53248
	ds_read_b128 v[214:217], v198 offset:54272
	ds_read_b128 v[218:221], v198 offset:55296
	ds_read_b128 v[222:225], v198 offset:56320
	global_load_lds_dwordx4 v148, s[98:99]
	s_add_i32 m0, s14, 0x2000
	s_add_u32 s14, s56, 0x58080
	s_addc_u32 s15, s57, 0
	s_add_i32 s16, s17, s28
	global_load_lds_dwordx4 v152, s[98:99]
	s_mov_b32 m0, s16
	s_nop 0
	global_load_lds_dwordx4 v148, s[14:15]
	s_add_i32 m0, s16, 0x2000
	s_nop 0
	global_load_lds_dwordx4 v152, s[14:15]
	s_mov_b32 m0, s61
	s_nop 0
	global_load_lds_dwordx4 v146, s[100:101]
	s_mov_b32 m0, s62
	s_nop 0
	global_load_lds_dwordx4 v150, s[100:101]
	s_waitcnt vmcnt(8)
	s_waitcnt lgkmcnt(0)
	s_barrier
	s_waitcnt lgkmcnt(0)
	v_mfma_f32_16x16x32_bf16 v[62:65], v[130:133], v[182:185], v[62:65]
	v_mfma_f32_16x16x32_bf16 v[58:61], v[138:141], v[182:185], v[58:61]
	v_mfma_f32_16x16x32_bf16 v[46:49], v[130:133], v[202:205], v[46:49]
	v_mfma_f32_16x16x32_bf16 v[42:45], v[138:141], v[202:205], v[42:45]
	v_mfma_f32_16x16x32_bf16 v[30:33], v[130:133], v[210:213], v[30:33]
	v_mfma_f32_16x16x32_bf16 v[26:29], v[138:141], v[210:213], v[26:29]
	v_mfma_f32_16x16x32_bf16 v[14:17], v[130:133], v[218:221], v[14:17]
	v_mfma_f32_16x16x32_bf16 v[10:13], v[138:141], v[218:221], v[10:13]
	v_mfma_f32_16x16x32_bf16 v[62:65], v[134:137], v[186:189], v[62:65]
	v_mfma_f32_16x16x32_bf16 v[58:61], v[142:145], v[186:189], v[58:61]
	v_mfma_f32_16x16x32_bf16 v[46:49], v[134:137], v[206:209], v[46:49]
	v_mfma_f32_16x16x32_bf16 v[42:45], v[142:145], v[206:209], v[42:45]
	v_mfma_f32_16x16x32_bf16 v[30:33], v[134:137], v[214:217], v[30:33]
	v_mfma_f32_16x16x32_bf16 v[26:29], v[142:145], v[214:217], v[26:29]
	v_mfma_f32_16x16x32_bf16 v[14:17], v[134:137], v[222:225], v[14:17]
	v_mfma_f32_16x16x32_bf16 v[10:13], v[142:145], v[222:225], v[10:13]
	v_mfma_f32_16x16x32_bf16 v[54:57], v[166:169], v[182:185], v[54:57]
	v_mfma_f32_16x16x32_bf16 v[50:53], v[174:177], v[182:185], v[50:53]
	v_mfma_f32_16x16x32_bf16 v[38:41], v[166:169], v[202:205], v[38:41]
	v_mfma_f32_16x16x32_bf16 v[34:37], v[174:177], v[202:205], v[34:37]
	v_mfma_f32_16x16x32_bf16 v[22:25], v[166:169], v[210:213], v[22:25]
	v_mfma_f32_16x16x32_bf16 v[18:21], v[174:177], v[210:213], v[18:21]
	v_mfma_f32_16x16x32_bf16 v[6:9], v[166:169], v[218:221], v[6:9]
	v_mfma_f32_16x16x32_bf16 v[2:5], v[174:177], v[218:221], v[2:5]
	v_mfma_f32_16x16x32_bf16 v[54:57], v[170:173], v[186:189], v[54:57]
	v_mfma_f32_16x16x32_bf16 v[50:53], v[178:181], v[186:189], v[50:53]
	v_mfma_f32_16x16x32_bf16 v[38:41], v[170:173], v[206:209], v[38:41]
	v_mfma_f32_16x16x32_bf16 v[34:37], v[178:181], v[206:209], v[34:37]
	v_mfma_f32_16x16x32_bf16 v[22:25], v[170:173], v[214:217], v[22:25]
	v_mfma_f32_16x16x32_bf16 v[18:21], v[178:181], v[214:217], v[18:21]
	v_mfma_f32_16x16x32_bf16 v[6:9], v[170:173], v[222:225], v[6:9]
	v_mfma_f32_16x16x32_bf16 v[2:5], v[178:181], v[222:225], v[2:5]
	s_barrier
	s_add_i32 s13, s13, 2
	s_add_u32 s5, s5, 0x100
	s_addc_u32 s12, s12, 0
	s_cmpk_gt_u32 s13, 0x55
	s_mov_b64 s[16:17], s[54:55]
; #define PG8_STAGE(bufoff, gbase, voff) do { _Pragma("unroll") for (int _i = 0; _i < 2; ++_i) \
;         __builtin_amdgcn_global_load_lds((const unsigned*)((const char*)(gbase) + (voff)[_i]), (LAS unsigned*)(lds + (bufoff) + ldsw + _i * 8192), 16, 0, 0); } while (0)
; #define PG8_LDA(dst, b, h) do { _Pragma("unroll") for (int m = 0; m < 4; ++m) _Pragma("unroll") for (int k = 0; k < 2; ++k) dst[m][k] = *(const LAS bf16x8*)(lds + PG8_SA(b, h) + aoff + m * 2048 + k * 1024); } while (0)
; #define PG8_LDB(dst, b, h) do { _Pragma("unroll") for (int n = 0; n < 2; ++n) _Pragma("unroll") for (int k = 0; k < 2; ++k) dst[n][k] = *(const LAS bf16x8*)(lds + PG8_SB(b, h) + boff + n * 2048 + k * 1024); } while (0)
; #define PG8_MMA(ai, bj, At, Bt) do { __builtin_amdgcn_s_setprio(1); _Pragma("unroll") for (int m = 0; m < 4; ++m) _Pragma("unroll") for (int n = 0; n < 2; ++n) _Pragma("unroll") for (int k = 0; k < 2; ++k) \
;         acc[ai][bj][m][n] = __builtin_amdgcn_mfma_f32_16x16x32_bf16(Bt[n][k], At[m][k], acc[ai][bj][m][n], 0, 0, 0); __builtin_amdgcn_s_setprio(0); } while (0)
; #define PG8_WAIT_V(n) asm volatile("s_waitcnt vmcnt(" #n ")" ::: "memory")
; #define PG8_WAIT_L(n) asm volatile("s_waitcnt lgkmcnt(" #n ")" ::: "memory")
; #define PG8_BAR __builtin_amdgcn_s_barrier()
; template <class Epi, class Sched, bool ALIGN_EPI = false, bool SP2 = false>
; __device__ __forceinline__ void gemm_phase(LAS unsigned char* lds, const Gemm g, const Sched& S, const Epi& E) {
;     ...
;             const bool last = (t == nt - 2);
;             const char* a1 = cA + (size_t)(t + 1) * kstep;
;             const char* a2 = last ? nA : cA + (size_t)(t + 2) * kstep; const char* b2 = last ? nB : cB + (size_t)(t + 2) * kstep;
;             const char* a3 = a2 + kstep; const char* b3 = b2 + kstep;
;             if (last && has_next) S.a_ready(nxt);
;             if constexpr (SP2) {
;             PG8_LDB(B0, 0, 0); PG8_LDB(B1, 0, 1); PG8_SCHED; PG8_LDA(At, 0, 0); PG8_STAGE(PG8_SA(1, 1), a1 + hstep, voffA);
;             PG8_WAIT_V(8); PG8_WAIT_L(0); PG8_BAR; PG8_MMA(0, 0, At, B0); PG8_MMA(0, 1, At, B1); PG8_BAR; PG8_SCHED;
;             PG8_LDA(At, 0, 1); PG8_STAGE(PG8_SB(0, 0), b2, voffB); PG8_STAGE(PG8_SB(0, 1), b2 + hstepB, voffB); PG8_STAGE(PG8_SA(0, 0), a2, voffA);
;             PG8_WAIT_V(8); PG8_WAIT_L(0); PG8_BAR; PG8_MMA(1, 0, At, B0); PG8_MMA(1, 1, At, B1); PG8_BAR; PG8_SCHED;
.LBB0_317:
	ds_read_b128 v[130:133], v196
	ds_read_b128 v[134:137], v196 offset:1024
	ds_read_b128 v[138:141], v196 offset:2048
	ds_read_b128 v[142:145], v196 offset:3072
	ds_read_b128 v[166:169], v197
	ds_read_b128 v[170:173], v197 offset:1024
	ds_read_b128 v[174:177], v197 offset:2048
	ds_read_b128 v[178:181], v197 offset:3072
	s_add_u32 s54, s16, 0x100
	s_addc_u32 s55, s17, 0
	s_cmpk_eq_i32 s13, 0x54
	s_cselect_b32 s59, s3, s55
	s_cselect_b32 s58, s2, s54
	s_cselect_b32 s57, s53, s12
	s_cselect_b32 s56, s52, s5
	v_lshl_add_u64 v[190:191], s[16:17], 0, v[158:159]
	s_add_i32 m0, s29, 0xc000
	ds_read_b128 v[182:185], v198
	ds_read_b128 v[186:189], v198 offset:1024
	ds_read_b128 v[202:205], v198 offset:2048
	ds_read_b128 v[206:209], v198 offset:3072
	ds_read_b128 v[210:213], v198 offset:4096
	ds_read_b128 v[214:217], v198 offset:5120
	ds_read_b128 v[218:221], v198 offset:6144
	ds_read_b128 v[222:225], v198 offset:7168
	global_load_lds_dwordx4 v[190:191], off
	v_lshl_add_u64 v[190:191], s[16:17], 0, v[160:161]
	s_add_i32 m0, s29, 0xe000
	s_nop 0
	global_load_lds_dwordx4 v[190:191], off
	s_waitcnt vmcnt(8)
	s_waitcnt lgkmcnt(0)
	s_barrier
	s_waitcnt lgkmcnt(0)
	v_mfma_f32_16x16x32_bf16 v[126:129], v[130:133], v[182:185], v[126:129]
	v_mfma_f32_16x16x32_bf16 v[122:125], v[138:141], v[182:185], v[122:125]
	v_mfma_f32_16x16x32_bf16 v[110:113], v[130:133], v[202:205], v[110:113]
	v_mfma_f32_16x16x32_bf16 v[106:109], v[138:141], v[202:205], v[106:109]
	v_mfma_f32_16x16x32_bf16 v[94:97], v[130:133], v[210:213], v[94:97]
	v_mfma_f32_16x16x32_bf16 v[90:93], v[138:141], v[210:213], v[90:93]
	v_mfma_f32_16x16x32_bf16 v[78:81], v[130:133], v[218:221], v[78:81]
	v_mfma_f32_16x16x32_bf16 v[74:77], v[138:141], v[218:221], v[74:77]
	v_mfma_f32_16x16x32_bf16 v[126:129], v[134:137], v[186:189], v[126:129]
	v_mfma_f32_16x16x32_bf16 v[122:125], v[142:145], v[186:189], v[122:125]
	v_mfma_f32_16x16x32_bf16 v[110:113], v[134:137], v[206:209], v[110:113]
	v_mfma_f32_16x16x32_bf16 v[106:109], v[142:145], v[206:209], v[106:109]
	v_mfma_f32_16x16x32_bf16 v[94:97], v[134:137], v[214:217], v[94:97]
	v_mfma_f32_16x16x32_bf16 v[90:93], v[142:145], v[214:217], v[90:93]
	v_mfma_f32_16x16x32_bf16 v[78:81], v[134:137], v[222:225], v[78:81]
	v_mfma_f32_16x16x32_bf16 v[74:77], v[142:145], v[222:225], v[74:77]
	v_mfma_f32_16x16x32_bf16 v[118:121], v[166:169], v[182:185], v[118:121]
	v_mfma_f32_16x16x32_bf16 v[114:117], v[174:177], v[182:185], v[114:117]
	v_mfma_f32_16x16x32_bf16 v[102:105], v[166:169], v[202:205], v[102:105]
	v_mfma_f32_16x16x32_bf16 v[98:101], v[174:177], v[202:205], v[98:101]
	v_mfma_f32_16x16x32_bf16 v[86:89], v[166:169], v[210:213], v[86:89]
	v_mfma_f32_16x16x32_bf16 v[82:85], v[174:177], v[210:213], v[82:85]
	v_mfma_f32_16x16x32_bf16 v[70:73], v[166:169], v[218:221], v[70:73]
	v_mfma_f32_16x16x32_bf16 v[66:69], v[174:177], v[218:221], v[66:69]
	v_mfma_f32_16x16x32_bf16 v[118:121], v[170:173], v[186:189], v[118:121]
	v_mfma_f32_16x16x32_bf16 v[114:117], v[178:181], v[186:189], v[114:117]
	v_mfma_f32_16x16x32_bf16 v[102:105], v[170:173], v[206:209], v[102:105]
	v_mfma_f32_16x16x32_bf16 v[98:101], v[178:181], v[206:209], v[98:101]
	v_mfma_f32_16x16x32_bf16 v[86:89], v[170:173], v[214:217], v[86:89]
	v_mfma_f32_16x16x32_bf16 v[82:85], v[178:181], v[214:217], v[82:85]
	v_mfma_f32_16x16x32_bf16 v[70:73], v[170:173], v[222:225], v[70:73]
	v_mfma_f32_16x16x32_bf16 v[66:69], v[178:181], v[222:225], v[66:69]
	s_barrier
	s_add_i32 s14, s64, s28
	s_mov_b32 m0, s14
	ds_read_b128 v[182:185], v198 offset:16384
	ds_read_b128 v[186:189], v198 offset:17408
	ds_read_b128 v[202:205], v198 offset:18432
	ds_read_b128 v[206:209], v198 offset:19456
	ds_read_b128 v[210:213], v198 offset:20480
	ds_read_b128 v[214:217], v198 offset:21504
	ds_read_b128 v[218:221], v198 offset:22528
	ds_read_b128 v[222:225], v198 offset:23552
	global_load_lds_dwordx4 v148, s[56:57]
	s_add_i32 m0, s14, 0x2000
	s_add_u32 s14, s56, 0x58000
	s_addc_u32 s15, s57, 0
	s_add_i32 s16, s65, s28
	global_load_lds_dwordx4 v152, s[56:57]
	s_mov_b32 m0, s16
	global_load_lds_dwordx4 v148, s[14:15]
	s_add_i32 m0, s16, 0x2000
	s_nop 0
	global_load_lds_dwordx4 v152, s[14:15]
	s_mov_b32 m0, s29
	s_nop 0
	global_load_lds_dwordx4 v146, s[58:59]
	s_mov_b32 m0, s30
	s_nop 0
	global_load_lds_dwordx4 v150, s[58:59]
	s_waitcnt vmcnt(8)
	s_waitcnt lgkmcnt(0)
	s_barrier
	s_waitcnt lgkmcnt(0)
	v_mfma_f32_16x16x32_bf16 v[62:65], v[130:133], v[182:185], v[62:65]
	v_mfma_f32_16x16x32_bf16 v[58:61], v[138:141], v[182:185], v[58:61]
	v_mfma_f32_16x16x32_bf16 v[46:49], v[130:133], v[202:205], v[46:49]
	v_mfma_f32_16x16x32_bf16 v[42:45], v[138:141], v[202:205], v[42:45]
	v_mfma_f32_16x16x32_bf16 v[30:33], v[130:133], v[210:213], v[30:33]
	v_mfma_f32_16x16x32_bf16 v[26:29], v[138:141], v[210:213], v[26:29]
	v_mfma_f32_16x16x32_bf16 v[14:17], v[130:133], v[218:221], v[14:17]
	v_mfma_f32_16x16x32_bf16 v[10:13], v[138:141], v[218:221], v[10:13]
	v_mfma_f32_16x16x32_bf16 v[62:65], v[134:137], v[186:189], v[62:65]
	v_mfma_f32_16x16x32_bf16 v[58:61], v[142:145], v[186:189], v[58:61]
	v_mfma_f32_16x16x32_bf16 v[46:49], v[134:137], v[206:209], v[46:49]
	v_mfma_f32_16x16x32_bf16 v[42:45], v[142:145], v[206:209], v[42:45]
	v_mfma_f32_16x16x32_bf16 v[30:33], v[134:137], v[214:217], v[30:33]
	v_mfma_f32_16x16x32_bf16 v[26:29], v[142:145], v[214:217], v[26:29]
	v_mfma_f32_16x16x32_bf16 v[14:17], v[134:137], v[222:225], v[14:17]
	v_mfma_f32_16x16x32_bf16 v[10:13], v[142:145], v[222:225], v[10:13]
	v_mfma_f32_16x16x32_bf16 v[54:57], v[166:169], v[182:185], v[54:57]
	v_mfma_f32_16x16x32_bf16 v[50:53], v[174:177], v[182:185], v[50:53]
	v_mfma_f32_16x16x32_bf16 v[38:41], v[166:169], v[202:205], v[38:41]
	v_mfma_f32_16x16x32_bf16 v[34:37], v[174:177], v[202:205], v[34:37]
	v_mfma_f32_16x16x32_bf16 v[22:25], v[166:169], v[210:213], v[22:25]
	v_mfma_f32_16x16x32_bf16 v[18:21], v[174:177], v[210:213], v[18:21]
	v_mfma_f32_16x16x32_bf16 v[6:9], v[166:169], v[218:221], v[6:9]
	v_mfma_f32_16x16x32_bf16 v[2:5], v[174:177], v[218:221], v[2:5]
	v_mfma_f32_16x16x32_bf16 v[54:57], v[170:173], v[186:189], v[54:57]
	v_mfma_f32_16x16x32_bf16 v[50:53], v[178:181], v[186:189], v[50:53]
	v_mfma_f32_16x16x32_bf16 v[38:41], v[170:173], v[206:209], v[38:41]
	v_mfma_f32_16x16x32_bf16 v[34:37], v[178:181], v[206:209], v[34:37]
	v_mfma_f32_16x16x32_bf16 v[22:25], v[170:173], v[214:217], v[22:25]
	v_mfma_f32_16x16x32_bf16 v[18:21], v[178:181], v[214:217], v[18:21]
	v_mfma_f32_16x16x32_bf16 v[6:9], v[170:173], v[222:225], v[6:9]
	v_mfma_f32_16x16x32_bf16 v[2:5], v[178:181], v[222:225], v[2:5]
	s_barrier
; #define PG8_STAGE(bufoff, gbase, voff) do { _Pragma("unroll") for (int _i = 0; _i < 2; ++_i) \
;         __builtin_amdgcn_global_load_lds((const unsigned*)((const char*)(gbase) + (voff)[_i]), (LAS unsigned*)(lds + (bufoff) + ldsw + _i * 8192), 16, 0, 0); } while (0)
; #define PG8_LDA(dst, b, h) do { _Pragma("unroll") for (int m = 0; m < 4; ++m) _Pragma("unroll") for (int k = 0; k < 2; ++k) dst[m][k] = *(const LAS bf16x8*)(lds + PG8_SA(b, h) + aoff + m * 2048 + k * 1024); } while (0)
; #define PG8_LDB(dst, b, h) do { _Pragma("unroll") for (int n = 0; n < 2; ++n) _Pragma("unroll") for (int k = 0; k < 2; ++k) dst[n][k] = *(const LAS bf16x8*)(lds + PG8_SB(b, h) + boff + n * 2048 + k * 1024); } while (0)
; #define PG8_MMA(ai, bj, At, Bt) do { __builtin_amdgcn_s_setprio(1); _Pragma("unroll") for (int m = 0; m < 4; ++m) _Pragma("unroll") for (int n = 0; n < 2; ++n) _Pragma("unroll") for (int k = 0; k < 2; ++k) \
;         acc[ai][bj][m][n] = __builtin_amdgcn_mfma_f32_16x16x32_bf16(Bt[n][k], At[m][k], acc[ai][bj][m][n], 0, 0, 0); __builtin_amdgcn_s_setprio(0); } while (0)
; #define PG8_WAIT_V(n) asm volatile("s_waitcnt vmcnt(" #n ")" ::: "memory")
; #define PG8_WAIT_L(n) asm volatile("s_waitcnt lgkmcnt(" #n ")" ::: "memory")
; #define PG8_BAR __builtin_amdgcn_s_barrier()
; #define PG8_SCHED __builtin_amdgcn_sched_barrier(0)
; template <class Epi, class Sched, bool ALIGN_EPI = false, bool SP2 = false>
; __device__ __forceinline__ void gemm_phase(LAS unsigned char* lds, const Gemm g, const Sched& S, const Epi& E) {
;     ...
;             PG8_LDB(B0, 1, 0); PG8_LDB(B1, 1, 1); PG8_SCHED; PG8_LDA(At, 1, 0); PG8_STAGE(PG8_SA(0, 1), a2 + hstep, voffA);
;             PG8_WAIT_V(8); PG8_WAIT_L(0); PG8_BAR; PG8_MMA(0, 0, At, B0); PG8_MMA(0, 1, At, B1); PG8_BAR; PG8_SCHED;
;             PG8_LDA(At, 1, 1); PG8_STAGE(PG8_SB(1, 0), b3, voffB); PG8_STAGE(PG8_SB(1, 1), b3 + hstepB, voffB); PG8_STAGE(PG8_SA(1, 0), a3, voffA);
;             PG8_WAIT_V(8); PG8_WAIT_L(0); PG8_BAR; PG8_MMA(1, 0, At, B0); PG8_MMA(1, 1, At, B1); PG8_BAR; PG8_SCHED;
	s_add_i32 s16, 0, 0x18000
	s_add_i32 s17, 0, 0x1c000
	v_add_u32_e32 v142, s16, v1
	v_add_u32_e32 v154, s17, v1
	ds_read_b128 v[130:133], v142
	ds_read_b128 v[134:137], v142 offset:1024
	ds_read_b128 v[138:141], v142 offset:2048
	ds_read_b128 v[142:145], v142 offset:3072
	ds_read_b128 v[166:169], v154
	ds_read_b128 v[170:173], v154 offset:1024
	ds_read_b128 v[174:177], v154 offset:2048
	ds_read_b128 v[178:181], v154 offset:3072
	s_add_u32 s14, s58, 0x160000
	s_addc_u32 s15, s59, 0
	s_mov_b32 m0, s31
	ds_read_b128 v[182:185], v198 offset:32768
	ds_read_b128 v[186:189], v198 offset:33792
	ds_read_b128 v[202:205], v198 offset:34816
	ds_read_b128 v[206:209], v198 offset:35840
	ds_read_b128 v[210:213], v198 offset:36864
	ds_read_b128 v[214:217], v198 offset:37888
	ds_read_b128 v[218:221], v198 offset:38912
	ds_read_b128 v[222:225], v198 offset:39936
	global_load_lds_dwordx4 v146, s[14:15]
	s_mov_b32 m0, s33
	s_nop 0
	global_load_lds_dwordx4 v150, s[14:15]
	s_waitcnt vmcnt(8)
	s_waitcnt lgkmcnt(0)
	s_barrier
	s_waitcnt lgkmcnt(0)
	v_mfma_f32_16x16x32_bf16 v[126:129], v[130:133], v[182:185], v[126:129]
	v_mfma_f32_16x16x32_bf16 v[122:125], v[138:141], v[182:185], v[122:125]
	v_mfma_f32_16x16x32_bf16 v[110:113], v[130:133], v[202:205], v[110:113]
	v_mfma_f32_16x16x32_bf16 v[106:109], v[138:141], v[202:205], v[106:109]
	v_mfma_f32_16x16x32_bf16 v[94:97], v[130:133], v[210:213], v[94:97]
	v_mfma_f32_16x16x32_bf16 v[90:93], v[138:141], v[210:213], v[90:93]
	v_mfma_f32_16x16x32_bf16 v[78:81], v[130:133], v[218:221], v[78:81]
	v_mfma_f32_16x16x32_bf16 v[74:77], v[138:141], v[218:221], v[74:77]
	v_mfma_f32_16x16x32_bf16 v[126:129], v[134:137], v[186:189], v[126:129]
	v_mfma_f32_16x16x32_bf16 v[122:125], v[142:145], v[186:189], v[122:125]
	v_mfma_f32_16x16x32_bf16 v[110:113], v[134:137], v[206:209], v[110:113]
	v_mfma_f32_16x16x32_bf16 v[106:109], v[142:145], v[206:209], v[106:109]
	v_mfma_f32_16x16x32_bf16 v[94:97], v[134:137], v[214:217], v[94:97]
	v_mfma_f32_16x16x32_bf16 v[90:93], v[142:145], v[214:217], v[90:93]
	v_mfma_f32_16x16x32_bf16 v[78:81], v[134:137], v[222:225], v[78:81]
	v_mfma_f32_16x16x32_bf16 v[74:77], v[142:145], v[222:225], v[74:77]
	v_mfma_f32_16x16x32_bf16 v[118:121], v[166:169], v[182:185], v[118:121]
	v_mfma_f32_16x16x32_bf16 v[114:117], v[174:177], v[182:185], v[114:117]
	v_mfma_f32_16x16x32_bf16 v[102:105], v[166:169], v[202:205], v[102:105]
	v_mfma_f32_16x16x32_bf16 v[98:101], v[174:177], v[202:205], v[98:101]
	v_mfma_f32_16x16x32_bf16 v[86:89], v[166:169], v[210:213], v[86:89]
	v_mfma_f32_16x16x32_bf16 v[82:85], v[174:177], v[210:213], v[82:85]
	v_mfma_f32_16x16x32_bf16 v[70:73], v[166:169], v[218:221], v[70:73]
	v_mfma_f32_16x16x32_bf16 v[66:69], v[174:177], v[218:221], v[66:69]
	v_mfma_f32_16x16x32_bf16 v[118:121], v[170:173], v[186:189], v[118:121]
	v_mfma_f32_16x16x32_bf16 v[114:117], v[178:181], v[186:189], v[114:117]
	v_mfma_f32_16x16x32_bf16 v[102:105], v[170:173], v[206:209], v[102:105]
	v_mfma_f32_16x16x32_bf16 v[98:101], v[178:181], v[206:209], v[98:101]
	v_mfma_f32_16x16x32_bf16 v[86:89], v[170:173], v[214:217], v[86:89]
	v_mfma_f32_16x16x32_bf16 v[82:85], v[178:181], v[214:217], v[82:85]
	v_mfma_f32_16x16x32_bf16 v[70:73], v[170:173], v[222:225], v[70:73]
	v_mfma_f32_16x16x32_bf16 v[66:69], v[178:181], v[222:225], v[66:69]
	s_barrier
	s_add_u32 s98, s56, 0x80
	s_addc_u32 s99, s57, 0
	s_add_u32 s100, s58, 0x80
	s_addc_u32 s101, s59, 0
	s_add_i32 s14, s16, s28
	s_mov_b32 m0, s14
	ds_read_b128 v[182:185], v198 offset:49152
	ds_read_b128 v[186:189], v198 offset:50176
	ds_read_b128 v[202:205], v198 offset:51200
	ds_read_b128 v[206:209], v198 offset:52224
	ds_read_b128 v[210:213], v198 offset:53248
	ds_read_b128 v[214:217], v198 offset:54272
	ds_read_b128 v[218:221], v198 offset:55296
	ds_read_b128 v[222:225], v198 offset:56320
	global_load_lds_dwordx4 v148, s[98:99]
	s_add_i32 m0, s14, 0x2000
	s_add_u32 s14, s56, 0x58080
	s_addc_u32 s15, s57, 0
	s_add_i32 s16, s17, s28
	global_load_lds_dwordx4 v152, s[98:99]
	s_mov_b32 m0, s16
	s_nop 0
	global_load_lds_dwordx4 v148, s[14:15]
	s_add_i32 m0, s16, 0x2000
	s_nop 0
	global_load_lds_dwordx4 v152, s[14:15]
	s_mov_b32 m0, s61
	s_nop 0
	global_load_lds_dwordx4 v146, s[100:101]
	s_mov_b32 m0, s62
	s_nop 0
	global_load_lds_dwordx4 v150, s[100:101]
	s_waitcnt vmcnt(8)
	s_waitcnt lgkmcnt(0)
	s_barrier
	s_waitcnt lgkmcnt(0)
	v_mfma_f32_16x16x32_bf16 v[62:65], v[130:133], v[182:185], v[62:65]
	v_mfma_f32_16x16x32_bf16 v[58:61], v[138:141], v[182:185], v[58:61]
	v_mfma_f32_16x16x32_bf16 v[46:49], v[130:133], v[202:205], v[46:49]
	v_mfma_f32_16x16x32_bf16 v[42:45], v[138:141], v[202:205], v[42:45]
	v_mfma_f32_16x16x32_bf16 v[30:33], v[130:133], v[210:213], v[30:33]
	v_mfma_f32_16x16x32_bf16 v[26:29], v[138:141], v[210:213], v[26:29]
	v_mfma_f32_16x16x32_bf16 v[14:17], v[130:133], v[218:221], v[14:17]
	v_mfma_f32_16x16x32_bf16 v[10:13], v[138:141], v[218:221], v[10:13]
	v_mfma_f32_16x16x32_bf16 v[62:65], v[134:137], v[186:189], v[62:65]
	v_mfma_f32_16x16x32_bf16 v[58:61], v[142:145], v[186:189], v[58:61]
	v_mfma_f32_16x16x32_bf16 v[46:49], v[134:137], v[206:209], v[46:49]
	v_mfma_f32_16x16x32_bf16 v[42:45], v[142:145], v[206:209], v[42:45]
	v_mfma_f32_16x16x32_bf16 v[30:33], v[134:137], v[214:217], v[30:33]
	v_mfma_f32_16x16x32_bf16 v[26:29], v[142:145], v[214:217], v[26:29]
	v_mfma_f32_16x16x32_bf16 v[14:17], v[134:137], v[222:225], v[14:17]
	v_mfma_f32_16x16x32_bf16 v[10:13], v[142:145], v[222:225], v[10:13]
	v_mfma_f32_16x16x32_bf16 v[54:57], v[166:169], v[182:185], v[54:57]
	v_mfma_f32_16x16x32_bf16 v[50:53], v[174:177], v[182:185], v[50:53]
	v_mfma_f32_16x16x32_bf16 v[38:41], v[166:169], v[202:205], v[38:41]
	v_mfma_f32_16x16x32_bf16 v[34:37], v[174:177], v[202:205], v[34:37]
	v_mfma_f32_16x16x32_bf16 v[22:25], v[166:169], v[210:213], v[22:25]
	v_mfma_f32_16x16x32_bf16 v[18:21], v[174:177], v[210:213], v[18:21]
	v_mfma_f32_16x16x32_bf16 v[6:9], v[166:169], v[218:221], v[6:9]
	v_mfma_f32_16x16x32_bf16 v[2:5], v[174:177], v[218:221], v[2:5]
	v_mfma_f32_16x16x32_bf16 v[54:57], v[170:173], v[186:189], v[54:57]
	v_mfma_f32_16x16x32_bf16 v[50:53], v[178:181], v[186:189], v[50:53]
	v_mfma_f32_16x16x32_bf16 v[38:41], v[170:173], v[206:209], v[38:41]
	v_mfma_f32_16x16x32_bf16 v[34:37], v[178:181], v[206:209], v[34:37]
	v_mfma_f32_16x16x32_bf16 v[22:25], v[170:173], v[214:217], v[22:25]
	v_mfma_f32_16x16x32_bf16 v[18:21], v[178:181], v[214:217], v[18:21]
	v_mfma_f32_16x16x32_bf16 v[6:9], v[170:173], v[222:225], v[6:9]
	v_mfma_f32_16x16x32_bf16 v[2:5], v[178:181], v[222:225], v[2:5]
	s_barrier
	s_add_i32 s13, s13, 2
	s_add_u32 s5, s5, 0x100
	s_addc_u32 s12, s12, 0
	s_cmpk_gt_u32 s13, 0x55
	s_mov_b64 s[16:17], s[54:55]
	s_cbranch_scc0 .LBB0_317
	s_setprio 0
	s_and_b64 vcc, exec, s[50:51]
	s_cbranch_vccz .LBB0_320
	s_barrier

; #define PG8_STAGE(bufoff, gbase, voff) do { _Pragma("unroll") for (int _i = 0; _i < 2; ++_i) \
;         __builtin_amdgcn_global_load_lds((const unsigned*)((const char*)(gbase) + (voff)[_i]), (LAS unsigned*)(lds + (bufoff) + ldsw + _i * 8192), 16, 0, 0); } while (0)
; #define PG8_LDA(dst, b, h) do { _Pragma("unroll") for (int m = 0; m < 4; ++m) _Pragma("unroll") for (int k = 0; k < 2; ++k) dst[m][k] = *(const LAS bf16x8*)(lds + PG8_SA(b, h) + aoff + m * 2048 + k * 1024); } while (0)
; #define PG8_LDB(dst, b, h) do { _Pragma("unroll") for (int n = 0; n < 2; ++n) _Pragma("unroll") for (int k = 0; k < 2; ++k) dst[n][k] = *(const LAS bf16x8*)(lds + PG8_SB(b, h) + boff + n * 2048 + k * 1024); } while (0)
; #define PG8_MMA(ai, bj, At, Bt) do { __builtin_amdgcn_s_setprio(1); _Pragma("unroll") for (int m = 0; m < 4; ++m) _Pragma("unroll") for (int n = 0; n < 2; ++n) _Pragma("unroll") for (int k = 0; k < 2; ++k) \
;         acc[ai][bj][m][n] = __builtin_amdgcn_mfma_f32_16x16x32_bf16(Bt[n][k], At[m][k], acc[ai][bj][m][n], 0, 0, 0); __builtin_amdgcn_s_setprio(0); } while (0)
; #define PG8_WAIT_V(n) asm volatile("s_waitcnt vmcnt(" #n ")" ::: "memory")
; #define PG8_WAIT_L(n) asm volatile("s_waitcnt lgkmcnt(" #n ")" ::: "memory")
; template <class Epi, class Sched, bool ALIGN_EPI = false, bool SP2 = false>
; __device__ __forceinline__ void gemm_phase(LAS unsigned char* lds, const Gemm g, const Sched& S, const Epi& E) {
;     ...
;         for (int t = 0; t < nt; t += 2) {
;             const bool last = (t == nt - 2);
;             const char* a1 = cA + (size_t)(t + 1) * kstep;
;             const char* a2 = last ? nA : cA + (size_t)(t + 2) * kstep; const char* b2 = last ? nB : cB + (size_t)(t + 2) * kstep;
;             const char* a3 = a2 + kstep; const char* b3 = b2 + kstep;
;             if (last && has_next) S.a_ready(nxt);
;             if constexpr (SP2) {
;             PG8_LDB(B0, 0, 0); PG8_LDB(B1, 0, 1); PG8_SCHED; PG8_LDA(At, 0, 0); PG8_STAGE(PG8_SA(1, 1), a1 + hstep, voffA);
;             PG8_WAIT_V(8); PG8_WAIT_L(0); PG8_BAR; PG8_MMA(0, 0, At, B0); PG8_MMA(0, 1, At, B1); PG8_BAR; PG8_SCHED;
;             PG8_LDA(At, 0, 1); PG8_STAGE(PG8_SB(0, 0), b2, voffB); PG8_STAGE(PG8_SB(0, 1), b2 + hstepB, voffB); PG8_STAGE(PG8_SA(0, 0), a2, voffA);
;             PG8_WAIT_V(8); PG8_WAIT_L(0); PG8_BAR; PG8_MMA(1, 0, At, B0); PG8_MMA(1, 1, At, B1); PG8_BAR; PG8_SCHED;
.Lprio_535:
	ds_read_b128 v[34:37], v203
	ds_read_b128 v[38:41], v203 offset:1024
	ds_read_b128 v[42:45], v203 offset:2048
	ds_read_b128 v[46:49], v203 offset:3072
	s_waitcnt vmcnt(0)
	ds_read_b128 v[98:101], v204
	ds_read_b128 v[102:105], v204 offset:1024
	ds_read_b128 v[106:109], v204 offset:2048
	ds_read_b128 v[110:113], v204 offset:3072
	s_add_u32 s21, s16, 0xfff80080
	s_addc_u32 s22, s17, -1
	s_cmp_eq_u32 s20, 28
	s_cselect_b32 s59, s0, s22
	s_cselect_b32 s58, s3, s21
	s_cselect_b32 s49, s14, s19
	s_cselect_b32 s48, s15, s18
	s_add_i32 m0, s30, 0xc000
	ds_read_b128 v[212:215], v205
	ds_read_b128 v[216:219], v205 offset:1024
	ds_read_b128 v[220:223], v205 offset:2048
	ds_read_b128 v[224:227], v205 offset:3072
	ds_read_b128 v[228:231], v205 offset:4096
	ds_read_b128 v[232:235], v205 offset:5120
	ds_read_b128 v[236:239], v205 offset:6144
	ds_read_b128 v[240:243], v205 offset:7168
	global_load_lds_dwordx4 v172, s[16:17]
	s_add_i32 m0, s30, 0xe000
	s_nop 0
	global_load_lds_dwordx4 v174, s[16:17]
	s_waitcnt lgkmcnt(0)
	s_barrier
	s_waitcnt lgkmcnt(0)
	v_mfma_f32_16x16x32_bf16 v[158:161], v[34:37], v[212:215], 0
	v_mfma_f32_16x16x32_bf16 v[154:157], v[42:45], v[212:215], 0
	v_mfma_f32_16x16x32_bf16 v[142:145], v[34:37], v[220:223], 0
	v_mfma_f32_16x16x32_bf16 v[138:141], v[42:45], v[220:223], 0
	v_mfma_f32_16x16x32_bf16 v[126:129], v[34:37], v[228:231], 0
	v_mfma_f32_16x16x32_bf16 v[122:125], v[42:45], v[228:231], 0
	v_mfma_f32_16x16x32_bf16 v[94:97], v[34:37], v[236:239], 0
	v_mfma_f32_16x16x32_bf16 v[90:93], v[42:45], v[236:239], 0
	v_mfma_f32_16x16x32_bf16 v[158:161], v[38:41], v[216:219], v[158:161]
	v_mfma_f32_16x16x32_bf16 v[154:157], v[46:49], v[216:219], v[154:157]
	v_mfma_f32_16x16x32_bf16 v[142:145], v[38:41], v[224:227], v[142:145]
	v_mfma_f32_16x16x32_bf16 v[138:141], v[46:49], v[224:227], v[138:141]
	v_mfma_f32_16x16x32_bf16 v[126:129], v[38:41], v[232:235], v[126:129]
	v_mfma_f32_16x16x32_bf16 v[122:125], v[46:49], v[232:235], v[122:125]
	v_mfma_f32_16x16x32_bf16 v[94:97], v[38:41], v[240:243], v[94:97]
	v_mfma_f32_16x16x32_bf16 v[90:93], v[46:49], v[240:243], v[90:93]
	v_mfma_f32_16x16x32_bf16 v[150:153], v[98:101], v[212:215], 0
	v_mfma_f32_16x16x32_bf16 v[146:149], v[106:109], v[212:215], 0
	v_mfma_f32_16x16x32_bf16 v[134:137], v[98:101], v[220:223], 0
	v_mfma_f32_16x16x32_bf16 v[130:133], v[106:109], v[220:223], 0
	v_mfma_f32_16x16x32_bf16 v[118:121], v[98:101], v[228:231], 0
	v_mfma_f32_16x16x32_bf16 v[114:117], v[106:109], v[228:231], 0
	v_mfma_f32_16x16x32_bf16 v[86:89], v[98:101], v[236:239], 0
	v_mfma_f32_16x16x32_bf16 v[82:85], v[106:109], v[236:239], 0
	v_mfma_f32_16x16x32_bf16 v[150:153], v[102:105], v[216:219], v[150:153]
	v_mfma_f32_16x16x32_bf16 v[146:149], v[110:113], v[216:219], v[146:149]
	v_mfma_f32_16x16x32_bf16 v[134:137], v[102:105], v[224:227], v[134:137]
	v_mfma_f32_16x16x32_bf16 v[130:133], v[110:113], v[224:227], v[130:133]
	v_mfma_f32_16x16x32_bf16 v[118:121], v[102:105], v[232:235], v[118:121]
	v_mfma_f32_16x16x32_bf16 v[114:117], v[110:113], v[232:235], v[114:117]
	v_mfma_f32_16x16x32_bf16 v[86:89], v[102:105], v[240:243], v[86:89]
	v_mfma_f32_16x16x32_bf16 v[82:85], v[110:113], v[240:243], v[82:85]
	s_barrier
	s_add_i32 s21, s68, s29
	s_mov_b32 m0, s21
	ds_read_b128 v[212:215], v205 offset:16384
	ds_read_b128 v[216:219], v205 offset:17408
	ds_read_b128 v[220:223], v205 offset:18432
	ds_read_b128 v[224:227], v205 offset:19456
	ds_read_b128 v[228:231], v205 offset:20480
	ds_read_b128 v[232:235], v205 offset:21504
	ds_read_b128 v[236:239], v205 offset:22528
	ds_read_b128 v[240:243], v205 offset:23552
	global_load_lds_dwordx4 v164, s[48:49]
	s_add_i32 m0, s21, 0x2000
	s_add_u32 s22, s48, 0x20000
	s_addc_u32 s23, s49, 0
	s_add_i32 s21, s69, s29
	global_load_lds_dwordx4 v168, s[48:49]
	s_mov_b32 m0, s21
	global_load_lds_dwordx4 v164, s[22:23]
	s_add_i32 m0, s21, 0x2000
	s_nop 0
	global_load_lds_dwordx4 v168, s[22:23]
	s_mov_b32 m0, s30
	s_nop 0
	global_load_lds_dwordx4 v162, s[58:59]
	s_mov_b32 m0, s31
	s_nop 0
	global_load_lds_dwordx4 v166, s[58:59]
	s_waitcnt lgkmcnt(0)
	s_barrier
	s_waitcnt lgkmcnt(0)
	v_mfma_f32_16x16x32_bf16 v[78:81], v[34:37], v[212:215], 0
	v_mfma_f32_16x16x32_bf16 v[74:77], v[42:45], v[212:215], 0
	v_mfma_f32_16x16x32_bf16 v[62:65], v[34:37], v[220:223], 0
	v_mfma_f32_16x16x32_bf16 v[58:61], v[42:45], v[220:223], 0
	v_mfma_f32_16x16x32_bf16 v[30:33], v[34:37], v[228:231], 0
	v_mfma_f32_16x16x32_bf16 v[26:29], v[42:45], v[228:231], 0
	v_mfma_f32_16x16x32_bf16 v[14:17], v[34:37], v[236:239], 0
	v_mfma_f32_16x16x32_bf16 v[10:13], v[42:45], v[236:239], 0
	v_mfma_f32_16x16x32_bf16 v[78:81], v[38:41], v[216:219], v[78:81]
	v_mfma_f32_16x16x32_bf16 v[74:77], v[46:49], v[216:219], v[74:77]
	v_mfma_f32_16x16x32_bf16 v[62:65], v[38:41], v[224:227], v[62:65]
	v_mfma_f32_16x16x32_bf16 v[58:61], v[46:49], v[224:227], v[58:61]
	v_mfma_f32_16x16x32_bf16 v[30:33], v[38:41], v[232:235], v[30:33]
	v_mfma_f32_16x16x32_bf16 v[26:29], v[46:49], v[232:235], v[26:29]
	v_mfma_f32_16x16x32_bf16 v[14:17], v[38:41], v[240:243], v[14:17]
	v_mfma_f32_16x16x32_bf16 v[10:13], v[46:49], v[240:243], v[10:13]
	v_mfma_f32_16x16x32_bf16 v[22:25], v[98:101], v[228:231], 0
	v_mfma_f32_16x16x32_bf16 v[18:21], v[106:109], v[228:231], 0
	v_mfma_f32_16x16x32_bf16 v[6:9], v[98:101], v[236:239], 0
	v_mfma_f32_16x16x32_bf16 v[2:5], v[106:109], v[236:239], 0
	v_mfma_f32_16x16x32_bf16 v[34:37], v[98:101], v[212:215], 0
	v_mfma_f32_16x16x32_bf16 v[38:41], v[106:109], v[212:215], 0
	v_mfma_f32_16x16x32_bf16 v[42:45], v[98:101], v[220:223], 0
	v_mfma_f32_16x16x32_bf16 v[46:49], v[106:109], v[220:223], 0
	v_mfma_f32_16x16x32_bf16 v[22:25], v[102:105], v[232:235], v[22:25]
	v_mfma_f32_16x16x32_bf16 v[18:21], v[110:113], v[232:235], v[18:21]
	v_mfma_f32_16x16x32_bf16 v[6:9], v[102:105], v[240:243], v[6:9]
	v_mfma_f32_16x16x32_bf16 v[2:5], v[110:113], v[240:243], v[2:5]
	v_mfma_f32_16x16x32_bf16 v[34:37], v[102:105], v[216:219], v[34:37]
	v_mfma_f32_16x16x32_bf16 v[38:41], v[110:113], v[216:219], v[38:41]
	v_mfma_f32_16x16x32_bf16 v[42:45], v[102:105], v[224:227], v[42:45]
	v_mfma_f32_16x16x32_bf16 v[46:49], v[110:113], v[224:227], v[46:49]
	s_barrier
; #define PG8_STAGE(bufoff, gbase, voff) do { _Pragma("unroll") for (int _i = 0; _i < 2; ++_i) \
;         __builtin_amdgcn_global_load_lds((const unsigned*)((const char*)(gbase) + (voff)[_i]), (LAS unsigned*)(lds + (bufoff) + ldsw + _i * 8192), 16, 0, 0); } while (0)
; #define PG8_LDA(dst, b, h) do { _Pragma("unroll") for (int m = 0; m < 4; ++m) _Pragma("unroll") for (int k = 0; k < 2; ++k) dst[m][k] = *(const LAS bf16x8*)(lds + PG8_SA(b, h) + aoff + m * 2048 + k * 1024); } while (0)
; #define PG8_LDB(dst, b, h) do { _Pragma("unroll") for (int n = 0; n < 2; ++n) _Pragma("unroll") for (int k = 0; k < 2; ++k) dst[n][k] = *(const LAS bf16x8*)(lds + PG8_SB(b, h) + boff + n * 2048 + k * 1024); } while (0)
; #define PG8_MMA(ai, bj, At, Bt) do { __builtin_amdgcn_s_setprio(1); _Pragma("unroll") for (int m = 0; m < 4; ++m) _Pragma("unroll") for (int n = 0; n < 2; ++n) _Pragma("unroll") for (int k = 0; k < 2; ++k) \
;         acc[ai][bj][m][n] = __builtin_amdgcn_mfma_f32_16x16x32_bf16(Bt[n][k], At[m][k], acc[ai][bj][m][n], 0, 0, 0); __builtin_amdgcn_s_setprio(0); } while (0)
; #define PG8_WAIT_V(n) asm volatile("s_waitcnt vmcnt(" #n ")" ::: "memory")
; #define PG8_WAIT_L(n) asm volatile("s_waitcnt lgkmcnt(" #n ")" ::: "memory")
; #define PG8_BAR __builtin_amdgcn_s_barrier()
; #define PG8_SCHED __builtin_amdgcn_sched_barrier(0)
; template <class Epi, class Sched, bool ALIGN_EPI = false, bool SP2 = false>
; __device__ __forceinline__ void gemm_phase(LAS unsigned char* lds, const Gemm g, const Sched& S, const Epi& E) {
;     ...
;             PG8_LDB(B0, 1, 0); PG8_LDB(B1, 1, 1); PG8_SCHED; PG8_LDA(At, 1, 0); PG8_STAGE(PG8_SA(0, 1), a2 + hstep, voffA);
;             PG8_WAIT_V(8); PG8_WAIT_L(0); PG8_BAR; PG8_MMA(0, 0, At, B0); PG8_MMA(0, 1, At, B1); PG8_BAR; PG8_SCHED;
;             PG8_LDA(At, 1, 1); PG8_STAGE(PG8_SB(1, 0), b3, voffB); PG8_STAGE(PG8_SB(1, 1), b3 + hstepB, voffB); PG8_STAGE(PG8_SA(1, 0), a3, voffA);
;             PG8_WAIT_V(8); PG8_WAIT_L(0); PG8_BAR; PG8_MMA(1, 0, At, B0); PG8_MMA(1, 1, At, B1); PG8_BAR; PG8_SCHED;
	s_add_i32 s21, 0, 0x18000
	s_add_i32 s24, 0, 0x1c000
	v_add_u32_e32 v70, s21, v186
	v_add_u32_e32 v110, s24, v186
	ds_read_b128 v[50:53], v70
	ds_read_b128 v[54:57], v70 offset:1024
	ds_read_b128 v[66:69], v70 offset:2048
	ds_read_b128 v[70:73], v70 offset:3072
	ds_read_b128 v[98:101], v110
	ds_read_b128 v[102:105], v110 offset:1024
	ds_read_b128 v[106:109], v110 offset:2048
	ds_read_b128 v[110:113], v110 offset:3072
	s_add_u32 s22, s58, 0x80000
	s_addc_u32 s23, s59, 0
	s_mov_b32 m0, s33
	ds_read_b128 v[212:215], v205 offset:32768
	ds_read_b128 v[216:219], v205 offset:33792
	ds_read_b128 v[220:223], v205 offset:34816
	ds_read_b128 v[224:227], v205 offset:35840
	ds_read_b128 v[228:231], v205 offset:36864
	ds_read_b128 v[232:235], v205 offset:37888
	ds_read_b128 v[236:239], v205 offset:38912
	ds_read_b128 v[240:243], v205 offset:39936
	global_load_lds_dwordx4 v162, s[22:23]
	s_mov_b32 m0, s60
	s_nop 0
	global_load_lds_dwordx4 v166, s[22:23]
	s_waitcnt vmcnt(8)
	s_waitcnt lgkmcnt(0)
	s_barrier
	s_waitcnt lgkmcnt(0)
	v_mfma_f32_16x16x32_bf16 v[158:161], v[50:53], v[212:215], v[158:161]
	v_mfma_f32_16x16x32_bf16 v[154:157], v[66:69], v[212:215], v[154:157]
	v_mfma_f32_16x16x32_bf16 v[142:145], v[50:53], v[220:223], v[142:145]
	v_mfma_f32_16x16x32_bf16 v[138:141], v[66:69], v[220:223], v[138:141]
	v_mfma_f32_16x16x32_bf16 v[126:129], v[50:53], v[228:231], v[126:129]
	v_mfma_f32_16x16x32_bf16 v[122:125], v[66:69], v[228:231], v[122:125]
	v_mfma_f32_16x16x32_bf16 v[94:97], v[50:53], v[236:239], v[94:97]
	v_mfma_f32_16x16x32_bf16 v[90:93], v[66:69], v[236:239], v[90:93]
	v_mfma_f32_16x16x32_bf16 v[158:161], v[54:57], v[216:219], v[158:161]
	v_mfma_f32_16x16x32_bf16 v[154:157], v[70:73], v[216:219], v[154:157]
	v_mfma_f32_16x16x32_bf16 v[142:145], v[54:57], v[224:227], v[142:145]
	v_mfma_f32_16x16x32_bf16 v[138:141], v[70:73], v[224:227], v[138:141]
	v_mfma_f32_16x16x32_bf16 v[126:129], v[54:57], v[232:235], v[126:129]
	v_mfma_f32_16x16x32_bf16 v[122:125], v[70:73], v[232:235], v[122:125]
	v_mfma_f32_16x16x32_bf16 v[94:97], v[54:57], v[240:243], v[94:97]
	v_mfma_f32_16x16x32_bf16 v[90:93], v[70:73], v[240:243], v[90:93]
	v_mfma_f32_16x16x32_bf16 v[150:153], v[98:101], v[212:215], v[150:153]
	v_mfma_f32_16x16x32_bf16 v[146:149], v[106:109], v[212:215], v[146:149]
	v_mfma_f32_16x16x32_bf16 v[134:137], v[98:101], v[220:223], v[134:137]
	v_mfma_f32_16x16x32_bf16 v[130:133], v[106:109], v[220:223], v[130:133]
	v_mfma_f32_16x16x32_bf16 v[118:121], v[98:101], v[228:231], v[118:121]
	v_mfma_f32_16x16x32_bf16 v[114:117], v[106:109], v[228:231], v[114:117]
	v_mfma_f32_16x16x32_bf16 v[86:89], v[98:101], v[236:239], v[86:89]
	v_mfma_f32_16x16x32_bf16 v[82:85], v[106:109], v[236:239], v[82:85]
	v_mfma_f32_16x16x32_bf16 v[150:153], v[102:105], v[216:219], v[150:153]
	v_mfma_f32_16x16x32_bf16 v[146:149], v[110:113], v[216:219], v[146:149]
	v_mfma_f32_16x16x32_bf16 v[134:137], v[102:105], v[224:227], v[134:137]
	v_mfma_f32_16x16x32_bf16 v[130:133], v[110:113], v[224:227], v[130:133]
	v_mfma_f32_16x16x32_bf16 v[118:121], v[102:105], v[232:235], v[118:121]
	v_mfma_f32_16x16x32_bf16 v[114:117], v[110:113], v[232:235], v[114:117]
	v_mfma_f32_16x16x32_bf16 v[86:89], v[102:105], v[240:243], v[86:89]
	v_mfma_f32_16x16x32_bf16 v[82:85], v[110:113], v[240:243], v[82:85]
	s_barrier
	s_add_u32 s98, s48, 0x80
	s_addc_u32 s99, s49, 0
	s_add_u32 s100, s58, 0x80
	s_addc_u32 s101, s59, 0
	s_add_i32 s21, s21, s29
	s_mov_b32 m0, s21
	ds_read_b128 v[212:215], v205 offset:49152
	ds_read_b128 v[216:219], v205 offset:50176
	ds_read_b128 v[220:223], v205 offset:51200
	ds_read_b128 v[224:227], v205 offset:52224
	ds_read_b128 v[228:231], v205 offset:53248
	ds_read_b128 v[232:235], v205 offset:54272
	ds_read_b128 v[236:239], v205 offset:55296
	ds_read_b128 v[240:243], v205 offset:56320
	global_load_lds_dwordx4 v164, s[98:99]
	s_add_i32 m0, s21, 0x2000
	s_add_u32 s22, s48, 0x20080
	s_addc_u32 s23, s49, 0
	s_add_i32 s21, s24, s29
	global_load_lds_dwordx4 v168, s[98:99]
	s_mov_b32 m0, s21
	s_nop 0
	global_load_lds_dwordx4 v164, s[22:23]
	s_add_i32 m0, s21, 0x2000
	s_nop 0
	global_load_lds_dwordx4 v168, s[22:23]
	s_mov_b32 m0, s65
	s_nop 0
	global_load_lds_dwordx4 v162, s[100:101]
	s_mov_b32 m0, s66
	s_nop 0
	global_load_lds_dwordx4 v166, s[100:101]
	s_waitcnt vmcnt(8)
	s_waitcnt lgkmcnt(0)
	s_barrier
	s_waitcnt lgkmcnt(0)
	v_mfma_f32_16x16x32_bf16 v[78:81], v[50:53], v[212:215], v[78:81]
	v_mfma_f32_16x16x32_bf16 v[74:77], v[66:69], v[212:215], v[74:77]
	v_mfma_f32_16x16x32_bf16 v[62:65], v[50:53], v[220:223], v[62:65]
	v_mfma_f32_16x16x32_bf16 v[58:61], v[66:69], v[220:223], v[58:61]
	v_mfma_f32_16x16x32_bf16 v[30:33], v[50:53], v[228:231], v[30:33]
	v_mfma_f32_16x16x32_bf16 v[26:29], v[66:69], v[228:231], v[26:29]
	v_mfma_f32_16x16x32_bf16 v[14:17], v[50:53], v[236:239], v[14:17]
	v_mfma_f32_16x16x32_bf16 v[10:13], v[66:69], v[236:239], v[10:13]
	v_mfma_f32_16x16x32_bf16 v[78:81], v[54:57], v[216:219], v[78:81]
	v_mfma_f32_16x16x32_bf16 v[74:77], v[70:73], v[216:219], v[74:77]
	v_mfma_f32_16x16x32_bf16 v[62:65], v[54:57], v[224:227], v[62:65]
	v_mfma_f32_16x16x32_bf16 v[58:61], v[70:73], v[224:227], v[58:61]
	v_mfma_f32_16x16x32_bf16 v[30:33], v[54:57], v[232:235], v[30:33]
	v_mfma_f32_16x16x32_bf16 v[26:29], v[70:73], v[232:235], v[26:29]
	v_mfma_f32_16x16x32_bf16 v[14:17], v[54:57], v[240:243], v[14:17]
	v_mfma_f32_16x16x32_bf16 v[10:13], v[70:73], v[240:243], v[10:13]
	v_mfma_f32_16x16x32_bf16 v[34:37], v[98:101], v[212:215], v[34:37]
	v_mfma_f32_16x16x32_bf16 v[70:73], v[102:105], v[216:219], v[34:37]
	v_mfma_f32_16x16x32_bf16 v[34:37], v[106:109], v[212:215], v[38:41]
	v_mfma_f32_16x16x32_bf16 v[66:69], v[110:113], v[216:219], v[34:37]
	v_mfma_f32_16x16x32_bf16 v[34:37], v[98:101], v[220:223], v[42:45]
	v_mfma_f32_16x16x32_bf16 v[54:57], v[102:105], v[224:227], v[34:37]
	v_mfma_f32_16x16x32_bf16 v[34:37], v[106:109], v[220:223], v[46:49]
	v_mfma_f32_16x16x32_bf16 v[22:25], v[98:101], v[228:231], v[22:25]
	v_mfma_f32_16x16x32_bf16 v[18:21], v[106:109], v[228:231], v[18:21]
	v_mfma_f32_16x16x32_bf16 v[6:9], v[98:101], v[236:239], v[6:9]
	v_mfma_f32_16x16x32_bf16 v[2:5], v[106:109], v[236:239], v[2:5]
	v_mfma_f32_16x16x32_bf16 v[50:53], v[110:113], v[224:227], v[34:37]
	v_mfma_f32_16x16x32_bf16 v[22:25], v[102:105], v[232:235], v[22:25]
	v_mfma_f32_16x16x32_bf16 v[18:21], v[110:113], v[232:235], v[18:21]
	v_mfma_f32_16x16x32_bf16 v[6:9], v[102:105], v[240:243], v[6:9]
	v_mfma_f32_16x16x32_bf16 v[2:5], v[110:113], v[240:243], v[2:5]
	s_barrier
	s_add_i32 s20, s20, 2
	s_add_u32 s16, s16, 0x100
	s_addc_u32 s17, s17, 0
	s_add_u32 s18, s18, 0x100
	s_addc_u32 s19, s19, 0
	s_cmp_gt_u32 s20, 29
; #define PG8_STAGE(bufoff, gbase, voff) do { _Pragma("unroll") for (int _i = 0; _i < 2; ++_i) \
;         __builtin_amdgcn_global_load_lds((const unsigned*)((const char*)(gbase) + (voff)[_i]), (LAS unsigned*)(lds + (bufoff) + ldsw + _i * 8192), 16, 0, 0); } while (0)
; #define PG8_LDA(dst, b, h) do { _Pragma("unroll") for (int m = 0; m < 4; ++m) _Pragma("unroll") for (int k = 0; k < 2; ++k) dst[m][k] = *(const LAS bf16x8*)(lds + PG8_SA(b, h) + aoff + m * 2048 + k * 1024); } while (0)
; #define PG8_LDB(dst, b, h) do { _Pragma("unroll") for (int n = 0; n < 2; ++n) _Pragma("unroll") for (int k = 0; k < 2; ++k) dst[n][k] = *(const LAS bf16x8*)(lds + PG8_SB(b, h) + boff + n * 2048 + k * 1024); } while (0)
; #define PG8_MMA(ai, bj, At, Bt) do { __builtin_amdgcn_s_setprio(1); _Pragma("unroll") for (int m = 0; m < 4; ++m) _Pragma("unroll") for (int n = 0; n < 2; ++n) _Pragma("unroll") for (int k = 0; k < 2; ++k) \
;         acc[ai][bj][m][n] = __builtin_amdgcn_mfma_f32_16x16x32_bf16(Bt[n][k], At[m][k], acc[ai][bj][m][n], 0, 0, 0); __builtin_amdgcn_s_setprio(0); } while (0)
; #define PG8_WAIT_V(n) asm volatile("s_waitcnt vmcnt(" #n ")" ::: "memory")
; #define PG8_WAIT_L(n) asm volatile("s_waitcnt lgkmcnt(" #n ")" ::: "memory")
; template <class Epi, class Sched, bool ALIGN_EPI = false, bool SP2 = false>
; __device__ __forceinline__ void gemm_phase(LAS unsigned char* lds, const Gemm g, const Sched& S, const Epi& E) {
;     ...
;         for (int t = 0; t < nt; t += 2) {
;             const bool last = (t == nt - 2);
;             const char* a1 = cA + (size_t)(t + 1) * kstep;
;             const char* a2 = last ? nA : cA + (size_t)(t + 2) * kstep; const char* b2 = last ? nB : cB + (size_t)(t + 2) * kstep;
;             const char* a3 = a2 + kstep; const char* b3 = b2 + kstep;
;             if (last && has_next) S.a_ready(nxt);
;             if constexpr (SP2) {
;             PG8_LDB(B0, 0, 0); PG8_LDB(B1, 0, 1); PG8_SCHED; PG8_LDA(At, 0, 0); PG8_STAGE(PG8_SA(1, 1), a1 + hstep, voffA);
;             PG8_WAIT_V(8); PG8_WAIT_L(0); PG8_BAR; PG8_MMA(0, 0, At, B0); PG8_MMA(0, 1, At, B1); PG8_BAR; PG8_SCHED;
;             PG8_LDA(At, 0, 1); PG8_STAGE(PG8_SB(0, 0), b2, voffB); PG8_STAGE(PG8_SB(0, 1), b2 + hstepB, voffB); PG8_STAGE(PG8_SA(0, 0), a2, voffA);
;             PG8_WAIT_V(8); PG8_WAIT_L(0); PG8_BAR; PG8_MMA(1, 0, At, B0); PG8_MMA(1, 1, At, B1); PG8_BAR; PG8_SCHED;
.LBB0_535:
	ds_read_b128 v[34:37], v203
	ds_read_b128 v[38:41], v203 offset:1024
	ds_read_b128 v[42:45], v203 offset:2048
	ds_read_b128 v[46:49], v203 offset:3072
	s_waitcnt vmcnt(0)
	ds_read_b128 v[98:101], v204
	ds_read_b128 v[102:105], v204 offset:1024
	ds_read_b128 v[106:109], v204 offset:2048
	ds_read_b128 v[110:113], v204 offset:3072
	s_add_u32 s21, s16, 0xfff80080
	s_addc_u32 s22, s17, -1
	s_cmp_eq_u32 s20, 28
	s_cselect_b32 s59, s0, s22
	s_cselect_b32 s58, s3, s21
	s_cselect_b32 s49, s14, s19
	s_cselect_b32 s48, s15, s18
	s_add_i32 m0, s30, 0xc000
	ds_read_b128 v[212:215], v205
	ds_read_b128 v[216:219], v205 offset:1024
	ds_read_b128 v[220:223], v205 offset:2048
	ds_read_b128 v[224:227], v205 offset:3072
	ds_read_b128 v[228:231], v205 offset:4096
	ds_read_b128 v[232:235], v205 offset:5120
	ds_read_b128 v[236:239], v205 offset:6144
	ds_read_b128 v[240:243], v205 offset:7168
	global_load_lds_dwordx4 v172, s[16:17]
	s_add_i32 m0, s30, 0xe000
	s_nop 0
	global_load_lds_dwordx4 v174, s[16:17]
	s_waitcnt vmcnt(8)
	s_waitcnt lgkmcnt(0)
	s_barrier
	s_waitcnt lgkmcnt(0)
	v_mfma_f32_16x16x32_bf16 v[158:161], v[34:37], v[212:215], v[158:161]
	v_mfma_f32_16x16x32_bf16 v[154:157], v[42:45], v[212:215], v[154:157]
	v_mfma_f32_16x16x32_bf16 v[142:145], v[34:37], v[220:223], v[142:145]
	v_mfma_f32_16x16x32_bf16 v[138:141], v[42:45], v[220:223], v[138:141]
	v_mfma_f32_16x16x32_bf16 v[126:129], v[34:37], v[228:231], v[126:129]
	v_mfma_f32_16x16x32_bf16 v[122:125], v[42:45], v[228:231], v[122:125]
	v_mfma_f32_16x16x32_bf16 v[94:97], v[34:37], v[236:239], v[94:97]
	v_mfma_f32_16x16x32_bf16 v[90:93], v[42:45], v[236:239], v[90:93]
	v_mfma_f32_16x16x32_bf16 v[158:161], v[38:41], v[216:219], v[158:161]
	v_mfma_f32_16x16x32_bf16 v[154:157], v[46:49], v[216:219], v[154:157]
	v_mfma_f32_16x16x32_bf16 v[142:145], v[38:41], v[224:227], v[142:145]
	v_mfma_f32_16x16x32_bf16 v[138:141], v[46:49], v[224:227], v[138:141]
	v_mfma_f32_16x16x32_bf16 v[126:129], v[38:41], v[232:235], v[126:129]
	v_mfma_f32_16x16x32_bf16 v[122:125], v[46:49], v[232:235], v[122:125]
	v_mfma_f32_16x16x32_bf16 v[94:97], v[38:41], v[240:243], v[94:97]
	v_mfma_f32_16x16x32_bf16 v[90:93], v[46:49], v[240:243], v[90:93]
	v_mfma_f32_16x16x32_bf16 v[150:153], v[98:101], v[212:215], v[150:153]
	v_mfma_f32_16x16x32_bf16 v[146:149], v[106:109], v[212:215], v[146:149]
	v_mfma_f32_16x16x32_bf16 v[134:137], v[98:101], v[220:223], v[134:137]
	v_mfma_f32_16x16x32_bf16 v[130:133], v[106:109], v[220:223], v[130:133]
	v_mfma_f32_16x16x32_bf16 v[118:121], v[98:101], v[228:231], v[118:121]
	v_mfma_f32_16x16x32_bf16 v[114:117], v[106:109], v[228:231], v[114:117]
	v_mfma_f32_16x16x32_bf16 v[86:89], v[98:101], v[236:239], v[86:89]
	v_mfma_f32_16x16x32_bf16 v[82:85], v[106:109], v[236:239], v[82:85]
	v_mfma_f32_16x16x32_bf16 v[150:153], v[102:105], v[216:219], v[150:153]
	v_mfma_f32_16x16x32_bf16 v[146:149], v[110:113], v[216:219], v[146:149]
	v_mfma_f32_16x16x32_bf16 v[134:137], v[102:105], v[224:227], v[134:137]
	v_mfma_f32_16x16x32_bf16 v[130:133], v[110:113], v[224:227], v[130:133]
	v_mfma_f32_16x16x32_bf16 v[118:121], v[102:105], v[232:235], v[118:121]
	v_mfma_f32_16x16x32_bf16 v[114:117], v[110:113], v[232:235], v[114:117]
	v_mfma_f32_16x16x32_bf16 v[86:89], v[102:105], v[240:243], v[86:89]
	v_mfma_f32_16x16x32_bf16 v[82:85], v[110:113], v[240:243], v[82:85]
	s_barrier
	s_add_i32 s21, s68, s29
	s_mov_b32 m0, s21
	ds_read_b128 v[212:215], v205 offset:16384
	ds_read_b128 v[216:219], v205 offset:17408
	ds_read_b128 v[220:223], v205 offset:18432
	ds_read_b128 v[224:227], v205 offset:19456
	ds_read_b128 v[228:231], v205 offset:20480
	ds_read_b128 v[232:235], v205 offset:21504
	ds_read_b128 v[236:239], v205 offset:22528
	ds_read_b128 v[240:243], v205 offset:23552
	global_load_lds_dwordx4 v164, s[48:49]
	s_add_i32 m0, s21, 0x2000
	s_add_u32 s22, s48, 0x20000
	s_addc_u32 s23, s49, 0
	s_add_i32 s21, s69, s29
	global_load_lds_dwordx4 v168, s[48:49]
	s_mov_b32 m0, s21
	global_load_lds_dwordx4 v164, s[22:23]
	s_add_i32 m0, s21, 0x2000
	s_nop 0
	global_load_lds_dwordx4 v168, s[22:23]
	s_mov_b32 m0, s30
	s_nop 0
	global_load_lds_dwordx4 v162, s[58:59]
	s_mov_b32 m0, s31
	s_nop 0
	global_load_lds_dwordx4 v166, s[58:59]
	s_waitcnt vmcnt(8)
	s_waitcnt lgkmcnt(0)
	s_barrier
	s_waitcnt lgkmcnt(0)
	v_mfma_f32_16x16x32_bf16 v[78:81], v[34:37], v[212:215], v[78:81]
	v_mfma_f32_16x16x32_bf16 v[74:77], v[42:45], v[212:215], v[74:77]
	v_mfma_f32_16x16x32_bf16 v[62:65], v[34:37], v[220:223], v[62:65]
	v_mfma_f32_16x16x32_bf16 v[58:61], v[42:45], v[220:223], v[58:61]
	v_mfma_f32_16x16x32_bf16 v[30:33], v[34:37], v[228:231], v[30:33]
	v_mfma_f32_16x16x32_bf16 v[26:29], v[42:45], v[228:231], v[26:29]
	v_mfma_f32_16x16x32_bf16 v[14:17], v[34:37], v[236:239], v[14:17]
	v_mfma_f32_16x16x32_bf16 v[10:13], v[42:45], v[236:239], v[10:13]
	v_mfma_f32_16x16x32_bf16 v[78:81], v[38:41], v[216:219], v[78:81]
	v_mfma_f32_16x16x32_bf16 v[74:77], v[46:49], v[216:219], v[74:77]
	v_mfma_f32_16x16x32_bf16 v[62:65], v[38:41], v[224:227], v[62:65]
	v_mfma_f32_16x16x32_bf16 v[58:61], v[46:49], v[224:227], v[58:61]
	v_mfma_f32_16x16x32_bf16 v[30:33], v[38:41], v[232:235], v[30:33]
	v_mfma_f32_16x16x32_bf16 v[26:29], v[46:49], v[232:235], v[26:29]
	v_mfma_f32_16x16x32_bf16 v[14:17], v[38:41], v[240:243], v[14:17]
	v_mfma_f32_16x16x32_bf16 v[10:13], v[46:49], v[240:243], v[10:13]
	v_mfma_f32_16x16x32_bf16 v[22:25], v[98:101], v[228:231], v[22:25]
	v_mfma_f32_16x16x32_bf16 v[18:21], v[106:109], v[228:231], v[18:21]
	v_mfma_f32_16x16x32_bf16 v[6:9], v[98:101], v[236:239], v[6:9]
	v_mfma_f32_16x16x32_bf16 v[2:5], v[106:109], v[236:239], v[2:5]
	v_mfma_f32_16x16x32_bf16 v[34:37], v[98:101], v[212:215], v[70:73]
	v_mfma_f32_16x16x32_bf16 v[38:41], v[106:109], v[212:215], v[66:69]
	v_mfma_f32_16x16x32_bf16 v[42:45], v[98:101], v[220:223], v[54:57]
	v_mfma_f32_16x16x32_bf16 v[46:49], v[106:109], v[220:223], v[50:53]
	v_mfma_f32_16x16x32_bf16 v[22:25], v[102:105], v[232:235], v[22:25]
	v_mfma_f32_16x16x32_bf16 v[18:21], v[110:113], v[232:235], v[18:21]
	v_mfma_f32_16x16x32_bf16 v[6:9], v[102:105], v[240:243], v[6:9]
	v_mfma_f32_16x16x32_bf16 v[2:5], v[110:113], v[240:243], v[2:5]
	v_mfma_f32_16x16x32_bf16 v[34:37], v[102:105], v[216:219], v[34:37]
	v_mfma_f32_16x16x32_bf16 v[38:41], v[110:113], v[216:219], v[38:41]
	v_mfma_f32_16x16x32_bf16 v[42:45], v[102:105], v[224:227], v[42:45]
	v_mfma_f32_16x16x32_bf16 v[46:49], v[110:113], v[224:227], v[46:49]
	s_barrier
; #define PG8_STAGE(bufoff, gbase, voff) do { _Pragma("unroll") for (int _i = 0; _i < 2; ++_i) \
;         __builtin_amdgcn_global_load_lds((const unsigned*)((const char*)(gbase) + (voff)[_i]), (LAS unsigned*)(lds + (bufoff) + ldsw + _i * 8192), 16, 0, 0); } while (0)
; #define PG8_LDA(dst, b, h) do { _Pragma("unroll") for (int m = 0; m < 4; ++m) _Pragma("unroll") for (int k = 0; k < 2; ++k) dst[m][k] = *(const LAS bf16x8*)(lds + PG8_SA(b, h) + aoff + m * 2048 + k * 1024); } while (0)
; #define PG8_LDB(dst, b, h) do { _Pragma("unroll") for (int n = 0; n < 2; ++n) _Pragma("unroll") for (int k = 0; k < 2; ++k) dst[n][k] = *(const LAS bf16x8*)(lds + PG8_SB(b, h) + boff + n * 2048 + k * 1024); } while (0)
; #define PG8_MMA(ai, bj, At, Bt) do { __builtin_amdgcn_s_setprio(1); _Pragma("unroll") for (int m = 0; m < 4; ++m) _Pragma("unroll") for (int n = 0; n < 2; ++n) _Pragma("unroll") for (int k = 0; k < 2; ++k) \
;         acc[ai][bj][m][n] = __builtin_amdgcn_mfma_f32_16x16x32_bf16(Bt[n][k], At[m][k], acc[ai][bj][m][n], 0, 0, 0); __builtin_amdgcn_s_setprio(0); } while (0)
; #define PG8_WAIT_V(n) asm volatile("s_waitcnt vmcnt(" #n ")" ::: "memory")
; #define PG8_WAIT_L(n) asm volatile("s_waitcnt lgkmcnt(" #n ")" ::: "memory")
; #define PG8_BAR __builtin_amdgcn_s_barrier()
; #define PG8_SCHED __builtin_amdgcn_sched_barrier(0)
; template <class Epi, class Sched, bool ALIGN_EPI = false, bool SP2 = false>
; __device__ __forceinline__ void gemm_phase(LAS unsigned char* lds, const Gemm g, const Sched& S, const Epi& E) {
;     ...
;             PG8_LDB(B0, 1, 0); PG8_LDB(B1, 1, 1); PG8_SCHED; PG8_LDA(At, 1, 0); PG8_STAGE(PG8_SA(0, 1), a2 + hstep, voffA);
;             PG8_WAIT_V(8); PG8_WAIT_L(0); PG8_BAR; PG8_MMA(0, 0, At, B0); PG8_MMA(0, 1, At, B1); PG8_BAR; PG8_SCHED;
;             PG8_LDA(At, 1, 1); PG8_STAGE(PG8_SB(1, 0), b3, voffB); PG8_STAGE(PG8_SB(1, 1), b3 + hstepB, voffB); PG8_STAGE(PG8_SA(1, 0), a3, voffA);
;             PG8_WAIT_V(8); PG8_WAIT_L(0); PG8_BAR; PG8_MMA(1, 0, At, B0); PG8_MMA(1, 1, At, B1); PG8_BAR; PG8_SCHED;
	s_add_i32 s21, 0, 0x18000
	s_add_i32 s24, 0, 0x1c000
	v_add_u32_e32 v70, s21, v186
	v_add_u32_e32 v110, s24, v186
	ds_read_b128 v[50:53], v70
	ds_read_b128 v[54:57], v70 offset:1024
	ds_read_b128 v[66:69], v70 offset:2048
	ds_read_b128 v[70:73], v70 offset:3072
	ds_read_b128 v[98:101], v110
	ds_read_b128 v[102:105], v110 offset:1024
	ds_read_b128 v[106:109], v110 offset:2048
	ds_read_b128 v[110:113], v110 offset:3072
	s_add_u32 s22, s58, 0x80000
	s_addc_u32 s23, s59, 0
	s_mov_b32 m0, s33
	ds_read_b128 v[212:215], v205 offset:32768
	ds_read_b128 v[216:219], v205 offset:33792
	ds_read_b128 v[220:223], v205 offset:34816
	ds_read_b128 v[224:227], v205 offset:35840
	ds_read_b128 v[228:231], v205 offset:36864
	ds_read_b128 v[232:235], v205 offset:37888
	ds_read_b128 v[236:239], v205 offset:38912
	ds_read_b128 v[240:243], v205 offset:39936
	global_load_lds_dwordx4 v162, s[22:23]
	s_mov_b32 m0, s60
	s_nop 0
	global_load_lds_dwordx4 v166, s[22:23]
	s_waitcnt vmcnt(8)
	s_waitcnt lgkmcnt(0)
	s_barrier
	s_waitcnt lgkmcnt(0)
	v_mfma_f32_16x16x32_bf16 v[158:161], v[50:53], v[212:215], v[158:161]
	v_mfma_f32_16x16x32_bf16 v[154:157], v[66:69], v[212:215], v[154:157]
	v_mfma_f32_16x16x32_bf16 v[142:145], v[50:53], v[220:223], v[142:145]
	v_mfma_f32_16x16x32_bf16 v[138:141], v[66:69], v[220:223], v[138:141]
	v_mfma_f32_16x16x32_bf16 v[126:129], v[50:53], v[228:231], v[126:129]
	v_mfma_f32_16x16x32_bf16 v[122:125], v[66:69], v[228:231], v[122:125]
	v_mfma_f32_16x16x32_bf16 v[94:97], v[50:53], v[236:239], v[94:97]
	v_mfma_f32_16x16x32_bf16 v[90:93], v[66:69], v[236:239], v[90:93]
	v_mfma_f32_16x16x32_bf16 v[158:161], v[54:57], v[216:219], v[158:161]
	v_mfma_f32_16x16x32_bf16 v[154:157], v[70:73], v[216:219], v[154:157]
	v_mfma_f32_16x16x32_bf16 v[142:145], v[54:57], v[224:227], v[142:145]
	v_mfma_f32_16x16x32_bf16 v[138:141], v[70:73], v[224:227], v[138:141]
	v_mfma_f32_16x16x32_bf16 v[126:129], v[54:57], v[232:235], v[126:129]
	v_mfma_f32_16x16x32_bf16 v[122:125], v[70:73], v[232:235], v[122:125]
	v_mfma_f32_16x16x32_bf16 v[94:97], v[54:57], v[240:243], v[94:97]
	v_mfma_f32_16x16x32_bf16 v[90:93], v[70:73], v[240:243], v[90:93]
	v_mfma_f32_16x16x32_bf16 v[150:153], v[98:101], v[212:215], v[150:153]
	v_mfma_f32_16x16x32_bf16 v[146:149], v[106:109], v[212:215], v[146:149]
	v_mfma_f32_16x16x32_bf16 v[134:137], v[98:101], v[220:223], v[134:137]
	v_mfma_f32_16x16x32_bf16 v[130:133], v[106:109], v[220:223], v[130:133]
	v_mfma_f32_16x16x32_bf16 v[118:121], v[98:101], v[228:231], v[118:121]
	v_mfma_f32_16x16x32_bf16 v[114:117], v[106:109], v[228:231], v[114:117]
	v_mfma_f32_16x16x32_bf16 v[86:89], v[98:101], v[236:239], v[86:89]
	v_mfma_f32_16x16x32_bf16 v[82:85], v[106:109], v[236:239], v[82:85]
	v_mfma_f32_16x16x32_bf16 v[150:153], v[102:105], v[216:219], v[150:153]
	v_mfma_f32_16x16x32_bf16 v[146:149], v[110:113], v[216:219], v[146:149]
	v_mfma_f32_16x16x32_bf16 v[134:137], v[102:105], v[224:227], v[134:137]
	v_mfma_f32_16x16x32_bf16 v[130:133], v[110:113], v[224:227], v[130:133]
	v_mfma_f32_16x16x32_bf16 v[118:121], v[102:105], v[232:235], v[118:121]
	v_mfma_f32_16x16x32_bf16 v[114:117], v[110:113], v[232:235], v[114:117]
	v_mfma_f32_16x16x32_bf16 v[86:89], v[102:105], v[240:243], v[86:89]
	v_mfma_f32_16x16x32_bf16 v[82:85], v[110:113], v[240:243], v[82:85]
	s_barrier
	s_add_u32 s98, s48, 0x80
	s_addc_u32 s99, s49, 0
	s_add_u32 s100, s58, 0x80
	s_addc_u32 s101, s59, 0
	s_add_i32 s21, s21, s29
	s_mov_b32 m0, s21
	ds_read_b128 v[212:215], v205 offset:49152
	ds_read_b128 v[216:219], v205 offset:50176
	ds_read_b128 v[220:223], v205 offset:51200
	ds_read_b128 v[224:227], v205 offset:52224
	ds_read_b128 v[228:231], v205 offset:53248
	ds_read_b128 v[232:235], v205 offset:54272
	ds_read_b128 v[236:239], v205 offset:55296
	ds_read_b128 v[240:243], v205 offset:56320
	global_load_lds_dwordx4 v164, s[98:99]
	s_add_i32 m0, s21, 0x2000
	s_add_u32 s22, s48, 0x20080
	s_addc_u32 s23, s49, 0
	s_add_i32 s21, s24, s29
	global_load_lds_dwordx4 v168, s[98:99]
	s_mov_b32 m0, s21
	s_nop 0
	global_load_lds_dwordx4 v164, s[22:23]
	s_add_i32 m0, s21, 0x2000
	s_nop 0
	global_load_lds_dwordx4 v168, s[22:23]
	s_mov_b32 m0, s65
	s_nop 0
	global_load_lds_dwordx4 v162, s[100:101]
	s_mov_b32 m0, s66
	s_nop 0
	global_load_lds_dwordx4 v166, s[100:101]
	s_waitcnt vmcnt(8)
	s_waitcnt lgkmcnt(0)
	s_barrier
	s_waitcnt lgkmcnt(0)
	v_mfma_f32_16x16x32_bf16 v[78:81], v[50:53], v[212:215], v[78:81]
	v_mfma_f32_16x16x32_bf16 v[74:77], v[66:69], v[212:215], v[74:77]
	v_mfma_f32_16x16x32_bf16 v[62:65], v[50:53], v[220:223], v[62:65]
	v_mfma_f32_16x16x32_bf16 v[58:61], v[66:69], v[220:223], v[58:61]
	v_mfma_f32_16x16x32_bf16 v[30:33], v[50:53], v[228:231], v[30:33]
	v_mfma_f32_16x16x32_bf16 v[26:29], v[66:69], v[228:231], v[26:29]
	v_mfma_f32_16x16x32_bf16 v[14:17], v[50:53], v[236:239], v[14:17]
	v_mfma_f32_16x16x32_bf16 v[10:13], v[66:69], v[236:239], v[10:13]
	v_mfma_f32_16x16x32_bf16 v[78:81], v[54:57], v[216:219], v[78:81]
	v_mfma_f32_16x16x32_bf16 v[74:77], v[70:73], v[216:219], v[74:77]
	v_mfma_f32_16x16x32_bf16 v[62:65], v[54:57], v[224:227], v[62:65]
	v_mfma_f32_16x16x32_bf16 v[58:61], v[70:73], v[224:227], v[58:61]
	v_mfma_f32_16x16x32_bf16 v[30:33], v[54:57], v[232:235], v[30:33]
	v_mfma_f32_16x16x32_bf16 v[26:29], v[70:73], v[232:235], v[26:29]
	v_mfma_f32_16x16x32_bf16 v[14:17], v[54:57], v[240:243], v[14:17]
	v_mfma_f32_16x16x32_bf16 v[10:13], v[70:73], v[240:243], v[10:13]
	v_mfma_f32_16x16x32_bf16 v[34:37], v[98:101], v[212:215], v[34:37]
	v_mfma_f32_16x16x32_bf16 v[70:73], v[102:105], v[216:219], v[34:37]
	v_mfma_f32_16x16x32_bf16 v[34:37], v[106:109], v[212:215], v[38:41]
	v_mfma_f32_16x16x32_bf16 v[66:69], v[110:113], v[216:219], v[34:37]
	v_mfma_f32_16x16x32_bf16 v[34:37], v[98:101], v[220:223], v[42:45]
	v_mfma_f32_16x16x32_bf16 v[54:57], v[102:105], v[224:227], v[34:37]
	v_mfma_f32_16x16x32_bf16 v[34:37], v[106:109], v[220:223], v[46:49]
	v_mfma_f32_16x16x32_bf16 v[22:25], v[98:101], v[228:231], v[22:25]
	v_mfma_f32_16x16x32_bf16 v[18:21], v[106:109], v[228:231], v[18:21]
	v_mfma_f32_16x16x32_bf16 v[6:9], v[98:101], v[236:239], v[6:9]
	v_mfma_f32_16x16x32_bf16 v[2:5], v[106:109], v[236:239], v[2:5]
	v_mfma_f32_16x16x32_bf16 v[50:53], v[110:113], v[224:227], v[34:37]
	v_mfma_f32_16x16x32_bf16 v[22:25], v[102:105], v[232:235], v[22:25]
	v_mfma_f32_16x16x32_bf16 v[18:21], v[110:113], v[232:235], v[18:21]
	v_mfma_f32_16x16x32_bf16 v[6:9], v[102:105], v[240:243], v[6:9]
	v_mfma_f32_16x16x32_bf16 v[2:5], v[110:113], v[240:243], v[2:5]
	s_barrier
	s_add_i32 s20, s20, 2
	s_add_u32 s16, s16, 0x100
	s_addc_u32 s17, s17, 0
	s_add_u32 s18, s18, 0x100
	s_addc_u32 s19, s19, 0
	s_cmp_gt_u32 s20, 29
	s_cbranch_scc0 .LBB0_535
	s_setprio 0
	s_and_b64 vcc, exec, s[76:77]
	s_cbranch_vccz .LBB0_538
	s_barrier

; #define PG8_STAGE(bufoff, gbase, voff) do { _Pragma("unroll") for (int _i = 0; _i < 2; ++_i) \
;         __builtin_amdgcn_global_load_lds((const unsigned*)((const char*)(gbase) + (voff)[_i]), (LAS unsigned*)(lds + (bufoff) + ldsw + _i * 8192), 16, 0, 0); } while (0)
; #define PG8_LDA(dst, b, h) do { _Pragma("unroll") for (int m = 0; m < 4; ++m) _Pragma("unroll") for (int k = 0; k < 2; ++k) dst[m][k] = *(const LAS bf16x8*)(lds + PG8_SA(b, h) + aoff + m * 2048 + k * 1024); } while (0)
; #define PG8_LDB(dst, b, h) do { _Pragma("unroll") for (int n = 0; n < 2; ++n) _Pragma("unroll") for (int k = 0; k < 2; ++k) dst[n][k] = *(const LAS bf16x8*)(lds + PG8_SB(b, h) + boff + n * 2048 + k * 1024); } while (0)
; #define PG8_MMA(ai, bj, At, Bt) do { __builtin_amdgcn_s_setprio(1); _Pragma("unroll") for (int m = 0; m < 4; ++m) _Pragma("unroll") for (int n = 0; n < 2; ++n) _Pragma("unroll") for (int k = 0; k < 2; ++k) \
;         acc[ai][bj][m][n] = __builtin_amdgcn_mfma_f32_16x16x32_bf16(Bt[n][k], At[m][k], acc[ai][bj][m][n], 0, 0, 0); __builtin_amdgcn_s_setprio(0); } while (0)
; #define PG8_WAIT_V(n) asm volatile("s_waitcnt vmcnt(" #n ")" ::: "memory")
; #define PG8_WAIT_L(n) asm volatile("s_waitcnt lgkmcnt(" #n ")" ::: "memory")
; template <class Epi, class Sched, bool ALIGN_EPI = false, bool SP2 = false>
; __device__ __forceinline__ void gemm_phase(LAS unsigned char* lds, const Gemm g, const Sched& S, const Epi& E) {
;     ...
;         for (int t = 0; t < nt; t += 2) {
;             const bool last = (t == nt - 2);
;             const char* a1 = cA + (size_t)(t + 1) * kstep;
;             const char* a2 = last ? nA : cA + (size_t)(t + 2) * kstep; const char* b2 = last ? nB : cB + (size_t)(t + 2) * kstep;
;             const char* a3 = a2 + kstep; const char* b3 = b2 + kstep;
;             if (last && has_next) S.a_ready(nxt);
;             if constexpr (SP2) {
;             PG8_LDB(B0, 0, 0); PG8_LDB(B1, 0, 1); PG8_SCHED; PG8_LDA(At, 0, 0); PG8_STAGE(PG8_SA(1, 1), a1 + hstep, voffA);
;             PG8_WAIT_V(8); PG8_WAIT_L(0); PG8_BAR; PG8_MMA(0, 0, At, B0); PG8_MMA(0, 1, At, B1); PG8_BAR; PG8_SCHED;
;             PG8_LDA(At, 0, 1); PG8_STAGE(PG8_SB(0, 0), b2, voffB); PG8_STAGE(PG8_SB(0, 1), b2 + hstepB, voffB); PG8_STAGE(PG8_SA(0, 0), a2, voffA);
;             PG8_WAIT_V(8); PG8_WAIT_L(0); PG8_BAR; PG8_MMA(1, 0, At, B0); PG8_MMA(1, 1, At, B1); PG8_BAR; PG8_SCHED;
.Lprio_1250:
	ds_read_b128 v[50:53], v196
	ds_read_b128 v[54:57], v196 offset:1024
	ds_read_b128 v[138:141], v196 offset:2048
	ds_read_b128 v[142:145], v196 offset:3072
	ds_read_b128 v[146:149], v197
	ds_read_b128 v[150:153], v197 offset:1024
	ds_read_b128 v[174:177], v197 offset:2048
	ds_read_b128 v[178:181], v197 offset:3072
	s_add_u32 s48, s16, 0xfff80080
	s_addc_u32 s49, s17, -1
	s_cmp_eq_u32 s47, 28
	s_cselect_b32 s51, s0, s49
	s_cselect_b32 s50, s3, s48
	s_cselect_b32 s49, s15, s25
	s_cselect_b32 s48, s19, s24
	s_add_i32 m0, s29, 0xc000
	ds_read_b128 v[182:185], v198
	ds_read_b128 v[186:189], v198 offset:1024
	ds_read_b128 v[202:205], v198 offset:2048
	ds_read_b128 v[206:209], v198 offset:3072
	ds_read_b128 v[210:213], v198 offset:4096
	ds_read_b128 v[214:217], v198 offset:5120
	ds_read_b128 v[218:221], v198 offset:6144
	ds_read_b128 v[222:225], v198 offset:7168
	global_load_lds_dwordx4 v166, s[16:17]
	s_add_i32 m0, s29, 0xe000
	s_nop 0
	global_load_lds_dwordx4 v168, s[16:17]
	s_waitcnt lgkmcnt(0)
	s_barrier
	s_waitcnt lgkmcnt(0)
	v_mfma_f32_16x16x32_bf16 v[134:137], v[50:53], v[182:185], 0
	v_mfma_f32_16x16x32_bf16 v[130:133], v[138:141], v[182:185], 0
	v_mfma_f32_16x16x32_bf16 v[118:121], v[50:53], v[202:205], 0
	v_mfma_f32_16x16x32_bf16 v[114:117], v[138:141], v[202:205], 0
	v_mfma_f32_16x16x32_bf16 v[102:105], v[50:53], v[210:213], 0
	v_mfma_f32_16x16x32_bf16 v[98:101], v[138:141], v[210:213], 0
	v_mfma_f32_16x16x32_bf16 v[86:89], v[50:53], v[218:221], 0
	v_mfma_f32_16x16x32_bf16 v[82:85], v[138:141], v[218:221], 0
	v_mfma_f32_16x16x32_bf16 v[134:137], v[54:57], v[186:189], v[134:137]
	v_mfma_f32_16x16x32_bf16 v[130:133], v[142:145], v[186:189], v[130:133]
	v_mfma_f32_16x16x32_bf16 v[118:121], v[54:57], v[206:209], v[118:121]
	v_mfma_f32_16x16x32_bf16 v[114:117], v[142:145], v[206:209], v[114:117]
	v_mfma_f32_16x16x32_bf16 v[102:105], v[54:57], v[214:217], v[102:105]
	v_mfma_f32_16x16x32_bf16 v[98:101], v[142:145], v[214:217], v[98:101]
	v_mfma_f32_16x16x32_bf16 v[86:89], v[54:57], v[222:225], v[86:89]
	v_mfma_f32_16x16x32_bf16 v[82:85], v[142:145], v[222:225], v[82:85]
	v_mfma_f32_16x16x32_bf16 v[126:129], v[146:149], v[182:185], 0
	v_mfma_f32_16x16x32_bf16 v[122:125], v[174:177], v[182:185], 0
	v_mfma_f32_16x16x32_bf16 v[110:113], v[146:149], v[202:205], 0
	v_mfma_f32_16x16x32_bf16 v[106:109], v[174:177], v[202:205], 0
	v_mfma_f32_16x16x32_bf16 v[94:97], v[146:149], v[210:213], 0
	v_mfma_f32_16x16x32_bf16 v[90:93], v[174:177], v[210:213], 0
	v_mfma_f32_16x16x32_bf16 v[78:81], v[146:149], v[218:221], 0
	v_mfma_f32_16x16x32_bf16 v[74:77], v[174:177], v[218:221], 0
	v_mfma_f32_16x16x32_bf16 v[126:129], v[150:153], v[186:189], v[126:129]
	v_mfma_f32_16x16x32_bf16 v[122:125], v[178:181], v[186:189], v[122:125]
	v_mfma_f32_16x16x32_bf16 v[110:113], v[150:153], v[206:209], v[110:113]
	v_mfma_f32_16x16x32_bf16 v[106:109], v[178:181], v[206:209], v[106:109]
	v_mfma_f32_16x16x32_bf16 v[94:97], v[150:153], v[214:217], v[94:97]
	v_mfma_f32_16x16x32_bf16 v[90:93], v[178:181], v[214:217], v[90:93]
	v_mfma_f32_16x16x32_bf16 v[78:81], v[150:153], v[222:225], v[78:81]
	v_mfma_f32_16x16x32_bf16 v[74:77], v[178:181], v[222:225], v[74:77]
	s_barrier
	s_add_i32 s58, s56, s28
	s_mov_b32 m0, s58
	ds_read_b128 v[182:185], v198 offset:16384
	ds_read_b128 v[186:189], v198 offset:17408
	ds_read_b128 v[202:205], v198 offset:18432
	ds_read_b128 v[206:209], v198 offset:19456
	ds_read_b128 v[210:213], v198 offset:20480
	ds_read_b128 v[214:217], v198 offset:21504
	ds_read_b128 v[218:221], v198 offset:22528
	ds_read_b128 v[222:225], v198 offset:23552
	global_load_lds_dwordx4 v156, s[48:49]
	s_add_i32 m0, s58, 0x2000
	s_add_u32 s58, s48, 0x20000
	v_lshl_add_u64 v[226:227], s[48:49], 0, v[160:161]
	s_addc_u32 s59, s49, 0
	s_add_i32 s60, s57, s28
	global_load_lds_dwordx4 v160, s[48:49]
	s_mov_b32 m0, s60
	v_lshl_add_u64 v[230:231], s[50:51], 0, v[158:159]
	global_load_lds_dwordx4 v156, s[58:59]
	s_add_i32 m0, s60, 0x2000
	s_nop 0
	global_load_lds_dwordx4 v160, s[58:59]
	v_lshl_add_u64 v[228:229], s[50:51], 0, v[154:155]
	s_mov_b32 m0, s29
	s_nop 0
	global_load_lds_dwordx4 v154, s[50:51]
	s_mov_b32 m0, s30
	s_nop 0
	global_load_lds_dwordx4 v158, s[50:51]
	s_waitcnt lgkmcnt(0)
	s_barrier
	s_waitcnt lgkmcnt(0)
	v_mfma_f32_16x16x32_bf16 v[70:73], v[50:53], v[182:185], 0
	v_mfma_f32_16x16x32_bf16 v[66:69], v[138:141], v[182:185], 0
	v_mfma_f32_16x16x32_bf16 v[46:49], v[50:53], v[202:205], 0
	v_mfma_f32_16x16x32_bf16 v[42:45], v[138:141], v[202:205], 0
	v_mfma_f32_16x16x32_bf16 v[30:33], v[50:53], v[210:213], 0
	v_mfma_f32_16x16x32_bf16 v[26:29], v[138:141], v[210:213], 0
	v_mfma_f32_16x16x32_bf16 v[14:17], v[50:53], v[218:221], 0
	v_mfma_f32_16x16x32_bf16 v[10:13], v[138:141], v[218:221], 0
	v_mfma_f32_16x16x32_bf16 v[70:73], v[54:57], v[186:189], v[70:73]
	v_mfma_f32_16x16x32_bf16 v[66:69], v[142:145], v[186:189], v[66:69]
	v_mfma_f32_16x16x32_bf16 v[46:49], v[54:57], v[206:209], v[46:49]
	v_mfma_f32_16x16x32_bf16 v[42:45], v[142:145], v[206:209], v[42:45]
	v_mfma_f32_16x16x32_bf16 v[30:33], v[54:57], v[214:217], v[30:33]
	v_mfma_f32_16x16x32_bf16 v[26:29], v[142:145], v[214:217], v[26:29]
	v_mfma_f32_16x16x32_bf16 v[14:17], v[54:57], v[222:225], v[14:17]
	v_mfma_f32_16x16x32_bf16 v[10:13], v[142:145], v[222:225], v[10:13]
	v_mfma_f32_16x16x32_bf16 v[38:41], v[146:149], v[202:205], 0
	v_mfma_f32_16x16x32_bf16 v[34:37], v[174:177], v[202:205], 0
	v_mfma_f32_16x16x32_bf16 v[22:25], v[146:149], v[210:213], 0
	v_mfma_f32_16x16x32_bf16 v[18:21], v[174:177], v[210:213], 0
	v_mfma_f32_16x16x32_bf16 v[6:9], v[146:149], v[218:221], 0
	v_mfma_f32_16x16x32_bf16 v[2:5], v[174:177], v[218:221], 0
	v_mfma_f32_16x16x32_bf16 v[50:53], v[146:149], v[182:185], 0
	v_mfma_f32_16x16x32_bf16 v[54:57], v[174:177], v[182:185], 0
	v_mfma_f32_16x16x32_bf16 v[38:41], v[150:153], v[206:209], v[38:41]
	v_mfma_f32_16x16x32_bf16 v[34:37], v[178:181], v[206:209], v[34:37]
	v_mfma_f32_16x16x32_bf16 v[22:25], v[150:153], v[214:217], v[22:25]
	v_mfma_f32_16x16x32_bf16 v[18:21], v[178:181], v[214:217], v[18:21]
	v_mfma_f32_16x16x32_bf16 v[6:9], v[150:153], v[222:225], v[6:9]
	v_mfma_f32_16x16x32_bf16 v[2:5], v[178:181], v[222:225], v[2:5]
	v_mfma_f32_16x16x32_bf16 v[50:53], v[150:153], v[186:189], v[50:53]
	v_mfma_f32_16x16x32_bf16 v[54:57], v[178:181], v[186:189], v[54:57]
	s_barrier
; #define PG8_STAGE(bufoff, gbase, voff) do { _Pragma("unroll") for (int _i = 0; _i < 2; ++_i) \
;         __builtin_amdgcn_global_load_lds((const unsigned*)((const char*)(gbase) + (voff)[_i]), (LAS unsigned*)(lds + (bufoff) + ldsw + _i * 8192), 16, 0, 0); } while (0)
; #define PG8_LDA(dst, b, h) do { _Pragma("unroll") for (int m = 0; m < 4; ++m) _Pragma("unroll") for (int k = 0; k < 2; ++k) dst[m][k] = *(const LAS bf16x8*)(lds + PG8_SA(b, h) + aoff + m * 2048 + k * 1024); } while (0)
; #define PG8_LDB(dst, b, h) do { _Pragma("unroll") for (int n = 0; n < 2; ++n) _Pragma("unroll") for (int k = 0; k < 2; ++k) dst[n][k] = *(const LAS bf16x8*)(lds + PG8_SB(b, h) + boff + n * 2048 + k * 1024); } while (0)
; #define PG8_MMA(ai, bj, At, Bt) do { __builtin_amdgcn_s_setprio(1); _Pragma("unroll") for (int m = 0; m < 4; ++m) _Pragma("unroll") for (int n = 0; n < 2; ++n) _Pragma("unroll") for (int k = 0; k < 2; ++k) \
;         acc[ai][bj][m][n] = __builtin_amdgcn_mfma_f32_16x16x32_bf16(Bt[n][k], At[m][k], acc[ai][bj][m][n], 0, 0, 0); __builtin_amdgcn_s_setprio(0); } while (0)
; #define PG8_WAIT_V(n) asm volatile("s_waitcnt vmcnt(" #n ")" ::: "memory")
; #define PG8_WAIT_L(n) asm volatile("s_waitcnt lgkmcnt(" #n ")" ::: "memory")
; #define PG8_BAR __builtin_amdgcn_s_barrier()
; #define PG8_SCHED __builtin_amdgcn_sched_barrier(0)
; template <class Epi, class Sched, bool ALIGN_EPI = false, bool SP2 = false>
; __device__ __forceinline__ void gemm_phase(LAS unsigned char* lds, const Gemm g, const Sched& S, const Epi& E) {
;     ...
;             PG8_LDB(B0, 1, 0); PG8_LDB(B1, 1, 1); PG8_SCHED; PG8_LDA(At, 1, 0); PG8_STAGE(PG8_SA(0, 1), a2 + hstep, voffA);
;             PG8_WAIT_V(8); PG8_WAIT_L(0); PG8_BAR; PG8_MMA(0, 0, At, B0); PG8_MMA(0, 1, At, B1); PG8_BAR; PG8_SCHED;
;             PG8_LDA(At, 1, 1); PG8_STAGE(PG8_SB(1, 0), b3, voffB); PG8_STAGE(PG8_SB(1, 1), b3 + hstepB, voffB); PG8_STAGE(PG8_SA(1, 0), a3, voffA);
;             PG8_WAIT_V(8); PG8_WAIT_L(0); PG8_BAR; PG8_MMA(1, 0, At, B0); PG8_MMA(1, 1, At, B1); PG8_BAR; PG8_SCHED;
	s_add_i32 s58, 0, 0x18000
	s_add_i32 s59, 0, 0x1c000
	v_add_u32_e32 v142, s58, v1
	v_add_u32_e32 v162, s59, v1
	ds_read_b128 v[58:61], v142
	ds_read_b128 v[62:65], v142 offset:1024
	ds_read_b128 v[138:141], v142 offset:2048
	ds_read_b128 v[142:145], v142 offset:3072
	ds_read_b128 v[146:149], v162
	ds_read_b128 v[150:153], v162 offset:1024
	ds_read_b128 v[174:177], v162 offset:2048
	ds_read_b128 v[178:181], v162 offset:3072
	s_add_u32 s50, s50, 0x80000
	s_addc_u32 s51, s51, 0
	s_mov_b32 m0, s31
	ds_read_b128 v[182:185], v198 offset:32768
	ds_read_b128 v[186:189], v198 offset:33792
	ds_read_b128 v[202:205], v198 offset:34816
	ds_read_b128 v[206:209], v198 offset:35840
	ds_read_b128 v[210:213], v198 offset:36864
	ds_read_b128 v[214:217], v198 offset:37888
	ds_read_b128 v[218:221], v198 offset:38912
	ds_read_b128 v[222:225], v198 offset:39936
	global_load_lds_dwordx4 v154, s[50:51]
	s_mov_b32 m0, s33
	s_nop 0
	global_load_lds_dwordx4 v158, s[50:51]
	s_waitcnt vmcnt(8)
	s_waitcnt lgkmcnt(0)
	s_barrier
	s_waitcnt lgkmcnt(0)
	v_mfma_f32_16x16x32_bf16 v[134:137], v[58:61], v[182:185], v[134:137]
	v_mfma_f32_16x16x32_bf16 v[130:133], v[138:141], v[182:185], v[130:133]
	v_mfma_f32_16x16x32_bf16 v[118:121], v[58:61], v[202:205], v[118:121]
	v_mfma_f32_16x16x32_bf16 v[114:117], v[138:141], v[202:205], v[114:117]
	v_mfma_f32_16x16x32_bf16 v[102:105], v[58:61], v[210:213], v[102:105]
	v_mfma_f32_16x16x32_bf16 v[98:101], v[138:141], v[210:213], v[98:101]
	v_mfma_f32_16x16x32_bf16 v[86:89], v[58:61], v[218:221], v[86:89]
	v_mfma_f32_16x16x32_bf16 v[82:85], v[138:141], v[218:221], v[82:85]
	v_mfma_f32_16x16x32_bf16 v[134:137], v[62:65], v[186:189], v[134:137]
	v_mfma_f32_16x16x32_bf16 v[130:133], v[142:145], v[186:189], v[130:133]
	v_mfma_f32_16x16x32_bf16 v[118:121], v[62:65], v[206:209], v[118:121]
	v_mfma_f32_16x16x32_bf16 v[114:117], v[142:145], v[206:209], v[114:117]
	v_mfma_f32_16x16x32_bf16 v[102:105], v[62:65], v[214:217], v[102:105]
	v_mfma_f32_16x16x32_bf16 v[98:101], v[142:145], v[214:217], v[98:101]
	v_mfma_f32_16x16x32_bf16 v[86:89], v[62:65], v[222:225], v[86:89]
	v_mfma_f32_16x16x32_bf16 v[82:85], v[142:145], v[222:225], v[82:85]
	v_mfma_f32_16x16x32_bf16 v[126:129], v[146:149], v[182:185], v[126:129]
	v_mfma_f32_16x16x32_bf16 v[122:125], v[174:177], v[182:185], v[122:125]
	v_mfma_f32_16x16x32_bf16 v[110:113], v[146:149], v[202:205], v[110:113]
	v_mfma_f32_16x16x32_bf16 v[106:109], v[174:177], v[202:205], v[106:109]
	v_mfma_f32_16x16x32_bf16 v[94:97], v[146:149], v[210:213], v[94:97]
	v_mfma_f32_16x16x32_bf16 v[90:93], v[174:177], v[210:213], v[90:93]
	v_mfma_f32_16x16x32_bf16 v[78:81], v[146:149], v[218:221], v[78:81]
	v_mfma_f32_16x16x32_bf16 v[74:77], v[174:177], v[218:221], v[74:77]
	v_mfma_f32_16x16x32_bf16 v[126:129], v[150:153], v[186:189], v[126:129]
	v_mfma_f32_16x16x32_bf16 v[122:125], v[178:181], v[186:189], v[122:125]
	v_mfma_f32_16x16x32_bf16 v[110:113], v[150:153], v[206:209], v[110:113]
	v_mfma_f32_16x16x32_bf16 v[106:109], v[178:181], v[206:209], v[106:109]
	v_mfma_f32_16x16x32_bf16 v[94:97], v[150:153], v[214:217], v[94:97]
	v_mfma_f32_16x16x32_bf16 v[90:93], v[178:181], v[214:217], v[90:93]
	v_mfma_f32_16x16x32_bf16 v[78:81], v[150:153], v[222:225], v[78:81]
	v_mfma_f32_16x16x32_bf16 v[74:77], v[178:181], v[222:225], v[74:77]
	s_barrier
	s_add_u32 s98, s48, 0x80
	s_addc_u32 s99, s49, 0
	s_add_i32 s50, s58, s28
	s_mov_b32 m0, s50
	ds_read_b128 v[182:185], v198 offset:49152
	ds_read_b128 v[186:189], v198 offset:50176
	ds_read_b128 v[202:205], v198 offset:51200
	ds_read_b128 v[206:209], v198 offset:52224
	ds_read_b128 v[210:213], v198 offset:53248
	ds_read_b128 v[214:217], v198 offset:54272
	ds_read_b128 v[218:221], v198 offset:55296
	ds_read_b128 v[222:225], v198 offset:56320
	global_load_lds_dwordx4 v156, s[98:99]
	s_add_i32 m0, s50, 0x2000
	s_add_u32 s48, s48, 0x20080
	v_lshl_add_u64 v[190:191], v[226:227], 0, s[10:11]
	s_addc_u32 s49, s49, 0
	s_add_i32 s50, s59, s28
	global_load_lds_dwordx4 v[190:191], off
	s_mov_b32 m0, s50
	s_nop 0
	global_load_lds_dwordx4 v156, s[48:49]
	s_add_i32 m0, s50, 0x2000
	s_nop 0
	global_load_lds_dwordx4 v160, s[48:49]
	v_lshl_add_u64 v[190:191], v[228:229], 0, s[10:11]
	s_mov_b32 m0, s53
	s_nop 0
	global_load_lds_dwordx4 v[190:191], off
	v_lshl_add_u64 v[190:191], v[230:231], 0, s[10:11]
	s_mov_b32 m0, s54
	s_nop 0
	global_load_lds_dwordx4 v[190:191], off
	s_waitcnt vmcnt(8)
	s_waitcnt lgkmcnt(0)
	s_barrier
	s_waitcnt lgkmcnt(0)
	v_mfma_f32_16x16x32_bf16 v[70:73], v[58:61], v[182:185], v[70:73]
	v_mfma_f32_16x16x32_bf16 v[66:69], v[138:141], v[182:185], v[66:69]
	v_mfma_f32_16x16x32_bf16 v[46:49], v[58:61], v[202:205], v[46:49]
	v_mfma_f32_16x16x32_bf16 v[42:45], v[138:141], v[202:205], v[42:45]
	v_mfma_f32_16x16x32_bf16 v[30:33], v[58:61], v[210:213], v[30:33]
	v_mfma_f32_16x16x32_bf16 v[26:29], v[138:141], v[210:213], v[26:29]
	v_mfma_f32_16x16x32_bf16 v[14:17], v[58:61], v[218:221], v[14:17]
	v_mfma_f32_16x16x32_bf16 v[10:13], v[138:141], v[218:221], v[10:13]
	v_mfma_f32_16x16x32_bf16 v[70:73], v[62:65], v[186:189], v[70:73]
	v_mfma_f32_16x16x32_bf16 v[66:69], v[142:145], v[186:189], v[66:69]
	v_mfma_f32_16x16x32_bf16 v[46:49], v[62:65], v[206:209], v[46:49]
	v_mfma_f32_16x16x32_bf16 v[42:45], v[142:145], v[206:209], v[42:45]
	v_mfma_f32_16x16x32_bf16 v[30:33], v[62:65], v[214:217], v[30:33]
	v_mfma_f32_16x16x32_bf16 v[26:29], v[142:145], v[214:217], v[26:29]
	v_mfma_f32_16x16x32_bf16 v[14:17], v[62:65], v[222:225], v[14:17]
	v_mfma_f32_16x16x32_bf16 v[10:13], v[142:145], v[222:225], v[10:13]
	v_mfma_f32_16x16x32_bf16 v[50:53], v[146:149], v[182:185], v[50:53]
	v_mfma_f32_16x16x32_bf16 v[62:65], v[150:153], v[186:189], v[50:53]
	v_mfma_f32_16x16x32_bf16 v[50:53], v[174:177], v[182:185], v[54:57]
	v_mfma_f32_16x16x32_bf16 v[38:41], v[146:149], v[202:205], v[38:41]
	v_mfma_f32_16x16x32_bf16 v[34:37], v[174:177], v[202:205], v[34:37]
	v_mfma_f32_16x16x32_bf16 v[22:25], v[146:149], v[210:213], v[22:25]
	v_mfma_f32_16x16x32_bf16 v[18:21], v[174:177], v[210:213], v[18:21]
	v_mfma_f32_16x16x32_bf16 v[6:9], v[146:149], v[218:221], v[6:9]
	v_mfma_f32_16x16x32_bf16 v[2:5], v[174:177], v[218:221], v[2:5]
	v_mfma_f32_16x16x32_bf16 v[58:61], v[178:181], v[186:189], v[50:53]
	v_mfma_f32_16x16x32_bf16 v[38:41], v[150:153], v[206:209], v[38:41]
	v_mfma_f32_16x16x32_bf16 v[34:37], v[178:181], v[206:209], v[34:37]
	v_mfma_f32_16x16x32_bf16 v[22:25], v[150:153], v[214:217], v[22:25]
	v_mfma_f32_16x16x32_bf16 v[18:21], v[178:181], v[214:217], v[18:21]
	v_mfma_f32_16x16x32_bf16 v[6:9], v[150:153], v[222:225], v[6:9]
	v_mfma_f32_16x16x32_bf16 v[2:5], v[178:181], v[222:225], v[2:5]
	s_barrier
	s_add_i32 s47, s47, 2
	s_add_u32 s16, s16, 0x100
	s_addc_u32 s17, s17, 0
	s_add_u32 s24, s24, 0x100
	s_addc_u32 s25, s25, 0
	s_cmp_gt_u32 s47, 29
; #define PG8_STAGE(bufoff, gbase, voff) do { _Pragma("unroll") for (int _i = 0; _i < 2; ++_i) \
;         __builtin_amdgcn_global_load_lds((const unsigned*)((const char*)(gbase) + (voff)[_i]), (LAS unsigned*)(lds + (bufoff) + ldsw + _i * 8192), 16, 0, 0); } while (0)
; #define PG8_LDA(dst, b, h) do { _Pragma("unroll") for (int m = 0; m < 4; ++m) _Pragma("unroll") for (int k = 0; k < 2; ++k) dst[m][k] = *(const LAS bf16x8*)(lds + PG8_SA(b, h) + aoff + m * 2048 + k * 1024); } while (0)
; #define PG8_LDB(dst, b, h) do { _Pragma("unroll") for (int n = 0; n < 2; ++n) _Pragma("unroll") for (int k = 0; k < 2; ++k) dst[n][k] = *(const LAS bf16x8*)(lds + PG8_SB(b, h) + boff + n * 2048 + k * 1024); } while (0)
; #define PG8_MMA(ai, bj, At, Bt) do { __builtin_amdgcn_s_setprio(1); _Pragma("unroll") for (int m = 0; m < 4; ++m) _Pragma("unroll") for (int n = 0; n < 2; ++n) _Pragma("unroll") for (int k = 0; k < 2; ++k) \
;         acc[ai][bj][m][n] = __builtin_amdgcn_mfma_f32_16x16x32_bf16(Bt[n][k], At[m][k], acc[ai][bj][m][n], 0, 0, 0); __builtin_amdgcn_s_setprio(0); } while (0)
; #define PG8_WAIT_V(n) asm volatile("s_waitcnt vmcnt(" #n ")" ::: "memory")
; #define PG8_WAIT_L(n) asm volatile("s_waitcnt lgkmcnt(" #n ")" ::: "memory")
; template <class Epi, class Sched, bool ALIGN_EPI = false, bool SP2 = false>
; __device__ __forceinline__ void gemm_phase(LAS unsigned char* lds, const Gemm g, const Sched& S, const Epi& E) {
;     ...
;         for (int t = 0; t < nt; t += 2) {
;             const bool last = (t == nt - 2);
;             const char* a1 = cA + (size_t)(t + 1) * kstep;
;             const char* a2 = last ? nA : cA + (size_t)(t + 2) * kstep; const char* b2 = last ? nB : cB + (size_t)(t + 2) * kstep;
;             const char* a3 = a2 + kstep; const char* b3 = b2 + kstep;
;             if (last && has_next) S.a_ready(nxt);
;             if constexpr (SP2) {
;             PG8_LDB(B0, 0, 0); PG8_LDB(B1, 0, 1); PG8_SCHED; PG8_LDA(At, 0, 0); PG8_STAGE(PG8_SA(1, 1), a1 + hstep, voffA);
;             PG8_WAIT_V(8); PG8_WAIT_L(0); PG8_BAR; PG8_MMA(0, 0, At, B0); PG8_MMA(0, 1, At, B1); PG8_BAR; PG8_SCHED;
;             PG8_LDA(At, 0, 1); PG8_STAGE(PG8_SB(0, 0), b2, voffB); PG8_STAGE(PG8_SB(0, 1), b2 + hstepB, voffB); PG8_STAGE(PG8_SA(0, 0), a2, voffA);
;             PG8_WAIT_V(8); PG8_WAIT_L(0); PG8_BAR; PG8_MMA(1, 0, At, B0); PG8_MMA(1, 1, At, B1); PG8_BAR; PG8_SCHED;
.LBB0_1250:
	ds_read_b128 v[50:53], v196
	ds_read_b128 v[54:57], v196 offset:1024
	ds_read_b128 v[138:141], v196 offset:2048
	ds_read_b128 v[142:145], v196 offset:3072
	ds_read_b128 v[146:149], v197
	ds_read_b128 v[150:153], v197 offset:1024
	ds_read_b128 v[174:177], v197 offset:2048
	ds_read_b128 v[178:181], v197 offset:3072
	s_add_u32 s48, s16, 0xfff80080
	s_addc_u32 s49, s17, -1
	s_cmp_eq_u32 s47, 28
	s_cselect_b32 s51, s0, s49
	s_cselect_b32 s50, s3, s48
	s_cselect_b32 s49, s15, s25
	s_cselect_b32 s48, s19, s24
	s_add_i32 m0, s29, 0xc000
	ds_read_b128 v[182:185], v198
	ds_read_b128 v[186:189], v198 offset:1024
	ds_read_b128 v[202:205], v198 offset:2048
	ds_read_b128 v[206:209], v198 offset:3072
	ds_read_b128 v[210:213], v198 offset:4096
	ds_read_b128 v[214:217], v198 offset:5120
	ds_read_b128 v[218:221], v198 offset:6144
	ds_read_b128 v[222:225], v198 offset:7168
	global_load_lds_dwordx4 v166, s[16:17]
	s_add_i32 m0, s29, 0xe000
	s_nop 0
	global_load_lds_dwordx4 v168, s[16:17]
	s_waitcnt vmcnt(8)
	s_waitcnt lgkmcnt(0)
	s_barrier
	s_waitcnt lgkmcnt(0)
	v_mfma_f32_16x16x32_bf16 v[134:137], v[50:53], v[182:185], v[134:137]
	v_mfma_f32_16x16x32_bf16 v[130:133], v[138:141], v[182:185], v[130:133]
	v_mfma_f32_16x16x32_bf16 v[118:121], v[50:53], v[202:205], v[118:121]
	v_mfma_f32_16x16x32_bf16 v[114:117], v[138:141], v[202:205], v[114:117]
	v_mfma_f32_16x16x32_bf16 v[102:105], v[50:53], v[210:213], v[102:105]
	v_mfma_f32_16x16x32_bf16 v[98:101], v[138:141], v[210:213], v[98:101]
	v_mfma_f32_16x16x32_bf16 v[86:89], v[50:53], v[218:221], v[86:89]
	v_mfma_f32_16x16x32_bf16 v[82:85], v[138:141], v[218:221], v[82:85]
	v_mfma_f32_16x16x32_bf16 v[134:137], v[54:57], v[186:189], v[134:137]
	v_mfma_f32_16x16x32_bf16 v[130:133], v[142:145], v[186:189], v[130:133]
	v_mfma_f32_16x16x32_bf16 v[118:121], v[54:57], v[206:209], v[118:121]
	v_mfma_f32_16x16x32_bf16 v[114:117], v[142:145], v[206:209], v[114:117]
	v_mfma_f32_16x16x32_bf16 v[102:105], v[54:57], v[214:217], v[102:105]
	v_mfma_f32_16x16x32_bf16 v[98:101], v[142:145], v[214:217], v[98:101]
	v_mfma_f32_16x16x32_bf16 v[86:89], v[54:57], v[222:225], v[86:89]
	v_mfma_f32_16x16x32_bf16 v[82:85], v[142:145], v[222:225], v[82:85]
	v_mfma_f32_16x16x32_bf16 v[126:129], v[146:149], v[182:185], v[126:129]
	v_mfma_f32_16x16x32_bf16 v[122:125], v[174:177], v[182:185], v[122:125]
	v_mfma_f32_16x16x32_bf16 v[110:113], v[146:149], v[202:205], v[110:113]
	v_mfma_f32_16x16x32_bf16 v[106:109], v[174:177], v[202:205], v[106:109]
	v_mfma_f32_16x16x32_bf16 v[94:97], v[146:149], v[210:213], v[94:97]
	v_mfma_f32_16x16x32_bf16 v[90:93], v[174:177], v[210:213], v[90:93]
	v_mfma_f32_16x16x32_bf16 v[78:81], v[146:149], v[218:221], v[78:81]
	v_mfma_f32_16x16x32_bf16 v[74:77], v[174:177], v[218:221], v[74:77]
	v_mfma_f32_16x16x32_bf16 v[126:129], v[150:153], v[186:189], v[126:129]
	v_mfma_f32_16x16x32_bf16 v[122:125], v[178:181], v[186:189], v[122:125]
	v_mfma_f32_16x16x32_bf16 v[110:113], v[150:153], v[206:209], v[110:113]
	v_mfma_f32_16x16x32_bf16 v[106:109], v[178:181], v[206:209], v[106:109]
	v_mfma_f32_16x16x32_bf16 v[94:97], v[150:153], v[214:217], v[94:97]
	v_mfma_f32_16x16x32_bf16 v[90:93], v[178:181], v[214:217], v[90:93]
	v_mfma_f32_16x16x32_bf16 v[78:81], v[150:153], v[222:225], v[78:81]
	v_mfma_f32_16x16x32_bf16 v[74:77], v[178:181], v[222:225], v[74:77]
	s_barrier
	s_add_i32 s58, s56, s28
	s_mov_b32 m0, s58
	ds_read_b128 v[182:185], v198 offset:16384
	ds_read_b128 v[186:189], v198 offset:17408
	ds_read_b128 v[202:205], v198 offset:18432
	ds_read_b128 v[206:209], v198 offset:19456
	ds_read_b128 v[210:213], v198 offset:20480
	ds_read_b128 v[214:217], v198 offset:21504
	ds_read_b128 v[218:221], v198 offset:22528
	ds_read_b128 v[222:225], v198 offset:23552
	global_load_lds_dwordx4 v156, s[48:49]
	s_add_i32 m0, s58, 0x2000
	s_add_u32 s58, s48, 0x20000
	v_lshl_add_u64 v[226:227], s[48:49], 0, v[160:161]
	s_addc_u32 s59, s49, 0
	s_add_i32 s60, s57, s28
	global_load_lds_dwordx4 v160, s[48:49]
	s_mov_b32 m0, s60
	v_lshl_add_u64 v[230:231], s[50:51], 0, v[158:159]
	global_load_lds_dwordx4 v156, s[58:59]
	s_add_i32 m0, s60, 0x2000
	s_nop 0
	global_load_lds_dwordx4 v160, s[58:59]
	v_lshl_add_u64 v[228:229], s[50:51], 0, v[154:155]
	s_mov_b32 m0, s29
	s_nop 0
	global_load_lds_dwordx4 v154, s[50:51]
	s_mov_b32 m0, s30
	s_nop 0
	global_load_lds_dwordx4 v158, s[50:51]
	s_waitcnt vmcnt(8)
	s_waitcnt lgkmcnt(0)
	s_barrier
	s_waitcnt lgkmcnt(0)
	v_mfma_f32_16x16x32_bf16 v[70:73], v[50:53], v[182:185], v[70:73]
	v_mfma_f32_16x16x32_bf16 v[66:69], v[138:141], v[182:185], v[66:69]
	v_mfma_f32_16x16x32_bf16 v[46:49], v[50:53], v[202:205], v[46:49]
	v_mfma_f32_16x16x32_bf16 v[42:45], v[138:141], v[202:205], v[42:45]
	v_mfma_f32_16x16x32_bf16 v[30:33], v[50:53], v[210:213], v[30:33]
	v_mfma_f32_16x16x32_bf16 v[26:29], v[138:141], v[210:213], v[26:29]
	v_mfma_f32_16x16x32_bf16 v[14:17], v[50:53], v[218:221], v[14:17]
	v_mfma_f32_16x16x32_bf16 v[10:13], v[138:141], v[218:221], v[10:13]
	v_mfma_f32_16x16x32_bf16 v[70:73], v[54:57], v[186:189], v[70:73]
	v_mfma_f32_16x16x32_bf16 v[66:69], v[142:145], v[186:189], v[66:69]
	v_mfma_f32_16x16x32_bf16 v[46:49], v[54:57], v[206:209], v[46:49]
	v_mfma_f32_16x16x32_bf16 v[42:45], v[142:145], v[206:209], v[42:45]
	v_mfma_f32_16x16x32_bf16 v[30:33], v[54:57], v[214:217], v[30:33]
	v_mfma_f32_16x16x32_bf16 v[26:29], v[142:145], v[214:217], v[26:29]
	v_mfma_f32_16x16x32_bf16 v[14:17], v[54:57], v[222:225], v[14:17]
	v_mfma_f32_16x16x32_bf16 v[10:13], v[142:145], v[222:225], v[10:13]
	v_mfma_f32_16x16x32_bf16 v[38:41], v[146:149], v[202:205], v[38:41]
	v_mfma_f32_16x16x32_bf16 v[34:37], v[174:177], v[202:205], v[34:37]
	v_mfma_f32_16x16x32_bf16 v[22:25], v[146:149], v[210:213], v[22:25]
	v_mfma_f32_16x16x32_bf16 v[18:21], v[174:177], v[210:213], v[18:21]
	v_mfma_f32_16x16x32_bf16 v[6:9], v[146:149], v[218:221], v[6:9]
	v_mfma_f32_16x16x32_bf16 v[2:5], v[174:177], v[218:221], v[2:5]
	v_mfma_f32_16x16x32_bf16 v[50:53], v[146:149], v[182:185], v[62:65]
	v_mfma_f32_16x16x32_bf16 v[54:57], v[174:177], v[182:185], v[58:61]
	v_mfma_f32_16x16x32_bf16 v[38:41], v[150:153], v[206:209], v[38:41]
	v_mfma_f32_16x16x32_bf16 v[34:37], v[178:181], v[206:209], v[34:37]
	v_mfma_f32_16x16x32_bf16 v[22:25], v[150:153], v[214:217], v[22:25]
	v_mfma_f32_16x16x32_bf16 v[18:21], v[178:181], v[214:217], v[18:21]
	v_mfma_f32_16x16x32_bf16 v[6:9], v[150:153], v[222:225], v[6:9]
	v_mfma_f32_16x16x32_bf16 v[2:5], v[178:181], v[222:225], v[2:5]
	v_mfma_f32_16x16x32_bf16 v[50:53], v[150:153], v[186:189], v[50:53]
	v_mfma_f32_16x16x32_bf16 v[54:57], v[178:181], v[186:189], v[54:57]
	s_barrier
; #define PG8_STAGE(bufoff, gbase, voff) do { _Pragma("unroll") for (int _i = 0; _i < 2; ++_i) \
;         __builtin_amdgcn_global_load_lds((const unsigned*)((const char*)(gbase) + (voff)[_i]), (LAS unsigned*)(lds + (bufoff) + ldsw + _i * 8192), 16, 0, 0); } while (0)
; #define PG8_LDA(dst, b, h) do { _Pragma("unroll") for (int m = 0; m < 4; ++m) _Pragma("unroll") for (int k = 0; k < 2; ++k) dst[m][k] = *(const LAS bf16x8*)(lds + PG8_SA(b, h) + aoff + m * 2048 + k * 1024); } while (0)
; #define PG8_LDB(dst, b, h) do { _Pragma("unroll") for (int n = 0; n < 2; ++n) _Pragma("unroll") for (int k = 0; k < 2; ++k) dst[n][k] = *(const LAS bf16x8*)(lds + PG8_SB(b, h) + boff + n * 2048 + k * 1024); } while (0)
; #define PG8_MMA(ai, bj, At, Bt) do { __builtin_amdgcn_s_setprio(1); _Pragma("unroll") for (int m = 0; m < 4; ++m) _Pragma("unroll") for (int n = 0; n < 2; ++n) _Pragma("unroll") for (int k = 0; k < 2; ++k) \
;         acc[ai][bj][m][n] = __builtin_amdgcn_mfma_f32_16x16x32_bf16(Bt[n][k], At[m][k], acc[ai][bj][m][n], 0, 0, 0); __builtin_amdgcn_s_setprio(0); } while (0)
; #define PG8_WAIT_V(n) asm volatile("s_waitcnt vmcnt(" #n ")" ::: "memory")
; #define PG8_WAIT_L(n) asm volatile("s_waitcnt lgkmcnt(" #n ")" ::: "memory")
; #define PG8_BAR __builtin_amdgcn_s_barrier()
; #define PG8_SCHED __builtin_amdgcn_sched_barrier(0)
; template <class Epi, class Sched, bool ALIGN_EPI = false, bool SP2 = false>
; __device__ __forceinline__ void gemm_phase(LAS unsigned char* lds, const Gemm g, const Sched& S, const Epi& E) {
;     ...
;             PG8_LDB(B0, 1, 0); PG8_LDB(B1, 1, 1); PG8_SCHED; PG8_LDA(At, 1, 0); PG8_STAGE(PG8_SA(0, 1), a2 + hstep, voffA);
;             PG8_WAIT_V(8); PG8_WAIT_L(0); PG8_BAR; PG8_MMA(0, 0, At, B0); PG8_MMA(0, 1, At, B1); PG8_BAR; PG8_SCHED;
;             PG8_LDA(At, 1, 1); PG8_STAGE(PG8_SB(1, 0), b3, voffB); PG8_STAGE(PG8_SB(1, 1), b3 + hstepB, voffB); PG8_STAGE(PG8_SA(1, 0), a3, voffA);
;             PG8_WAIT_V(8); PG8_WAIT_L(0); PG8_BAR; PG8_MMA(1, 0, At, B0); PG8_MMA(1, 1, At, B1); PG8_BAR; PG8_SCHED;
	s_add_i32 s58, 0, 0x18000
	s_add_i32 s59, 0, 0x1c000
	v_add_u32_e32 v142, s58, v1
	v_add_u32_e32 v162, s59, v1
	ds_read_b128 v[58:61], v142
	ds_read_b128 v[62:65], v142 offset:1024
	ds_read_b128 v[138:141], v142 offset:2048
	ds_read_b128 v[142:145], v142 offset:3072
	ds_read_b128 v[146:149], v162
	ds_read_b128 v[150:153], v162 offset:1024
	ds_read_b128 v[174:177], v162 offset:2048
	ds_read_b128 v[178:181], v162 offset:3072
	s_add_u32 s50, s50, 0x80000
	s_addc_u32 s51, s51, 0
	s_mov_b32 m0, s31
	ds_read_b128 v[182:185], v198 offset:32768
	ds_read_b128 v[186:189], v198 offset:33792
	ds_read_b128 v[202:205], v198 offset:34816
	ds_read_b128 v[206:209], v198 offset:35840
	ds_read_b128 v[210:213], v198 offset:36864
	ds_read_b128 v[214:217], v198 offset:37888
	ds_read_b128 v[218:221], v198 offset:38912
	ds_read_b128 v[222:225], v198 offset:39936
	global_load_lds_dwordx4 v154, s[50:51]
	s_mov_b32 m0, s33
	s_nop 0
	global_load_lds_dwordx4 v158, s[50:51]
	s_waitcnt vmcnt(8)
	s_waitcnt lgkmcnt(0)
	s_barrier
	s_waitcnt lgkmcnt(0)
	v_mfma_f32_16x16x32_bf16 v[134:137], v[58:61], v[182:185], v[134:137]
	v_mfma_f32_16x16x32_bf16 v[130:133], v[138:141], v[182:185], v[130:133]
	v_mfma_f32_16x16x32_bf16 v[118:121], v[58:61], v[202:205], v[118:121]
	v_mfma_f32_16x16x32_bf16 v[114:117], v[138:141], v[202:205], v[114:117]
	v_mfma_f32_16x16x32_bf16 v[102:105], v[58:61], v[210:213], v[102:105]
	v_mfma_f32_16x16x32_bf16 v[98:101], v[138:141], v[210:213], v[98:101]
	v_mfma_f32_16x16x32_bf16 v[86:89], v[58:61], v[218:221], v[86:89]
	v_mfma_f32_16x16x32_bf16 v[82:85], v[138:141], v[218:221], v[82:85]
	v_mfma_f32_16x16x32_bf16 v[134:137], v[62:65], v[186:189], v[134:137]
	v_mfma_f32_16x16x32_bf16 v[130:133], v[142:145], v[186:189], v[130:133]
	v_mfma_f32_16x16x32_bf16 v[118:121], v[62:65], v[206:209], v[118:121]
	v_mfma_f32_16x16x32_bf16 v[114:117], v[142:145], v[206:209], v[114:117]
	v_mfma_f32_16x16x32_bf16 v[102:105], v[62:65], v[214:217], v[102:105]
	v_mfma_f32_16x16x32_bf16 v[98:101], v[142:145], v[214:217], v[98:101]
	v_mfma_f32_16x16x32_bf16 v[86:89], v[62:65], v[222:225], v[86:89]
	v_mfma_f32_16x16x32_bf16 v[82:85], v[142:145], v[222:225], v[82:85]
	v_mfma_f32_16x16x32_bf16 v[126:129], v[146:149], v[182:185], v[126:129]
	v_mfma_f32_16x16x32_bf16 v[122:125], v[174:177], v[182:185], v[122:125]
	v_mfma_f32_16x16x32_bf16 v[110:113], v[146:149], v[202:205], v[110:113]
	v_mfma_f32_16x16x32_bf16 v[106:109], v[174:177], v[202:205], v[106:109]
	v_mfma_f32_16x16x32_bf16 v[94:97], v[146:149], v[210:213], v[94:97]
	v_mfma_f32_16x16x32_bf16 v[90:93], v[174:177], v[210:213], v[90:93]
	v_mfma_f32_16x16x32_bf16 v[78:81], v[146:149], v[218:221], v[78:81]
	v_mfma_f32_16x16x32_bf16 v[74:77], v[174:177], v[218:221], v[74:77]
	v_mfma_f32_16x16x32_bf16 v[126:129], v[150:153], v[186:189], v[126:129]
	v_mfma_f32_16x16x32_bf16 v[122:125], v[178:181], v[186:189], v[122:125]
	v_mfma_f32_16x16x32_bf16 v[110:113], v[150:153], v[206:209], v[110:113]
	v_mfma_f32_16x16x32_bf16 v[106:109], v[178:181], v[206:209], v[106:109]
	v_mfma_f32_16x16x32_bf16 v[94:97], v[150:153], v[214:217], v[94:97]
	v_mfma_f32_16x16x32_bf16 v[90:93], v[178:181], v[214:217], v[90:93]
	v_mfma_f32_16x16x32_bf16 v[78:81], v[150:153], v[222:225], v[78:81]
	v_mfma_f32_16x16x32_bf16 v[74:77], v[178:181], v[222:225], v[74:77]
	s_barrier
	s_add_u32 s98, s48, 0x80
	s_addc_u32 s99, s49, 0
	s_add_i32 s50, s58, s28
	s_mov_b32 m0, s50
	ds_read_b128 v[182:185], v198 offset:49152
	ds_read_b128 v[186:189], v198 offset:50176
	ds_read_b128 v[202:205], v198 offset:51200
	ds_read_b128 v[206:209], v198 offset:52224
	ds_read_b128 v[210:213], v198 offset:53248
	ds_read_b128 v[214:217], v198 offset:54272
	ds_read_b128 v[218:221], v198 offset:55296
	ds_read_b128 v[222:225], v198 offset:56320
	global_load_lds_dwordx4 v156, s[98:99]
	s_add_i32 m0, s50, 0x2000
	s_add_u32 s48, s48, 0x20080
	v_lshl_add_u64 v[190:191], v[226:227], 0, s[10:11]
	s_addc_u32 s49, s49, 0
	s_add_i32 s50, s59, s28
	global_load_lds_dwordx4 v[190:191], off
	s_mov_b32 m0, s50
	s_nop 0
	global_load_lds_dwordx4 v156, s[48:49]
	s_add_i32 m0, s50, 0x2000
	s_nop 0
	global_load_lds_dwordx4 v160, s[48:49]
	v_lshl_add_u64 v[190:191], v[228:229], 0, s[10:11]
	s_mov_b32 m0, s53
	s_nop 0
	global_load_lds_dwordx4 v[190:191], off
	v_lshl_add_u64 v[190:191], v[230:231], 0, s[10:11]
	s_mov_b32 m0, s54
	s_nop 0
	global_load_lds_dwordx4 v[190:191], off
	s_waitcnt vmcnt(8)
	s_waitcnt lgkmcnt(0)
	s_barrier
	s_waitcnt lgkmcnt(0)
	v_mfma_f32_16x16x32_bf16 v[70:73], v[58:61], v[182:185], v[70:73]
	v_mfma_f32_16x16x32_bf16 v[66:69], v[138:141], v[182:185], v[66:69]
	v_mfma_f32_16x16x32_bf16 v[46:49], v[58:61], v[202:205], v[46:49]
	v_mfma_f32_16x16x32_bf16 v[42:45], v[138:141], v[202:205], v[42:45]
	v_mfma_f32_16x16x32_bf16 v[30:33], v[58:61], v[210:213], v[30:33]
	v_mfma_f32_16x16x32_bf16 v[26:29], v[138:141], v[210:213], v[26:29]
	v_mfma_f32_16x16x32_bf16 v[14:17], v[58:61], v[218:221], v[14:17]
	v_mfma_f32_16x16x32_bf16 v[10:13], v[138:141], v[218:221], v[10:13]
	v_mfma_f32_16x16x32_bf16 v[70:73], v[62:65], v[186:189], v[70:73]
	v_mfma_f32_16x16x32_bf16 v[66:69], v[142:145], v[186:189], v[66:69]
	v_mfma_f32_16x16x32_bf16 v[46:49], v[62:65], v[206:209], v[46:49]
	v_mfma_f32_16x16x32_bf16 v[42:45], v[142:145], v[206:209], v[42:45]
	v_mfma_f32_16x16x32_bf16 v[30:33], v[62:65], v[214:217], v[30:33]
	v_mfma_f32_16x16x32_bf16 v[26:29], v[142:145], v[214:217], v[26:29]
	v_mfma_f32_16x16x32_bf16 v[14:17], v[62:65], v[222:225], v[14:17]
	v_mfma_f32_16x16x32_bf16 v[10:13], v[142:145], v[222:225], v[10:13]
	v_mfma_f32_16x16x32_bf16 v[50:53], v[146:149], v[182:185], v[50:53]
	v_mfma_f32_16x16x32_bf16 v[62:65], v[150:153], v[186:189], v[50:53]
	v_mfma_f32_16x16x32_bf16 v[50:53], v[174:177], v[182:185], v[54:57]
	v_mfma_f32_16x16x32_bf16 v[38:41], v[146:149], v[202:205], v[38:41]
	v_mfma_f32_16x16x32_bf16 v[34:37], v[174:177], v[202:205], v[34:37]
	v_mfma_f32_16x16x32_bf16 v[22:25], v[146:149], v[210:213], v[22:25]
	v_mfma_f32_16x16x32_bf16 v[18:21], v[174:177], v[210:213], v[18:21]
	v_mfma_f32_16x16x32_bf16 v[6:9], v[146:149], v[218:221], v[6:9]
	v_mfma_f32_16x16x32_bf16 v[2:5], v[174:177], v[218:221], v[2:5]
	v_mfma_f32_16x16x32_bf16 v[58:61], v[178:181], v[186:189], v[50:53]
	v_mfma_f32_16x16x32_bf16 v[38:41], v[150:153], v[206:209], v[38:41]
	v_mfma_f32_16x16x32_bf16 v[34:37], v[178:181], v[206:209], v[34:37]
	v_mfma_f32_16x16x32_bf16 v[22:25], v[150:153], v[214:217], v[22:25]
	v_mfma_f32_16x16x32_bf16 v[18:21], v[178:181], v[214:217], v[18:21]
	v_mfma_f32_16x16x32_bf16 v[6:9], v[150:153], v[222:225], v[6:9]
	v_mfma_f32_16x16x32_bf16 v[2:5], v[178:181], v[222:225], v[2:5]
	s_barrier
	s_add_i32 s47, s47, 2
	s_add_u32 s16, s16, 0x100
	s_addc_u32 s17, s17, 0
	s_add_u32 s24, s24, 0x100
	s_addc_u32 s25, s25, 0
	s_cmp_gt_u32 s47, 29
	s_cbranch_scc0 .LBB0_1250
	s_setprio 0
	s_and_b64 vcc, exec, s[12:13]
	s_cbranch_vccz .LBB0_1253
	s_barrier

; #define PG8_STAGE(bufoff, gbase, voff) do { _Pragma("unroll") for (int _i = 0; _i < 2; ++_i) \
;         __builtin_amdgcn_global_load_lds((const unsigned*)((const char*)(gbase) + (voff)[_i]), (LAS unsigned*)(lds + (bufoff) + ldsw + _i * 8192), 16, 0, 0); } while (0)
; #define PG8_LDA(dst, b, h) do { _Pragma("unroll") for (int m = 0; m < 4; ++m) _Pragma("unroll") for (int k = 0; k < 2; ++k) dst[m][k] = *(const LAS bf16x8*)(lds + PG8_SA(b, h) + aoff + m * 2048 + k * 1024); } while (0)
; #define PG8_LDB(dst, b, h) do { _Pragma("unroll") for (int n = 0; n < 2; ++n) _Pragma("unroll") for (int k = 0; k < 2; ++k) dst[n][k] = *(const LAS bf16x8*)(lds + PG8_SB(b, h) + boff + n * 2048 + k * 1024); } while (0)
; #define PG8_MMA(ai, bj, At, Bt) do { __builtin_amdgcn_s_setprio(1); _Pragma("unroll") for (int m = 0; m < 4; ++m) _Pragma("unroll") for (int n = 0; n < 2; ++n) _Pragma("unroll") for (int k = 0; k < 2; ++k) \
;         acc[ai][bj][m][n] = __builtin_amdgcn_mfma_f32_16x16x32_bf16(Bt[n][k], At[m][k], acc[ai][bj][m][n], 0, 0, 0); __builtin_amdgcn_s_setprio(0); } while (0)
; #define PG8_WAIT_V(n) asm volatile("s_waitcnt vmcnt(" #n ")" ::: "memory")
; #define PG8_WAIT_L(n) asm volatile("s_waitcnt lgkmcnt(" #n ")" ::: "memory")
; template <class Epi, class Sched, bool ALIGN_EPI = false, bool SP2 = false>
; __device__ __forceinline__ void gemm_phase(LAS unsigned char* lds, const Gemm g, const Sched& S, const Epi& E) {
;     ...
;         for (int t = 0; t < nt; t += 2) {
;             const bool last = (t == nt - 2);
;             const char* a1 = cA + (size_t)(t + 1) * kstep;
;             const char* a2 = last ? nA : cA + (size_t)(t + 2) * kstep; const char* b2 = last ? nB : cB + (size_t)(t + 2) * kstep;
;             const char* a3 = a2 + kstep; const char* b3 = b2 + kstep;
;             if (last && has_next) S.a_ready(nxt);
;             if constexpr (SP2) {
;             PG8_LDB(B0, 0, 0); PG8_LDB(B1, 0, 1); PG8_SCHED; PG8_LDA(At, 0, 0); PG8_STAGE(PG8_SA(1, 1), a1 + hstep, voffA);
;             PG8_WAIT_V(8); PG8_WAIT_L(0); PG8_BAR; PG8_MMA(0, 0, At, B0); PG8_MMA(0, 1, At, B1); PG8_BAR; PG8_SCHED;
;             PG8_LDA(At, 0, 1); PG8_STAGE(PG8_SB(0, 0), b2, voffB); PG8_STAGE(PG8_SB(0, 1), b2 + hstepB, voffB); PG8_STAGE(PG8_SA(0, 0), a2, voffA);
;             PG8_WAIT_V(8); PG8_WAIT_L(0); PG8_BAR; PG8_MMA(1, 0, At, B0); PG8_MMA(1, 1, At, B1); PG8_BAR; PG8_SCHED;
.Lprio_1465:
	ds_read_b128 v[66:69], v174
	ds_read_b128 v[70:73], v174 offset:1024
	ds_read_b128 v[74:77], v174 offset:2048
	ds_read_b128 v[78:81], v174 offset:3072
	ds_read_b128 v[162:165], v175
	ds_read_b128 v[182:185], v175 offset:1024
	ds_read_b128 v[186:189], v175 offset:2048
	ds_read_b128 v[190:193], v175 offset:3072
	s_add_u32 s22, s16, 0xfff80080
	s_addc_u32 s23, s17, -1
	s_cmp_eq_u32 s53, 28
	s_cselect_b32 s41, s3, s23
	s_cselect_b32 s40, s15, s22
	s_cselect_b32 s23, s13, s52
	s_cselect_b32 s22, s24, s25
	s_add_i32 m0, s33, 0xc000
	ds_read_b128 v[194:197], v176
	ds_read_b128 v[198:201], v176 offset:1024
	ds_read_b128 v[202:205], v176 offset:2048
	ds_read_b128 v[206:209], v176 offset:3072
	ds_read_b128 v[210:213], v176 offset:4096
	ds_read_b128 v[214:217], v176 offset:5120
	ds_read_b128 v[218:221], v176 offset:6144
	ds_read_b128 v[222:225], v176 offset:7168
	global_load_lds_dwordx4 v154, s[16:17]
	s_add_i32 m0, s33, 0xe000
	s_nop 0
	global_load_lds_dwordx4 v156, s[16:17]
	s_waitcnt lgkmcnt(0)
	s_barrier
	s_waitcnt lgkmcnt(0)
	v_mfma_f32_16x16x32_bf16 v[142:145], v[66:69], v[194:197], 0
	v_mfma_f32_16x16x32_bf16 v[138:141], v[74:77], v[194:197], 0
	v_mfma_f32_16x16x32_bf16 v[126:129], v[66:69], v[202:205], 0
	v_mfma_f32_16x16x32_bf16 v[122:125], v[74:77], v[202:205], 0
	v_mfma_f32_16x16x32_bf16 v[110:113], v[66:69], v[210:213], 0
	v_mfma_f32_16x16x32_bf16 v[106:109], v[74:77], v[210:213], 0
	v_mfma_f32_16x16x32_bf16 v[94:97], v[66:69], v[218:221], 0
	v_mfma_f32_16x16x32_bf16 v[90:93], v[74:77], v[218:221], 0
	v_mfma_f32_16x16x32_bf16 v[142:145], v[70:73], v[198:201], v[142:145]
	v_mfma_f32_16x16x32_bf16 v[138:141], v[78:81], v[198:201], v[138:141]
	v_mfma_f32_16x16x32_bf16 v[126:129], v[70:73], v[206:209], v[126:129]
	v_mfma_f32_16x16x32_bf16 v[122:125], v[78:81], v[206:209], v[122:125]
	v_mfma_f32_16x16x32_bf16 v[110:113], v[70:73], v[214:217], v[110:113]
	v_mfma_f32_16x16x32_bf16 v[106:109], v[78:81], v[214:217], v[106:109]
	v_mfma_f32_16x16x32_bf16 v[94:97], v[70:73], v[222:225], v[94:97]
	v_mfma_f32_16x16x32_bf16 v[90:93], v[78:81], v[222:225], v[90:93]
	v_mfma_f32_16x16x32_bf16 v[134:137], v[162:165], v[194:197], 0
	v_mfma_f32_16x16x32_bf16 v[130:133], v[186:189], v[194:197], 0
	v_mfma_f32_16x16x32_bf16 v[118:121], v[162:165], v[202:205], 0
	v_mfma_f32_16x16x32_bf16 v[114:117], v[186:189], v[202:205], 0
	v_mfma_f32_16x16x32_bf16 v[102:105], v[162:165], v[210:213], 0
	v_mfma_f32_16x16x32_bf16 v[98:101], v[186:189], v[210:213], 0
	v_mfma_f32_16x16x32_bf16 v[86:89], v[162:165], v[218:221], 0
	v_mfma_f32_16x16x32_bf16 v[82:85], v[186:189], v[218:221], 0
	v_mfma_f32_16x16x32_bf16 v[134:137], v[182:185], v[198:201], v[134:137]
	v_mfma_f32_16x16x32_bf16 v[130:133], v[190:193], v[198:201], v[130:133]
	v_mfma_f32_16x16x32_bf16 v[118:121], v[182:185], v[206:209], v[118:121]
	v_mfma_f32_16x16x32_bf16 v[114:117], v[190:193], v[206:209], v[114:117]
	v_mfma_f32_16x16x32_bf16 v[102:105], v[182:185], v[214:217], v[102:105]
	v_mfma_f32_16x16x32_bf16 v[98:101], v[190:193], v[214:217], v[98:101]
	v_mfma_f32_16x16x32_bf16 v[86:89], v[182:185], v[222:225], v[86:89]
	v_mfma_f32_16x16x32_bf16 v[82:85], v[190:193], v[222:225], v[82:85]
	s_barrier
	s_add_i32 s54, s47, s29
	s_mov_b32 m0, s54
	ds_read_b128 v[194:197], v176 offset:16384
	ds_read_b128 v[198:201], v176 offset:17408
	ds_read_b128 v[202:205], v176 offset:18432
	ds_read_b128 v[206:209], v176 offset:19456
	ds_read_b128 v[210:213], v176 offset:20480
	ds_read_b128 v[214:217], v176 offset:21504
	ds_read_b128 v[218:221], v176 offset:22528
	ds_read_b128 v[222:225], v176 offset:23552
	global_load_lds_dwordx4 v150, s[22:23]
	s_add_i32 m0, s54, 0x2000
	s_add_u32 s54, s22, 0x80000
	v_lshl_add_u64 v[226:227], s[22:23], 0, v[146:147]
	s_addc_u32 s55, s23, 0
	s_add_i32 s56, s48, s29
	global_load_lds_dwordx4 v146, s[22:23]
	s_mov_b32 m0, s56
	v_lshl_add_u64 v[230:231], s[40:41], 0, v[148:149]
	global_load_lds_dwordx4 v150, s[54:55]
	s_add_i32 m0, s56, 0x2000
	s_nop 0
	global_load_lds_dwordx4 v146, s[54:55]
	v_lshl_add_u64 v[228:229], s[40:41], 0, v[152:153]
	s_mov_b32 m0, s33
	s_nop 0
	global_load_lds_dwordx4 v152, s[40:41]
	s_mov_b32 m0, s34
	s_nop 0
	global_load_lds_dwordx4 v148, s[40:41]
	s_waitcnt lgkmcnt(0)
	s_barrier
	s_waitcnt lgkmcnt(0)
	v_mfma_f32_16x16x32_bf16 v[62:65], v[66:69], v[194:197], 0
	v_mfma_f32_16x16x32_bf16 v[58:61], v[74:77], v[194:197], 0
	v_mfma_f32_16x16x32_bf16 v[46:49], v[66:69], v[202:205], 0
	v_mfma_f32_16x16x32_bf16 v[42:45], v[74:77], v[202:205], 0
	v_mfma_f32_16x16x32_bf16 v[30:33], v[66:69], v[210:213], 0
	v_mfma_f32_16x16x32_bf16 v[26:29], v[74:77], v[210:213], 0
	v_mfma_f32_16x16x32_bf16 v[14:17], v[66:69], v[218:221], 0
	v_mfma_f32_16x16x32_bf16 v[10:13], v[74:77], v[218:221], 0
	v_mfma_f32_16x16x32_bf16 v[62:65], v[70:73], v[198:201], v[62:65]
	v_mfma_f32_16x16x32_bf16 v[58:61], v[78:81], v[198:201], v[58:61]
	v_mfma_f32_16x16x32_bf16 v[46:49], v[70:73], v[206:209], v[46:49]
	v_mfma_f32_16x16x32_bf16 v[42:45], v[78:81], v[206:209], v[42:45]
	v_mfma_f32_16x16x32_bf16 v[30:33], v[70:73], v[214:217], v[30:33]
	v_mfma_f32_16x16x32_bf16 v[26:29], v[78:81], v[214:217], v[26:29]
	v_mfma_f32_16x16x32_bf16 v[14:17], v[70:73], v[222:225], v[14:17]
	v_mfma_f32_16x16x32_bf16 v[10:13], v[78:81], v[222:225], v[10:13]
	v_mfma_f32_16x16x32_bf16 v[54:57], v[162:165], v[194:197], 0
	v_mfma_f32_16x16x32_bf16 v[50:53], v[186:189], v[194:197], 0
	v_mfma_f32_16x16x32_bf16 v[38:41], v[162:165], v[202:205], 0
	v_mfma_f32_16x16x32_bf16 v[34:37], v[186:189], v[202:205], 0
	v_mfma_f32_16x16x32_bf16 v[22:25], v[162:165], v[210:213], 0
	v_mfma_f32_16x16x32_bf16 v[18:21], v[186:189], v[210:213], 0
	v_mfma_f32_16x16x32_bf16 v[6:9], v[162:165], v[218:221], 0
	v_mfma_f32_16x16x32_bf16 v[2:5], v[186:189], v[218:221], 0
	v_mfma_f32_16x16x32_bf16 v[54:57], v[182:185], v[198:201], v[54:57]
	v_mfma_f32_16x16x32_bf16 v[50:53], v[190:193], v[198:201], v[50:53]
	v_mfma_f32_16x16x32_bf16 v[38:41], v[182:185], v[206:209], v[38:41]
	v_mfma_f32_16x16x32_bf16 v[34:37], v[190:193], v[206:209], v[34:37]
	v_mfma_f32_16x16x32_bf16 v[22:25], v[182:185], v[214:217], v[22:25]
	v_mfma_f32_16x16x32_bf16 v[18:21], v[190:193], v[214:217], v[18:21]
	v_mfma_f32_16x16x32_bf16 v[6:9], v[182:185], v[222:225], v[6:9]
	v_mfma_f32_16x16x32_bf16 v[2:5], v[190:193], v[222:225], v[2:5]
	s_barrier
; #define PG8_STAGE(bufoff, gbase, voff) do { _Pragma("unroll") for (int _i = 0; _i < 2; ++_i) \
;         __builtin_amdgcn_global_load_lds((const unsigned*)((const char*)(gbase) + (voff)[_i]), (LAS unsigned*)(lds + (bufoff) + ldsw + _i * 8192), 16, 0, 0); } while (0)
; #define PG8_LDA(dst, b, h) do { _Pragma("unroll") for (int m = 0; m < 4; ++m) _Pragma("unroll") for (int k = 0; k < 2; ++k) dst[m][k] = *(const LAS bf16x8*)(lds + PG8_SA(b, h) + aoff + m * 2048 + k * 1024); } while (0)
; #define PG8_LDB(dst, b, h) do { _Pragma("unroll") for (int n = 0; n < 2; ++n) _Pragma("unroll") for (int k = 0; k < 2; ++k) dst[n][k] = *(const LAS bf16x8*)(lds + PG8_SB(b, h) + boff + n * 2048 + k * 1024); } while (0)
; #define PG8_MMA(ai, bj, At, Bt) do { __builtin_amdgcn_s_setprio(1); _Pragma("unroll") for (int m = 0; m < 4; ++m) _Pragma("unroll") for (int n = 0; n < 2; ++n) _Pragma("unroll") for (int k = 0; k < 2; ++k) \
;         acc[ai][bj][m][n] = __builtin_amdgcn_mfma_f32_16x16x32_bf16(Bt[n][k], At[m][k], acc[ai][bj][m][n], 0, 0, 0); __builtin_amdgcn_s_setprio(0); } while (0)
; #define PG8_WAIT_V(n) asm volatile("s_waitcnt vmcnt(" #n ")" ::: "memory")
; #define PG8_WAIT_L(n) asm volatile("s_waitcnt lgkmcnt(" #n ")" ::: "memory")
; #define PG8_BAR __builtin_amdgcn_s_barrier()
; #define PG8_SCHED __builtin_amdgcn_sched_barrier(0)
; template <class Epi, class Sched, bool ALIGN_EPI = false, bool SP2 = false>
; __device__ __forceinline__ void gemm_phase(LAS unsigned char* lds, const Gemm g, const Sched& S, const Epi& E) {
;     ...
;             PG8_LDB(B0, 1, 0); PG8_LDB(B1, 1, 1); PG8_SCHED; PG8_LDA(At, 1, 0); PG8_STAGE(PG8_SA(0, 1), a2 + hstep, voffA);
;             PG8_WAIT_V(8); PG8_WAIT_L(0); PG8_BAR; PG8_MMA(0, 0, At, B0); PG8_MMA(0, 1, At, B1); PG8_BAR; PG8_SCHED;
;             PG8_LDA(At, 1, 1); PG8_STAGE(PG8_SB(1, 0), b3, voffB); PG8_STAGE(PG8_SB(1, 1), b3 + hstepB, voffB); PG8_STAGE(PG8_SA(1, 0), a3, voffA);
;             PG8_WAIT_V(8); PG8_WAIT_L(0); PG8_BAR; PG8_MMA(1, 0, At, B0); PG8_MMA(1, 1, At, B1); PG8_BAR; PG8_SCHED;
	s_add_i32 s54, 0, 0x18000
	s_add_i32 s55, 0, 0x1c000
	v_add_u32_e32 v78, s54, v170
	v_add_u32_e32 v168, s55, v170
	ds_read_b128 v[66:69], v78
	ds_read_b128 v[70:73], v78 offset:1024
	ds_read_b128 v[74:77], v78 offset:2048
	ds_read_b128 v[78:81], v78 offset:3072
	ds_read_b128 v[162:165], v168
	ds_read_b128 v[182:185], v168 offset:1024
	ds_read_b128 v[186:189], v168 offset:2048
	ds_read_b128 v[190:193], v168 offset:3072
	s_add_u32 s40, s40, 0x80000
	s_addc_u32 s41, s41, 0
	s_mov_b32 m0, s35
	ds_read_b128 v[194:197], v176 offset:32768
	ds_read_b128 v[198:201], v176 offset:33792
	ds_read_b128 v[202:205], v176 offset:34816
	ds_read_b128 v[206:209], v176 offset:35840
	ds_read_b128 v[210:213], v176 offset:36864
	ds_read_b128 v[214:217], v176 offset:37888
	ds_read_b128 v[218:221], v176 offset:38912
	ds_read_b128 v[222:225], v176 offset:39936
	global_load_lds_dwordx4 v152, s[40:41]
	s_mov_b32 m0, s36
	s_nop 0
	global_load_lds_dwordx4 v148, s[40:41]
	s_waitcnt vmcnt(8)
	s_waitcnt lgkmcnt(0)
	s_barrier
	s_waitcnt lgkmcnt(0)
	v_mfma_f32_16x16x32_bf16 v[142:145], v[66:69], v[194:197], v[142:145]
	v_mfma_f32_16x16x32_bf16 v[138:141], v[74:77], v[194:197], v[138:141]
	v_mfma_f32_16x16x32_bf16 v[126:129], v[66:69], v[202:205], v[126:129]
	v_mfma_f32_16x16x32_bf16 v[122:125], v[74:77], v[202:205], v[122:125]
	v_mfma_f32_16x16x32_bf16 v[110:113], v[66:69], v[210:213], v[110:113]
	v_mfma_f32_16x16x32_bf16 v[106:109], v[74:77], v[210:213], v[106:109]
	v_mfma_f32_16x16x32_bf16 v[94:97], v[66:69], v[218:221], v[94:97]
	v_mfma_f32_16x16x32_bf16 v[90:93], v[74:77], v[218:221], v[90:93]
	v_mfma_f32_16x16x32_bf16 v[142:145], v[70:73], v[198:201], v[142:145]
	v_mfma_f32_16x16x32_bf16 v[138:141], v[78:81], v[198:201], v[138:141]
	v_mfma_f32_16x16x32_bf16 v[126:129], v[70:73], v[206:209], v[126:129]
	v_mfma_f32_16x16x32_bf16 v[122:125], v[78:81], v[206:209], v[122:125]
	v_mfma_f32_16x16x32_bf16 v[110:113], v[70:73], v[214:217], v[110:113]
	v_mfma_f32_16x16x32_bf16 v[106:109], v[78:81], v[214:217], v[106:109]
	v_mfma_f32_16x16x32_bf16 v[94:97], v[70:73], v[222:225], v[94:97]
	v_mfma_f32_16x16x32_bf16 v[90:93], v[78:81], v[222:225], v[90:93]
	v_mfma_f32_16x16x32_bf16 v[134:137], v[162:165], v[194:197], v[134:137]
	v_mfma_f32_16x16x32_bf16 v[130:133], v[186:189], v[194:197], v[130:133]
	v_mfma_f32_16x16x32_bf16 v[118:121], v[162:165], v[202:205], v[118:121]
	v_mfma_f32_16x16x32_bf16 v[114:117], v[186:189], v[202:205], v[114:117]
	v_mfma_f32_16x16x32_bf16 v[102:105], v[162:165], v[210:213], v[102:105]
	v_mfma_f32_16x16x32_bf16 v[98:101], v[186:189], v[210:213], v[98:101]
	v_mfma_f32_16x16x32_bf16 v[86:89], v[162:165], v[218:221], v[86:89]
	v_mfma_f32_16x16x32_bf16 v[82:85], v[186:189], v[218:221], v[82:85]
	v_mfma_f32_16x16x32_bf16 v[134:137], v[182:185], v[198:201], v[134:137]
	v_mfma_f32_16x16x32_bf16 v[130:133], v[190:193], v[198:201], v[130:133]
	v_mfma_f32_16x16x32_bf16 v[118:121], v[182:185], v[206:209], v[118:121]
	v_mfma_f32_16x16x32_bf16 v[114:117], v[190:193], v[206:209], v[114:117]
	v_mfma_f32_16x16x32_bf16 v[102:105], v[182:185], v[214:217], v[102:105]
	v_mfma_f32_16x16x32_bf16 v[98:101], v[190:193], v[214:217], v[98:101]
	v_mfma_f32_16x16x32_bf16 v[86:89], v[182:185], v[222:225], v[86:89]
	v_mfma_f32_16x16x32_bf16 v[82:85], v[190:193], v[222:225], v[82:85]
	s_barrier
	s_add_u32 s98, s22, 0x80
	s_addc_u32 s99, s23, 0
	s_add_i32 s40, s54, s29
	s_mov_b32 m0, s40
	ds_read_b128 v[194:197], v176 offset:49152
	ds_read_b128 v[198:201], v176 offset:50176
	ds_read_b128 v[202:205], v176 offset:51200
	ds_read_b128 v[206:209], v176 offset:52224
	ds_read_b128 v[210:213], v176 offset:53248
	ds_read_b128 v[214:217], v176 offset:54272
	ds_read_b128 v[218:221], v176 offset:55296
	ds_read_b128 v[222:225], v176 offset:56320
	global_load_lds_dwordx4 v150, s[98:99]
	s_add_i32 m0, s40, 0x2000
	s_add_u32 s22, s22, 0x80080
	v_lshl_add_u64 v[166:167], v[226:227], 0, s[8:9]
	s_addc_u32 s23, s23, 0
	s_add_i32 s40, s55, s29
	global_load_lds_dwordx4 v[166:167], off
	s_mov_b32 m0, s40
	s_nop 0
	global_load_lds_dwordx4 v150, s[22:23]
	s_add_i32 m0, s40, 0x2000
	s_nop 0
	global_load_lds_dwordx4 v146, s[22:23]
	v_lshl_add_u64 v[166:167], v[228:229], 0, s[8:9]
	s_mov_b32 m0, s45
	s_nop 0
	global_load_lds_dwordx4 v[166:167], off
	v_lshl_add_u64 v[166:167], v[230:231], 0, s[8:9]
	s_mov_b32 m0, s46
	s_nop 0
	global_load_lds_dwordx4 v[166:167], off
	s_waitcnt vmcnt(8)
	s_waitcnt lgkmcnt(0)
	s_barrier
	s_waitcnt lgkmcnt(0)
	v_mfma_f32_16x16x32_bf16 v[62:65], v[66:69], v[194:197], v[62:65]
	v_mfma_f32_16x16x32_bf16 v[58:61], v[74:77], v[194:197], v[58:61]
	v_mfma_f32_16x16x32_bf16 v[46:49], v[66:69], v[202:205], v[46:49]
	v_mfma_f32_16x16x32_bf16 v[42:45], v[74:77], v[202:205], v[42:45]
	v_mfma_f32_16x16x32_bf16 v[30:33], v[66:69], v[210:213], v[30:33]
	v_mfma_f32_16x16x32_bf16 v[26:29], v[74:77], v[210:213], v[26:29]
	v_mfma_f32_16x16x32_bf16 v[14:17], v[66:69], v[218:221], v[14:17]
	v_mfma_f32_16x16x32_bf16 v[10:13], v[74:77], v[218:221], v[10:13]
	v_mfma_f32_16x16x32_bf16 v[62:65], v[70:73], v[198:201], v[62:65]
	v_mfma_f32_16x16x32_bf16 v[58:61], v[78:81], v[198:201], v[58:61]
	v_mfma_f32_16x16x32_bf16 v[46:49], v[70:73], v[206:209], v[46:49]
	v_mfma_f32_16x16x32_bf16 v[42:45], v[78:81], v[206:209], v[42:45]
	v_mfma_f32_16x16x32_bf16 v[30:33], v[70:73], v[214:217], v[30:33]
	v_mfma_f32_16x16x32_bf16 v[26:29], v[78:81], v[214:217], v[26:29]
	v_mfma_f32_16x16x32_bf16 v[14:17], v[70:73], v[222:225], v[14:17]
	v_mfma_f32_16x16x32_bf16 v[10:13], v[78:81], v[222:225], v[10:13]
	v_mfma_f32_16x16x32_bf16 v[54:57], v[162:165], v[194:197], v[54:57]
	v_mfma_f32_16x16x32_bf16 v[50:53], v[186:189], v[194:197], v[50:53]
	v_mfma_f32_16x16x32_bf16 v[38:41], v[162:165], v[202:205], v[38:41]
	v_mfma_f32_16x16x32_bf16 v[34:37], v[186:189], v[202:205], v[34:37]
	v_mfma_f32_16x16x32_bf16 v[22:25], v[162:165], v[210:213], v[22:25]
	v_mfma_f32_16x16x32_bf16 v[18:21], v[186:189], v[210:213], v[18:21]
	v_mfma_f32_16x16x32_bf16 v[6:9], v[162:165], v[218:221], v[6:9]
	v_mfma_f32_16x16x32_bf16 v[2:5], v[186:189], v[218:221], v[2:5]
	v_mfma_f32_16x16x32_bf16 v[54:57], v[182:185], v[198:201], v[54:57]
	v_mfma_f32_16x16x32_bf16 v[50:53], v[190:193], v[198:201], v[50:53]
	v_mfma_f32_16x16x32_bf16 v[38:41], v[182:185], v[206:209], v[38:41]
	v_mfma_f32_16x16x32_bf16 v[34:37], v[190:193], v[206:209], v[34:37]
	v_mfma_f32_16x16x32_bf16 v[22:25], v[182:185], v[214:217], v[22:25]
	v_mfma_f32_16x16x32_bf16 v[18:21], v[190:193], v[214:217], v[18:21]
	v_mfma_f32_16x16x32_bf16 v[6:9], v[182:185], v[222:225], v[6:9]
	v_mfma_f32_16x16x32_bf16 v[2:5], v[190:193], v[222:225], v[2:5]
	s_barrier
	s_add_i32 s53, s53, 2
	s_add_u32 s16, s16, 0x100
	s_addc_u32 s17, s17, 0
	s_add_u32 s25, s25, 0x100
	s_addc_u32 s52, s52, 0
	s_cmp_gt_u32 s53, 29
; #define PG8_STAGE(bufoff, gbase, voff) do { _Pragma("unroll") for (int _i = 0; _i < 2; ++_i) \
;         __builtin_amdgcn_global_load_lds((const unsigned*)((const char*)(gbase) + (voff)[_i]), (LAS unsigned*)(lds + (bufoff) + ldsw + _i * 8192), 16, 0, 0); } while (0)
; #define PG8_LDA(dst, b, h) do { _Pragma("unroll") for (int m = 0; m < 4; ++m) _Pragma("unroll") for (int k = 0; k < 2; ++k) dst[m][k] = *(const LAS bf16x8*)(lds + PG8_SA(b, h) + aoff + m * 2048 + k * 1024); } while (0)
; #define PG8_LDB(dst, b, h) do { _Pragma("unroll") for (int n = 0; n < 2; ++n) _Pragma("unroll") for (int k = 0; k < 2; ++k) dst[n][k] = *(const LAS bf16x8*)(lds + PG8_SB(b, h) + boff + n * 2048 + k * 1024); } while (0)
; #define PG8_MMA(ai, bj, At, Bt) do { __builtin_amdgcn_s_setprio(1); _Pragma("unroll") for (int m = 0; m < 4; ++m) _Pragma("unroll") for (int n = 0; n < 2; ++n) _Pragma("unroll") for (int k = 0; k < 2; ++k) \
;         acc[ai][bj][m][n] = __builtin_amdgcn_mfma_f32_16x16x32_bf16(Bt[n][k], At[m][k], acc[ai][bj][m][n], 0, 0, 0); __builtin_amdgcn_s_setprio(0); } while (0)
; #define PG8_WAIT_V(n) asm volatile("s_waitcnt vmcnt(" #n ")" ::: "memory")
; #define PG8_WAIT_L(n) asm volatile("s_waitcnt lgkmcnt(" #n ")" ::: "memory")
; template <class Epi, class Sched, bool ALIGN_EPI = false, bool SP2 = false>
; __device__ __forceinline__ void gemm_phase(LAS unsigned char* lds, const Gemm g, const Sched& S, const Epi& E) {
;     ...
;         for (int t = 0; t < nt; t += 2) {
;             const bool last = (t == nt - 2);
;             const char* a1 = cA + (size_t)(t + 1) * kstep;
;             const char* a2 = last ? nA : cA + (size_t)(t + 2) * kstep; const char* b2 = last ? nB : cB + (size_t)(t + 2) * kstep;
;             const char* a3 = a2 + kstep; const char* b3 = b2 + kstep;
;             if (last && has_next) S.a_ready(nxt);
;             if constexpr (SP2) {
;             PG8_LDB(B0, 0, 0); PG8_LDB(B1, 0, 1); PG8_SCHED; PG8_LDA(At, 0, 0); PG8_STAGE(PG8_SA(1, 1), a1 + hstep, voffA);
;             PG8_WAIT_V(8); PG8_WAIT_L(0); PG8_BAR; PG8_MMA(0, 0, At, B0); PG8_MMA(0, 1, At, B1); PG8_BAR; PG8_SCHED;
;             PG8_LDA(At, 0, 1); PG8_STAGE(PG8_SB(0, 0), b2, voffB); PG8_STAGE(PG8_SB(0, 1), b2 + hstepB, voffB); PG8_STAGE(PG8_SA(0, 0), a2, voffA);
;             PG8_WAIT_V(8); PG8_WAIT_L(0); PG8_BAR; PG8_MMA(1, 0, At, B0); PG8_MMA(1, 1, At, B1); PG8_BAR; PG8_SCHED;
.LBB0_1465:
	ds_read_b128 v[66:69], v174
	ds_read_b128 v[70:73], v174 offset:1024
	ds_read_b128 v[74:77], v174 offset:2048
	ds_read_b128 v[78:81], v174 offset:3072
	ds_read_b128 v[162:165], v175
	ds_read_b128 v[182:185], v175 offset:1024
	ds_read_b128 v[186:189], v175 offset:2048
	ds_read_b128 v[190:193], v175 offset:3072
	s_add_u32 s22, s16, 0xfff80080
	s_addc_u32 s23, s17, -1
	s_cmp_eq_u32 s53, 28
	s_cselect_b32 s41, s3, s23
	s_cselect_b32 s40, s15, s22
	s_cselect_b32 s23, s13, s52
	s_cselect_b32 s22, s24, s25
	s_add_i32 m0, s33, 0xc000
	ds_read_b128 v[194:197], v176
	ds_read_b128 v[198:201], v176 offset:1024
	ds_read_b128 v[202:205], v176 offset:2048
	ds_read_b128 v[206:209], v176 offset:3072
	ds_read_b128 v[210:213], v176 offset:4096
	ds_read_b128 v[214:217], v176 offset:5120
	ds_read_b128 v[218:221], v176 offset:6144
	ds_read_b128 v[222:225], v176 offset:7168
	global_load_lds_dwordx4 v154, s[16:17]
	s_add_i32 m0, s33, 0xe000
	s_nop 0
	global_load_lds_dwordx4 v156, s[16:17]
	s_waitcnt vmcnt(8)
	s_waitcnt lgkmcnt(0)
	s_barrier
	s_waitcnt lgkmcnt(0)
	v_mfma_f32_16x16x32_bf16 v[142:145], v[66:69], v[194:197], v[142:145]
	v_mfma_f32_16x16x32_bf16 v[138:141], v[74:77], v[194:197], v[138:141]
	v_mfma_f32_16x16x32_bf16 v[126:129], v[66:69], v[202:205], v[126:129]
	v_mfma_f32_16x16x32_bf16 v[122:125], v[74:77], v[202:205], v[122:125]
	v_mfma_f32_16x16x32_bf16 v[110:113], v[66:69], v[210:213], v[110:113]
	v_mfma_f32_16x16x32_bf16 v[106:109], v[74:77], v[210:213], v[106:109]
	v_mfma_f32_16x16x32_bf16 v[94:97], v[66:69], v[218:221], v[94:97]
	v_mfma_f32_16x16x32_bf16 v[90:93], v[74:77], v[218:221], v[90:93]
	v_mfma_f32_16x16x32_bf16 v[142:145], v[70:73], v[198:201], v[142:145]
	v_mfma_f32_16x16x32_bf16 v[138:141], v[78:81], v[198:201], v[138:141]
	v_mfma_f32_16x16x32_bf16 v[126:129], v[70:73], v[206:209], v[126:129]
	v_mfma_f32_16x16x32_bf16 v[122:125], v[78:81], v[206:209], v[122:125]
	v_mfma_f32_16x16x32_bf16 v[110:113], v[70:73], v[214:217], v[110:113]
	v_mfma_f32_16x16x32_bf16 v[106:109], v[78:81], v[214:217], v[106:109]
	v_mfma_f32_16x16x32_bf16 v[94:97], v[70:73], v[222:225], v[94:97]
	v_mfma_f32_16x16x32_bf16 v[90:93], v[78:81], v[222:225], v[90:93]
	v_mfma_f32_16x16x32_bf16 v[134:137], v[162:165], v[194:197], v[134:137]
	v_mfma_f32_16x16x32_bf16 v[130:133], v[186:189], v[194:197], v[130:133]
	v_mfma_f32_16x16x32_bf16 v[118:121], v[162:165], v[202:205], v[118:121]
	v_mfma_f32_16x16x32_bf16 v[114:117], v[186:189], v[202:205], v[114:117]
	v_mfma_f32_16x16x32_bf16 v[102:105], v[162:165], v[210:213], v[102:105]
	v_mfma_f32_16x16x32_bf16 v[98:101], v[186:189], v[210:213], v[98:101]
	v_mfma_f32_16x16x32_bf16 v[86:89], v[162:165], v[218:221], v[86:89]
	v_mfma_f32_16x16x32_bf16 v[82:85], v[186:189], v[218:221], v[82:85]
	v_mfma_f32_16x16x32_bf16 v[134:137], v[182:185], v[198:201], v[134:137]
	v_mfma_f32_16x16x32_bf16 v[130:133], v[190:193], v[198:201], v[130:133]
	v_mfma_f32_16x16x32_bf16 v[118:121], v[182:185], v[206:209], v[118:121]
	v_mfma_f32_16x16x32_bf16 v[114:117], v[190:193], v[206:209], v[114:117]
	v_mfma_f32_16x16x32_bf16 v[102:105], v[182:185], v[214:217], v[102:105]
	v_mfma_f32_16x16x32_bf16 v[98:101], v[190:193], v[214:217], v[98:101]
	v_mfma_f32_16x16x32_bf16 v[86:89], v[182:185], v[222:225], v[86:89]
	v_mfma_f32_16x16x32_bf16 v[82:85], v[190:193], v[222:225], v[82:85]
	s_barrier
	s_add_i32 s54, s47, s29
	s_mov_b32 m0, s54
	ds_read_b128 v[194:197], v176 offset:16384
	ds_read_b128 v[198:201], v176 offset:17408
	ds_read_b128 v[202:205], v176 offset:18432
	ds_read_b128 v[206:209], v176 offset:19456
	ds_read_b128 v[210:213], v176 offset:20480
	ds_read_b128 v[214:217], v176 offset:21504
	ds_read_b128 v[218:221], v176 offset:22528
	ds_read_b128 v[222:225], v176 offset:23552
	global_load_lds_dwordx4 v150, s[22:23]
	s_add_i32 m0, s54, 0x2000
	s_add_u32 s54, s22, 0x80000
	v_lshl_add_u64 v[226:227], s[22:23], 0, v[146:147]
	s_addc_u32 s55, s23, 0
	s_add_i32 s56, s48, s29
	global_load_lds_dwordx4 v146, s[22:23]
	s_mov_b32 m0, s56
	v_lshl_add_u64 v[230:231], s[40:41], 0, v[148:149]
	global_load_lds_dwordx4 v150, s[54:55]
	s_add_i32 m0, s56, 0x2000
	s_nop 0
	global_load_lds_dwordx4 v146, s[54:55]
	v_lshl_add_u64 v[228:229], s[40:41], 0, v[152:153]
	s_mov_b32 m0, s33
	s_nop 0
	global_load_lds_dwordx4 v152, s[40:41]
	s_mov_b32 m0, s34
	s_nop 0
	global_load_lds_dwordx4 v148, s[40:41]
	s_waitcnt vmcnt(8)
	s_waitcnt lgkmcnt(0)
	s_barrier
	s_waitcnt lgkmcnt(0)
	v_mfma_f32_16x16x32_bf16 v[62:65], v[66:69], v[194:197], v[62:65]
	v_mfma_f32_16x16x32_bf16 v[58:61], v[74:77], v[194:197], v[58:61]
	v_mfma_f32_16x16x32_bf16 v[46:49], v[66:69], v[202:205], v[46:49]
	v_mfma_f32_16x16x32_bf16 v[42:45], v[74:77], v[202:205], v[42:45]
	v_mfma_f32_16x16x32_bf16 v[30:33], v[66:69], v[210:213], v[30:33]
	v_mfma_f32_16x16x32_bf16 v[26:29], v[74:77], v[210:213], v[26:29]
	v_mfma_f32_16x16x32_bf16 v[14:17], v[66:69], v[218:221], v[14:17]
	v_mfma_f32_16x16x32_bf16 v[10:13], v[74:77], v[218:221], v[10:13]
	v_mfma_f32_16x16x32_bf16 v[62:65], v[70:73], v[198:201], v[62:65]
	v_mfma_f32_16x16x32_bf16 v[58:61], v[78:81], v[198:201], v[58:61]
	v_mfma_f32_16x16x32_bf16 v[46:49], v[70:73], v[206:209], v[46:49]
	v_mfma_f32_16x16x32_bf16 v[42:45], v[78:81], v[206:209], v[42:45]
	v_mfma_f32_16x16x32_bf16 v[30:33], v[70:73], v[214:217], v[30:33]
	v_mfma_f32_16x16x32_bf16 v[26:29], v[78:81], v[214:217], v[26:29]
	v_mfma_f32_16x16x32_bf16 v[14:17], v[70:73], v[222:225], v[14:17]
	v_mfma_f32_16x16x32_bf16 v[10:13], v[78:81], v[222:225], v[10:13]
	v_mfma_f32_16x16x32_bf16 v[54:57], v[162:165], v[194:197], v[54:57]
	v_mfma_f32_16x16x32_bf16 v[50:53], v[186:189], v[194:197], v[50:53]
	v_mfma_f32_16x16x32_bf16 v[38:41], v[162:165], v[202:205], v[38:41]
	v_mfma_f32_16x16x32_bf16 v[34:37], v[186:189], v[202:205], v[34:37]
	v_mfma_f32_16x16x32_bf16 v[22:25], v[162:165], v[210:213], v[22:25]
	v_mfma_f32_16x16x32_bf16 v[18:21], v[186:189], v[210:213], v[18:21]
	v_mfma_f32_16x16x32_bf16 v[6:9], v[162:165], v[218:221], v[6:9]
	v_mfma_f32_16x16x32_bf16 v[2:5], v[186:189], v[218:221], v[2:5]
	v_mfma_f32_16x16x32_bf16 v[54:57], v[182:185], v[198:201], v[54:57]
	v_mfma_f32_16x16x32_bf16 v[50:53], v[190:193], v[198:201], v[50:53]
	v_mfma_f32_16x16x32_bf16 v[38:41], v[182:185], v[206:209], v[38:41]
	v_mfma_f32_16x16x32_bf16 v[34:37], v[190:193], v[206:209], v[34:37]
	v_mfma_f32_16x16x32_bf16 v[22:25], v[182:185], v[214:217], v[22:25]
	v_mfma_f32_16x16x32_bf16 v[18:21], v[190:193], v[214:217], v[18:21]
	v_mfma_f32_16x16x32_bf16 v[6:9], v[182:185], v[222:225], v[6:9]
	v_mfma_f32_16x16x32_bf16 v[2:5], v[190:193], v[222:225], v[2:5]
	s_barrier
; #define PG8_STAGE(bufoff, gbase, voff) do { _Pragma("unroll") for (int _i = 0; _i < 2; ++_i) \
;         __builtin_amdgcn_global_load_lds((const unsigned*)((const char*)(gbase) + (voff)[_i]), (LAS unsigned*)(lds + (bufoff) + ldsw + _i * 8192), 16, 0, 0); } while (0)
; #define PG8_LDA(dst, b, h) do { _Pragma("unroll") for (int m = 0; m < 4; ++m) _Pragma("unroll") for (int k = 0; k < 2; ++k) dst[m][k] = *(const LAS bf16x8*)(lds + PG8_SA(b, h) + aoff + m * 2048 + k * 1024); } while (0)
; #define PG8_LDB(dst, b, h) do { _Pragma("unroll") for (int n = 0; n < 2; ++n) _Pragma("unroll") for (int k = 0; k < 2; ++k) dst[n][k] = *(const LAS bf16x8*)(lds + PG8_SB(b, h) + boff + n * 2048 + k * 1024); } while (0)
; #define PG8_MMA(ai, bj, At, Bt) do { __builtin_amdgcn_s_setprio(1); _Pragma("unroll") for (int m = 0; m < 4; ++m) _Pragma("unroll") for (int n = 0; n < 2; ++n) _Pragma("unroll") for (int k = 0; k < 2; ++k) \
;         acc[ai][bj][m][n] = __builtin_amdgcn_mfma_f32_16x16x32_bf16(Bt[n][k], At[m][k], acc[ai][bj][m][n], 0, 0, 0); __builtin_amdgcn_s_setprio(0); } while (0)
; #define PG8_WAIT_V(n) asm volatile("s_waitcnt vmcnt(" #n ")" ::: "memory")
; #define PG8_WAIT_L(n) asm volatile("s_waitcnt lgkmcnt(" #n ")" ::: "memory")
; #define PG8_BAR __builtin_amdgcn_s_barrier()
; #define PG8_SCHED __builtin_amdgcn_sched_barrier(0)
; template <class Epi, class Sched, bool ALIGN_EPI = false, bool SP2 = false>
; __device__ __forceinline__ void gemm_phase(LAS unsigned char* lds, const Gemm g, const Sched& S, const Epi& E) {
;     ...
;             PG8_LDB(B0, 1, 0); PG8_LDB(B1, 1, 1); PG8_SCHED; PG8_LDA(At, 1, 0); PG8_STAGE(PG8_SA(0, 1), a2 + hstep, voffA);
;             PG8_WAIT_V(8); PG8_WAIT_L(0); PG8_BAR; PG8_MMA(0, 0, At, B0); PG8_MMA(0, 1, At, B1); PG8_BAR; PG8_SCHED;
;             PG8_LDA(At, 1, 1); PG8_STAGE(PG8_SB(1, 0), b3, voffB); PG8_STAGE(PG8_SB(1, 1), b3 + hstepB, voffB); PG8_STAGE(PG8_SA(1, 0), a3, voffA);
;             PG8_WAIT_V(8); PG8_WAIT_L(0); PG8_BAR; PG8_MMA(1, 0, At, B0); PG8_MMA(1, 1, At, B1); PG8_BAR; PG8_SCHED;
	s_add_i32 s54, 0, 0x18000
	s_add_i32 s55, 0, 0x1c000
	v_add_u32_e32 v78, s54, v170
	v_add_u32_e32 v168, s55, v170
	ds_read_b128 v[66:69], v78
	ds_read_b128 v[70:73], v78 offset:1024
	ds_read_b128 v[74:77], v78 offset:2048
	ds_read_b128 v[78:81], v78 offset:3072
	ds_read_b128 v[162:165], v168
	ds_read_b128 v[182:185], v168 offset:1024
	ds_read_b128 v[186:189], v168 offset:2048
	ds_read_b128 v[190:193], v168 offset:3072
	s_add_u32 s40, s40, 0x80000
	s_addc_u32 s41, s41, 0
	s_mov_b32 m0, s35
	ds_read_b128 v[194:197], v176 offset:32768
	ds_read_b128 v[198:201], v176 offset:33792
	ds_read_b128 v[202:205], v176 offset:34816
	ds_read_b128 v[206:209], v176 offset:35840
	ds_read_b128 v[210:213], v176 offset:36864
	ds_read_b128 v[214:217], v176 offset:37888
	ds_read_b128 v[218:221], v176 offset:38912
	ds_read_b128 v[222:225], v176 offset:39936
	global_load_lds_dwordx4 v152, s[40:41]
	s_mov_b32 m0, s36
	s_nop 0
	global_load_lds_dwordx4 v148, s[40:41]
	s_waitcnt vmcnt(8)
	s_waitcnt lgkmcnt(0)
	s_barrier
	s_waitcnt lgkmcnt(0)
	v_mfma_f32_16x16x32_bf16 v[142:145], v[66:69], v[194:197], v[142:145]
	v_mfma_f32_16x16x32_bf16 v[138:141], v[74:77], v[194:197], v[138:141]
	v_mfma_f32_16x16x32_bf16 v[126:129], v[66:69], v[202:205], v[126:129]
	v_mfma_f32_16x16x32_bf16 v[122:125], v[74:77], v[202:205], v[122:125]
	v_mfma_f32_16x16x32_bf16 v[110:113], v[66:69], v[210:213], v[110:113]
	v_mfma_f32_16x16x32_bf16 v[106:109], v[74:77], v[210:213], v[106:109]
	v_mfma_f32_16x16x32_bf16 v[94:97], v[66:69], v[218:221], v[94:97]
	v_mfma_f32_16x16x32_bf16 v[90:93], v[74:77], v[218:221], v[90:93]
	v_mfma_f32_16x16x32_bf16 v[142:145], v[70:73], v[198:201], v[142:145]
	v_mfma_f32_16x16x32_bf16 v[138:141], v[78:81], v[198:201], v[138:141]
	v_mfma_f32_16x16x32_bf16 v[126:129], v[70:73], v[206:209], v[126:129]
	v_mfma_f32_16x16x32_bf16 v[122:125], v[78:81], v[206:209], v[122:125]
	v_mfma_f32_16x16x32_bf16 v[110:113], v[70:73], v[214:217], v[110:113]
	v_mfma_f32_16x16x32_bf16 v[106:109], v[78:81], v[214:217], v[106:109]
	v_mfma_f32_16x16x32_bf16 v[94:97], v[70:73], v[222:225], v[94:97]
	v_mfma_f32_16x16x32_bf16 v[90:93], v[78:81], v[222:225], v[90:93]
	v_mfma_f32_16x16x32_bf16 v[134:137], v[162:165], v[194:197], v[134:137]
	v_mfma_f32_16x16x32_bf16 v[130:133], v[186:189], v[194:197], v[130:133]
	v_mfma_f32_16x16x32_bf16 v[118:121], v[162:165], v[202:205], v[118:121]
	v_mfma_f32_16x16x32_bf16 v[114:117], v[186:189], v[202:205], v[114:117]
	v_mfma_f32_16x16x32_bf16 v[102:105], v[162:165], v[210:213], v[102:105]
	v_mfma_f32_16x16x32_bf16 v[98:101], v[186:189], v[210:213], v[98:101]
	v_mfma_f32_16x16x32_bf16 v[86:89], v[162:165], v[218:221], v[86:89]
	v_mfma_f32_16x16x32_bf16 v[82:85], v[186:189], v[218:221], v[82:85]
	v_mfma_f32_16x16x32_bf16 v[134:137], v[182:185], v[198:201], v[134:137]
	v_mfma_f32_16x16x32_bf16 v[130:133], v[190:193], v[198:201], v[130:133]
	v_mfma_f32_16x16x32_bf16 v[118:121], v[182:185], v[206:209], v[118:121]
	v_mfma_f32_16x16x32_bf16 v[114:117], v[190:193], v[206:209], v[114:117]
	v_mfma_f32_16x16x32_bf16 v[102:105], v[182:185], v[214:217], v[102:105]
	v_mfma_f32_16x16x32_bf16 v[98:101], v[190:193], v[214:217], v[98:101]
	v_mfma_f32_16x16x32_bf16 v[86:89], v[182:185], v[222:225], v[86:89]
	v_mfma_f32_16x16x32_bf16 v[82:85], v[190:193], v[222:225], v[82:85]
	s_barrier
	s_add_u32 s98, s22, 0x80
	s_addc_u32 s99, s23, 0
	s_add_i32 s40, s54, s29
	s_mov_b32 m0, s40
	ds_read_b128 v[194:197], v176 offset:49152
	ds_read_b128 v[198:201], v176 offset:50176
	ds_read_b128 v[202:205], v176 offset:51200
	ds_read_b128 v[206:209], v176 offset:52224
	ds_read_b128 v[210:213], v176 offset:53248
	ds_read_b128 v[214:217], v176 offset:54272
	ds_read_b128 v[218:221], v176 offset:55296
	ds_read_b128 v[222:225], v176 offset:56320
	global_load_lds_dwordx4 v150, s[98:99]
	s_add_i32 m0, s40, 0x2000
	s_add_u32 s22, s22, 0x80080
	v_lshl_add_u64 v[166:167], v[226:227], 0, s[8:9]
	s_addc_u32 s23, s23, 0
	s_add_i32 s40, s55, s29
	global_load_lds_dwordx4 v[166:167], off
	s_mov_b32 m0, s40
	s_nop 0
	global_load_lds_dwordx4 v150, s[22:23]
	s_add_i32 m0, s40, 0x2000
	s_nop 0
	global_load_lds_dwordx4 v146, s[22:23]
	v_lshl_add_u64 v[166:167], v[228:229], 0, s[8:9]
	s_mov_b32 m0, s45
	s_nop 0
	global_load_lds_dwordx4 v[166:167], off
	v_lshl_add_u64 v[166:167], v[230:231], 0, s[8:9]
	s_mov_b32 m0, s46
	s_nop 0
	global_load_lds_dwordx4 v[166:167], off
	s_waitcnt vmcnt(8)
	s_waitcnt lgkmcnt(0)
	s_barrier
	s_waitcnt lgkmcnt(0)
	v_mfma_f32_16x16x32_bf16 v[62:65], v[66:69], v[194:197], v[62:65]
	v_mfma_f32_16x16x32_bf16 v[58:61], v[74:77], v[194:197], v[58:61]
	v_mfma_f32_16x16x32_bf16 v[46:49], v[66:69], v[202:205], v[46:49]
	v_mfma_f32_16x16x32_bf16 v[42:45], v[74:77], v[202:205], v[42:45]
	v_mfma_f32_16x16x32_bf16 v[30:33], v[66:69], v[210:213], v[30:33]
	v_mfma_f32_16x16x32_bf16 v[26:29], v[74:77], v[210:213], v[26:29]
	v_mfma_f32_16x16x32_bf16 v[14:17], v[66:69], v[218:221], v[14:17]
	v_mfma_f32_16x16x32_bf16 v[10:13], v[74:77], v[218:221], v[10:13]
	v_mfma_f32_16x16x32_bf16 v[62:65], v[70:73], v[198:201], v[62:65]
	v_mfma_f32_16x16x32_bf16 v[58:61], v[78:81], v[198:201], v[58:61]
	v_mfma_f32_16x16x32_bf16 v[46:49], v[70:73], v[206:209], v[46:49]
	v_mfma_f32_16x16x32_bf16 v[42:45], v[78:81], v[206:209], v[42:45]
	v_mfma_f32_16x16x32_bf16 v[30:33], v[70:73], v[214:217], v[30:33]
	v_mfma_f32_16x16x32_bf16 v[26:29], v[78:81], v[214:217], v[26:29]
	v_mfma_f32_16x16x32_bf16 v[14:17], v[70:73], v[222:225], v[14:17]
	v_mfma_f32_16x16x32_bf16 v[10:13], v[78:81], v[222:225], v[10:13]
	v_mfma_f32_16x16x32_bf16 v[54:57], v[162:165], v[194:197], v[54:57]
	v_mfma_f32_16x16x32_bf16 v[50:53], v[186:189], v[194:197], v[50:53]
	v_mfma_f32_16x16x32_bf16 v[38:41], v[162:165], v[202:205], v[38:41]
	v_mfma_f32_16x16x32_bf16 v[34:37], v[186:189], v[202:205], v[34:37]
	v_mfma_f32_16x16x32_bf16 v[22:25], v[162:165], v[210:213], v[22:25]
	v_mfma_f32_16x16x32_bf16 v[18:21], v[186:189], v[210:213], v[18:21]
	v_mfma_f32_16x16x32_bf16 v[6:9], v[162:165], v[218:221], v[6:9]
	v_mfma_f32_16x16x32_bf16 v[2:5], v[186:189], v[218:221], v[2:5]
	v_mfma_f32_16x16x32_bf16 v[54:57], v[182:185], v[198:201], v[54:57]
	v_mfma_f32_16x16x32_bf16 v[50:53], v[190:193], v[198:201], v[50:53]
	v_mfma_f32_16x16x32_bf16 v[38:41], v[182:185], v[206:209], v[38:41]
	v_mfma_f32_16x16x32_bf16 v[34:37], v[190:193], v[206:209], v[34:37]
	v_mfma_f32_16x16x32_bf16 v[22:25], v[182:185], v[214:217], v[22:25]
	v_mfma_f32_16x16x32_bf16 v[18:21], v[190:193], v[214:217], v[18:21]
	v_mfma_f32_16x16x32_bf16 v[6:9], v[182:185], v[222:225], v[6:9]
	v_mfma_f32_16x16x32_bf16 v[2:5], v[190:193], v[222:225], v[2:5]
	s_barrier
	s_add_i32 s53, s53, 2
	s_add_u32 s16, s16, 0x100
	s_addc_u32 s17, s17, 0
	s_add_u32 s25, s25, 0x100
	s_addc_u32 s52, s52, 0
	s_cmp_gt_u32 s53, 29
	s_cbranch_scc0 .LBB0_1465
	s_setprio 0
	s_and_b64 vcc, exec, s[10:11]
	s_cbranch_vccz .LBB0_1468
	s_barrier

; #define PG8_STAGE(bufoff, gbase, voff) do { _Pragma("unroll") for (int _i = 0; _i < 2; ++_i) \
;         __builtin_amdgcn_global_load_lds((const unsigned*)((const char*)(gbase) + (voff)[_i]), (LAS unsigned*)(lds + (bufoff) + ldsw + _i * 8192), 16, 0, 0); } while (0)
; #define PG8_LDA(dst, b, h) do { _Pragma("unroll") for (int m = 0; m < 4; ++m) _Pragma("unroll") for (int k = 0; k < 2; ++k) dst[m][k] = *(const LAS bf16x8*)(lds + PG8_SA(b, h) + aoff + m * 2048 + k * 1024); } while (0)
; #define PG8_LDB(dst, b, h) do { _Pragma("unroll") for (int n = 0; n < 2; ++n) _Pragma("unroll") for (int k = 0; k < 2; ++k) dst[n][k] = *(const LAS bf16x8*)(lds + PG8_SB(b, h) + boff + n * 2048 + k * 1024); } while (0)
; #define PG8_MMA(ai, bj, At, Bt) do { __builtin_amdgcn_s_setprio(1); _Pragma("unroll") for (int m = 0; m < 4; ++m) _Pragma("unroll") for (int n = 0; n < 2; ++n) _Pragma("unroll") for (int k = 0; k < 2; ++k) \
;         acc[ai][bj][m][n] = __builtin_amdgcn_mfma_f32_16x16x32_bf16(Bt[n][k], At[m][k], acc[ai][bj][m][n], 0, 0, 0); __builtin_amdgcn_s_setprio(0); } while (0)
; #define PG8_WAIT_V(n) asm volatile("s_waitcnt vmcnt(" #n ")" ::: "memory")
; #define PG8_WAIT_L(n) asm volatile("s_waitcnt lgkmcnt(" #n ")" ::: "memory")
; template <class Epi, class Sched, bool ALIGN_EPI = false, bool SP2 = false>
; __device__ __forceinline__ void gemm_phase(LAS unsigned char* lds, const Gemm g, const Sched& S, const Epi& E) {
;     ...
;         for (int t = 0; t < nt; t += 2) {
;             const bool last = (t == nt - 2);
;             const char* a1 = cA + (size_t)(t + 1) * kstep;
;             const char* a2 = last ? nA : cA + (size_t)(t + 2) * kstep; const char* b2 = last ? nB : cB + (size_t)(t + 2) * kstep;
;             const char* a3 = a2 + kstep; const char* b3 = b2 + kstep;
;             if (last && has_next) S.a_ready(nxt);
;             if constexpr (SP2) {
;             PG8_LDB(B0, 0, 0); PG8_LDB(B1, 0, 1); PG8_SCHED; PG8_LDA(At, 0, 0); PG8_STAGE(PG8_SA(1, 1), a1 + hstep, voffA);
;             PG8_WAIT_V(8); PG8_WAIT_L(0); PG8_BAR; PG8_MMA(0, 0, At, B0); PG8_MMA(0, 1, At, B1); PG8_BAR; PG8_SCHED;
;             PG8_LDA(At, 0, 1); PG8_STAGE(PG8_SB(0, 0), b2, voffB); PG8_STAGE(PG8_SB(0, 1), b2 + hstepB, voffB); PG8_STAGE(PG8_SA(0, 0), a2, voffA);
;             PG8_WAIT_V(8); PG8_WAIT_L(0); PG8_BAR; PG8_MMA(1, 0, At, B0); PG8_MMA(1, 1, At, B1); PG8_BAR; PG8_SCHED;
.Lprio_1595:
	ds_read_b128 v[130:133], v196
	ds_read_b128 v[134:137], v196 offset:1024
	ds_read_b128 v[138:141], v196 offset:2048
	ds_read_b128 v[142:145], v196 offset:3072
	ds_read_b128 v[166:169], v197
	ds_read_b128 v[170:173], v197 offset:1024
	ds_read_b128 v[174:177], v197 offset:2048
	ds_read_b128 v[178:181], v197 offset:3072
	s_add_u32 s20, s16, 0x100
	s_addc_u32 s21, s17, 0
	s_cmpk_eq_i32 s25, 0x54
	s_cselect_b32 s47, s3, s21
	s_cselect_b32 s46, s2, s20
	s_cselect_b32 s23, s19, s24
	s_cselect_b32 s22, s18, s9
	v_lshl_add_u64 v[190:191], s[16:17], 0, v[158:159]
	s_add_i32 m0, s31, 0xc000
	ds_read_b128 v[182:185], v198
	ds_read_b128 v[186:189], v198 offset:1024
	ds_read_b128 v[202:205], v198 offset:2048
	ds_read_b128 v[206:209], v198 offset:3072
	ds_read_b128 v[210:213], v198 offset:4096
	ds_read_b128 v[214:217], v198 offset:5120
	ds_read_b128 v[218:221], v198 offset:6144
	ds_read_b128 v[222:225], v198 offset:7168
	global_load_lds_dwordx4 v[190:191], off
	v_lshl_add_u64 v[190:191], s[16:17], 0, v[160:161]
	s_add_i32 m0, s31, 0xe000
	s_nop 0
	global_load_lds_dwordx4 v[190:191], off
	s_waitcnt lgkmcnt(0)
	s_barrier
	s_waitcnt lgkmcnt(0)
	v_mfma_f32_16x16x32_bf16 v[126:129], v[130:133], v[182:185], 0
	v_mfma_f32_16x16x32_bf16 v[122:125], v[138:141], v[182:185], 0
	v_mfma_f32_16x16x32_bf16 v[110:113], v[130:133], v[202:205], 0
	v_mfma_f32_16x16x32_bf16 v[106:109], v[138:141], v[202:205], 0
	v_mfma_f32_16x16x32_bf16 v[94:97], v[130:133], v[210:213], 0
	v_mfma_f32_16x16x32_bf16 v[90:93], v[138:141], v[210:213], 0
	v_mfma_f32_16x16x32_bf16 v[78:81], v[130:133], v[218:221], 0
	v_mfma_f32_16x16x32_bf16 v[74:77], v[138:141], v[218:221], 0
	v_mfma_f32_16x16x32_bf16 v[126:129], v[134:137], v[186:189], v[126:129]
	v_mfma_f32_16x16x32_bf16 v[122:125], v[142:145], v[186:189], v[122:125]
	v_mfma_f32_16x16x32_bf16 v[110:113], v[134:137], v[206:209], v[110:113]
	v_mfma_f32_16x16x32_bf16 v[106:109], v[142:145], v[206:209], v[106:109]
	v_mfma_f32_16x16x32_bf16 v[94:97], v[134:137], v[214:217], v[94:97]
	v_mfma_f32_16x16x32_bf16 v[90:93], v[142:145], v[214:217], v[90:93]
	v_mfma_f32_16x16x32_bf16 v[78:81], v[134:137], v[222:225], v[78:81]
	v_mfma_f32_16x16x32_bf16 v[74:77], v[142:145], v[222:225], v[74:77]
	v_mfma_f32_16x16x32_bf16 v[118:121], v[166:169], v[182:185], 0
	v_mfma_f32_16x16x32_bf16 v[114:117], v[174:177], v[182:185], 0
	v_mfma_f32_16x16x32_bf16 v[102:105], v[166:169], v[202:205], 0
	v_mfma_f32_16x16x32_bf16 v[98:101], v[174:177], v[202:205], 0
	v_mfma_f32_16x16x32_bf16 v[86:89], v[166:169], v[210:213], 0
	v_mfma_f32_16x16x32_bf16 v[82:85], v[174:177], v[210:213], 0
	v_mfma_f32_16x16x32_bf16 v[70:73], v[166:169], v[218:221], 0
	v_mfma_f32_16x16x32_bf16 v[66:69], v[174:177], v[218:221], 0
	v_mfma_f32_16x16x32_bf16 v[118:121], v[170:173], v[186:189], v[118:121]
	v_mfma_f32_16x16x32_bf16 v[114:117], v[178:181], v[186:189], v[114:117]
	v_mfma_f32_16x16x32_bf16 v[102:105], v[170:173], v[206:209], v[102:105]
	v_mfma_f32_16x16x32_bf16 v[98:101], v[178:181], v[206:209], v[98:101]
	v_mfma_f32_16x16x32_bf16 v[86:89], v[170:173], v[214:217], v[86:89]
	v_mfma_f32_16x16x32_bf16 v[82:85], v[178:181], v[214:217], v[82:85]
	v_mfma_f32_16x16x32_bf16 v[70:73], v[170:173], v[222:225], v[70:73]
	v_mfma_f32_16x16x32_bf16 v[66:69], v[178:181], v[222:225], v[66:69]
	s_barrier
	s_add_i32 s16, s52, s30
	s_mov_b32 m0, s16
	ds_read_b128 v[182:185], v198 offset:16384
	ds_read_b128 v[186:189], v198 offset:17408
	ds_read_b128 v[202:205], v198 offset:18432
	ds_read_b128 v[206:209], v198 offset:19456
	ds_read_b128 v[210:213], v198 offset:20480
	ds_read_b128 v[214:217], v198 offset:21504
	ds_read_b128 v[218:221], v198 offset:22528
	ds_read_b128 v[222:225], v198 offset:23552
	global_load_lds_dwordx4 v148, s[22:23]
	s_add_i32 m0, s16, 0x2000
	s_add_u32 s16, s22, 0x58000
	v_lshl_add_u64 v[226:227], s[22:23], 0, v[152:153]
	s_addc_u32 s17, s23, 0
	s_add_i32 s56, s53, s30
	global_load_lds_dwordx4 v152, s[22:23]
	s_mov_b32 m0, s56
	global_load_lds_dwordx4 v148, s[16:17]
	s_add_i32 m0, s56, 0x2000
	s_nop 0
	global_load_lds_dwordx4 v152, s[16:17]
	s_mov_b32 m0, s31
	s_nop 0
	global_load_lds_dwordx4 v146, s[46:47]
	s_mov_b32 m0, s33
	s_nop 0
	global_load_lds_dwordx4 v150, s[46:47]
	s_waitcnt lgkmcnt(0)
	s_barrier
	s_waitcnt lgkmcnt(0)
	v_mfma_f32_16x16x32_bf16 v[62:65], v[130:133], v[182:185], 0
	v_mfma_f32_16x16x32_bf16 v[58:61], v[138:141], v[182:185], 0
	v_mfma_f32_16x16x32_bf16 v[46:49], v[130:133], v[202:205], 0
	v_mfma_f32_16x16x32_bf16 v[42:45], v[138:141], v[202:205], 0
	v_mfma_f32_16x16x32_bf16 v[30:33], v[130:133], v[210:213], 0
	v_mfma_f32_16x16x32_bf16 v[26:29], v[138:141], v[210:213], 0
	v_mfma_f32_16x16x32_bf16 v[14:17], v[130:133], v[218:221], 0
	v_mfma_f32_16x16x32_bf16 v[10:13], v[138:141], v[218:221], 0
	v_mfma_f32_16x16x32_bf16 v[62:65], v[134:137], v[186:189], v[62:65]
	v_mfma_f32_16x16x32_bf16 v[58:61], v[142:145], v[186:189], v[58:61]
	v_mfma_f32_16x16x32_bf16 v[46:49], v[134:137], v[206:209], v[46:49]
	v_mfma_f32_16x16x32_bf16 v[42:45], v[142:145], v[206:209], v[42:45]
	v_mfma_f32_16x16x32_bf16 v[30:33], v[134:137], v[214:217], v[30:33]
	v_mfma_f32_16x16x32_bf16 v[26:29], v[142:145], v[214:217], v[26:29]
	v_mfma_f32_16x16x32_bf16 v[14:17], v[134:137], v[222:225], v[14:17]
	v_mfma_f32_16x16x32_bf16 v[10:13], v[142:145], v[222:225], v[10:13]
	v_mfma_f32_16x16x32_bf16 v[54:57], v[166:169], v[182:185], 0
	v_mfma_f32_16x16x32_bf16 v[50:53], v[174:177], v[182:185], 0
	v_mfma_f32_16x16x32_bf16 v[38:41], v[166:169], v[202:205], 0
	v_mfma_f32_16x16x32_bf16 v[34:37], v[174:177], v[202:205], 0
	v_mfma_f32_16x16x32_bf16 v[22:25], v[166:169], v[210:213], 0
	v_mfma_f32_16x16x32_bf16 v[18:21], v[174:177], v[210:213], 0
	v_mfma_f32_16x16x32_bf16 v[6:9], v[166:169], v[218:221], 0
	v_mfma_f32_16x16x32_bf16 v[2:5], v[174:177], v[218:221], 0
	v_mfma_f32_16x16x32_bf16 v[54:57], v[170:173], v[186:189], v[54:57]
	v_mfma_f32_16x16x32_bf16 v[50:53], v[178:181], v[186:189], v[50:53]
	v_mfma_f32_16x16x32_bf16 v[38:41], v[170:173], v[206:209], v[38:41]
	v_mfma_f32_16x16x32_bf16 v[34:37], v[178:181], v[206:209], v[34:37]
	v_mfma_f32_16x16x32_bf16 v[22:25], v[170:173], v[214:217], v[22:25]
	v_mfma_f32_16x16x32_bf16 v[18:21], v[178:181], v[214:217], v[18:21]
	v_mfma_f32_16x16x32_bf16 v[6:9], v[170:173], v[222:225], v[6:9]
	v_mfma_f32_16x16x32_bf16 v[2:5], v[178:181], v[222:225], v[2:5]
	s_barrier
; #define PG8_STAGE(bufoff, gbase, voff) do { _Pragma("unroll") for (int _i = 0; _i < 2; ++_i) \
;         __builtin_amdgcn_global_load_lds((const unsigned*)((const char*)(gbase) + (voff)[_i]), (LAS unsigned*)(lds + (bufoff) + ldsw + _i * 8192), 16, 0, 0); } while (0)
; #define PG8_LDA(dst, b, h) do { _Pragma("unroll") for (int m = 0; m < 4; ++m) _Pragma("unroll") for (int k = 0; k < 2; ++k) dst[m][k] = *(const LAS bf16x8*)(lds + PG8_SA(b, h) + aoff + m * 2048 + k * 1024); } while (0)
; #define PG8_LDB(dst, b, h) do { _Pragma("unroll") for (int n = 0; n < 2; ++n) _Pragma("unroll") for (int k = 0; k < 2; ++k) dst[n][k] = *(const LAS bf16x8*)(lds + PG8_SB(b, h) + boff + n * 2048 + k * 1024); } while (0)
; #define PG8_MMA(ai, bj, At, Bt) do { __builtin_amdgcn_s_setprio(1); _Pragma("unroll") for (int m = 0; m < 4; ++m) _Pragma("unroll") for (int n = 0; n < 2; ++n) _Pragma("unroll") for (int k = 0; k < 2; ++k) \
;         acc[ai][bj][m][n] = __builtin_amdgcn_mfma_f32_16x16x32_bf16(Bt[n][k], At[m][k], acc[ai][bj][m][n], 0, 0, 0); __builtin_amdgcn_s_setprio(0); } while (0)
; #define PG8_WAIT_V(n) asm volatile("s_waitcnt vmcnt(" #n ")" ::: "memory")
; #define PG8_WAIT_L(n) asm volatile("s_waitcnt lgkmcnt(" #n ")" ::: "memory")
; #define PG8_BAR __builtin_amdgcn_s_barrier()
; #define PG8_SCHED __builtin_amdgcn_sched_barrier(0)
; template <class Epi, class Sched, bool ALIGN_EPI = false, bool SP2 = false>
; __device__ __forceinline__ void gemm_phase(LAS unsigned char* lds, const Gemm g, const Sched& S, const Epi& E) {
;     ...
;             PG8_LDB(B0, 1, 0); PG8_LDB(B1, 1, 1); PG8_SCHED; PG8_LDA(At, 1, 0); PG8_STAGE(PG8_SA(0, 1), a2 + hstep, voffA);
;             PG8_WAIT_V(8); PG8_WAIT_L(0); PG8_BAR; PG8_MMA(0, 0, At, B0); PG8_MMA(0, 1, At, B1); PG8_BAR; PG8_SCHED;
;             PG8_LDA(At, 1, 1); PG8_STAGE(PG8_SB(1, 0), b3, voffB); PG8_STAGE(PG8_SB(1, 1), b3 + hstepB, voffB); PG8_STAGE(PG8_SA(1, 0), a3, voffA);
;             PG8_WAIT_V(8); PG8_WAIT_L(0); PG8_BAR; PG8_MMA(1, 0, At, B0); PG8_MMA(1, 1, At, B1); PG8_BAR; PG8_SCHED;
	s_add_i32 s56, 0, 0x18000
	s_add_i32 s57, 0, 0x1c000
	v_add_u32_e32 v142, s56, v1
	v_add_u32_e32 v154, s57, v1
	ds_read_b128 v[130:133], v142
	ds_read_b128 v[134:137], v142 offset:1024
	ds_read_b128 v[138:141], v142 offset:2048
	ds_read_b128 v[142:145], v142 offset:3072
	ds_read_b128 v[166:169], v154
	ds_read_b128 v[170:173], v154 offset:1024
	ds_read_b128 v[174:177], v154 offset:2048
	ds_read_b128 v[178:181], v154 offset:3072
	s_add_u32 s16, s46, 0x160000
	s_addc_u32 s17, s47, 0
	s_mov_b32 m0, s34
	ds_read_b128 v[182:185], v198 offset:32768
	ds_read_b128 v[186:189], v198 offset:33792
	ds_read_b128 v[202:205], v198 offset:34816
	ds_read_b128 v[206:209], v198 offset:35840
	ds_read_b128 v[210:213], v198 offset:36864
	ds_read_b128 v[214:217], v198 offset:37888
	ds_read_b128 v[218:221], v198 offset:38912
	ds_read_b128 v[222:225], v198 offset:39936
	global_load_lds_dwordx4 v146, s[16:17]
	s_mov_b32 m0, s35
	s_nop 0
	global_load_lds_dwordx4 v150, s[16:17]
	s_waitcnt vmcnt(8)
	s_waitcnt lgkmcnt(0)
	s_barrier
	s_waitcnt lgkmcnt(0)
	v_mfma_f32_16x16x32_bf16 v[126:129], v[130:133], v[182:185], v[126:129]
	v_mfma_f32_16x16x32_bf16 v[122:125], v[138:141], v[182:185], v[122:125]
	v_mfma_f32_16x16x32_bf16 v[110:113], v[130:133], v[202:205], v[110:113]
	v_mfma_f32_16x16x32_bf16 v[106:109], v[138:141], v[202:205], v[106:109]
	v_mfma_f32_16x16x32_bf16 v[94:97], v[130:133], v[210:213], v[94:97]
	v_mfma_f32_16x16x32_bf16 v[90:93], v[138:141], v[210:213], v[90:93]
	v_mfma_f32_16x16x32_bf16 v[78:81], v[130:133], v[218:221], v[78:81]
	v_mfma_f32_16x16x32_bf16 v[74:77], v[138:141], v[218:221], v[74:77]
	v_mfma_f32_16x16x32_bf16 v[126:129], v[134:137], v[186:189], v[126:129]
	v_mfma_f32_16x16x32_bf16 v[122:125], v[142:145], v[186:189], v[122:125]
	v_mfma_f32_16x16x32_bf16 v[110:113], v[134:137], v[206:209], v[110:113]
	v_mfma_f32_16x16x32_bf16 v[106:109], v[142:145], v[206:209], v[106:109]
	v_mfma_f32_16x16x32_bf16 v[94:97], v[134:137], v[214:217], v[94:97]
	v_mfma_f32_16x16x32_bf16 v[90:93], v[142:145], v[214:217], v[90:93]
	v_mfma_f32_16x16x32_bf16 v[78:81], v[134:137], v[222:225], v[78:81]
	v_mfma_f32_16x16x32_bf16 v[74:77], v[142:145], v[222:225], v[74:77]
	v_mfma_f32_16x16x32_bf16 v[118:121], v[166:169], v[182:185], v[118:121]
	v_mfma_f32_16x16x32_bf16 v[114:117], v[174:177], v[182:185], v[114:117]
	v_mfma_f32_16x16x32_bf16 v[102:105], v[166:169], v[202:205], v[102:105]
	v_mfma_f32_16x16x32_bf16 v[98:101], v[174:177], v[202:205], v[98:101]
	v_mfma_f32_16x16x32_bf16 v[86:89], v[166:169], v[210:213], v[86:89]
	v_mfma_f32_16x16x32_bf16 v[82:85], v[174:177], v[210:213], v[82:85]
	v_mfma_f32_16x16x32_bf16 v[70:73], v[166:169], v[218:221], v[70:73]
	v_mfma_f32_16x16x32_bf16 v[66:69], v[174:177], v[218:221], v[66:69]
	v_mfma_f32_16x16x32_bf16 v[118:121], v[170:173], v[186:189], v[118:121]
	v_mfma_f32_16x16x32_bf16 v[114:117], v[178:181], v[186:189], v[114:117]
	v_mfma_f32_16x16x32_bf16 v[102:105], v[170:173], v[206:209], v[102:105]
	v_mfma_f32_16x16x32_bf16 v[98:101], v[178:181], v[206:209], v[98:101]
	v_mfma_f32_16x16x32_bf16 v[86:89], v[170:173], v[214:217], v[86:89]
	v_mfma_f32_16x16x32_bf16 v[82:85], v[178:181], v[214:217], v[82:85]
	v_mfma_f32_16x16x32_bf16 v[70:73], v[170:173], v[222:225], v[70:73]
	v_mfma_f32_16x16x32_bf16 v[66:69], v[178:181], v[222:225], v[66:69]
	s_barrier
	s_add_u32 s98, s22, 0x80
	s_addc_u32 s99, s23, 0
	s_add_u32 s100, s46, 0x80
	s_addc_u32 s101, s47, 0
	s_add_i32 s16, s56, s30
	s_mov_b32 m0, s16
	ds_read_b128 v[182:185], v198 offset:49152
	ds_read_b128 v[186:189], v198 offset:50176
	ds_read_b128 v[202:205], v198 offset:51200
	ds_read_b128 v[206:209], v198 offset:52224
	ds_read_b128 v[210:213], v198 offset:53248
	ds_read_b128 v[214:217], v198 offset:54272
	ds_read_b128 v[218:221], v198 offset:55296
	ds_read_b128 v[222:225], v198 offset:56320
	global_load_lds_dwordx4 v148, s[98:99]
	s_add_i32 m0, s16, 0x2000
	s_add_u32 s16, s22, 0x58080
	v_lshl_add_u64 v[190:191], v[226:227], 0, s[12:13]
	s_addc_u32 s17, s23, 0
	s_add_i32 s22, s57, s30
	global_load_lds_dwordx4 v[190:191], off
	s_mov_b32 m0, s22
	s_nop 0
	global_load_lds_dwordx4 v148, s[16:17]
	s_add_i32 m0, s22, 0x2000
	s_nop 0
	global_load_lds_dwordx4 v152, s[16:17]
	s_mov_b32 m0, s49
	s_nop 0
	global_load_lds_dwordx4 v146, s[100:101]
	s_mov_b32 m0, s50
	s_nop 0
	global_load_lds_dwordx4 v150, s[100:101]
	s_waitcnt vmcnt(8)
	s_waitcnt lgkmcnt(0)
	s_barrier
	s_waitcnt lgkmcnt(0)
	v_mfma_f32_16x16x32_bf16 v[62:65], v[130:133], v[182:185], v[62:65]
	v_mfma_f32_16x16x32_bf16 v[58:61], v[138:141], v[182:185], v[58:61]
	v_mfma_f32_16x16x32_bf16 v[46:49], v[130:133], v[202:205], v[46:49]
	v_mfma_f32_16x16x32_bf16 v[42:45], v[138:141], v[202:205], v[42:45]
	v_mfma_f32_16x16x32_bf16 v[30:33], v[130:133], v[210:213], v[30:33]
	v_mfma_f32_16x16x32_bf16 v[26:29], v[138:141], v[210:213], v[26:29]
	v_mfma_f32_16x16x32_bf16 v[14:17], v[130:133], v[218:221], v[14:17]
	v_mfma_f32_16x16x32_bf16 v[10:13], v[138:141], v[218:221], v[10:13]
	v_mfma_f32_16x16x32_bf16 v[62:65], v[134:137], v[186:189], v[62:65]
	v_mfma_f32_16x16x32_bf16 v[58:61], v[142:145], v[186:189], v[58:61]
	v_mfma_f32_16x16x32_bf16 v[46:49], v[134:137], v[206:209], v[46:49]
	v_mfma_f32_16x16x32_bf16 v[42:45], v[142:145], v[206:209], v[42:45]
	v_mfma_f32_16x16x32_bf16 v[30:33], v[134:137], v[214:217], v[30:33]
	v_mfma_f32_16x16x32_bf16 v[26:29], v[142:145], v[214:217], v[26:29]
	v_mfma_f32_16x16x32_bf16 v[14:17], v[134:137], v[222:225], v[14:17]
	v_mfma_f32_16x16x32_bf16 v[10:13], v[142:145], v[222:225], v[10:13]
	v_mfma_f32_16x16x32_bf16 v[54:57], v[166:169], v[182:185], v[54:57]
	v_mfma_f32_16x16x32_bf16 v[50:53], v[174:177], v[182:185], v[50:53]
	v_mfma_f32_16x16x32_bf16 v[38:41], v[166:169], v[202:205], v[38:41]
	v_mfma_f32_16x16x32_bf16 v[34:37], v[174:177], v[202:205], v[34:37]
	v_mfma_f32_16x16x32_bf16 v[22:25], v[166:169], v[210:213], v[22:25]
	v_mfma_f32_16x16x32_bf16 v[18:21], v[174:177], v[210:213], v[18:21]
	v_mfma_f32_16x16x32_bf16 v[6:9], v[166:169], v[218:221], v[6:9]
	v_mfma_f32_16x16x32_bf16 v[2:5], v[174:177], v[218:221], v[2:5]
	v_mfma_f32_16x16x32_bf16 v[54:57], v[170:173], v[186:189], v[54:57]
	v_mfma_f32_16x16x32_bf16 v[50:53], v[178:181], v[186:189], v[50:53]
	v_mfma_f32_16x16x32_bf16 v[38:41], v[170:173], v[206:209], v[38:41]
	v_mfma_f32_16x16x32_bf16 v[34:37], v[178:181], v[206:209], v[34:37]
	v_mfma_f32_16x16x32_bf16 v[22:25], v[170:173], v[214:217], v[22:25]
	v_mfma_f32_16x16x32_bf16 v[18:21], v[178:181], v[214:217], v[18:21]
	v_mfma_f32_16x16x32_bf16 v[6:9], v[170:173], v[222:225], v[6:9]
	v_mfma_f32_16x16x32_bf16 v[2:5], v[178:181], v[222:225], v[2:5]
	s_barrier
	s_add_i32 s25, s25, 2
	s_add_u32 s9, s9, 0x100
	s_addc_u32 s24, s24, 0
	s_cmpk_gt_u32 s25, 0x55
	s_mov_b64 s[16:17], s[20:21]
; #define PG8_STAGE(bufoff, gbase, voff) do { _Pragma("unroll") for (int _i = 0; _i < 2; ++_i) \
;         __builtin_amdgcn_global_load_lds((const unsigned*)((const char*)(gbase) + (voff)[_i]), (LAS unsigned*)(lds + (bufoff) + ldsw + _i * 8192), 16, 0, 0); } while (0)
; #define PG8_LDA(dst, b, h) do { _Pragma("unroll") for (int m = 0; m < 4; ++m) _Pragma("unroll") for (int k = 0; k < 2; ++k) dst[m][k] = *(const LAS bf16x8*)(lds + PG8_SA(b, h) + aoff + m * 2048 + k * 1024); } while (0)
; #define PG8_LDB(dst, b, h) do { _Pragma("unroll") for (int n = 0; n < 2; ++n) _Pragma("unroll") for (int k = 0; k < 2; ++k) dst[n][k] = *(const LAS bf16x8*)(lds + PG8_SB(b, h) + boff + n * 2048 + k * 1024); } while (0)
; #define PG8_MMA(ai, bj, At, Bt) do { __builtin_amdgcn_s_setprio(1); _Pragma("unroll") for (int m = 0; m < 4; ++m) _Pragma("unroll") for (int n = 0; n < 2; ++n) _Pragma("unroll") for (int k = 0; k < 2; ++k) \
;         acc[ai][bj][m][n] = __builtin_amdgcn_mfma_f32_16x16x32_bf16(Bt[n][k], At[m][k], acc[ai][bj][m][n], 0, 0, 0); __builtin_amdgcn_s_setprio(0); } while (0)
; #define PG8_WAIT_V(n) asm volatile("s_waitcnt vmcnt(" #n ")" ::: "memory")
; #define PG8_WAIT_L(n) asm volatile("s_waitcnt lgkmcnt(" #n ")" ::: "memory")
; template <class Epi, class Sched, bool ALIGN_EPI = false, bool SP2 = false>
; __device__ __forceinline__ void gemm_phase(LAS unsigned char* lds, const Gemm g, const Sched& S, const Epi& E) {
;     ...
;         for (int t = 0; t < nt; t += 2) {
;             const bool last = (t == nt - 2);
;             const char* a1 = cA + (size_t)(t + 1) * kstep;
;             const char* a2 = last ? nA : cA + (size_t)(t + 2) * kstep; const char* b2 = last ? nB : cB + (size_t)(t + 2) * kstep;
;             const char* a3 = a2 + kstep; const char* b3 = b2 + kstep;
;             if (last && has_next) S.a_ready(nxt);
;             if constexpr (SP2) {
;             PG8_LDB(B0, 0, 0); PG8_LDB(B1, 0, 1); PG8_SCHED; PG8_LDA(At, 0, 0); PG8_STAGE(PG8_SA(1, 1), a1 + hstep, voffA);
;             PG8_WAIT_V(8); PG8_WAIT_L(0); PG8_BAR; PG8_MMA(0, 0, At, B0); PG8_MMA(0, 1, At, B1); PG8_BAR; PG8_SCHED;
;             PG8_LDA(At, 0, 1); PG8_STAGE(PG8_SB(0, 0), b2, voffB); PG8_STAGE(PG8_SB(0, 1), b2 + hstepB, voffB); PG8_STAGE(PG8_SA(0, 0), a2, voffA);
;             PG8_WAIT_V(8); PG8_WAIT_L(0); PG8_BAR; PG8_MMA(1, 0, At, B0); PG8_MMA(1, 1, At, B1); PG8_BAR; PG8_SCHED;
.LBB0_1595:
	ds_read_b128 v[130:133], v196
	ds_read_b128 v[134:137], v196 offset:1024
	ds_read_b128 v[138:141], v196 offset:2048
	ds_read_b128 v[142:145], v196 offset:3072
	ds_read_b128 v[166:169], v197
	ds_read_b128 v[170:173], v197 offset:1024
	ds_read_b128 v[174:177], v197 offset:2048
	ds_read_b128 v[178:181], v197 offset:3072
	s_add_u32 s20, s16, 0x100
	s_addc_u32 s21, s17, 0
	s_cmpk_eq_i32 s25, 0x54
	s_cselect_b32 s47, s3, s21
	s_cselect_b32 s46, s2, s20
	s_cselect_b32 s23, s19, s24
	s_cselect_b32 s22, s18, s9
	v_lshl_add_u64 v[190:191], s[16:17], 0, v[158:159]
	s_add_i32 m0, s31, 0xc000
	ds_read_b128 v[182:185], v198
	ds_read_b128 v[186:189], v198 offset:1024
	ds_read_b128 v[202:205], v198 offset:2048
	ds_read_b128 v[206:209], v198 offset:3072
	ds_read_b128 v[210:213], v198 offset:4096
	ds_read_b128 v[214:217], v198 offset:5120
	ds_read_b128 v[218:221], v198 offset:6144
	ds_read_b128 v[222:225], v198 offset:7168
	global_load_lds_dwordx4 v[190:191], off
	v_lshl_add_u64 v[190:191], s[16:17], 0, v[160:161]
	s_add_i32 m0, s31, 0xe000
	s_nop 0
	global_load_lds_dwordx4 v[190:191], off
	s_waitcnt vmcnt(8)
	s_waitcnt lgkmcnt(0)
	s_barrier
	s_waitcnt lgkmcnt(0)
	v_mfma_f32_16x16x32_bf16 v[126:129], v[130:133], v[182:185], v[126:129]
	v_mfma_f32_16x16x32_bf16 v[122:125], v[138:141], v[182:185], v[122:125]
	v_mfma_f32_16x16x32_bf16 v[110:113], v[130:133], v[202:205], v[110:113]
	v_mfma_f32_16x16x32_bf16 v[106:109], v[138:141], v[202:205], v[106:109]
	v_mfma_f32_16x16x32_bf16 v[94:97], v[130:133], v[210:213], v[94:97]
	v_mfma_f32_16x16x32_bf16 v[90:93], v[138:141], v[210:213], v[90:93]
	v_mfma_f32_16x16x32_bf16 v[78:81], v[130:133], v[218:221], v[78:81]
	v_mfma_f32_16x16x32_bf16 v[74:77], v[138:141], v[218:221], v[74:77]
	v_mfma_f32_16x16x32_bf16 v[126:129], v[134:137], v[186:189], v[126:129]
	v_mfma_f32_16x16x32_bf16 v[122:125], v[142:145], v[186:189], v[122:125]
	v_mfma_f32_16x16x32_bf16 v[110:113], v[134:137], v[206:209], v[110:113]
	v_mfma_f32_16x16x32_bf16 v[106:109], v[142:145], v[206:209], v[106:109]
	v_mfma_f32_16x16x32_bf16 v[94:97], v[134:137], v[214:217], v[94:97]
	v_mfma_f32_16x16x32_bf16 v[90:93], v[142:145], v[214:217], v[90:93]
	v_mfma_f32_16x16x32_bf16 v[78:81], v[134:137], v[222:225], v[78:81]
	v_mfma_f32_16x16x32_bf16 v[74:77], v[142:145], v[222:225], v[74:77]
	v_mfma_f32_16x16x32_bf16 v[118:121], v[166:169], v[182:185], v[118:121]
	v_mfma_f32_16x16x32_bf16 v[114:117], v[174:177], v[182:185], v[114:117]
	v_mfma_f32_16x16x32_bf16 v[102:105], v[166:169], v[202:205], v[102:105]
	v_mfma_f32_16x16x32_bf16 v[98:101], v[174:177], v[202:205], v[98:101]
	v_mfma_f32_16x16x32_bf16 v[86:89], v[166:169], v[210:213], v[86:89]
	v_mfma_f32_16x16x32_bf16 v[82:85], v[174:177], v[210:213], v[82:85]
	v_mfma_f32_16x16x32_bf16 v[70:73], v[166:169], v[218:221], v[70:73]
	v_mfma_f32_16x16x32_bf16 v[66:69], v[174:177], v[218:221], v[66:69]
	v_mfma_f32_16x16x32_bf16 v[118:121], v[170:173], v[186:189], v[118:121]
	v_mfma_f32_16x16x32_bf16 v[114:117], v[178:181], v[186:189], v[114:117]
	v_mfma_f32_16x16x32_bf16 v[102:105], v[170:173], v[206:209], v[102:105]
	v_mfma_f32_16x16x32_bf16 v[98:101], v[178:181], v[206:209], v[98:101]
	v_mfma_f32_16x16x32_bf16 v[86:89], v[170:173], v[214:217], v[86:89]
	v_mfma_f32_16x16x32_bf16 v[82:85], v[178:181], v[214:217], v[82:85]
	v_mfma_f32_16x16x32_bf16 v[70:73], v[170:173], v[222:225], v[70:73]
	v_mfma_f32_16x16x32_bf16 v[66:69], v[178:181], v[222:225], v[66:69]
	s_barrier
	s_add_i32 s16, s52, s30
	s_mov_b32 m0, s16
	ds_read_b128 v[182:185], v198 offset:16384
	ds_read_b128 v[186:189], v198 offset:17408
	ds_read_b128 v[202:205], v198 offset:18432
	ds_read_b128 v[206:209], v198 offset:19456
	ds_read_b128 v[210:213], v198 offset:20480
	ds_read_b128 v[214:217], v198 offset:21504
	ds_read_b128 v[218:221], v198 offset:22528
	ds_read_b128 v[222:225], v198 offset:23552
	global_load_lds_dwordx4 v148, s[22:23]
	s_add_i32 m0, s16, 0x2000
	s_add_u32 s16, s22, 0x58000
	v_lshl_add_u64 v[226:227], s[22:23], 0, v[152:153]
	s_addc_u32 s17, s23, 0
	s_add_i32 s56, s53, s30
	global_load_lds_dwordx4 v152, s[22:23]
	s_mov_b32 m0, s56
	global_load_lds_dwordx4 v148, s[16:17]
	s_add_i32 m0, s56, 0x2000
	s_nop 0
	global_load_lds_dwordx4 v152, s[16:17]
	s_mov_b32 m0, s31
	s_nop 0
	global_load_lds_dwordx4 v146, s[46:47]
	s_mov_b32 m0, s33
	s_nop 0
	global_load_lds_dwordx4 v150, s[46:47]
	s_waitcnt vmcnt(8)
	s_waitcnt lgkmcnt(0)
	s_barrier
	s_waitcnt lgkmcnt(0)
	v_mfma_f32_16x16x32_bf16 v[62:65], v[130:133], v[182:185], v[62:65]
	v_mfma_f32_16x16x32_bf16 v[58:61], v[138:141], v[182:185], v[58:61]
	v_mfma_f32_16x16x32_bf16 v[46:49], v[130:133], v[202:205], v[46:49]
	v_mfma_f32_16x16x32_bf16 v[42:45], v[138:141], v[202:205], v[42:45]
	v_mfma_f32_16x16x32_bf16 v[30:33], v[130:133], v[210:213], v[30:33]
	v_mfma_f32_16x16x32_bf16 v[26:29], v[138:141], v[210:213], v[26:29]
	v_mfma_f32_16x16x32_bf16 v[14:17], v[130:133], v[218:221], v[14:17]
	v_mfma_f32_16x16x32_bf16 v[10:13], v[138:141], v[218:221], v[10:13]
	v_mfma_f32_16x16x32_bf16 v[62:65], v[134:137], v[186:189], v[62:65]
	v_mfma_f32_16x16x32_bf16 v[58:61], v[142:145], v[186:189], v[58:61]
	v_mfma_f32_16x16x32_bf16 v[46:49], v[134:137], v[206:209], v[46:49]
	v_mfma_f32_16x16x32_bf16 v[42:45], v[142:145], v[206:209], v[42:45]
	v_mfma_f32_16x16x32_bf16 v[30:33], v[134:137], v[214:217], v[30:33]
	v_mfma_f32_16x16x32_bf16 v[26:29], v[142:145], v[214:217], v[26:29]
	v_mfma_f32_16x16x32_bf16 v[14:17], v[134:137], v[222:225], v[14:17]
	v_mfma_f32_16x16x32_bf16 v[10:13], v[142:145], v[222:225], v[10:13]
	v_mfma_f32_16x16x32_bf16 v[54:57], v[166:169], v[182:185], v[54:57]
	v_mfma_f32_16x16x32_bf16 v[50:53], v[174:177], v[182:185], v[50:53]
	v_mfma_f32_16x16x32_bf16 v[38:41], v[166:169], v[202:205], v[38:41]
	v_mfma_f32_16x16x32_bf16 v[34:37], v[174:177], v[202:205], v[34:37]
	v_mfma_f32_16x16x32_bf16 v[22:25], v[166:169], v[210:213], v[22:25]
	v_mfma_f32_16x16x32_bf16 v[18:21], v[174:177], v[210:213], v[18:21]
	v_mfma_f32_16x16x32_bf16 v[6:9], v[166:169], v[218:221], v[6:9]
	v_mfma_f32_16x16x32_bf16 v[2:5], v[174:177], v[218:221], v[2:5]
	v_mfma_f32_16x16x32_bf16 v[54:57], v[170:173], v[186:189], v[54:57]
	v_mfma_f32_16x16x32_bf16 v[50:53], v[178:181], v[186:189], v[50:53]
	v_mfma_f32_16x16x32_bf16 v[38:41], v[170:173], v[206:209], v[38:41]
	v_mfma_f32_16x16x32_bf16 v[34:37], v[178:181], v[206:209], v[34:37]
	v_mfma_f32_16x16x32_bf16 v[22:25], v[170:173], v[214:217], v[22:25]
	v_mfma_f32_16x16x32_bf16 v[18:21], v[178:181], v[214:217], v[18:21]
	v_mfma_f32_16x16x32_bf16 v[6:9], v[170:173], v[222:225], v[6:9]
	v_mfma_f32_16x16x32_bf16 v[2:5], v[178:181], v[222:225], v[2:5]
	s_barrier
; #define PG8_STAGE(bufoff, gbase, voff) do { _Pragma("unroll") for (int _i = 0; _i < 2; ++_i) \
;         __builtin_amdgcn_global_load_lds((const unsigned*)((const char*)(gbase) + (voff)[_i]), (LAS unsigned*)(lds + (bufoff) + ldsw + _i * 8192), 16, 0, 0); } while (0)
; #define PG8_LDA(dst, b, h) do { _Pragma("unroll") for (int m = 0; m < 4; ++m) _Pragma("unroll") for (int k = 0; k < 2; ++k) dst[m][k] = *(const LAS bf16x8*)(lds + PG8_SA(b, h) + aoff + m * 2048 + k * 1024); } while (0)
; #define PG8_LDB(dst, b, h) do { _Pragma("unroll") for (int n = 0; n < 2; ++n) _Pragma("unroll") for (int k = 0; k < 2; ++k) dst[n][k] = *(const LAS bf16x8*)(lds + PG8_SB(b, h) + boff + n * 2048 + k * 1024); } while (0)
; #define PG8_MMA(ai, bj, At, Bt) do { __builtin_amdgcn_s_setprio(1); _Pragma("unroll") for (int m = 0; m < 4; ++m) _Pragma("unroll") for (int n = 0; n < 2; ++n) _Pragma("unroll") for (int k = 0; k < 2; ++k) \
;         acc[ai][bj][m][n] = __builtin_amdgcn_mfma_f32_16x16x32_bf16(Bt[n][k], At[m][k], acc[ai][bj][m][n], 0, 0, 0); __builtin_amdgcn_s_setprio(0); } while (0)
; #define PG8_WAIT_V(n) asm volatile("s_waitcnt vmcnt(" #n ")" ::: "memory")
; #define PG8_WAIT_L(n) asm volatile("s_waitcnt lgkmcnt(" #n ")" ::: "memory")
; #define PG8_BAR __builtin_amdgcn_s_barrier()
; #define PG8_SCHED __builtin_amdgcn_sched_barrier(0)
; template <class Epi, class Sched, bool ALIGN_EPI = false, bool SP2 = false>
; __device__ __forceinline__ void gemm_phase(LAS unsigned char* lds, const Gemm g, const Sched& S, const Epi& E) {
;     ...
;             PG8_LDB(B0, 1, 0); PG8_LDB(B1, 1, 1); PG8_SCHED; PG8_LDA(At, 1, 0); PG8_STAGE(PG8_SA(0, 1), a2 + hstep, voffA);
;             PG8_WAIT_V(8); PG8_WAIT_L(0); PG8_BAR; PG8_MMA(0, 0, At, B0); PG8_MMA(0, 1, At, B1); PG8_BAR; PG8_SCHED;
;             PG8_LDA(At, 1, 1); PG8_STAGE(PG8_SB(1, 0), b3, voffB); PG8_STAGE(PG8_SB(1, 1), b3 + hstepB, voffB); PG8_STAGE(PG8_SA(1, 0), a3, voffA);
;             PG8_WAIT_V(8); PG8_WAIT_L(0); PG8_BAR; PG8_MMA(1, 0, At, B0); PG8_MMA(1, 1, At, B1); PG8_BAR; PG8_SCHED;
	s_add_i32 s56, 0, 0x18000
	s_add_i32 s57, 0, 0x1c000
	v_add_u32_e32 v142, s56, v1
	v_add_u32_e32 v154, s57, v1
	ds_read_b128 v[130:133], v142
	ds_read_b128 v[134:137], v142 offset:1024
	ds_read_b128 v[138:141], v142 offset:2048
	ds_read_b128 v[142:145], v142 offset:3072
	ds_read_b128 v[166:169], v154
	ds_read_b128 v[170:173], v154 offset:1024
	ds_read_b128 v[174:177], v154 offset:2048
	ds_read_b128 v[178:181], v154 offset:3072
	s_add_u32 s16, s46, 0x160000
	s_addc_u32 s17, s47, 0
	s_mov_b32 m0, s34
	ds_read_b128 v[182:185], v198 offset:32768
	ds_read_b128 v[186:189], v198 offset:33792
	ds_read_b128 v[202:205], v198 offset:34816
	ds_read_b128 v[206:209], v198 offset:35840
	ds_read_b128 v[210:213], v198 offset:36864
	ds_read_b128 v[214:217], v198 offset:37888
	ds_read_b128 v[218:221], v198 offset:38912
	ds_read_b128 v[222:225], v198 offset:39936
	global_load_lds_dwordx4 v146, s[16:17]
	s_mov_b32 m0, s35
	s_nop 0
	global_load_lds_dwordx4 v150, s[16:17]
	s_waitcnt vmcnt(8)
	s_waitcnt lgkmcnt(0)
	s_barrier
	s_waitcnt lgkmcnt(0)
	v_mfma_f32_16x16x32_bf16 v[126:129], v[130:133], v[182:185], v[126:129]
	v_mfma_f32_16x16x32_bf16 v[122:125], v[138:141], v[182:185], v[122:125]
	v_mfma_f32_16x16x32_bf16 v[110:113], v[130:133], v[202:205], v[110:113]
	v_mfma_f32_16x16x32_bf16 v[106:109], v[138:141], v[202:205], v[106:109]
	v_mfma_f32_16x16x32_bf16 v[94:97], v[130:133], v[210:213], v[94:97]
	v_mfma_f32_16x16x32_bf16 v[90:93], v[138:141], v[210:213], v[90:93]
	v_mfma_f32_16x16x32_bf16 v[78:81], v[130:133], v[218:221], v[78:81]
	v_mfma_f32_16x16x32_bf16 v[74:77], v[138:141], v[218:221], v[74:77]
	v_mfma_f32_16x16x32_bf16 v[126:129], v[134:137], v[186:189], v[126:129]
	v_mfma_f32_16x16x32_bf16 v[122:125], v[142:145], v[186:189], v[122:125]
	v_mfma_f32_16x16x32_bf16 v[110:113], v[134:137], v[206:209], v[110:113]
	v_mfma_f32_16x16x32_bf16 v[106:109], v[142:145], v[206:209], v[106:109]
	v_mfma_f32_16x16x32_bf16 v[94:97], v[134:137], v[214:217], v[94:97]
	v_mfma_f32_16x16x32_bf16 v[90:93], v[142:145], v[214:217], v[90:93]
	v_mfma_f32_16x16x32_bf16 v[78:81], v[134:137], v[222:225], v[78:81]
	v_mfma_f32_16x16x32_bf16 v[74:77], v[142:145], v[222:225], v[74:77]
	v_mfma_f32_16x16x32_bf16 v[118:121], v[166:169], v[182:185], v[118:121]
	v_mfma_f32_16x16x32_bf16 v[114:117], v[174:177], v[182:185], v[114:117]
	v_mfma_f32_16x16x32_bf16 v[102:105], v[166:169], v[202:205], v[102:105]
	v_mfma_f32_16x16x32_bf16 v[98:101], v[174:177], v[202:205], v[98:101]
	v_mfma_f32_16x16x32_bf16 v[86:89], v[166:169], v[210:213], v[86:89]
	v_mfma_f32_16x16x32_bf16 v[82:85], v[174:177], v[210:213], v[82:85]
	v_mfma_f32_16x16x32_bf16 v[70:73], v[166:169], v[218:221], v[70:73]
	v_mfma_f32_16x16x32_bf16 v[66:69], v[174:177], v[218:221], v[66:69]
	v_mfma_f32_16x16x32_bf16 v[118:121], v[170:173], v[186:189], v[118:121]
	v_mfma_f32_16x16x32_bf16 v[114:117], v[178:181], v[186:189], v[114:117]
	v_mfma_f32_16x16x32_bf16 v[102:105], v[170:173], v[206:209], v[102:105]
	v_mfma_f32_16x16x32_bf16 v[98:101], v[178:181], v[206:209], v[98:101]
	v_mfma_f32_16x16x32_bf16 v[86:89], v[170:173], v[214:217], v[86:89]
	v_mfma_f32_16x16x32_bf16 v[82:85], v[178:181], v[214:217], v[82:85]
	v_mfma_f32_16x16x32_bf16 v[70:73], v[170:173], v[222:225], v[70:73]
	v_mfma_f32_16x16x32_bf16 v[66:69], v[178:181], v[222:225], v[66:69]
	s_barrier
	s_add_u32 s98, s22, 0x80
	s_addc_u32 s99, s23, 0
	s_add_u32 s100, s46, 0x80
	s_addc_u32 s101, s47, 0
	s_add_i32 s16, s56, s30
	s_mov_b32 m0, s16
	ds_read_b128 v[182:185], v198 offset:49152
	ds_read_b128 v[186:189], v198 offset:50176
	ds_read_b128 v[202:205], v198 offset:51200
	ds_read_b128 v[206:209], v198 offset:52224
	ds_read_b128 v[210:213], v198 offset:53248
	ds_read_b128 v[214:217], v198 offset:54272
	ds_read_b128 v[218:221], v198 offset:55296
	ds_read_b128 v[222:225], v198 offset:56320
	global_load_lds_dwordx4 v148, s[98:99]
	s_add_i32 m0, s16, 0x2000
	s_add_u32 s16, s22, 0x58080
	v_lshl_add_u64 v[190:191], v[226:227], 0, s[12:13]
	s_addc_u32 s17, s23, 0
	s_add_i32 s22, s57, s30
	global_load_lds_dwordx4 v[190:191], off
	s_mov_b32 m0, s22
	s_nop 0
	global_load_lds_dwordx4 v148, s[16:17]
	s_add_i32 m0, s22, 0x2000
	s_nop 0
	global_load_lds_dwordx4 v152, s[16:17]
	s_mov_b32 m0, s49
	s_nop 0
	global_load_lds_dwordx4 v146, s[100:101]
	s_mov_b32 m0, s50
	s_nop 0
	global_load_lds_dwordx4 v150, s[100:101]
	s_waitcnt vmcnt(8)
	s_waitcnt lgkmcnt(0)
	s_barrier
	s_waitcnt lgkmcnt(0)
	v_mfma_f32_16x16x32_bf16 v[62:65], v[130:133], v[182:185], v[62:65]
	v_mfma_f32_16x16x32_bf16 v[58:61], v[138:141], v[182:185], v[58:61]
	v_mfma_f32_16x16x32_bf16 v[46:49], v[130:133], v[202:205], v[46:49]
	v_mfma_f32_16x16x32_bf16 v[42:45], v[138:141], v[202:205], v[42:45]
	v_mfma_f32_16x16x32_bf16 v[30:33], v[130:133], v[210:213], v[30:33]
	v_mfma_f32_16x16x32_bf16 v[26:29], v[138:141], v[210:213], v[26:29]
	v_mfma_f32_16x16x32_bf16 v[14:17], v[130:133], v[218:221], v[14:17]
	v_mfma_f32_16x16x32_bf16 v[10:13], v[138:141], v[218:221], v[10:13]
	v_mfma_f32_16x16x32_bf16 v[62:65], v[134:137], v[186:189], v[62:65]
	v_mfma_f32_16x16x32_bf16 v[58:61], v[142:145], v[186:189], v[58:61]
	v_mfma_f32_16x16x32_bf16 v[46:49], v[134:137], v[206:209], v[46:49]
	v_mfma_f32_16x16x32_bf16 v[42:45], v[142:145], v[206:209], v[42:45]
	v_mfma_f32_16x16x32_bf16 v[30:33], v[134:137], v[214:217], v[30:33]
	v_mfma_f32_16x16x32_bf16 v[26:29], v[142:145], v[214:217], v[26:29]
	v_mfma_f32_16x16x32_bf16 v[14:17], v[134:137], v[222:225], v[14:17]
	v_mfma_f32_16x16x32_bf16 v[10:13], v[142:145], v[222:225], v[10:13]
	v_mfma_f32_16x16x32_bf16 v[54:57], v[166:169], v[182:185], v[54:57]
	v_mfma_f32_16x16x32_bf16 v[50:53], v[174:177], v[182:185], v[50:53]
	v_mfma_f32_16x16x32_bf16 v[38:41], v[166:169], v[202:205], v[38:41]
	v_mfma_f32_16x16x32_bf16 v[34:37], v[174:177], v[202:205], v[34:37]
	v_mfma_f32_16x16x32_bf16 v[22:25], v[166:169], v[210:213], v[22:25]
	v_mfma_f32_16x16x32_bf16 v[18:21], v[174:177], v[210:213], v[18:21]
	v_mfma_f32_16x16x32_bf16 v[6:9], v[166:169], v[218:221], v[6:9]
	v_mfma_f32_16x16x32_bf16 v[2:5], v[174:177], v[218:221], v[2:5]
	v_mfma_f32_16x16x32_bf16 v[54:57], v[170:173], v[186:189], v[54:57]
	v_mfma_f32_16x16x32_bf16 v[50:53], v[178:181], v[186:189], v[50:53]
	v_mfma_f32_16x16x32_bf16 v[38:41], v[170:173], v[206:209], v[38:41]
	v_mfma_f32_16x16x32_bf16 v[34:37], v[178:181], v[206:209], v[34:37]
	v_mfma_f32_16x16x32_bf16 v[22:25], v[170:173], v[214:217], v[22:25]
	v_mfma_f32_16x16x32_bf16 v[18:21], v[178:181], v[214:217], v[18:21]
	v_mfma_f32_16x16x32_bf16 v[6:9], v[170:173], v[222:225], v[6:9]
	v_mfma_f32_16x16x32_bf16 v[2:5], v[178:181], v[222:225], v[2:5]
	s_barrier
	s_add_i32 s25, s25, 2
	s_add_u32 s9, s9, 0x100
	s_addc_u32 s24, s24, 0
	s_cmpk_gt_u32 s25, 0x55
	s_mov_b64 s[16:17], s[20:21]
	s_cbranch_scc0 .LBB0_1595
	s_setprio 0
	s_and_b64 vcc, exec, s[14:15]
	s_cbranch_vccz .LBB0_1598
	s_barrier

; #define PG8_STAGE(bufoff, gbase, voff) do { _Pragma("unroll") for (int _i = 0; _i < 2; ++_i) \
;         __builtin_amdgcn_global_load_lds((const unsigned*)((const char*)(gbase) + (voff)[_i]), (LAS unsigned*)(lds + (bufoff) + ldsw + _i * 8192), 16, 0, 0); } while (0)
; #define PG8_LDA(dst, b, h) do { _Pragma("unroll") for (int m = 0; m < 4; ++m) _Pragma("unroll") for (int k = 0; k < 2; ++k) dst[m][k] = *(const LAS bf16x8*)(lds + PG8_SA(b, h) + aoff + m * 2048 + k * 1024); } while (0)
; #define PG8_LDB(dst, b, h) do { _Pragma("unroll") for (int n = 0; n < 2; ++n) _Pragma("unroll") for (int k = 0; k < 2; ++k) dst[n][k] = *(const LAS bf16x8*)(lds + PG8_SB(b, h) + boff + n * 2048 + k * 1024); } while (0)
; #define PG8_MMA(ai, bj, At, Bt) do { __builtin_amdgcn_s_setprio(1); _Pragma("unroll") for (int m = 0; m < 4; ++m) _Pragma("unroll") for (int n = 0; n < 2; ++n) _Pragma("unroll") for (int k = 0; k < 2; ++k) \
;         acc[ai][bj][m][n] = __builtin_amdgcn_mfma_f32_16x16x32_bf16(Bt[n][k], At[m][k], acc[ai][bj][m][n], 0, 0, 0); __builtin_amdgcn_s_setprio(0); } while (0)
; #define PG8_WAIT_V(n) asm volatile("s_waitcnt vmcnt(" #n ")" ::: "memory")
; #define PG8_WAIT_L(n) asm volatile("s_waitcnt lgkmcnt(" #n ")" ::: "memory")
; template <class Epi, class Sched, bool ALIGN_EPI = false, bool SP2 = false>
; __device__ __forceinline__ void gemm_phase(LAS unsigned char* lds, const Gemm g, const Sched& S, const Epi& E) {
;     ...
;         for (int t = 0; t < nt; t += 2) {
;             const bool last = (t == nt - 2);
;             const char* a1 = cA + (size_t)(t + 1) * kstep;
;             const char* a2 = last ? nA : cA + (size_t)(t + 2) * kstep; const char* b2 = last ? nB : cB + (size_t)(t + 2) * kstep;
;             const char* a3 = a2 + kstep; const char* b3 = b2 + kstep;
;             if (last && has_next) S.a_ready(nxt);
;             if constexpr (SP2) {
;             PG8_LDB(B0, 0, 0); PG8_LDB(B1, 0, 1); PG8_SCHED; PG8_LDA(At, 0, 0); PG8_STAGE(PG8_SA(1, 1), a1 + hstep, voffA);
;             PG8_WAIT_V(8); PG8_WAIT_L(0); PG8_BAR; PG8_MMA(0, 0, At, B0); PG8_MMA(0, 1, At, B1); PG8_BAR; PG8_SCHED;
;             PG8_LDA(At, 0, 1); PG8_STAGE(PG8_SB(0, 0), b2, voffB); PG8_STAGE(PG8_SB(0, 1), b2 + hstepB, voffB); PG8_STAGE(PG8_SA(0, 0), a2, voffA);
;             PG8_WAIT_V(8); PG8_WAIT_L(0); PG8_BAR; PG8_MMA(1, 0, At, B0); PG8_MMA(1, 1, At, B1); PG8_BAR; PG8_SCHED;
.Lprio_1822:
	ds_read_b128 v[66:69], v173
	ds_read_b128 v[70:73], v173 offset:1024
	ds_read_b128 v[74:77], v173 offset:2048
	ds_read_b128 v[78:81], v173 offset:3072
	ds_read_b128 v[162:165], v174
	ds_read_b128 v[180:183], v174 offset:1024
	ds_read_b128 v[184:187], v174 offset:2048
	ds_read_b128 v[188:191], v174 offset:3072
	s_add_u32 s22, s16, 0xfff80080
	s_addc_u32 s23, s17, -1
	s_cmp_eq_u32 s50, 28
	s_cselect_b32 s41, s3, s23
	s_cselect_b32 s40, s15, s22
	s_cselect_b32 s23, s13, s49
	s_cselect_b32 s22, s24, s25
	s_add_i32 m0, s29, 0xc000
	ds_read_b128 v[192:195], v175
	ds_read_b128 v[196:199], v175 offset:1024
	ds_read_b128 v[200:203], v175 offset:2048
	ds_read_b128 v[204:207], v175 offset:3072
	ds_read_b128 v[208:211], v175 offset:4096
	ds_read_b128 v[212:215], v175 offset:5120
	ds_read_b128 v[216:219], v175 offset:6144
	ds_read_b128 v[220:223], v175 offset:7168
	global_load_lds_dwordx4 v156, s[16:17]
	s_add_i32 m0, s29, 0xe000
	s_nop 0
	global_load_lds_dwordx4 v154, s[16:17]
	s_waitcnt lgkmcnt(0)
	s_barrier
	s_waitcnt lgkmcnt(0)
	v_mfma_f32_16x16x32_bf16 v[142:145], v[66:69], v[192:195], 0
	v_mfma_f32_16x16x32_bf16 v[138:141], v[74:77], v[192:195], 0
	v_mfma_f32_16x16x32_bf16 v[126:129], v[66:69], v[200:203], 0
	v_mfma_f32_16x16x32_bf16 v[122:125], v[74:77], v[200:203], 0
	v_mfma_f32_16x16x32_bf16 v[110:113], v[66:69], v[208:211], 0
	v_mfma_f32_16x16x32_bf16 v[106:109], v[74:77], v[208:211], 0
	v_mfma_f32_16x16x32_bf16 v[94:97], v[66:69], v[216:219], 0
	v_mfma_f32_16x16x32_bf16 v[90:93], v[74:77], v[216:219], 0
	v_mfma_f32_16x16x32_bf16 v[142:145], v[70:73], v[196:199], v[142:145]
	v_mfma_f32_16x16x32_bf16 v[138:141], v[78:81], v[196:199], v[138:141]
	v_mfma_f32_16x16x32_bf16 v[126:129], v[70:73], v[204:207], v[126:129]
	v_mfma_f32_16x16x32_bf16 v[122:125], v[78:81], v[204:207], v[122:125]
	v_mfma_f32_16x16x32_bf16 v[110:113], v[70:73], v[212:215], v[110:113]
	v_mfma_f32_16x16x32_bf16 v[106:109], v[78:81], v[212:215], v[106:109]
	v_mfma_f32_16x16x32_bf16 v[94:97], v[70:73], v[220:223], v[94:97]
	v_mfma_f32_16x16x32_bf16 v[90:93], v[78:81], v[220:223], v[90:93]
	v_mfma_f32_16x16x32_bf16 v[134:137], v[162:165], v[192:195], 0
	v_mfma_f32_16x16x32_bf16 v[130:133], v[184:187], v[192:195], 0
	v_mfma_f32_16x16x32_bf16 v[118:121], v[162:165], v[200:203], 0
	v_mfma_f32_16x16x32_bf16 v[114:117], v[184:187], v[200:203], 0
	v_mfma_f32_16x16x32_bf16 v[102:105], v[162:165], v[208:211], 0
	v_mfma_f32_16x16x32_bf16 v[98:101], v[184:187], v[208:211], 0
	v_mfma_f32_16x16x32_bf16 v[86:89], v[162:165], v[216:219], 0
	v_mfma_f32_16x16x32_bf16 v[82:85], v[184:187], v[216:219], 0
	v_mfma_f32_16x16x32_bf16 v[134:137], v[180:183], v[196:199], v[134:137]
	v_mfma_f32_16x16x32_bf16 v[130:133], v[188:191], v[196:199], v[130:133]
	v_mfma_f32_16x16x32_bf16 v[118:121], v[180:183], v[204:207], v[118:121]
	v_mfma_f32_16x16x32_bf16 v[114:117], v[188:191], v[204:207], v[114:117]
	v_mfma_f32_16x16x32_bf16 v[102:105], v[180:183], v[212:215], v[102:105]
	v_mfma_f32_16x16x32_bf16 v[98:101], v[188:191], v[212:215], v[98:101]
	v_mfma_f32_16x16x32_bf16 v[86:89], v[180:183], v[220:223], v[86:89]
	v_mfma_f32_16x16x32_bf16 v[82:85], v[188:191], v[220:223], v[82:85]
	s_barrier
	s_add_i32 s51, s44, s26
	s_mov_b32 m0, s51
	ds_read_b128 v[192:195], v175 offset:16384
	ds_read_b128 v[196:199], v175 offset:17408
	ds_read_b128 v[200:203], v175 offset:18432
	ds_read_b128 v[204:207], v175 offset:19456
	ds_read_b128 v[208:211], v175 offset:20480
	ds_read_b128 v[212:215], v175 offset:21504
	ds_read_b128 v[216:219], v175 offset:22528
	ds_read_b128 v[220:223], v175 offset:23552
	global_load_lds_dwordx4 v150, s[22:23]
	s_add_i32 m0, s51, 0x2000
	s_add_u32 s52, s22, 0x80000
	v_lshl_add_u64 v[224:225], s[22:23], 0, v[146:147]
	s_addc_u32 s53, s23, 0
	s_add_i32 s51, s45, s26
	global_load_lds_dwordx4 v146, s[22:23]
	s_mov_b32 m0, s51
	v_lshl_add_u64 v[228:229], s[40:41], 0, v[148:149]
	global_load_lds_dwordx4 v150, s[52:53]
	s_add_i32 m0, s51, 0x2000
	s_nop 0
	global_load_lds_dwordx4 v146, s[52:53]
	v_lshl_add_u64 v[226:227], s[40:41], 0, v[152:153]
	s_mov_b32 m0, s29
	s_nop 0
	global_load_lds_dwordx4 v152, s[40:41]
	s_mov_b32 m0, s30
	s_nop 0
	global_load_lds_dwordx4 v148, s[40:41]
	s_waitcnt lgkmcnt(0)
	s_barrier
	s_waitcnt lgkmcnt(0)
	v_mfma_f32_16x16x32_bf16 v[62:65], v[66:69], v[192:195], 0
	v_mfma_f32_16x16x32_bf16 v[58:61], v[74:77], v[192:195], 0
	v_mfma_f32_16x16x32_bf16 v[46:49], v[66:69], v[200:203], 0
	v_mfma_f32_16x16x32_bf16 v[42:45], v[74:77], v[200:203], 0
	v_mfma_f32_16x16x32_bf16 v[30:33], v[66:69], v[208:211], 0
	v_mfma_f32_16x16x32_bf16 v[26:29], v[74:77], v[208:211], 0
	v_mfma_f32_16x16x32_bf16 v[14:17], v[66:69], v[216:219], 0
	v_mfma_f32_16x16x32_bf16 v[10:13], v[74:77], v[216:219], 0
	v_mfma_f32_16x16x32_bf16 v[62:65], v[70:73], v[196:199], v[62:65]
	v_mfma_f32_16x16x32_bf16 v[58:61], v[78:81], v[196:199], v[58:61]
	v_mfma_f32_16x16x32_bf16 v[46:49], v[70:73], v[204:207], v[46:49]
	v_mfma_f32_16x16x32_bf16 v[42:45], v[78:81], v[204:207], v[42:45]
	v_mfma_f32_16x16x32_bf16 v[30:33], v[70:73], v[212:215], v[30:33]
	v_mfma_f32_16x16x32_bf16 v[26:29], v[78:81], v[212:215], v[26:29]
	v_mfma_f32_16x16x32_bf16 v[14:17], v[70:73], v[220:223], v[14:17]
	v_mfma_f32_16x16x32_bf16 v[10:13], v[78:81], v[220:223], v[10:13]
	v_mfma_f32_16x16x32_bf16 v[54:57], v[162:165], v[192:195], 0
	v_mfma_f32_16x16x32_bf16 v[50:53], v[184:187], v[192:195], 0
	v_mfma_f32_16x16x32_bf16 v[38:41], v[162:165], v[200:203], 0
	v_mfma_f32_16x16x32_bf16 v[34:37], v[184:187], v[200:203], 0
	v_mfma_f32_16x16x32_bf16 v[22:25], v[162:165], v[208:211], 0
	v_mfma_f32_16x16x32_bf16 v[18:21], v[184:187], v[208:211], 0
	v_mfma_f32_16x16x32_bf16 v[6:9], v[162:165], v[216:219], 0
	v_mfma_f32_16x16x32_bf16 v[2:5], v[184:187], v[216:219], 0
	v_mfma_f32_16x16x32_bf16 v[54:57], v[180:183], v[196:199], v[54:57]
	v_mfma_f32_16x16x32_bf16 v[50:53], v[188:191], v[196:199], v[50:53]
	v_mfma_f32_16x16x32_bf16 v[38:41], v[180:183], v[204:207], v[38:41]
	v_mfma_f32_16x16x32_bf16 v[34:37], v[188:191], v[204:207], v[34:37]
	v_mfma_f32_16x16x32_bf16 v[22:25], v[180:183], v[212:215], v[22:25]
	v_mfma_f32_16x16x32_bf16 v[18:21], v[188:191], v[212:215], v[18:21]
	v_mfma_f32_16x16x32_bf16 v[6:9], v[180:183], v[220:223], v[6:9]
	v_mfma_f32_16x16x32_bf16 v[2:5], v[188:191], v[220:223], v[2:5]
	s_barrier
; #define PG8_STAGE(bufoff, gbase, voff) do { _Pragma("unroll") for (int _i = 0; _i < 2; ++_i) \
;         __builtin_amdgcn_global_load_lds((const unsigned*)((const char*)(gbase) + (voff)[_i]), (LAS unsigned*)(lds + (bufoff) + ldsw + _i * 8192), 16, 0, 0); } while (0)
; #define PG8_LDA(dst, b, h) do { _Pragma("unroll") for (int m = 0; m < 4; ++m) _Pragma("unroll") for (int k = 0; k < 2; ++k) dst[m][k] = *(const LAS bf16x8*)(lds + PG8_SA(b, h) + aoff + m * 2048 + k * 1024); } while (0)
; #define PG8_LDB(dst, b, h) do { _Pragma("unroll") for (int n = 0; n < 2; ++n) _Pragma("unroll") for (int k = 0; k < 2; ++k) dst[n][k] = *(const LAS bf16x8*)(lds + PG8_SB(b, h) + boff + n * 2048 + k * 1024); } while (0)
; #define PG8_MMA(ai, bj, At, Bt) do { __builtin_amdgcn_s_setprio(1); _Pragma("unroll") for (int m = 0; m < 4; ++m) _Pragma("unroll") for (int n = 0; n < 2; ++n) _Pragma("unroll") for (int k = 0; k < 2; ++k) \
;         acc[ai][bj][m][n] = __builtin_amdgcn_mfma_f32_16x16x32_bf16(Bt[n][k], At[m][k], acc[ai][bj][m][n], 0, 0, 0); __builtin_amdgcn_s_setprio(0); } while (0)
; #define PG8_WAIT_V(n) asm volatile("s_waitcnt vmcnt(" #n ")" ::: "memory")
; #define PG8_WAIT_L(n) asm volatile("s_waitcnt lgkmcnt(" #n ")" ::: "memory")
; #define PG8_BAR __builtin_amdgcn_s_barrier()
; #define PG8_SCHED __builtin_amdgcn_sched_barrier(0)
; template <class Epi, class Sched, bool ALIGN_EPI = false, bool SP2 = false>
; __device__ __forceinline__ void gemm_phase(LAS unsigned char* lds, const Gemm g, const Sched& S, const Epi& E) {
;     ...
;             PG8_LDB(B0, 1, 0); PG8_LDB(B1, 1, 1); PG8_SCHED; PG8_LDA(At, 1, 0); PG8_STAGE(PG8_SA(0, 1), a2 + hstep, voffA);
;             PG8_WAIT_V(8); PG8_WAIT_L(0); PG8_BAR; PG8_MMA(0, 0, At, B0); PG8_MMA(0, 1, At, B1); PG8_BAR; PG8_SCHED;
;             PG8_LDA(At, 1, 1); PG8_STAGE(PG8_SB(1, 0), b3, voffB); PG8_STAGE(PG8_SB(1, 1), b3 + hstepB, voffB); PG8_STAGE(PG8_SA(1, 0), a3, voffA);
;             PG8_WAIT_V(8); PG8_WAIT_L(0); PG8_BAR; PG8_MMA(1, 0, At, B0); PG8_MMA(1, 1, At, B1); PG8_BAR; PG8_SCHED;
	s_add_i32 s51, 0, 0x18000
	s_add_i32 s52, 0, 0x1c000
	v_add_u32_e32 v78, s51, v169
	v_add_u32_e32 v168, s52, v169
	ds_read_b128 v[66:69], v78
	ds_read_b128 v[70:73], v78 offset:1024
	ds_read_b128 v[74:77], v78 offset:2048
	ds_read_b128 v[78:81], v78 offset:3072
	ds_read_b128 v[162:165], v168
	ds_read_b128 v[180:183], v168 offset:1024
	ds_read_b128 v[184:187], v168 offset:2048
	ds_read_b128 v[188:191], v168 offset:3072
	s_add_u32 s40, s40, 0x80000
	s_addc_u32 s41, s41, 0
	s_mov_b32 m0, s31
	ds_read_b128 v[192:195], v175 offset:32768
	ds_read_b128 v[196:199], v175 offset:33792
	ds_read_b128 v[200:203], v175 offset:34816
	ds_read_b128 v[204:207], v175 offset:35840
	ds_read_b128 v[208:211], v175 offset:36864
	ds_read_b128 v[212:215], v175 offset:37888
	ds_read_b128 v[216:219], v175 offset:38912
	ds_read_b128 v[220:223], v175 offset:39936
	global_load_lds_dwordx4 v152, s[40:41]
	s_mov_b32 m0, s33
	s_nop 0
	global_load_lds_dwordx4 v148, s[40:41]
	s_waitcnt vmcnt(8)
	s_waitcnt lgkmcnt(0)
	s_barrier
	s_waitcnt lgkmcnt(0)
	v_mfma_f32_16x16x32_bf16 v[142:145], v[66:69], v[192:195], v[142:145]
	v_mfma_f32_16x16x32_bf16 v[138:141], v[74:77], v[192:195], v[138:141]
	v_mfma_f32_16x16x32_bf16 v[126:129], v[66:69], v[200:203], v[126:129]
	v_mfma_f32_16x16x32_bf16 v[122:125], v[74:77], v[200:203], v[122:125]
	v_mfma_f32_16x16x32_bf16 v[110:113], v[66:69], v[208:211], v[110:113]
	v_mfma_f32_16x16x32_bf16 v[106:109], v[74:77], v[208:211], v[106:109]
	v_mfma_f32_16x16x32_bf16 v[94:97], v[66:69], v[216:219], v[94:97]
	v_mfma_f32_16x16x32_bf16 v[90:93], v[74:77], v[216:219], v[90:93]
	v_mfma_f32_16x16x32_bf16 v[142:145], v[70:73], v[196:199], v[142:145]
	v_mfma_f32_16x16x32_bf16 v[138:141], v[78:81], v[196:199], v[138:141]
	v_mfma_f32_16x16x32_bf16 v[126:129], v[70:73], v[204:207], v[126:129]
	v_mfma_f32_16x16x32_bf16 v[122:125], v[78:81], v[204:207], v[122:125]
	v_mfma_f32_16x16x32_bf16 v[110:113], v[70:73], v[212:215], v[110:113]
	v_mfma_f32_16x16x32_bf16 v[106:109], v[78:81], v[212:215], v[106:109]
	v_mfma_f32_16x16x32_bf16 v[94:97], v[70:73], v[220:223], v[94:97]
	v_mfma_f32_16x16x32_bf16 v[90:93], v[78:81], v[220:223], v[90:93]
	v_mfma_f32_16x16x32_bf16 v[134:137], v[162:165], v[192:195], v[134:137]
	v_mfma_f32_16x16x32_bf16 v[130:133], v[184:187], v[192:195], v[130:133]
	v_mfma_f32_16x16x32_bf16 v[118:121], v[162:165], v[200:203], v[118:121]
	v_mfma_f32_16x16x32_bf16 v[114:117], v[184:187], v[200:203], v[114:117]
	v_mfma_f32_16x16x32_bf16 v[102:105], v[162:165], v[208:211], v[102:105]
	v_mfma_f32_16x16x32_bf16 v[98:101], v[184:187], v[208:211], v[98:101]
	v_mfma_f32_16x16x32_bf16 v[86:89], v[162:165], v[216:219], v[86:89]
	v_mfma_f32_16x16x32_bf16 v[82:85], v[184:187], v[216:219], v[82:85]
	v_mfma_f32_16x16x32_bf16 v[134:137], v[180:183], v[196:199], v[134:137]
	v_mfma_f32_16x16x32_bf16 v[130:133], v[188:191], v[196:199], v[130:133]
	v_mfma_f32_16x16x32_bf16 v[118:121], v[180:183], v[204:207], v[118:121]
	v_mfma_f32_16x16x32_bf16 v[114:117], v[188:191], v[204:207], v[114:117]
	v_mfma_f32_16x16x32_bf16 v[102:105], v[180:183], v[212:215], v[102:105]
	v_mfma_f32_16x16x32_bf16 v[98:101], v[188:191], v[212:215], v[98:101]
	v_mfma_f32_16x16x32_bf16 v[86:89], v[180:183], v[220:223], v[86:89]
	v_mfma_f32_16x16x32_bf16 v[82:85], v[188:191], v[220:223], v[82:85]
	s_barrier
	s_add_u32 s98, s22, 0x80
	s_addc_u32 s99, s23, 0
	s_add_i32 s40, s51, s26
	s_mov_b32 m0, s40
	ds_read_b128 v[192:195], v175 offset:49152
	ds_read_b128 v[196:199], v175 offset:50176
	ds_read_b128 v[200:203], v175 offset:51200
	ds_read_b128 v[204:207], v175 offset:52224
	ds_read_b128 v[208:211], v175 offset:53248
	ds_read_b128 v[212:215], v175 offset:54272
	ds_read_b128 v[216:219], v175 offset:55296
	ds_read_b128 v[220:223], v175 offset:56320
	global_load_lds_dwordx4 v150, s[98:99]
	s_add_i32 m0, s40, 0x2000
	s_add_u32 s22, s22, 0x80080
	v_lshl_add_u64 v[166:167], v[224:225], 0, s[8:9]
	s_addc_u32 s23, s23, 0
	s_add_i32 s40, s52, s26
	global_load_lds_dwordx4 v[166:167], off
	s_mov_b32 m0, s40
	s_nop 0
	global_load_lds_dwordx4 v150, s[22:23]
	s_add_i32 m0, s40, 0x2000
	s_nop 0
	global_load_lds_dwordx4 v146, s[22:23]
	v_lshl_add_u64 v[166:167], v[226:227], 0, s[8:9]
	s_mov_b32 m0, s42
	s_nop 0
	global_load_lds_dwordx4 v[166:167], off
	v_lshl_add_u64 v[166:167], v[228:229], 0, s[8:9]
	s_mov_b32 m0, s43
	s_nop 0
	global_load_lds_dwordx4 v[166:167], off
	s_waitcnt vmcnt(8)
	s_waitcnt lgkmcnt(0)
	s_barrier
	s_waitcnt lgkmcnt(0)
	v_mfma_f32_16x16x32_bf16 v[62:65], v[66:69], v[192:195], v[62:65]
	v_mfma_f32_16x16x32_bf16 v[58:61], v[74:77], v[192:195], v[58:61]
	v_mfma_f32_16x16x32_bf16 v[46:49], v[66:69], v[200:203], v[46:49]
	v_mfma_f32_16x16x32_bf16 v[42:45], v[74:77], v[200:203], v[42:45]
	v_mfma_f32_16x16x32_bf16 v[30:33], v[66:69], v[208:211], v[30:33]
	v_mfma_f32_16x16x32_bf16 v[26:29], v[74:77], v[208:211], v[26:29]
	v_mfma_f32_16x16x32_bf16 v[14:17], v[66:69], v[216:219], v[14:17]
	v_mfma_f32_16x16x32_bf16 v[10:13], v[74:77], v[216:219], v[10:13]
	v_mfma_f32_16x16x32_bf16 v[62:65], v[70:73], v[196:199], v[62:65]
	v_mfma_f32_16x16x32_bf16 v[58:61], v[78:81], v[196:199], v[58:61]
	v_mfma_f32_16x16x32_bf16 v[46:49], v[70:73], v[204:207], v[46:49]
	v_mfma_f32_16x16x32_bf16 v[42:45], v[78:81], v[204:207], v[42:45]
	v_mfma_f32_16x16x32_bf16 v[30:33], v[70:73], v[212:215], v[30:33]
	v_mfma_f32_16x16x32_bf16 v[26:29], v[78:81], v[212:215], v[26:29]
	v_mfma_f32_16x16x32_bf16 v[14:17], v[70:73], v[220:223], v[14:17]
	v_mfma_f32_16x16x32_bf16 v[10:13], v[78:81], v[220:223], v[10:13]
	v_mfma_f32_16x16x32_bf16 v[54:57], v[162:165], v[192:195], v[54:57]
	v_mfma_f32_16x16x32_bf16 v[50:53], v[184:187], v[192:195], v[50:53]
	v_mfma_f32_16x16x32_bf16 v[38:41], v[162:165], v[200:203], v[38:41]
	v_mfma_f32_16x16x32_bf16 v[34:37], v[184:187], v[200:203], v[34:37]
	v_mfma_f32_16x16x32_bf16 v[22:25], v[162:165], v[208:211], v[22:25]
	v_mfma_f32_16x16x32_bf16 v[18:21], v[184:187], v[208:211], v[18:21]
	v_mfma_f32_16x16x32_bf16 v[6:9], v[162:165], v[216:219], v[6:9]
	v_mfma_f32_16x16x32_bf16 v[2:5], v[184:187], v[216:219], v[2:5]
	v_mfma_f32_16x16x32_bf16 v[54:57], v[180:183], v[196:199], v[54:57]
	v_mfma_f32_16x16x32_bf16 v[50:53], v[188:191], v[196:199], v[50:53]
	v_mfma_f32_16x16x32_bf16 v[38:41], v[180:183], v[204:207], v[38:41]
	v_mfma_f32_16x16x32_bf16 v[34:37], v[188:191], v[204:207], v[34:37]
	v_mfma_f32_16x16x32_bf16 v[22:25], v[180:183], v[212:215], v[22:25]
	v_mfma_f32_16x16x32_bf16 v[18:21], v[188:191], v[212:215], v[18:21]
	v_mfma_f32_16x16x32_bf16 v[6:9], v[180:183], v[220:223], v[6:9]
	v_mfma_f32_16x16x32_bf16 v[2:5], v[188:191], v[220:223], v[2:5]
	s_barrier
	s_add_i32 s50, s50, 2
	s_add_u32 s25, s25, 0x100
	s_addc_u32 s49, s49, 0
	s_add_u32 s16, s16, 0x100
	s_addc_u32 s17, s17, 0
	s_cmp_lt_u32 s50, 30
; #define PG8_STAGE(bufoff, gbase, voff) do { _Pragma("unroll") for (int _i = 0; _i < 2; ++_i) \
;         __builtin_amdgcn_global_load_lds((const unsigned*)((const char*)(gbase) + (voff)[_i]), (LAS unsigned*)(lds + (bufoff) + ldsw + _i * 8192), 16, 0, 0); } while (0)
; #define PG8_LDA(dst, b, h) do { _Pragma("unroll") for (int m = 0; m < 4; ++m) _Pragma("unroll") for (int k = 0; k < 2; ++k) dst[m][k] = *(const LAS bf16x8*)(lds + PG8_SA(b, h) + aoff + m * 2048 + k * 1024); } while (0)
; #define PG8_LDB(dst, b, h) do { _Pragma("unroll") for (int n = 0; n < 2; ++n) _Pragma("unroll") for (int k = 0; k < 2; ++k) dst[n][k] = *(const LAS bf16x8*)(lds + PG8_SB(b, h) + boff + n * 2048 + k * 1024); } while (0)
; #define PG8_MMA(ai, bj, At, Bt) do { __builtin_amdgcn_s_setprio(1); _Pragma("unroll") for (int m = 0; m < 4; ++m) _Pragma("unroll") for (int n = 0; n < 2; ++n) _Pragma("unroll") for (int k = 0; k < 2; ++k) \
;         acc[ai][bj][m][n] = __builtin_amdgcn_mfma_f32_16x16x32_bf16(Bt[n][k], At[m][k], acc[ai][bj][m][n], 0, 0, 0); __builtin_amdgcn_s_setprio(0); } while (0)
; #define PG8_WAIT_V(n) asm volatile("s_waitcnt vmcnt(" #n ")" ::: "memory")
; #define PG8_WAIT_L(n) asm volatile("s_waitcnt lgkmcnt(" #n ")" ::: "memory")
; template <class Epi, class Sched, bool ALIGN_EPI = false, bool SP2 = false>
; __device__ __forceinline__ void gemm_phase(LAS unsigned char* lds, const Gemm g, const Sched& S, const Epi& E) {
;     ...
;         for (int t = 0; t < nt; t += 2) {
;             const bool last = (t == nt - 2);
;             const char* a1 = cA + (size_t)(t + 1) * kstep;
;             const char* a2 = last ? nA : cA + (size_t)(t + 2) * kstep; const char* b2 = last ? nB : cB + (size_t)(t + 2) * kstep;
;             const char* a3 = a2 + kstep; const char* b3 = b2 + kstep;
;             if (last && has_next) S.a_ready(nxt);
;             if constexpr (SP2) {
;             PG8_LDB(B0, 0, 0); PG8_LDB(B1, 0, 1); PG8_SCHED; PG8_LDA(At, 0, 0); PG8_STAGE(PG8_SA(1, 1), a1 + hstep, voffA);
;             PG8_WAIT_V(8); PG8_WAIT_L(0); PG8_BAR; PG8_MMA(0, 0, At, B0); PG8_MMA(0, 1, At, B1); PG8_BAR; PG8_SCHED;
;             PG8_LDA(At, 0, 1); PG8_STAGE(PG8_SB(0, 0), b2, voffB); PG8_STAGE(PG8_SB(0, 1), b2 + hstepB, voffB); PG8_STAGE(PG8_SA(0, 0), a2, voffA);
;             PG8_WAIT_V(8); PG8_WAIT_L(0); PG8_BAR; PG8_MMA(1, 0, At, B0); PG8_MMA(1, 1, At, B1); PG8_BAR; PG8_SCHED;
.LBB0_1822:
	ds_read_b128 v[66:69], v173
	ds_read_b128 v[70:73], v173 offset:1024
	ds_read_b128 v[74:77], v173 offset:2048
	ds_read_b128 v[78:81], v173 offset:3072
	ds_read_b128 v[162:165], v174
	ds_read_b128 v[180:183], v174 offset:1024
	ds_read_b128 v[184:187], v174 offset:2048
	ds_read_b128 v[188:191], v174 offset:3072
	s_add_u32 s22, s16, 0xfff80080
	s_addc_u32 s23, s17, -1
	s_cmp_eq_u32 s50, 28
	s_cselect_b32 s41, s3, s23
	s_cselect_b32 s40, s15, s22
	s_cselect_b32 s23, s13, s49
	s_cselect_b32 s22, s24, s25
	s_add_i32 m0, s29, 0xc000
	ds_read_b128 v[192:195], v175
	ds_read_b128 v[196:199], v175 offset:1024
	ds_read_b128 v[200:203], v175 offset:2048
	ds_read_b128 v[204:207], v175 offset:3072
	ds_read_b128 v[208:211], v175 offset:4096
	ds_read_b128 v[212:215], v175 offset:5120
	ds_read_b128 v[216:219], v175 offset:6144
	ds_read_b128 v[220:223], v175 offset:7168
	global_load_lds_dwordx4 v156, s[16:17]
	s_add_i32 m0, s29, 0xe000
	s_nop 0
	global_load_lds_dwordx4 v154, s[16:17]
	s_waitcnt vmcnt(8)
	s_waitcnt lgkmcnt(0)
	s_barrier
	s_waitcnt lgkmcnt(0)
	v_mfma_f32_16x16x32_bf16 v[142:145], v[66:69], v[192:195], v[142:145]
	v_mfma_f32_16x16x32_bf16 v[138:141], v[74:77], v[192:195], v[138:141]
	v_mfma_f32_16x16x32_bf16 v[126:129], v[66:69], v[200:203], v[126:129]
	v_mfma_f32_16x16x32_bf16 v[122:125], v[74:77], v[200:203], v[122:125]
	v_mfma_f32_16x16x32_bf16 v[110:113], v[66:69], v[208:211], v[110:113]
	v_mfma_f32_16x16x32_bf16 v[106:109], v[74:77], v[208:211], v[106:109]
	v_mfma_f32_16x16x32_bf16 v[94:97], v[66:69], v[216:219], v[94:97]
	v_mfma_f32_16x16x32_bf16 v[90:93], v[74:77], v[216:219], v[90:93]
	v_mfma_f32_16x16x32_bf16 v[142:145], v[70:73], v[196:199], v[142:145]
	v_mfma_f32_16x16x32_bf16 v[138:141], v[78:81], v[196:199], v[138:141]
	v_mfma_f32_16x16x32_bf16 v[126:129], v[70:73], v[204:207], v[126:129]
	v_mfma_f32_16x16x32_bf16 v[122:125], v[78:81], v[204:207], v[122:125]
	v_mfma_f32_16x16x32_bf16 v[110:113], v[70:73], v[212:215], v[110:113]
	v_mfma_f32_16x16x32_bf16 v[106:109], v[78:81], v[212:215], v[106:109]
	v_mfma_f32_16x16x32_bf16 v[94:97], v[70:73], v[220:223], v[94:97]
	v_mfma_f32_16x16x32_bf16 v[90:93], v[78:81], v[220:223], v[90:93]
	v_mfma_f32_16x16x32_bf16 v[134:137], v[162:165], v[192:195], v[134:137]
	v_mfma_f32_16x16x32_bf16 v[130:133], v[184:187], v[192:195], v[130:133]
	v_mfma_f32_16x16x32_bf16 v[118:121], v[162:165], v[200:203], v[118:121]
	v_mfma_f32_16x16x32_bf16 v[114:117], v[184:187], v[200:203], v[114:117]
	v_mfma_f32_16x16x32_bf16 v[102:105], v[162:165], v[208:211], v[102:105]
	v_mfma_f32_16x16x32_bf16 v[98:101], v[184:187], v[208:211], v[98:101]
	v_mfma_f32_16x16x32_bf16 v[86:89], v[162:165], v[216:219], v[86:89]
	v_mfma_f32_16x16x32_bf16 v[82:85], v[184:187], v[216:219], v[82:85]
	v_mfma_f32_16x16x32_bf16 v[134:137], v[180:183], v[196:199], v[134:137]
	v_mfma_f32_16x16x32_bf16 v[130:133], v[188:191], v[196:199], v[130:133]
	v_mfma_f32_16x16x32_bf16 v[118:121], v[180:183], v[204:207], v[118:121]
	v_mfma_f32_16x16x32_bf16 v[114:117], v[188:191], v[204:207], v[114:117]
	v_mfma_f32_16x16x32_bf16 v[102:105], v[180:183], v[212:215], v[102:105]
	v_mfma_f32_16x16x32_bf16 v[98:101], v[188:191], v[212:215], v[98:101]
	v_mfma_f32_16x16x32_bf16 v[86:89], v[180:183], v[220:223], v[86:89]
	v_mfma_f32_16x16x32_bf16 v[82:85], v[188:191], v[220:223], v[82:85]
	s_barrier
	s_add_i32 s51, s44, s26
	s_mov_b32 m0, s51
	ds_read_b128 v[192:195], v175 offset:16384
	ds_read_b128 v[196:199], v175 offset:17408
	ds_read_b128 v[200:203], v175 offset:18432
	ds_read_b128 v[204:207], v175 offset:19456
	ds_read_b128 v[208:211], v175 offset:20480
	ds_read_b128 v[212:215], v175 offset:21504
	ds_read_b128 v[216:219], v175 offset:22528
	ds_read_b128 v[220:223], v175 offset:23552
	global_load_lds_dwordx4 v150, s[22:23]
	s_add_i32 m0, s51, 0x2000
	s_add_u32 s52, s22, 0x80000
	v_lshl_add_u64 v[224:225], s[22:23], 0, v[146:147]
	s_addc_u32 s53, s23, 0
	s_add_i32 s51, s45, s26
	global_load_lds_dwordx4 v146, s[22:23]
	s_mov_b32 m0, s51
	v_lshl_add_u64 v[228:229], s[40:41], 0, v[148:149]
	global_load_lds_dwordx4 v150, s[52:53]
	s_add_i32 m0, s51, 0x2000
	s_nop 0
	global_load_lds_dwordx4 v146, s[52:53]
	v_lshl_add_u64 v[226:227], s[40:41], 0, v[152:153]
	s_mov_b32 m0, s29
	s_nop 0
	global_load_lds_dwordx4 v152, s[40:41]
	s_mov_b32 m0, s30
	s_nop 0
	global_load_lds_dwordx4 v148, s[40:41]
	s_waitcnt vmcnt(8)
	s_waitcnt lgkmcnt(0)
	s_barrier
	s_waitcnt lgkmcnt(0)
	v_mfma_f32_16x16x32_bf16 v[62:65], v[66:69], v[192:195], v[62:65]
	v_mfma_f32_16x16x32_bf16 v[58:61], v[74:77], v[192:195], v[58:61]
	v_mfma_f32_16x16x32_bf16 v[46:49], v[66:69], v[200:203], v[46:49]
	v_mfma_f32_16x16x32_bf16 v[42:45], v[74:77], v[200:203], v[42:45]
	v_mfma_f32_16x16x32_bf16 v[30:33], v[66:69], v[208:211], v[30:33]
	v_mfma_f32_16x16x32_bf16 v[26:29], v[74:77], v[208:211], v[26:29]
	v_mfma_f32_16x16x32_bf16 v[14:17], v[66:69], v[216:219], v[14:17]
	v_mfma_f32_16x16x32_bf16 v[10:13], v[74:77], v[216:219], v[10:13]
	v_mfma_f32_16x16x32_bf16 v[62:65], v[70:73], v[196:199], v[62:65]
	v_mfma_f32_16x16x32_bf16 v[58:61], v[78:81], v[196:199], v[58:61]
	v_mfma_f32_16x16x32_bf16 v[46:49], v[70:73], v[204:207], v[46:49]
	v_mfma_f32_16x16x32_bf16 v[42:45], v[78:81], v[204:207], v[42:45]
	v_mfma_f32_16x16x32_bf16 v[30:33], v[70:73], v[212:215], v[30:33]
	v_mfma_f32_16x16x32_bf16 v[26:29], v[78:81], v[212:215], v[26:29]
	v_mfma_f32_16x16x32_bf16 v[14:17], v[70:73], v[220:223], v[14:17]
	v_mfma_f32_16x16x32_bf16 v[10:13], v[78:81], v[220:223], v[10:13]
	v_mfma_f32_16x16x32_bf16 v[54:57], v[162:165], v[192:195], v[54:57]
	v_mfma_f32_16x16x32_bf16 v[50:53], v[184:187], v[192:195], v[50:53]
	v_mfma_f32_16x16x32_bf16 v[38:41], v[162:165], v[200:203], v[38:41]
	v_mfma_f32_16x16x32_bf16 v[34:37], v[184:187], v[200:203], v[34:37]
	v_mfma_f32_16x16x32_bf16 v[22:25], v[162:165], v[208:211], v[22:25]
	v_mfma_f32_16x16x32_bf16 v[18:21], v[184:187], v[208:211], v[18:21]
	v_mfma_f32_16x16x32_bf16 v[6:9], v[162:165], v[216:219], v[6:9]
	v_mfma_f32_16x16x32_bf16 v[2:5], v[184:187], v[216:219], v[2:5]
	v_mfma_f32_16x16x32_bf16 v[54:57], v[180:183], v[196:199], v[54:57]
	v_mfma_f32_16x16x32_bf16 v[50:53], v[188:191], v[196:199], v[50:53]
	v_mfma_f32_16x16x32_bf16 v[38:41], v[180:183], v[204:207], v[38:41]
	v_mfma_f32_16x16x32_bf16 v[34:37], v[188:191], v[204:207], v[34:37]
	v_mfma_f32_16x16x32_bf16 v[22:25], v[180:183], v[212:215], v[22:25]
	v_mfma_f32_16x16x32_bf16 v[18:21], v[188:191], v[212:215], v[18:21]
	v_mfma_f32_16x16x32_bf16 v[6:9], v[180:183], v[220:223], v[6:9]
	v_mfma_f32_16x16x32_bf16 v[2:5], v[188:191], v[220:223], v[2:5]
	s_barrier
; #define PG8_STAGE(bufoff, gbase, voff) do { _Pragma("unroll") for (int _i = 0; _i < 2; ++_i) \
;         __builtin_amdgcn_global_load_lds((const unsigned*)((const char*)(gbase) + (voff)[_i]), (LAS unsigned*)(lds + (bufoff) + ldsw + _i * 8192), 16, 0, 0); } while (0)
; #define PG8_LDA(dst, b, h) do { _Pragma("unroll") for (int m = 0; m < 4; ++m) _Pragma("unroll") for (int k = 0; k < 2; ++k) dst[m][k] = *(const LAS bf16x8*)(lds + PG8_SA(b, h) + aoff + m * 2048 + k * 1024); } while (0)
; #define PG8_LDB(dst, b, h) do { _Pragma("unroll") for (int n = 0; n < 2; ++n) _Pragma("unroll") for (int k = 0; k < 2; ++k) dst[n][k] = *(const LAS bf16x8*)(lds + PG8_SB(b, h) + boff + n * 2048 + k * 1024); } while (0)
; #define PG8_MMA(ai, bj, At, Bt) do { __builtin_amdgcn_s_setprio(1); _Pragma("unroll") for (int m = 0; m < 4; ++m) _Pragma("unroll") for (int n = 0; n < 2; ++n) _Pragma("unroll") for (int k = 0; k < 2; ++k) \
;         acc[ai][bj][m][n] = __builtin_amdgcn_mfma_f32_16x16x32_bf16(Bt[n][k], At[m][k], acc[ai][bj][m][n], 0, 0, 0); __builtin_amdgcn_s_setprio(0); } while (0)
; #define PG8_WAIT_V(n) asm volatile("s_waitcnt vmcnt(" #n ")" ::: "memory")
; #define PG8_WAIT_L(n) asm volatile("s_waitcnt lgkmcnt(" #n ")" ::: "memory")
; #define PG8_BAR __builtin_amdgcn_s_barrier()
; #define PG8_SCHED __builtin_amdgcn_sched_barrier(0)
; template <class Epi, class Sched, bool ALIGN_EPI = false, bool SP2 = false>
; __device__ __forceinline__ void gemm_phase(LAS unsigned char* lds, const Gemm g, const Sched& S, const Epi& E) {
;     ...
;         for (int t = 0; t < nt; t += 2) {
;     ...
;             PG8_LDB(B0, 1, 0); PG8_LDB(B1, 1, 1); PG8_SCHED; PG8_LDA(At, 1, 0); PG8_STAGE(PG8_SA(0, 1), a2 + hstep, voffA);
;             PG8_WAIT_V(8); PG8_WAIT_L(0); PG8_BAR; PG8_MMA(0, 0, At, B0); PG8_MMA(0, 1, At, B1); PG8_BAR; PG8_SCHED;
;             PG8_LDA(At, 1, 1); PG8_STAGE(PG8_SB(1, 0), b3, voffB); PG8_STAGE(PG8_SB(1, 1), b3 + hstepB, voffB); PG8_STAGE(PG8_SA(1, 0), a3, voffA);
;             PG8_WAIT_V(8); PG8_WAIT_L(0); PG8_BAR; PG8_MMA(1, 0, At, B0); PG8_MMA(1, 1, At, B1); PG8_BAR; PG8_SCHED;
	s_add_i32 s51, 0, 0x18000
	s_add_i32 s52, 0, 0x1c000
	v_add_u32_e32 v78, s51, v169
	v_add_u32_e32 v168, s52, v169
	ds_read_b128 v[66:69], v78
	ds_read_b128 v[70:73], v78 offset:1024
	ds_read_b128 v[74:77], v78 offset:2048
	ds_read_b128 v[78:81], v78 offset:3072
	ds_read_b128 v[162:165], v168
	ds_read_b128 v[180:183], v168 offset:1024
	ds_read_b128 v[184:187], v168 offset:2048
	ds_read_b128 v[188:191], v168 offset:3072
	s_add_u32 s40, s40, 0x80000
	s_addc_u32 s41, s41, 0
	s_mov_b32 m0, s31
	ds_read_b128 v[192:195], v175 offset:32768
	ds_read_b128 v[196:199], v175 offset:33792
	ds_read_b128 v[200:203], v175 offset:34816
	ds_read_b128 v[204:207], v175 offset:35840
	ds_read_b128 v[208:211], v175 offset:36864
	ds_read_b128 v[212:215], v175 offset:37888
	ds_read_b128 v[216:219], v175 offset:38912
	ds_read_b128 v[220:223], v175 offset:39936
	global_load_lds_dwordx4 v152, s[40:41]
	s_mov_b32 m0, s33
	s_nop 0
	global_load_lds_dwordx4 v148, s[40:41]
	s_waitcnt vmcnt(8)
	s_waitcnt lgkmcnt(0)
	s_barrier
	s_waitcnt lgkmcnt(0)
	v_mfma_f32_16x16x32_bf16 v[142:145], v[66:69], v[192:195], v[142:145]
	v_mfma_f32_16x16x32_bf16 v[138:141], v[74:77], v[192:195], v[138:141]
	v_mfma_f32_16x16x32_bf16 v[126:129], v[66:69], v[200:203], v[126:129]
	v_mfma_f32_16x16x32_bf16 v[122:125], v[74:77], v[200:203], v[122:125]
	v_mfma_f32_16x16x32_bf16 v[110:113], v[66:69], v[208:211], v[110:113]
	v_mfma_f32_16x16x32_bf16 v[106:109], v[74:77], v[208:211], v[106:109]
	v_mfma_f32_16x16x32_bf16 v[94:97], v[66:69], v[216:219], v[94:97]
	v_mfma_f32_16x16x32_bf16 v[90:93], v[74:77], v[216:219], v[90:93]
	v_mfma_f32_16x16x32_bf16 v[142:145], v[70:73], v[196:199], v[142:145]
	v_mfma_f32_16x16x32_bf16 v[138:141], v[78:81], v[196:199], v[138:141]
	v_mfma_f32_16x16x32_bf16 v[126:129], v[70:73], v[204:207], v[126:129]
	v_mfma_f32_16x16x32_bf16 v[122:125], v[78:81], v[204:207], v[122:125]
	v_mfma_f32_16x16x32_bf16 v[110:113], v[70:73], v[212:215], v[110:113]
	v_mfma_f32_16x16x32_bf16 v[106:109], v[78:81], v[212:215], v[106:109]
	v_mfma_f32_16x16x32_bf16 v[94:97], v[70:73], v[220:223], v[94:97]
	v_mfma_f32_16x16x32_bf16 v[90:93], v[78:81], v[220:223], v[90:93]
	v_mfma_f32_16x16x32_bf16 v[134:137], v[162:165], v[192:195], v[134:137]
	v_mfma_f32_16x16x32_bf16 v[130:133], v[184:187], v[192:195], v[130:133]
	v_mfma_f32_16x16x32_bf16 v[118:121], v[162:165], v[200:203], v[118:121]
	v_mfma_f32_16x16x32_bf16 v[114:117], v[184:187], v[200:203], v[114:117]
	v_mfma_f32_16x16x32_bf16 v[102:105], v[162:165], v[208:211], v[102:105]
	v_mfma_f32_16x16x32_bf16 v[98:101], v[184:187], v[208:211], v[98:101]
	v_mfma_f32_16x16x32_bf16 v[86:89], v[162:165], v[216:219], v[86:89]
	v_mfma_f32_16x16x32_bf16 v[82:85], v[184:187], v[216:219], v[82:85]
	v_mfma_f32_16x16x32_bf16 v[134:137], v[180:183], v[196:199], v[134:137]
	v_mfma_f32_16x16x32_bf16 v[130:133], v[188:191], v[196:199], v[130:133]
	v_mfma_f32_16x16x32_bf16 v[118:121], v[180:183], v[204:207], v[118:121]
	v_mfma_f32_16x16x32_bf16 v[114:117], v[188:191], v[204:207], v[114:117]
	v_mfma_f32_16x16x32_bf16 v[102:105], v[180:183], v[212:215], v[102:105]
	v_mfma_f32_16x16x32_bf16 v[98:101], v[188:191], v[212:215], v[98:101]
	v_mfma_f32_16x16x32_bf16 v[86:89], v[180:183], v[220:223], v[86:89]
	v_mfma_f32_16x16x32_bf16 v[82:85], v[188:191], v[220:223], v[82:85]
	s_barrier
	s_add_u32 s98, s22, 0x80
	s_addc_u32 s99, s23, 0
	s_add_i32 s40, s51, s26
	s_mov_b32 m0, s40
	ds_read_b128 v[192:195], v175 offset:49152
	ds_read_b128 v[196:199], v175 offset:50176
	ds_read_b128 v[200:203], v175 offset:51200
	ds_read_b128 v[204:207], v175 offset:52224
	ds_read_b128 v[208:211], v175 offset:53248
	ds_read_b128 v[212:215], v175 offset:54272
	ds_read_b128 v[216:219], v175 offset:55296
	ds_read_b128 v[220:223], v175 offset:56320
	global_load_lds_dwordx4 v150, s[98:99]
	s_add_i32 m0, s40, 0x2000
	s_add_u32 s22, s22, 0x80080
	v_lshl_add_u64 v[166:167], v[224:225], 0, s[8:9]
	s_addc_u32 s23, s23, 0
	s_add_i32 s40, s52, s26
	global_load_lds_dwordx4 v[166:167], off
	s_mov_b32 m0, s40
	s_nop 0
	global_load_lds_dwordx4 v150, s[22:23]
	s_add_i32 m0, s40, 0x2000
	s_nop 0
	global_load_lds_dwordx4 v146, s[22:23]
	v_lshl_add_u64 v[166:167], v[226:227], 0, s[8:9]
	s_mov_b32 m0, s42
	s_nop 0
	global_load_lds_dwordx4 v[166:167], off
	v_lshl_add_u64 v[166:167], v[228:229], 0, s[8:9]
	s_mov_b32 m0, s43
	s_nop 0
	global_load_lds_dwordx4 v[166:167], off
	s_waitcnt vmcnt(8)
	s_waitcnt lgkmcnt(0)
	s_barrier
	s_waitcnt lgkmcnt(0)
	v_mfma_f32_16x16x32_bf16 v[62:65], v[66:69], v[192:195], v[62:65]
	v_mfma_f32_16x16x32_bf16 v[58:61], v[74:77], v[192:195], v[58:61]
	v_mfma_f32_16x16x32_bf16 v[46:49], v[66:69], v[200:203], v[46:49]
	v_mfma_f32_16x16x32_bf16 v[42:45], v[74:77], v[200:203], v[42:45]
	v_mfma_f32_16x16x32_bf16 v[30:33], v[66:69], v[208:211], v[30:33]
	v_mfma_f32_16x16x32_bf16 v[26:29], v[74:77], v[208:211], v[26:29]
	v_mfma_f32_16x16x32_bf16 v[14:17], v[66:69], v[216:219], v[14:17]
	v_mfma_f32_16x16x32_bf16 v[10:13], v[74:77], v[216:219], v[10:13]
	v_mfma_f32_16x16x32_bf16 v[62:65], v[70:73], v[196:199], v[62:65]
	v_mfma_f32_16x16x32_bf16 v[58:61], v[78:81], v[196:199], v[58:61]
	v_mfma_f32_16x16x32_bf16 v[46:49], v[70:73], v[204:207], v[46:49]
	v_mfma_f32_16x16x32_bf16 v[42:45], v[78:81], v[204:207], v[42:45]
	v_mfma_f32_16x16x32_bf16 v[30:33], v[70:73], v[212:215], v[30:33]
	v_mfma_f32_16x16x32_bf16 v[26:29], v[78:81], v[212:215], v[26:29]
	v_mfma_f32_16x16x32_bf16 v[14:17], v[70:73], v[220:223], v[14:17]
	v_mfma_f32_16x16x32_bf16 v[10:13], v[78:81], v[220:223], v[10:13]
	v_mfma_f32_16x16x32_bf16 v[54:57], v[162:165], v[192:195], v[54:57]
	v_mfma_f32_16x16x32_bf16 v[50:53], v[184:187], v[192:195], v[50:53]
	v_mfma_f32_16x16x32_bf16 v[38:41], v[162:165], v[200:203], v[38:41]
	v_mfma_f32_16x16x32_bf16 v[34:37], v[184:187], v[200:203], v[34:37]
	v_mfma_f32_16x16x32_bf16 v[22:25], v[162:165], v[208:211], v[22:25]
	v_mfma_f32_16x16x32_bf16 v[18:21], v[184:187], v[208:211], v[18:21]
	v_mfma_f32_16x16x32_bf16 v[6:9], v[162:165], v[216:219], v[6:9]
	v_mfma_f32_16x16x32_bf16 v[2:5], v[184:187], v[216:219], v[2:5]
	v_mfma_f32_16x16x32_bf16 v[54:57], v[180:183], v[196:199], v[54:57]
	v_mfma_f32_16x16x32_bf16 v[50:53], v[188:191], v[196:199], v[50:53]
	v_mfma_f32_16x16x32_bf16 v[38:41], v[180:183], v[204:207], v[38:41]
	v_mfma_f32_16x16x32_bf16 v[34:37], v[188:191], v[204:207], v[34:37]
	v_mfma_f32_16x16x32_bf16 v[22:25], v[180:183], v[212:215], v[22:25]
	v_mfma_f32_16x16x32_bf16 v[18:21], v[188:191], v[212:215], v[18:21]
	v_mfma_f32_16x16x32_bf16 v[6:9], v[180:183], v[220:223], v[6:9]
	v_mfma_f32_16x16x32_bf16 v[2:5], v[188:191], v[220:223], v[2:5]
	s_barrier
	s_add_i32 s50, s50, 2
	s_add_u32 s25, s25, 0x100
	s_addc_u32 s49, s49, 0
	s_add_u32 s16, s16, 0x100
	s_addc_u32 s17, s17, 0
	s_cmp_lt_u32 s50, 30
	s_cbranch_scc1 .LBB0_1822
	s_setprio 0
	s_andn2_b64 vcc, exec, s[10:11]
	s_cbranch_vccnz .LBB0_1825
	s_barrier

; #define PG8_STAGE(bufoff, gbase, voff) do { _Pragma("unroll") for (int _i = 0; _i < 2; ++_i) \
;         __builtin_amdgcn_global_load_lds((const unsigned*)((const char*)(gbase) + (voff)[_i]), (LAS unsigned*)(lds + (bufoff) + ldsw + _i * 8192), 16, 0, 0); } while (0)
; #define PG8_LDA(dst, b, h) do { _Pragma("unroll") for (int m = 0; m < 4; ++m) _Pragma("unroll") for (int k = 0; k < 2; ++k) dst[m][k] = *(const LAS bf16x8*)(lds + PG8_SA(b, h) + aoff + m * 2048 + k * 1024); } while (0)
; #define PG8_LDB(dst, b, h) do { _Pragma("unroll") for (int n = 0; n < 2; ++n) _Pragma("unroll") for (int k = 0; k < 2; ++k) dst[n][k] = *(const LAS bf16x8*)(lds + PG8_SB(b, h) + boff + n * 2048 + k * 1024); } while (0)
; #define PG8_MMA(ai, bj, At, Bt) do { __builtin_amdgcn_s_setprio(1); _Pragma("unroll") for (int m = 0; m < 4; ++m) _Pragma("unroll") for (int n = 0; n < 2; ++n) _Pragma("unroll") for (int k = 0; k < 2; ++k) \
;         acc[ai][bj][m][n] = __builtin_amdgcn_mfma_f32_16x16x32_bf16(Bt[n][k], At[m][k], acc[ai][bj][m][n], 0, 0, 0); __builtin_amdgcn_s_setprio(0); } while (0)
; #define PG8_WAIT_V(n) asm volatile("s_waitcnt vmcnt(" #n ")" ::: "memory")
; #define PG8_WAIT_L(n) asm volatile("s_waitcnt lgkmcnt(" #n ")" ::: "memory")
; template <class Epi, class Sched, bool ALIGN_EPI = false, bool SP2 = false>
; __device__ __forceinline__ void gemm_phase(LAS unsigned char* lds, const Gemm g, const Sched& S, const Epi& E) {
;     ...
;         for (int t = 0; t < nt; t += 2) {
;             const bool last = (t == nt - 2);
;             const char* a1 = cA + (size_t)(t + 1) * kstep;
;             const char* a2 = last ? nA : cA + (size_t)(t + 2) * kstep; const char* b2 = last ? nB : cB + (size_t)(t + 2) * kstep;
;             const char* a3 = a2 + kstep; const char* b3 = b2 + kstep;
;             if (last && has_next) S.a_ready(nxt);
;             if constexpr (SP2) {
;             PG8_LDB(B0, 0, 0); PG8_LDB(B1, 0, 1); PG8_SCHED; PG8_LDA(At, 0, 0); PG8_STAGE(PG8_SA(1, 1), a1 + hstep, voffA);
;             PG8_WAIT_V(8); PG8_WAIT_L(0); PG8_BAR; PG8_MMA(0, 0, At, B0); PG8_MMA(0, 1, At, B1); PG8_BAR; PG8_SCHED;
;             PG8_LDA(At, 0, 1); PG8_STAGE(PG8_SB(0, 0), b2, voffB); PG8_STAGE(PG8_SB(0, 1), b2 + hstepB, voffB); PG8_STAGE(PG8_SA(0, 0), a2, voffA);
;             PG8_WAIT_V(8); PG8_WAIT_L(0); PG8_BAR; PG8_MMA(1, 0, At, B0); PG8_MMA(1, 1, At, B1); PG8_BAR; PG8_SCHED;
.Lprio_1926:
	ds_read_b128 v[130:133], v196
	ds_read_b128 v[134:137], v196 offset:1024
	ds_read_b128 v[138:141], v196 offset:2048
	ds_read_b128 v[142:145], v196 offset:3072
	ds_read_b128 v[166:169], v197
	ds_read_b128 v[170:173], v197 offset:1024
	ds_read_b128 v[174:177], v197 offset:2048
	ds_read_b128 v[178:181], v197 offset:3072
	s_add_u32 s20, s18, 0x100
	s_addc_u32 s21, s19, 0
	s_cmpk_eq_i32 s25, 0x54
	s_cselect_b32 s47, s17, s21
	s_cselect_b32 s46, s16, s20
	s_cselect_b32 s23, s3, s24
	s_cselect_b32 s22, s2, s5
	v_lshl_add_u64 v[190:191], s[18:19], 0, v[160:161]
	s_add_i32 m0, s27, 0xc000
	ds_read_b128 v[182:185], v198
	ds_read_b128 v[186:189], v198 offset:1024
	ds_read_b128 v[202:205], v198 offset:2048
	ds_read_b128 v[206:209], v198 offset:3072
	ds_read_b128 v[210:213], v198 offset:4096
	ds_read_b128 v[214:217], v198 offset:5120
	ds_read_b128 v[218:221], v198 offset:6144
	ds_read_b128 v[222:225], v198 offset:7168
	global_load_lds_dwordx4 v[190:191], off
	v_lshl_add_u64 v[190:191], s[18:19], 0, v[158:159]
	s_add_i32 m0, s27, 0xe000
	s_nop 0
	global_load_lds_dwordx4 v[190:191], off
	s_waitcnt lgkmcnt(0)
	s_barrier
	s_waitcnt lgkmcnt(0)
	v_mfma_f32_16x16x32_bf16 v[126:129], v[130:133], v[182:185], 0
	v_mfma_f32_16x16x32_bf16 v[122:125], v[138:141], v[182:185], 0
	v_mfma_f32_16x16x32_bf16 v[110:113], v[130:133], v[202:205], 0
	v_mfma_f32_16x16x32_bf16 v[106:109], v[138:141], v[202:205], 0
	v_mfma_f32_16x16x32_bf16 v[94:97], v[130:133], v[210:213], 0
	v_mfma_f32_16x16x32_bf16 v[90:93], v[138:141], v[210:213], 0
	v_mfma_f32_16x16x32_bf16 v[78:81], v[130:133], v[218:221], 0
	v_mfma_f32_16x16x32_bf16 v[74:77], v[138:141], v[218:221], 0
	v_mfma_f32_16x16x32_bf16 v[126:129], v[134:137], v[186:189], v[126:129]
	v_mfma_f32_16x16x32_bf16 v[122:125], v[142:145], v[186:189], v[122:125]
	v_mfma_f32_16x16x32_bf16 v[110:113], v[134:137], v[206:209], v[110:113]
	v_mfma_f32_16x16x32_bf16 v[106:109], v[142:145], v[206:209], v[106:109]
	v_mfma_f32_16x16x32_bf16 v[94:97], v[134:137], v[214:217], v[94:97]
	v_mfma_f32_16x16x32_bf16 v[90:93], v[142:145], v[214:217], v[90:93]
	v_mfma_f32_16x16x32_bf16 v[78:81], v[134:137], v[222:225], v[78:81]
	v_mfma_f32_16x16x32_bf16 v[74:77], v[142:145], v[222:225], v[74:77]
	v_mfma_f32_16x16x32_bf16 v[118:121], v[166:169], v[182:185], 0
	v_mfma_f32_16x16x32_bf16 v[114:117], v[174:177], v[182:185], 0
	v_mfma_f32_16x16x32_bf16 v[102:105], v[166:169], v[202:205], 0
	v_mfma_f32_16x16x32_bf16 v[98:101], v[174:177], v[202:205], 0
	v_mfma_f32_16x16x32_bf16 v[86:89], v[166:169], v[210:213], 0
	v_mfma_f32_16x16x32_bf16 v[82:85], v[174:177], v[210:213], 0
	v_mfma_f32_16x16x32_bf16 v[70:73], v[166:169], v[218:221], 0
	v_mfma_f32_16x16x32_bf16 v[66:69], v[174:177], v[218:221], 0
	v_mfma_f32_16x16x32_bf16 v[118:121], v[170:173], v[186:189], v[118:121]
	v_mfma_f32_16x16x32_bf16 v[114:117], v[178:181], v[186:189], v[114:117]
	v_mfma_f32_16x16x32_bf16 v[102:105], v[170:173], v[206:209], v[102:105]
	v_mfma_f32_16x16x32_bf16 v[98:101], v[178:181], v[206:209], v[98:101]
	v_mfma_f32_16x16x32_bf16 v[86:89], v[170:173], v[214:217], v[86:89]
	v_mfma_f32_16x16x32_bf16 v[82:85], v[178:181], v[214:217], v[82:85]
	v_mfma_f32_16x16x32_bf16 v[70:73], v[170:173], v[222:225], v[70:73]
	v_mfma_f32_16x16x32_bf16 v[66:69], v[178:181], v[222:225], v[66:69]
	s_barrier
	s_add_i32 s18, s50, s26
	s_mov_b32 m0, s18
	ds_read_b128 v[182:185], v198 offset:16384
	ds_read_b128 v[186:189], v198 offset:17408
	ds_read_b128 v[202:205], v198 offset:18432
	ds_read_b128 v[206:209], v198 offset:19456
	ds_read_b128 v[210:213], v198 offset:20480
	ds_read_b128 v[214:217], v198 offset:21504
	ds_read_b128 v[218:221], v198 offset:22528
	ds_read_b128 v[222:225], v198 offset:23552
	global_load_lds_dwordx4 v148, s[22:23]
	s_add_i32 m0, s18, 0x2000
	s_add_u32 s18, s22, 0x58000
	v_lshl_add_u64 v[226:227], s[22:23], 0, v[152:153]
	s_addc_u32 s19, s23, 0
	s_add_i32 s54, s51, s26
	global_load_lds_dwordx4 v152, s[22:23]
	s_mov_b32 m0, s54
	global_load_lds_dwordx4 v148, s[18:19]
	s_add_i32 m0, s54, 0x2000
	s_nop 0
	global_load_lds_dwordx4 v152, s[18:19]
	s_mov_b32 m0, s27
	s_nop 0
	global_load_lds_dwordx4 v146, s[46:47]
	s_mov_b32 m0, s28
	s_nop 0
	global_load_lds_dwordx4 v150, s[46:47]
	s_waitcnt lgkmcnt(0)
	s_barrier
	s_waitcnt lgkmcnt(0)
	v_mfma_f32_16x16x32_bf16 v[62:65], v[130:133], v[182:185], 0
	v_mfma_f32_16x16x32_bf16 v[58:61], v[138:141], v[182:185], 0
	v_mfma_f32_16x16x32_bf16 v[46:49], v[130:133], v[202:205], 0
	v_mfma_f32_16x16x32_bf16 v[42:45], v[138:141], v[202:205], 0
	v_mfma_f32_16x16x32_bf16 v[30:33], v[130:133], v[210:213], 0
	v_mfma_f32_16x16x32_bf16 v[26:29], v[138:141], v[210:213], 0
	v_mfma_f32_16x16x32_bf16 v[14:17], v[130:133], v[218:221], 0
	v_mfma_f32_16x16x32_bf16 v[10:13], v[138:141], v[218:221], 0
	v_mfma_f32_16x16x32_bf16 v[62:65], v[134:137], v[186:189], v[62:65]
	v_mfma_f32_16x16x32_bf16 v[58:61], v[142:145], v[186:189], v[58:61]
	v_mfma_f32_16x16x32_bf16 v[46:49], v[134:137], v[206:209], v[46:49]
	v_mfma_f32_16x16x32_bf16 v[42:45], v[142:145], v[206:209], v[42:45]
	v_mfma_f32_16x16x32_bf16 v[30:33], v[134:137], v[214:217], v[30:33]
	v_mfma_f32_16x16x32_bf16 v[26:29], v[142:145], v[214:217], v[26:29]
	v_mfma_f32_16x16x32_bf16 v[14:17], v[134:137], v[222:225], v[14:17]
	v_mfma_f32_16x16x32_bf16 v[10:13], v[142:145], v[222:225], v[10:13]
	v_mfma_f32_16x16x32_bf16 v[54:57], v[166:169], v[182:185], 0
	v_mfma_f32_16x16x32_bf16 v[50:53], v[174:177], v[182:185], 0
	v_mfma_f32_16x16x32_bf16 v[38:41], v[166:169], v[202:205], 0
	v_mfma_f32_16x16x32_bf16 v[34:37], v[174:177], v[202:205], 0
	v_mfma_f32_16x16x32_bf16 v[22:25], v[166:169], v[210:213], 0
	v_mfma_f32_16x16x32_bf16 v[18:21], v[174:177], v[210:213], 0
	v_mfma_f32_16x16x32_bf16 v[6:9], v[166:169], v[218:221], 0
	v_mfma_f32_16x16x32_bf16 v[2:5], v[174:177], v[218:221], 0
	v_mfma_f32_16x16x32_bf16 v[54:57], v[170:173], v[186:189], v[54:57]
	v_mfma_f32_16x16x32_bf16 v[50:53], v[178:181], v[186:189], v[50:53]
	v_mfma_f32_16x16x32_bf16 v[38:41], v[170:173], v[206:209], v[38:41]
	v_mfma_f32_16x16x32_bf16 v[34:37], v[178:181], v[206:209], v[34:37]
	v_mfma_f32_16x16x32_bf16 v[22:25], v[170:173], v[214:217], v[22:25]
	v_mfma_f32_16x16x32_bf16 v[18:21], v[178:181], v[214:217], v[18:21]
	v_mfma_f32_16x16x32_bf16 v[6:9], v[170:173], v[222:225], v[6:9]
	v_mfma_f32_16x16x32_bf16 v[2:5], v[178:181], v[222:225], v[2:5]
	s_barrier
; #define PG8_STAGE(bufoff, gbase, voff) do { _Pragma("unroll") for (int _i = 0; _i < 2; ++_i) \
;         __builtin_amdgcn_global_load_lds((const unsigned*)((const char*)(gbase) + (voff)[_i]), (LAS unsigned*)(lds + (bufoff) + ldsw + _i * 8192), 16, 0, 0); } while (0)
; #define PG8_LDA(dst, b, h) do { _Pragma("unroll") for (int m = 0; m < 4; ++m) _Pragma("unroll") for (int k = 0; k < 2; ++k) dst[m][k] = *(const LAS bf16x8*)(lds + PG8_SA(b, h) + aoff + m * 2048 + k * 1024); } while (0)
; #define PG8_LDB(dst, b, h) do { _Pragma("unroll") for (int n = 0; n < 2; ++n) _Pragma("unroll") for (int k = 0; k < 2; ++k) dst[n][k] = *(const LAS bf16x8*)(lds + PG8_SB(b, h) + boff + n * 2048 + k * 1024); } while (0)
; #define PG8_MMA(ai, bj, At, Bt) do { __builtin_amdgcn_s_setprio(1); _Pragma("unroll") for (int m = 0; m < 4; ++m) _Pragma("unroll") for (int n = 0; n < 2; ++n) _Pragma("unroll") for (int k = 0; k < 2; ++k) \
;         acc[ai][bj][m][n] = __builtin_amdgcn_mfma_f32_16x16x32_bf16(Bt[n][k], At[m][k], acc[ai][bj][m][n], 0, 0, 0); __builtin_amdgcn_s_setprio(0); } while (0)
; #define PG8_WAIT_V(n) asm volatile("s_waitcnt vmcnt(" #n ")" ::: "memory")
; #define PG8_WAIT_L(n) asm volatile("s_waitcnt lgkmcnt(" #n ")" ::: "memory")
; #define PG8_BAR __builtin_amdgcn_s_barrier()
; #define PG8_SCHED __builtin_amdgcn_sched_barrier(0)
; template <class Epi, class Sched, bool ALIGN_EPI = false, bool SP2 = false>
; __device__ __forceinline__ void gemm_phase(LAS unsigned char* lds, const Gemm g, const Sched& S, const Epi& E) {
;     ...
;             PG8_LDB(B0, 1, 0); PG8_LDB(B1, 1, 1); PG8_SCHED; PG8_LDA(At, 1, 0); PG8_STAGE(PG8_SA(0, 1), a2 + hstep, voffA);
;             PG8_WAIT_V(8); PG8_WAIT_L(0); PG8_BAR; PG8_MMA(0, 0, At, B0); PG8_MMA(0, 1, At, B1); PG8_BAR; PG8_SCHED;
;             PG8_LDA(At, 1, 1); PG8_STAGE(PG8_SB(1, 0), b3, voffB); PG8_STAGE(PG8_SB(1, 1), b3 + hstepB, voffB); PG8_STAGE(PG8_SA(1, 0), a3, voffA);
;             PG8_WAIT_V(8); PG8_WAIT_L(0); PG8_BAR; PG8_MMA(1, 0, At, B0); PG8_MMA(1, 1, At, B1); PG8_BAR; PG8_SCHED;
	s_add_i32 s54, 0, 0x18000
	s_add_i32 s55, 0, 0x1c000
	v_add_u32_e32 v142, s54, v1
	v_add_u32_e32 v154, s55, v1
	ds_read_b128 v[130:133], v142
	ds_read_b128 v[134:137], v142 offset:1024
	ds_read_b128 v[138:141], v142 offset:2048
	ds_read_b128 v[142:145], v142 offset:3072
	ds_read_b128 v[166:169], v154
	ds_read_b128 v[170:173], v154 offset:1024
	ds_read_b128 v[174:177], v154 offset:2048
	ds_read_b128 v[178:181], v154 offset:3072
	s_add_u32 s18, s46, 0x160000
	s_addc_u32 s19, s47, 0
	s_mov_b32 m0, s29
	ds_read_b128 v[182:185], v198 offset:32768
	ds_read_b128 v[186:189], v198 offset:33792
	ds_read_b128 v[202:205], v198 offset:34816
	ds_read_b128 v[206:209], v198 offset:35840
	ds_read_b128 v[210:213], v198 offset:36864
	ds_read_b128 v[214:217], v198 offset:37888
	ds_read_b128 v[218:221], v198 offset:38912
	ds_read_b128 v[222:225], v198 offset:39936
	global_load_lds_dwordx4 v146, s[18:19]
	s_mov_b32 m0, s30
	s_nop 0
	global_load_lds_dwordx4 v150, s[18:19]
	s_waitcnt vmcnt(8)
	s_waitcnt lgkmcnt(0)
	s_barrier
	s_waitcnt lgkmcnt(0)
	v_mfma_f32_16x16x32_bf16 v[126:129], v[130:133], v[182:185], v[126:129]
	v_mfma_f32_16x16x32_bf16 v[122:125], v[138:141], v[182:185], v[122:125]
	v_mfma_f32_16x16x32_bf16 v[110:113], v[130:133], v[202:205], v[110:113]
	v_mfma_f32_16x16x32_bf16 v[106:109], v[138:141], v[202:205], v[106:109]
	v_mfma_f32_16x16x32_bf16 v[94:97], v[130:133], v[210:213], v[94:97]
	v_mfma_f32_16x16x32_bf16 v[90:93], v[138:141], v[210:213], v[90:93]
	v_mfma_f32_16x16x32_bf16 v[78:81], v[130:133], v[218:221], v[78:81]
	v_mfma_f32_16x16x32_bf16 v[74:77], v[138:141], v[218:221], v[74:77]
	v_mfma_f32_16x16x32_bf16 v[126:129], v[134:137], v[186:189], v[126:129]
	v_mfma_f32_16x16x32_bf16 v[122:125], v[142:145], v[186:189], v[122:125]
	v_mfma_f32_16x16x32_bf16 v[110:113], v[134:137], v[206:209], v[110:113]
	v_mfma_f32_16x16x32_bf16 v[106:109], v[142:145], v[206:209], v[106:109]
	v_mfma_f32_16x16x32_bf16 v[94:97], v[134:137], v[214:217], v[94:97]
	v_mfma_f32_16x16x32_bf16 v[90:93], v[142:145], v[214:217], v[90:93]
	v_mfma_f32_16x16x32_bf16 v[78:81], v[134:137], v[222:225], v[78:81]
	v_mfma_f32_16x16x32_bf16 v[74:77], v[142:145], v[222:225], v[74:77]
	v_mfma_f32_16x16x32_bf16 v[118:121], v[166:169], v[182:185], v[118:121]
	v_mfma_f32_16x16x32_bf16 v[114:117], v[174:177], v[182:185], v[114:117]
	v_mfma_f32_16x16x32_bf16 v[102:105], v[166:169], v[202:205], v[102:105]
	v_mfma_f32_16x16x32_bf16 v[98:101], v[174:177], v[202:205], v[98:101]
	v_mfma_f32_16x16x32_bf16 v[86:89], v[166:169], v[210:213], v[86:89]
	v_mfma_f32_16x16x32_bf16 v[82:85], v[174:177], v[210:213], v[82:85]
	v_mfma_f32_16x16x32_bf16 v[70:73], v[166:169], v[218:221], v[70:73]
	v_mfma_f32_16x16x32_bf16 v[66:69], v[174:177], v[218:221], v[66:69]
	v_mfma_f32_16x16x32_bf16 v[118:121], v[170:173], v[186:189], v[118:121]
	v_mfma_f32_16x16x32_bf16 v[114:117], v[178:181], v[186:189], v[114:117]
	v_mfma_f32_16x16x32_bf16 v[102:105], v[170:173], v[206:209], v[102:105]
	v_mfma_f32_16x16x32_bf16 v[98:101], v[178:181], v[206:209], v[98:101]
	v_mfma_f32_16x16x32_bf16 v[86:89], v[170:173], v[214:217], v[86:89]
	v_mfma_f32_16x16x32_bf16 v[82:85], v[178:181], v[214:217], v[82:85]
	v_mfma_f32_16x16x32_bf16 v[70:73], v[170:173], v[222:225], v[70:73]
	v_mfma_f32_16x16x32_bf16 v[66:69], v[178:181], v[222:225], v[66:69]
	s_barrier
	s_add_u32 s98, s22, 0x80
	s_addc_u32 s99, s23, 0
	s_add_u32 s100, s46, 0x80
	s_addc_u32 s101, s47, 0
	s_add_i32 s18, s54, s26
	s_mov_b32 m0, s18
	ds_read_b128 v[182:185], v198 offset:49152
	ds_read_b128 v[186:189], v198 offset:50176
	ds_read_b128 v[202:205], v198 offset:51200
	ds_read_b128 v[206:209], v198 offset:52224
	ds_read_b128 v[210:213], v198 offset:53248
	ds_read_b128 v[214:217], v198 offset:54272
	ds_read_b128 v[218:221], v198 offset:55296
	ds_read_b128 v[222:225], v198 offset:56320
	global_load_lds_dwordx4 v148, s[98:99]
	s_add_i32 m0, s18, 0x2000
	s_add_u32 s18, s22, 0x58080
	v_lshl_add_u64 v[190:191], v[226:227], 0, s[12:13]
	s_addc_u32 s19, s23, 0
	s_add_i32 s22, s55, s26
	global_load_lds_dwordx4 v[190:191], off
	s_mov_b32 m0, s22
	s_nop 0
	global_load_lds_dwordx4 v148, s[18:19]
	s_add_i32 m0, s22, 0x2000
	s_nop 0
	global_load_lds_dwordx4 v152, s[18:19]
	s_mov_b32 m0, s37
	s_nop 0
	global_load_lds_dwordx4 v146, s[100:101]
	s_mov_b32 m0, s48
	s_nop 0
	global_load_lds_dwordx4 v150, s[100:101]
	s_waitcnt vmcnt(8)
	s_waitcnt lgkmcnt(0)
	s_barrier
	s_waitcnt lgkmcnt(0)
	v_mfma_f32_16x16x32_bf16 v[62:65], v[130:133], v[182:185], v[62:65]
	v_mfma_f32_16x16x32_bf16 v[58:61], v[138:141], v[182:185], v[58:61]
	v_mfma_f32_16x16x32_bf16 v[46:49], v[130:133], v[202:205], v[46:49]
	v_mfma_f32_16x16x32_bf16 v[42:45], v[138:141], v[202:205], v[42:45]
	v_mfma_f32_16x16x32_bf16 v[30:33], v[130:133], v[210:213], v[30:33]
	v_mfma_f32_16x16x32_bf16 v[26:29], v[138:141], v[210:213], v[26:29]
	v_mfma_f32_16x16x32_bf16 v[14:17], v[130:133], v[218:221], v[14:17]
	v_mfma_f32_16x16x32_bf16 v[10:13], v[138:141], v[218:221], v[10:13]
	v_mfma_f32_16x16x32_bf16 v[62:65], v[134:137], v[186:189], v[62:65]
	v_mfma_f32_16x16x32_bf16 v[58:61], v[142:145], v[186:189], v[58:61]
	v_mfma_f32_16x16x32_bf16 v[46:49], v[134:137], v[206:209], v[46:49]
	v_mfma_f32_16x16x32_bf16 v[42:45], v[142:145], v[206:209], v[42:45]
	v_mfma_f32_16x16x32_bf16 v[30:33], v[134:137], v[214:217], v[30:33]
	v_mfma_f32_16x16x32_bf16 v[26:29], v[142:145], v[214:217], v[26:29]
	v_mfma_f32_16x16x32_bf16 v[14:17], v[134:137], v[222:225], v[14:17]
	v_mfma_f32_16x16x32_bf16 v[10:13], v[142:145], v[222:225], v[10:13]
	v_mfma_f32_16x16x32_bf16 v[54:57], v[166:169], v[182:185], v[54:57]
	v_mfma_f32_16x16x32_bf16 v[50:53], v[174:177], v[182:185], v[50:53]
	v_mfma_f32_16x16x32_bf16 v[38:41], v[166:169], v[202:205], v[38:41]
	v_mfma_f32_16x16x32_bf16 v[34:37], v[174:177], v[202:205], v[34:37]
	v_mfma_f32_16x16x32_bf16 v[22:25], v[166:169], v[210:213], v[22:25]
	v_mfma_f32_16x16x32_bf16 v[18:21], v[174:177], v[210:213], v[18:21]
	v_mfma_f32_16x16x32_bf16 v[6:9], v[166:169], v[218:221], v[6:9]
	v_mfma_f32_16x16x32_bf16 v[2:5], v[174:177], v[218:221], v[2:5]
	v_mfma_f32_16x16x32_bf16 v[54:57], v[170:173], v[186:189], v[54:57]
	v_mfma_f32_16x16x32_bf16 v[50:53], v[178:181], v[186:189], v[50:53]
	v_mfma_f32_16x16x32_bf16 v[38:41], v[170:173], v[206:209], v[38:41]
	v_mfma_f32_16x16x32_bf16 v[34:37], v[178:181], v[206:209], v[34:37]
	v_mfma_f32_16x16x32_bf16 v[22:25], v[170:173], v[214:217], v[22:25]
	v_mfma_f32_16x16x32_bf16 v[18:21], v[178:181], v[214:217], v[18:21]
	v_mfma_f32_16x16x32_bf16 v[6:9], v[170:173], v[222:225], v[6:9]
	v_mfma_f32_16x16x32_bf16 v[2:5], v[178:181], v[222:225], v[2:5]
	s_barrier
	s_add_i32 s25, s25, 2
	s_add_u32 s5, s5, 0x100
	s_addc_u32 s24, s24, 0
	s_cmpk_lt_u32 s25, 0x56
	s_mov_b64 s[18:19], s[20:21]
; #define PG8_STAGE(bufoff, gbase, voff) do { _Pragma("unroll") for (int _i = 0; _i < 2; ++_i) \
;         __builtin_amdgcn_global_load_lds((const unsigned*)((const char*)(gbase) + (voff)[_i]), (LAS unsigned*)(lds + (bufoff) + ldsw + _i * 8192), 16, 0, 0); } while (0)
; #define PG8_LDA(dst, b, h) do { _Pragma("unroll") for (int m = 0; m < 4; ++m) _Pragma("unroll") for (int k = 0; k < 2; ++k) dst[m][k] = *(const LAS bf16x8*)(lds + PG8_SA(b, h) + aoff + m * 2048 + k * 1024); } while (0)
; #define PG8_LDB(dst, b, h) do { _Pragma("unroll") for (int n = 0; n < 2; ++n) _Pragma("unroll") for (int k = 0; k < 2; ++k) dst[n][k] = *(const LAS bf16x8*)(lds + PG8_SB(b, h) + boff + n * 2048 + k * 1024); } while (0)
; #define PG8_MMA(ai, bj, At, Bt) do { __builtin_amdgcn_s_setprio(1); _Pragma("unroll") for (int m = 0; m < 4; ++m) _Pragma("unroll") for (int n = 0; n < 2; ++n) _Pragma("unroll") for (int k = 0; k < 2; ++k) \
;         acc[ai][bj][m][n] = __builtin_amdgcn_mfma_f32_16x16x32_bf16(Bt[n][k], At[m][k], acc[ai][bj][m][n], 0, 0, 0); __builtin_amdgcn_s_setprio(0); } while (0)
; #define PG8_WAIT_V(n) asm volatile("s_waitcnt vmcnt(" #n ")" ::: "memory")
; #define PG8_WAIT_L(n) asm volatile("s_waitcnt lgkmcnt(" #n ")" ::: "memory")
; template <class Epi, class Sched, bool ALIGN_EPI = false, bool SP2 = false>
; __device__ __forceinline__ void gemm_phase(LAS unsigned char* lds, const Gemm g, const Sched& S, const Epi& E) {
;     ...
;         for (int t = 0; t < nt; t += 2) {
;             const bool last = (t == nt - 2);
;             const char* a1 = cA + (size_t)(t + 1) * kstep;
;             const char* a2 = last ? nA : cA + (size_t)(t + 2) * kstep; const char* b2 = last ? nB : cB + (size_t)(t + 2) * kstep;
;             const char* a3 = a2 + kstep; const char* b3 = b2 + kstep;
;             if (last && has_next) S.a_ready(nxt);
;             if constexpr (SP2) {
;             PG8_LDB(B0, 0, 0); PG8_LDB(B1, 0, 1); PG8_SCHED; PG8_LDA(At, 0, 0); PG8_STAGE(PG8_SA(1, 1), a1 + hstep, voffA);
;             PG8_WAIT_V(8); PG8_WAIT_L(0); PG8_BAR; PG8_MMA(0, 0, At, B0); PG8_MMA(0, 1, At, B1); PG8_BAR; PG8_SCHED;
;             PG8_LDA(At, 0, 1); PG8_STAGE(PG8_SB(0, 0), b2, voffB); PG8_STAGE(PG8_SB(0, 1), b2 + hstepB, voffB); PG8_STAGE(PG8_SA(0, 0), a2, voffA);
;             PG8_WAIT_V(8); PG8_WAIT_L(0); PG8_BAR; PG8_MMA(1, 0, At, B0); PG8_MMA(1, 1, At, B1); PG8_BAR; PG8_SCHED;
.LBB0_1926:
	ds_read_b128 v[130:133], v196
	ds_read_b128 v[134:137], v196 offset:1024
	ds_read_b128 v[138:141], v196 offset:2048
	ds_read_b128 v[142:145], v196 offset:3072
	ds_read_b128 v[166:169], v197
	ds_read_b128 v[170:173], v197 offset:1024
	ds_read_b128 v[174:177], v197 offset:2048
	ds_read_b128 v[178:181], v197 offset:3072
	s_add_u32 s20, s18, 0x100
	s_addc_u32 s21, s19, 0
	s_cmpk_eq_i32 s25, 0x54
	s_cselect_b32 s47, s17, s21
	s_cselect_b32 s46, s16, s20
	s_cselect_b32 s23, s3, s24
	s_cselect_b32 s22, s2, s5
	v_lshl_add_u64 v[190:191], s[18:19], 0, v[160:161]
	s_add_i32 m0, s27, 0xc000
	ds_read_b128 v[182:185], v198
	ds_read_b128 v[186:189], v198 offset:1024
	ds_read_b128 v[202:205], v198 offset:2048
	ds_read_b128 v[206:209], v198 offset:3072
	ds_read_b128 v[210:213], v198 offset:4096
	ds_read_b128 v[214:217], v198 offset:5120
	ds_read_b128 v[218:221], v198 offset:6144
	ds_read_b128 v[222:225], v198 offset:7168
	global_load_lds_dwordx4 v[190:191], off
	v_lshl_add_u64 v[190:191], s[18:19], 0, v[158:159]
	s_add_i32 m0, s27, 0xe000
	s_nop 0
	global_load_lds_dwordx4 v[190:191], off
	s_waitcnt vmcnt(8)
	s_waitcnt lgkmcnt(0)
	s_barrier
	s_waitcnt lgkmcnt(0)
	v_mfma_f32_16x16x32_bf16 v[126:129], v[130:133], v[182:185], v[126:129]
	v_mfma_f32_16x16x32_bf16 v[122:125], v[138:141], v[182:185], v[122:125]
	v_mfma_f32_16x16x32_bf16 v[110:113], v[130:133], v[202:205], v[110:113]
	v_mfma_f32_16x16x32_bf16 v[106:109], v[138:141], v[202:205], v[106:109]
	v_mfma_f32_16x16x32_bf16 v[94:97], v[130:133], v[210:213], v[94:97]
	v_mfma_f32_16x16x32_bf16 v[90:93], v[138:141], v[210:213], v[90:93]
	v_mfma_f32_16x16x32_bf16 v[78:81], v[130:133], v[218:221], v[78:81]
	v_mfma_f32_16x16x32_bf16 v[74:77], v[138:141], v[218:221], v[74:77]
	v_mfma_f32_16x16x32_bf16 v[126:129], v[134:137], v[186:189], v[126:129]
	v_mfma_f32_16x16x32_bf16 v[122:125], v[142:145], v[186:189], v[122:125]
	v_mfma_f32_16x16x32_bf16 v[110:113], v[134:137], v[206:209], v[110:113]
	v_mfma_f32_16x16x32_bf16 v[106:109], v[142:145], v[206:209], v[106:109]
	v_mfma_f32_16x16x32_bf16 v[94:97], v[134:137], v[214:217], v[94:97]
	v_mfma_f32_16x16x32_bf16 v[90:93], v[142:145], v[214:217], v[90:93]
	v_mfma_f32_16x16x32_bf16 v[78:81], v[134:137], v[222:225], v[78:81]
	v_mfma_f32_16x16x32_bf16 v[74:77], v[142:145], v[222:225], v[74:77]
	v_mfma_f32_16x16x32_bf16 v[118:121], v[166:169], v[182:185], v[118:121]
	v_mfma_f32_16x16x32_bf16 v[114:117], v[174:177], v[182:185], v[114:117]
	v_mfma_f32_16x16x32_bf16 v[102:105], v[166:169], v[202:205], v[102:105]
	v_mfma_f32_16x16x32_bf16 v[98:101], v[174:177], v[202:205], v[98:101]
	v_mfma_f32_16x16x32_bf16 v[86:89], v[166:169], v[210:213], v[86:89]
	v_mfma_f32_16x16x32_bf16 v[82:85], v[174:177], v[210:213], v[82:85]
	v_mfma_f32_16x16x32_bf16 v[70:73], v[166:169], v[218:221], v[70:73]
	v_mfma_f32_16x16x32_bf16 v[66:69], v[174:177], v[218:221], v[66:69]
	v_mfma_f32_16x16x32_bf16 v[118:121], v[170:173], v[186:189], v[118:121]
	v_mfma_f32_16x16x32_bf16 v[114:117], v[178:181], v[186:189], v[114:117]
	v_mfma_f32_16x16x32_bf16 v[102:105], v[170:173], v[206:209], v[102:105]
	v_mfma_f32_16x16x32_bf16 v[98:101], v[178:181], v[206:209], v[98:101]
	v_mfma_f32_16x16x32_bf16 v[86:89], v[170:173], v[214:217], v[86:89]
	v_mfma_f32_16x16x32_bf16 v[82:85], v[178:181], v[214:217], v[82:85]
	v_mfma_f32_16x16x32_bf16 v[70:73], v[170:173], v[222:225], v[70:73]
	v_mfma_f32_16x16x32_bf16 v[66:69], v[178:181], v[222:225], v[66:69]
	s_barrier
	s_add_i32 s18, s50, s26
	s_mov_b32 m0, s18
	ds_read_b128 v[182:185], v198 offset:16384
	ds_read_b128 v[186:189], v198 offset:17408
	ds_read_b128 v[202:205], v198 offset:18432
	ds_read_b128 v[206:209], v198 offset:19456
	ds_read_b128 v[210:213], v198 offset:20480
	ds_read_b128 v[214:217], v198 offset:21504
	ds_read_b128 v[218:221], v198 offset:22528
	ds_read_b128 v[222:225], v198 offset:23552
	global_load_lds_dwordx4 v148, s[22:23]
	s_add_i32 m0, s18, 0x2000
	s_add_u32 s18, s22, 0x58000
	v_lshl_add_u64 v[226:227], s[22:23], 0, v[152:153]
	s_addc_u32 s19, s23, 0
	s_add_i32 s54, s51, s26
	global_load_lds_dwordx4 v152, s[22:23]
	s_mov_b32 m0, s54
	global_load_lds_dwordx4 v148, s[18:19]
	s_add_i32 m0, s54, 0x2000
	s_nop 0
	global_load_lds_dwordx4 v152, s[18:19]
	s_mov_b32 m0, s27
	s_nop 0
	global_load_lds_dwordx4 v146, s[46:47]
	s_mov_b32 m0, s28
	s_nop 0
	global_load_lds_dwordx4 v150, s[46:47]
	s_waitcnt vmcnt(8)
	s_waitcnt lgkmcnt(0)
	s_barrier
	s_waitcnt lgkmcnt(0)
	v_mfma_f32_16x16x32_bf16 v[62:65], v[130:133], v[182:185], v[62:65]
	v_mfma_f32_16x16x32_bf16 v[58:61], v[138:141], v[182:185], v[58:61]
	v_mfma_f32_16x16x32_bf16 v[46:49], v[130:133], v[202:205], v[46:49]
	v_mfma_f32_16x16x32_bf16 v[42:45], v[138:141], v[202:205], v[42:45]
	v_mfma_f32_16x16x32_bf16 v[30:33], v[130:133], v[210:213], v[30:33]
	v_mfma_f32_16x16x32_bf16 v[26:29], v[138:141], v[210:213], v[26:29]
	v_mfma_f32_16x16x32_bf16 v[14:17], v[130:133], v[218:221], v[14:17]
	v_mfma_f32_16x16x32_bf16 v[10:13], v[138:141], v[218:221], v[10:13]
	v_mfma_f32_16x16x32_bf16 v[62:65], v[134:137], v[186:189], v[62:65]
	v_mfma_f32_16x16x32_bf16 v[58:61], v[142:145], v[186:189], v[58:61]
	v_mfma_f32_16x16x32_bf16 v[46:49], v[134:137], v[206:209], v[46:49]
	v_mfma_f32_16x16x32_bf16 v[42:45], v[142:145], v[206:209], v[42:45]
	v_mfma_f32_16x16x32_bf16 v[30:33], v[134:137], v[214:217], v[30:33]
	v_mfma_f32_16x16x32_bf16 v[26:29], v[142:145], v[214:217], v[26:29]
	v_mfma_f32_16x16x32_bf16 v[14:17], v[134:137], v[222:225], v[14:17]
	v_mfma_f32_16x16x32_bf16 v[10:13], v[142:145], v[222:225], v[10:13]
	v_mfma_f32_16x16x32_bf16 v[54:57], v[166:169], v[182:185], v[54:57]
	v_mfma_f32_16x16x32_bf16 v[50:53], v[174:177], v[182:185], v[50:53]
	v_mfma_f32_16x16x32_bf16 v[38:41], v[166:169], v[202:205], v[38:41]
	v_mfma_f32_16x16x32_bf16 v[34:37], v[174:177], v[202:205], v[34:37]
	v_mfma_f32_16x16x32_bf16 v[22:25], v[166:169], v[210:213], v[22:25]
	v_mfma_f32_16x16x32_bf16 v[18:21], v[174:177], v[210:213], v[18:21]
	v_mfma_f32_16x16x32_bf16 v[6:9], v[166:169], v[218:221], v[6:9]
	v_mfma_f32_16x16x32_bf16 v[2:5], v[174:177], v[218:221], v[2:5]
	v_mfma_f32_16x16x32_bf16 v[54:57], v[170:173], v[186:189], v[54:57]
	v_mfma_f32_16x16x32_bf16 v[50:53], v[178:181], v[186:189], v[50:53]
	v_mfma_f32_16x16x32_bf16 v[38:41], v[170:173], v[206:209], v[38:41]
	v_mfma_f32_16x16x32_bf16 v[34:37], v[178:181], v[206:209], v[34:37]
	v_mfma_f32_16x16x32_bf16 v[22:25], v[170:173], v[214:217], v[22:25]
	v_mfma_f32_16x16x32_bf16 v[18:21], v[178:181], v[214:217], v[18:21]
	v_mfma_f32_16x16x32_bf16 v[6:9], v[170:173], v[222:225], v[6:9]
	v_mfma_f32_16x16x32_bf16 v[2:5], v[178:181], v[222:225], v[2:5]
	s_barrier
; #define PG8_STAGE(bufoff, gbase, voff) do { _Pragma("unroll") for (int _i = 0; _i < 2; ++_i) \
;         __builtin_amdgcn_global_load_lds((const unsigned*)((const char*)(gbase) + (voff)[_i]), (LAS unsigned*)(lds + (bufoff) + ldsw + _i * 8192), 16, 0, 0); } while (0)
; #define PG8_LDA(dst, b, h) do { _Pragma("unroll") for (int m = 0; m < 4; ++m) _Pragma("unroll") for (int k = 0; k < 2; ++k) dst[m][k] = *(const LAS bf16x8*)(lds + PG8_SA(b, h) + aoff + m * 2048 + k * 1024); } while (0)
; #define PG8_LDB(dst, b, h) do { _Pragma("unroll") for (int n = 0; n < 2; ++n) _Pragma("unroll") for (int k = 0; k < 2; ++k) dst[n][k] = *(const LAS bf16x8*)(lds + PG8_SB(b, h) + boff + n * 2048 + k * 1024); } while (0)
; #define PG8_MMA(ai, bj, At, Bt) do { __builtin_amdgcn_s_setprio(1); _Pragma("unroll") for (int m = 0; m < 4; ++m) _Pragma("unroll") for (int n = 0; n < 2; ++n) _Pragma("unroll") for (int k = 0; k < 2; ++k) \
;         acc[ai][bj][m][n] = __builtin_amdgcn_mfma_f32_16x16x32_bf16(Bt[n][k], At[m][k], acc[ai][bj][m][n], 0, 0, 0); __builtin_amdgcn_s_setprio(0); } while (0)
; #define PG8_WAIT_V(n) asm volatile("s_waitcnt vmcnt(" #n ")" ::: "memory")
; #define PG8_WAIT_L(n) asm volatile("s_waitcnt lgkmcnt(" #n ")" ::: "memory")
; #define PG8_BAR __builtin_amdgcn_s_barrier()
; #define PG8_SCHED __builtin_amdgcn_sched_barrier(0)
; template <class Epi, class Sched, bool ALIGN_EPI = false, bool SP2 = false>
; __device__ __forceinline__ void gemm_phase(LAS unsigned char* lds, const Gemm g, const Sched& S, const Epi& E) {
;     ...
;         for (int t = 0; t < nt; t += 2) {
;     ...
;             PG8_LDB(B0, 1, 0); PG8_LDB(B1, 1, 1); PG8_SCHED; PG8_LDA(At, 1, 0); PG8_STAGE(PG8_SA(0, 1), a2 + hstep, voffA);
;             PG8_WAIT_V(8); PG8_WAIT_L(0); PG8_BAR; PG8_MMA(0, 0, At, B0); PG8_MMA(0, 1, At, B1); PG8_BAR; PG8_SCHED;
;             PG8_LDA(At, 1, 1); PG8_STAGE(PG8_SB(1, 0), b3, voffB); PG8_STAGE(PG8_SB(1, 1), b3 + hstepB, voffB); PG8_STAGE(PG8_SA(1, 0), a3, voffA);
;             PG8_WAIT_V(8); PG8_WAIT_L(0); PG8_BAR; PG8_MMA(1, 0, At, B0); PG8_MMA(1, 1, At, B1); PG8_BAR; PG8_SCHED;
	s_add_i32 s54, 0, 0x18000
	s_add_i32 s55, 0, 0x1c000
	v_add_u32_e32 v142, s54, v1
	v_add_u32_e32 v154, s55, v1
	ds_read_b128 v[130:133], v142
	ds_read_b128 v[134:137], v142 offset:1024
	ds_read_b128 v[138:141], v142 offset:2048
	ds_read_b128 v[142:145], v142 offset:3072
	ds_read_b128 v[166:169], v154
	ds_read_b128 v[170:173], v154 offset:1024
	ds_read_b128 v[174:177], v154 offset:2048
	ds_read_b128 v[178:181], v154 offset:3072
	s_add_u32 s18, s46, 0x160000
	s_addc_u32 s19, s47, 0
	s_mov_b32 m0, s29
	ds_read_b128 v[182:185], v198 offset:32768
	ds_read_b128 v[186:189], v198 offset:33792
	ds_read_b128 v[202:205], v198 offset:34816
	ds_read_b128 v[206:209], v198 offset:35840
	ds_read_b128 v[210:213], v198 offset:36864
	ds_read_b128 v[214:217], v198 offset:37888
	ds_read_b128 v[218:221], v198 offset:38912
	ds_read_b128 v[222:225], v198 offset:39936
	global_load_lds_dwordx4 v146, s[18:19]
	s_mov_b32 m0, s30
	s_nop 0
	global_load_lds_dwordx4 v150, s[18:19]
	s_waitcnt vmcnt(8)
	s_waitcnt lgkmcnt(0)
	s_barrier
	s_waitcnt lgkmcnt(0)
	v_mfma_f32_16x16x32_bf16 v[126:129], v[130:133], v[182:185], v[126:129]
	v_mfma_f32_16x16x32_bf16 v[122:125], v[138:141], v[182:185], v[122:125]
	v_mfma_f32_16x16x32_bf16 v[110:113], v[130:133], v[202:205], v[110:113]
	v_mfma_f32_16x16x32_bf16 v[106:109], v[138:141], v[202:205], v[106:109]
	v_mfma_f32_16x16x32_bf16 v[94:97], v[130:133], v[210:213], v[94:97]
	v_mfma_f32_16x16x32_bf16 v[90:93], v[138:141], v[210:213], v[90:93]
	v_mfma_f32_16x16x32_bf16 v[78:81], v[130:133], v[218:221], v[78:81]
	v_mfma_f32_16x16x32_bf16 v[74:77], v[138:141], v[218:221], v[74:77]
	v_mfma_f32_16x16x32_bf16 v[126:129], v[134:137], v[186:189], v[126:129]
	v_mfma_f32_16x16x32_bf16 v[122:125], v[142:145], v[186:189], v[122:125]
	v_mfma_f32_16x16x32_bf16 v[110:113], v[134:137], v[206:209], v[110:113]
	v_mfma_f32_16x16x32_bf16 v[106:109], v[142:145], v[206:209], v[106:109]
	v_mfma_f32_16x16x32_bf16 v[94:97], v[134:137], v[214:217], v[94:97]
	v_mfma_f32_16x16x32_bf16 v[90:93], v[142:145], v[214:217], v[90:93]
	v_mfma_f32_16x16x32_bf16 v[78:81], v[134:137], v[222:225], v[78:81]
	v_mfma_f32_16x16x32_bf16 v[74:77], v[142:145], v[222:225], v[74:77]
	v_mfma_f32_16x16x32_bf16 v[118:121], v[166:169], v[182:185], v[118:121]
	v_mfma_f32_16x16x32_bf16 v[114:117], v[174:177], v[182:185], v[114:117]
	v_mfma_f32_16x16x32_bf16 v[102:105], v[166:169], v[202:205], v[102:105]
	v_mfma_f32_16x16x32_bf16 v[98:101], v[174:177], v[202:205], v[98:101]
	v_mfma_f32_16x16x32_bf16 v[86:89], v[166:169], v[210:213], v[86:89]
	v_mfma_f32_16x16x32_bf16 v[82:85], v[174:177], v[210:213], v[82:85]
	v_mfma_f32_16x16x32_bf16 v[70:73], v[166:169], v[218:221], v[70:73]
	v_mfma_f32_16x16x32_bf16 v[66:69], v[174:177], v[218:221], v[66:69]
	v_mfma_f32_16x16x32_bf16 v[118:121], v[170:173], v[186:189], v[118:121]
	v_mfma_f32_16x16x32_bf16 v[114:117], v[178:181], v[186:189], v[114:117]
	v_mfma_f32_16x16x32_bf16 v[102:105], v[170:173], v[206:209], v[102:105]
	v_mfma_f32_16x16x32_bf16 v[98:101], v[178:181], v[206:209], v[98:101]
	v_mfma_f32_16x16x32_bf16 v[86:89], v[170:173], v[214:217], v[86:89]
	v_mfma_f32_16x16x32_bf16 v[82:85], v[178:181], v[214:217], v[82:85]
	v_mfma_f32_16x16x32_bf16 v[70:73], v[170:173], v[222:225], v[70:73]
	v_mfma_f32_16x16x32_bf16 v[66:69], v[178:181], v[222:225], v[66:69]
	s_barrier
	s_add_u32 s98, s22, 0x80
	s_addc_u32 s99, s23, 0
	s_add_u32 s100, s46, 0x80
	s_addc_u32 s101, s47, 0
	s_add_i32 s18, s54, s26
	s_mov_b32 m0, s18
	ds_read_b128 v[182:185], v198 offset:49152
	ds_read_b128 v[186:189], v198 offset:50176
	ds_read_b128 v[202:205], v198 offset:51200
	ds_read_b128 v[206:209], v198 offset:52224
	ds_read_b128 v[210:213], v198 offset:53248
	ds_read_b128 v[214:217], v198 offset:54272
	ds_read_b128 v[218:221], v198 offset:55296
	ds_read_b128 v[222:225], v198 offset:56320
	global_load_lds_dwordx4 v148, s[98:99]
	s_add_i32 m0, s18, 0x2000
	s_add_u32 s18, s22, 0x58080
	v_lshl_add_u64 v[190:191], v[226:227], 0, s[12:13]
	s_addc_u32 s19, s23, 0
	s_add_i32 s22, s55, s26
	global_load_lds_dwordx4 v[190:191], off
	s_mov_b32 m0, s22
	s_nop 0
	global_load_lds_dwordx4 v148, s[18:19]
	s_add_i32 m0, s22, 0x2000
	s_nop 0
	global_load_lds_dwordx4 v152, s[18:19]
	s_mov_b32 m0, s37
	s_nop 0
	global_load_lds_dwordx4 v146, s[100:101]
	s_mov_b32 m0, s48
	s_nop 0
	global_load_lds_dwordx4 v150, s[100:101]
	s_waitcnt vmcnt(8)
	s_waitcnt lgkmcnt(0)
	s_barrier
	s_waitcnt lgkmcnt(0)
	v_mfma_f32_16x16x32_bf16 v[62:65], v[130:133], v[182:185], v[62:65]
	v_mfma_f32_16x16x32_bf16 v[58:61], v[138:141], v[182:185], v[58:61]
	v_mfma_f32_16x16x32_bf16 v[46:49], v[130:133], v[202:205], v[46:49]
	v_mfma_f32_16x16x32_bf16 v[42:45], v[138:141], v[202:205], v[42:45]
	v_mfma_f32_16x16x32_bf16 v[30:33], v[130:133], v[210:213], v[30:33]
	v_mfma_f32_16x16x32_bf16 v[26:29], v[138:141], v[210:213], v[26:29]
	v_mfma_f32_16x16x32_bf16 v[14:17], v[130:133], v[218:221], v[14:17]
	v_mfma_f32_16x16x32_bf16 v[10:13], v[138:141], v[218:221], v[10:13]
	v_mfma_f32_16x16x32_bf16 v[62:65], v[134:137], v[186:189], v[62:65]
	v_mfma_f32_16x16x32_bf16 v[58:61], v[142:145], v[186:189], v[58:61]
	v_mfma_f32_16x16x32_bf16 v[46:49], v[134:137], v[206:209], v[46:49]
	v_mfma_f32_16x16x32_bf16 v[42:45], v[142:145], v[206:209], v[42:45]
	v_mfma_f32_16x16x32_bf16 v[30:33], v[134:137], v[214:217], v[30:33]
	v_mfma_f32_16x16x32_bf16 v[26:29], v[142:145], v[214:217], v[26:29]
	v_mfma_f32_16x16x32_bf16 v[14:17], v[134:137], v[222:225], v[14:17]
	v_mfma_f32_16x16x32_bf16 v[10:13], v[142:145], v[222:225], v[10:13]
	v_mfma_f32_16x16x32_bf16 v[54:57], v[166:169], v[182:185], v[54:57]
	v_mfma_f32_16x16x32_bf16 v[50:53], v[174:177], v[182:185], v[50:53]
	v_mfma_f32_16x16x32_bf16 v[38:41], v[166:169], v[202:205], v[38:41]
	v_mfma_f32_16x16x32_bf16 v[34:37], v[174:177], v[202:205], v[34:37]
	v_mfma_f32_16x16x32_bf16 v[22:25], v[166:169], v[210:213], v[22:25]
	v_mfma_f32_16x16x32_bf16 v[18:21], v[174:177], v[210:213], v[18:21]
	v_mfma_f32_16x16x32_bf16 v[6:9], v[166:169], v[218:221], v[6:9]
	v_mfma_f32_16x16x32_bf16 v[2:5], v[174:177], v[218:221], v[2:5]
	v_mfma_f32_16x16x32_bf16 v[54:57], v[170:173], v[186:189], v[54:57]
	v_mfma_f32_16x16x32_bf16 v[50:53], v[178:181], v[186:189], v[50:53]
	v_mfma_f32_16x16x32_bf16 v[38:41], v[170:173], v[206:209], v[38:41]
	v_mfma_f32_16x16x32_bf16 v[34:37], v[178:181], v[206:209], v[34:37]
	v_mfma_f32_16x16x32_bf16 v[22:25], v[170:173], v[214:217], v[22:25]
	v_mfma_f32_16x16x32_bf16 v[18:21], v[178:181], v[214:217], v[18:21]
	v_mfma_f32_16x16x32_bf16 v[6:9], v[170:173], v[222:225], v[6:9]
	v_mfma_f32_16x16x32_bf16 v[2:5], v[178:181], v[222:225], v[2:5]
	s_barrier
	s_add_i32 s25, s25, 2
	s_add_u32 s5, s5, 0x100
	s_addc_u32 s24, s24, 0
	s_cmpk_lt_u32 s25, 0x56
	s_mov_b64 s[18:19], s[20:21]
	s_cbranch_scc1 .LBB0_1926
	s_setprio 0
	s_andn2_b64 vcc, exec, s[14:15]
	s_cbranch_vccnz .LBB0_1929
	s_barrier

; #define PG8_STAGE(bufoff, gbase, voff) do { _Pragma("unroll") for (int _i = 0; _i < 2; ++_i) \
;         __builtin_amdgcn_global_load_lds((const unsigned*)((const char*)(gbase) + (voff)[_i]), (LAS unsigned*)(lds + (bufoff) + ldsw + _i * 8192), 16, 0, 0); } while (0)
; #define PG8_LDA(dst, b, h) do { _Pragma("unroll") for (int m = 0; m < 4; ++m) _Pragma("unroll") for (int k = 0; k < 2; ++k) dst[m][k] = *(const LAS bf16x8*)(lds + PG8_SA(b, h) + aoff + m * 2048 + k * 1024); } while (0)
; #define PG8_LDB(dst, b, h) do { _Pragma("unroll") for (int n = 0; n < 2; ++n) _Pragma("unroll") for (int k = 0; k < 2; ++k) dst[n][k] = *(const LAS bf16x8*)(lds + PG8_SB(b, h) + boff + n * 2048 + k * 1024); } while (0)
; #define PG8_MMA(ai, bj, At, Bt) do { __builtin_amdgcn_s_setprio(1); _Pragma("unroll") for (int m = 0; m < 4; ++m) _Pragma("unroll") for (int n = 0; n < 2; ++n) _Pragma("unroll") for (int k = 0; k < 2; ++k) \
;         acc[ai][bj][m][n] = __builtin_amdgcn_mfma_f32_16x16x32_bf16(Bt[n][k], At[m][k], acc[ai][bj][m][n], 0, 0, 0); __builtin_amdgcn_s_setprio(0); } while (0)
; #define PG8_WAIT_V(n) asm volatile("s_waitcnt vmcnt(" #n ")" ::: "memory")
; #define PG8_WAIT_L(n) asm volatile("s_waitcnt lgkmcnt(" #n ")" ::: "memory")
; template <class Epi, class Sched, bool ALIGN_EPI = false, bool SP2 = false>
; __device__ __forceinline__ void gemm_phase(LAS unsigned char* lds, const Gemm g, const Sched& S, const Epi& E) {
;     ...
;         for (int t = 0; t < nt; t += 2) {
;             const bool last = (t == nt - 2);
;             const char* a1 = cA + (size_t)(t + 1) * kstep;
;             const char* a2 = last ? nA : cA + (size_t)(t + 2) * kstep; const char* b2 = last ? nB : cB + (size_t)(t + 2) * kstep;
;             const char* a3 = a2 + kstep; const char* b3 = b2 + kstep;
;             if (last && has_next) S.a_ready(nxt);
;             if constexpr (SP2) {
;             PG8_LDB(B0, 0, 0); PG8_LDB(B1, 0, 1); PG8_SCHED; PG8_LDA(At, 0, 0); PG8_STAGE(PG8_SA(1, 1), a1 + hstep, voffA);
;             PG8_WAIT_V(8); PG8_WAIT_L(0); PG8_BAR; PG8_MMA(0, 0, At, B0); PG8_MMA(0, 1, At, B1); PG8_BAR; PG8_SCHED;
;             PG8_LDA(At, 0, 1); PG8_STAGE(PG8_SB(0, 0), b2, voffB); PG8_STAGE(PG8_SB(0, 1), b2 + hstepB, voffB); PG8_STAGE(PG8_SA(0, 0), a2, voffA);
;             PG8_WAIT_V(8); PG8_WAIT_L(0); PG8_BAR; PG8_MMA(1, 0, At, B0); PG8_MMA(1, 1, At, B1); PG8_BAR; PG8_SCHED;
.Lprio_2143:
	ds_read_b128 v[34:37], v202
	ds_read_b128 v[38:41], v202 offset:1024
	ds_read_b128 v[42:45], v202 offset:2048
	ds_read_b128 v[46:49], v202 offset:3072
	ds_read_b128 v[98:101], v203
	ds_read_b128 v[102:105], v203 offset:1024
	ds_read_b128 v[106:109], v203 offset:2048
	ds_read_b128 v[110:113], v203 offset:3072
	s_add_u32 s22, s20, 0xfff80080
	s_addc_u32 s23, s21, -1
	s_cmp_eq_u32 s34, 28
	s_cselect_b32 s37, s3, s23
	s_cselect_b32 s36, s13, s22
	s_cselect_b32 s23, s11, s25
	s_cselect_b32 s22, s19, s24
	s_add_i32 m0, s28, 0xc000
	ds_read_b128 v[210:213], v204
	ds_read_b128 v[214:217], v204 offset:1024
	ds_read_b128 v[218:221], v204 offset:2048
	ds_read_b128 v[222:225], v204 offset:3072
	ds_read_b128 v[226:229], v204 offset:4096
	ds_read_b128 v[230:233], v204 offset:5120
	ds_read_b128 v[234:237], v204 offset:6144
	ds_read_b128 v[238:241], v204 offset:7168
	global_load_lds_dwordx4 v174, s[20:21]
	s_add_i32 m0, s28, 0xe000
	s_nop 0
	global_load_lds_dwordx4 v172, s[20:21]
	s_waitcnt lgkmcnt(0)
	s_barrier
	s_waitcnt lgkmcnt(0)
	v_mfma_f32_16x16x32_bf16 v[158:161], v[34:37], v[210:213], 0
	v_mfma_f32_16x16x32_bf16 v[154:157], v[42:45], v[210:213], 0
	v_mfma_f32_16x16x32_bf16 v[142:145], v[34:37], v[218:221], 0
	v_mfma_f32_16x16x32_bf16 v[138:141], v[42:45], v[218:221], 0
	v_mfma_f32_16x16x32_bf16 v[126:129], v[34:37], v[226:229], 0
	v_mfma_f32_16x16x32_bf16 v[122:125], v[42:45], v[226:229], 0
	v_mfma_f32_16x16x32_bf16 v[94:97], v[34:37], v[234:237], 0
	v_mfma_f32_16x16x32_bf16 v[90:93], v[42:45], v[234:237], 0
	v_mfma_f32_16x16x32_bf16 v[158:161], v[38:41], v[214:217], v[158:161]
	v_mfma_f32_16x16x32_bf16 v[154:157], v[46:49], v[214:217], v[154:157]
	v_mfma_f32_16x16x32_bf16 v[142:145], v[38:41], v[222:225], v[142:145]
	v_mfma_f32_16x16x32_bf16 v[138:141], v[46:49], v[222:225], v[138:141]
	v_mfma_f32_16x16x32_bf16 v[126:129], v[38:41], v[230:233], v[126:129]
	v_mfma_f32_16x16x32_bf16 v[122:125], v[46:49], v[230:233], v[122:125]
	v_mfma_f32_16x16x32_bf16 v[94:97], v[38:41], v[238:241], v[94:97]
	v_mfma_f32_16x16x32_bf16 v[90:93], v[46:49], v[238:241], v[90:93]
	v_mfma_f32_16x16x32_bf16 v[150:153], v[98:101], v[210:213], 0
	v_mfma_f32_16x16x32_bf16 v[146:149], v[106:109], v[210:213], 0
	v_mfma_f32_16x16x32_bf16 v[134:137], v[98:101], v[218:221], 0
	v_mfma_f32_16x16x32_bf16 v[130:133], v[106:109], v[218:221], 0
	v_mfma_f32_16x16x32_bf16 v[118:121], v[98:101], v[226:229], 0
	v_mfma_f32_16x16x32_bf16 v[114:117], v[106:109], v[226:229], 0
	v_mfma_f32_16x16x32_bf16 v[86:89], v[98:101], v[234:237], 0
	v_mfma_f32_16x16x32_bf16 v[82:85], v[106:109], v[234:237], 0
	v_mfma_f32_16x16x32_bf16 v[150:153], v[102:105], v[214:217], v[150:153]
	v_mfma_f32_16x16x32_bf16 v[146:149], v[110:113], v[214:217], v[146:149]
	v_mfma_f32_16x16x32_bf16 v[134:137], v[102:105], v[222:225], v[134:137]
	v_mfma_f32_16x16x32_bf16 v[130:133], v[110:113], v[222:225], v[130:133]
	v_mfma_f32_16x16x32_bf16 v[118:121], v[102:105], v[230:233], v[118:121]
	v_mfma_f32_16x16x32_bf16 v[114:117], v[110:113], v[230:233], v[114:117]
	v_mfma_f32_16x16x32_bf16 v[86:89], v[102:105], v[238:241], v[86:89]
	v_mfma_f32_16x16x32_bf16 v[82:85], v[110:113], v[238:241], v[82:85]
	s_barrier
	s_add_i32 s35, s56, s27
	s_mov_b32 m0, s35
	ds_read_b128 v[210:213], v204 offset:16384
	ds_read_b128 v[214:217], v204 offset:17408
	ds_read_b128 v[218:221], v204 offset:18432
	ds_read_b128 v[222:225], v204 offset:19456
	ds_read_b128 v[226:229], v204 offset:20480
	ds_read_b128 v[230:233], v204 offset:21504
	ds_read_b128 v[234:237], v204 offset:22528
	ds_read_b128 v[238:241], v204 offset:23552
	global_load_lds_dwordx4 v164, s[22:23]
	s_add_i32 m0, s35, 0x2000
	s_add_u32 s46, s22, 0x20000
	v_lshl_add_u64 v[242:243], s[22:23], 0, v[168:169]
	s_addc_u32 s47, s23, 0
	s_add_i32 s35, s57, s27
	global_load_lds_dwordx4 v168, s[22:23]
	s_mov_b32 m0, s35
	v_lshl_add_u64 v[246:247], s[36:37], 0, v[166:167]
	global_load_lds_dwordx4 v164, s[46:47]
	s_add_i32 m0, s35, 0x2000
	s_nop 0
	global_load_lds_dwordx4 v168, s[46:47]
	v_lshl_add_u64 v[244:245], s[36:37], 0, v[162:163]
	s_mov_b32 m0, s28
	s_nop 0
	global_load_lds_dwordx4 v162, s[36:37]
	s_mov_b32 m0, s29
	s_nop 0
	global_load_lds_dwordx4 v166, s[36:37]
	s_waitcnt lgkmcnt(0)
	s_barrier
	s_waitcnt lgkmcnt(0)
	v_mfma_f32_16x16x32_bf16 v[78:81], v[34:37], v[210:213], 0
	v_mfma_f32_16x16x32_bf16 v[74:77], v[42:45], v[210:213], 0
	v_mfma_f32_16x16x32_bf16 v[62:65], v[34:37], v[218:221], 0
	v_mfma_f32_16x16x32_bf16 v[58:61], v[42:45], v[218:221], 0
	v_mfma_f32_16x16x32_bf16 v[30:33], v[34:37], v[226:229], 0
	v_mfma_f32_16x16x32_bf16 v[26:29], v[42:45], v[226:229], 0
	v_mfma_f32_16x16x32_bf16 v[14:17], v[34:37], v[234:237], 0
	v_mfma_f32_16x16x32_bf16 v[10:13], v[42:45], v[234:237], 0
	v_mfma_f32_16x16x32_bf16 v[78:81], v[38:41], v[214:217], v[78:81]
	v_mfma_f32_16x16x32_bf16 v[74:77], v[46:49], v[214:217], v[74:77]
	v_mfma_f32_16x16x32_bf16 v[62:65], v[38:41], v[222:225], v[62:65]
	v_mfma_f32_16x16x32_bf16 v[58:61], v[46:49], v[222:225], v[58:61]
	v_mfma_f32_16x16x32_bf16 v[30:33], v[38:41], v[230:233], v[30:33]
	v_mfma_f32_16x16x32_bf16 v[26:29], v[46:49], v[230:233], v[26:29]
	v_mfma_f32_16x16x32_bf16 v[14:17], v[38:41], v[238:241], v[14:17]
	v_mfma_f32_16x16x32_bf16 v[10:13], v[46:49], v[238:241], v[10:13]
	v_mfma_f32_16x16x32_bf16 v[22:25], v[98:101], v[226:229], 0
	v_mfma_f32_16x16x32_bf16 v[18:21], v[106:109], v[226:229], 0
	v_mfma_f32_16x16x32_bf16 v[6:9], v[98:101], v[234:237], 0
	v_mfma_f32_16x16x32_bf16 v[2:5], v[106:109], v[234:237], 0
	v_mfma_f32_16x16x32_bf16 v[34:37], v[98:101], v[210:213], 0
	v_mfma_f32_16x16x32_bf16 v[38:41], v[106:109], v[210:213], 0
	v_mfma_f32_16x16x32_bf16 v[42:45], v[98:101], v[218:221], 0
	v_mfma_f32_16x16x32_bf16 v[46:49], v[106:109], v[218:221], 0
	v_mfma_f32_16x16x32_bf16 v[22:25], v[102:105], v[230:233], v[22:25]
	v_mfma_f32_16x16x32_bf16 v[18:21], v[110:113], v[230:233], v[18:21]
	v_mfma_f32_16x16x32_bf16 v[6:9], v[102:105], v[238:241], v[6:9]
	v_mfma_f32_16x16x32_bf16 v[2:5], v[110:113], v[238:241], v[2:5]
	v_mfma_f32_16x16x32_bf16 v[34:37], v[102:105], v[214:217], v[34:37]
	v_mfma_f32_16x16x32_bf16 v[38:41], v[110:113], v[214:217], v[38:41]
	v_mfma_f32_16x16x32_bf16 v[42:45], v[102:105], v[222:225], v[42:45]
	v_mfma_f32_16x16x32_bf16 v[46:49], v[110:113], v[222:225], v[46:49]
	s_barrier
; #define PG8_STAGE(bufoff, gbase, voff) do { _Pragma("unroll") for (int _i = 0; _i < 2; ++_i) \
;         __builtin_amdgcn_global_load_lds((const unsigned*)((const char*)(gbase) + (voff)[_i]), (LAS unsigned*)(lds + (bufoff) + ldsw + _i * 8192), 16, 0, 0); } while (0)
; #define PG8_LDA(dst, b, h) do { _Pragma("unroll") for (int m = 0; m < 4; ++m) _Pragma("unroll") for (int k = 0; k < 2; ++k) dst[m][k] = *(const LAS bf16x8*)(lds + PG8_SA(b, h) + aoff + m * 2048 + k * 1024); } while (0)
; #define PG8_LDB(dst, b, h) do { _Pragma("unroll") for (int n = 0; n < 2; ++n) _Pragma("unroll") for (int k = 0; k < 2; ++k) dst[n][k] = *(const LAS bf16x8*)(lds + PG8_SB(b, h) + boff + n * 2048 + k * 1024); } while (0)
; #define PG8_MMA(ai, bj, At, Bt) do { __builtin_amdgcn_s_setprio(1); _Pragma("unroll") for (int m = 0; m < 4; ++m) _Pragma("unroll") for (int n = 0; n < 2; ++n) _Pragma("unroll") for (int k = 0; k < 2; ++k) \
;         acc[ai][bj][m][n] = __builtin_amdgcn_mfma_f32_16x16x32_bf16(Bt[n][k], At[m][k], acc[ai][bj][m][n], 0, 0, 0); __builtin_amdgcn_s_setprio(0); } while (0)
; #define PG8_WAIT_V(n) asm volatile("s_waitcnt vmcnt(" #n ")" ::: "memory")
; #define PG8_WAIT_L(n) asm volatile("s_waitcnt lgkmcnt(" #n ")" ::: "memory")
; #define PG8_BAR __builtin_amdgcn_s_barrier()
; #define PG8_SCHED __builtin_amdgcn_sched_barrier(0)
; template <class Epi, class Sched, bool ALIGN_EPI = false, bool SP2 = false>
; __device__ __forceinline__ void gemm_phase(LAS unsigned char* lds, const Gemm g, const Sched& S, const Epi& E) {
;     ...
;             PG8_LDB(B0, 1, 0); PG8_LDB(B1, 1, 1); PG8_SCHED; PG8_LDA(At, 1, 0); PG8_STAGE(PG8_SA(0, 1), a2 + hstep, voffA);
;             PG8_WAIT_V(8); PG8_WAIT_L(0); PG8_BAR; PG8_MMA(0, 0, At, B0); PG8_MMA(0, 1, At, B1); PG8_BAR; PG8_SCHED;
;             PG8_LDA(At, 1, 1); PG8_STAGE(PG8_SB(1, 0), b3, voffB); PG8_STAGE(PG8_SB(1, 1), b3 + hstepB, voffB); PG8_STAGE(PG8_SA(1, 0), a3, voffA);
;             PG8_WAIT_V(8); PG8_WAIT_L(0); PG8_BAR; PG8_MMA(1, 0, At, B0); PG8_MMA(1, 1, At, B1); PG8_BAR; PG8_SCHED;
	s_add_i32 s35, 0, 0x18000
	s_add_i32 s46, 0, 0x1c000
	v_add_u32_e32 v70, s35, v185
	v_add_u32_e32 v110, s46, v185
	ds_read_b128 v[50:53], v70
	ds_read_b128 v[54:57], v70 offset:1024
	ds_read_b128 v[66:69], v70 offset:2048
	ds_read_b128 v[70:73], v70 offset:3072
	ds_read_b128 v[98:101], v110
	ds_read_b128 v[102:105], v110 offset:1024
	ds_read_b128 v[106:109], v110 offset:2048
	ds_read_b128 v[110:113], v110 offset:3072
	s_add_u32 s36, s36, 0x80000
	s_addc_u32 s37, s37, 0
	s_mov_b32 m0, s30
	ds_read_b128 v[210:213], v204 offset:32768
	ds_read_b128 v[214:217], v204 offset:33792
	ds_read_b128 v[218:221], v204 offset:34816
	ds_read_b128 v[222:225], v204 offset:35840
	ds_read_b128 v[226:229], v204 offset:36864
	ds_read_b128 v[230:233], v204 offset:37888
	ds_read_b128 v[234:237], v204 offset:38912
	ds_read_b128 v[238:241], v204 offset:39936
	global_load_lds_dwordx4 v162, s[36:37]
	s_mov_b32 m0, s31
	s_nop 0
	global_load_lds_dwordx4 v166, s[36:37]
	s_waitcnt vmcnt(8)
	s_waitcnt lgkmcnt(0)
	s_barrier
	s_waitcnt lgkmcnt(0)
	v_mfma_f32_16x16x32_bf16 v[158:161], v[50:53], v[210:213], v[158:161]
	v_mfma_f32_16x16x32_bf16 v[154:157], v[66:69], v[210:213], v[154:157]
	v_mfma_f32_16x16x32_bf16 v[142:145], v[50:53], v[218:221], v[142:145]
	v_mfma_f32_16x16x32_bf16 v[138:141], v[66:69], v[218:221], v[138:141]
	v_mfma_f32_16x16x32_bf16 v[126:129], v[50:53], v[226:229], v[126:129]
	v_mfma_f32_16x16x32_bf16 v[122:125], v[66:69], v[226:229], v[122:125]
	v_mfma_f32_16x16x32_bf16 v[94:97], v[50:53], v[234:237], v[94:97]
	v_mfma_f32_16x16x32_bf16 v[90:93], v[66:69], v[234:237], v[90:93]
	v_mfma_f32_16x16x32_bf16 v[158:161], v[54:57], v[214:217], v[158:161]
	v_mfma_f32_16x16x32_bf16 v[154:157], v[70:73], v[214:217], v[154:157]
	v_mfma_f32_16x16x32_bf16 v[142:145], v[54:57], v[222:225], v[142:145]
	v_mfma_f32_16x16x32_bf16 v[138:141], v[70:73], v[222:225], v[138:141]
	v_mfma_f32_16x16x32_bf16 v[126:129], v[54:57], v[230:233], v[126:129]
	v_mfma_f32_16x16x32_bf16 v[122:125], v[70:73], v[230:233], v[122:125]
	v_mfma_f32_16x16x32_bf16 v[94:97], v[54:57], v[238:241], v[94:97]
	v_mfma_f32_16x16x32_bf16 v[90:93], v[70:73], v[238:241], v[90:93]
	v_mfma_f32_16x16x32_bf16 v[150:153], v[98:101], v[210:213], v[150:153]
	v_mfma_f32_16x16x32_bf16 v[146:149], v[106:109], v[210:213], v[146:149]
	v_mfma_f32_16x16x32_bf16 v[134:137], v[98:101], v[218:221], v[134:137]
	v_mfma_f32_16x16x32_bf16 v[130:133], v[106:109], v[218:221], v[130:133]
	v_mfma_f32_16x16x32_bf16 v[118:121], v[98:101], v[226:229], v[118:121]
	v_mfma_f32_16x16x32_bf16 v[114:117], v[106:109], v[226:229], v[114:117]
	v_mfma_f32_16x16x32_bf16 v[86:89], v[98:101], v[234:237], v[86:89]
	v_mfma_f32_16x16x32_bf16 v[82:85], v[106:109], v[234:237], v[82:85]
	v_mfma_f32_16x16x32_bf16 v[150:153], v[102:105], v[214:217], v[150:153]
	v_mfma_f32_16x16x32_bf16 v[146:149], v[110:113], v[214:217], v[146:149]
	v_mfma_f32_16x16x32_bf16 v[134:137], v[102:105], v[222:225], v[134:137]
	v_mfma_f32_16x16x32_bf16 v[130:133], v[110:113], v[222:225], v[130:133]
	v_mfma_f32_16x16x32_bf16 v[118:121], v[102:105], v[230:233], v[118:121]
	v_mfma_f32_16x16x32_bf16 v[114:117], v[110:113], v[230:233], v[114:117]
	v_mfma_f32_16x16x32_bf16 v[86:89], v[102:105], v[238:241], v[86:89]
	v_mfma_f32_16x16x32_bf16 v[82:85], v[110:113], v[238:241], v[82:85]
	s_barrier
	s_add_u32 s98, s22, 0x80
	s_addc_u32 s99, s23, 0
	s_add_i32 s35, s35, s27
	s_mov_b32 m0, s35
	ds_read_b128 v[210:213], v204 offset:49152
	ds_read_b128 v[214:217], v204 offset:50176
	ds_read_b128 v[218:221], v204 offset:51200
	ds_read_b128 v[222:225], v204 offset:52224
	ds_read_b128 v[226:229], v204 offset:53248
	ds_read_b128 v[230:233], v204 offset:54272
	ds_read_b128 v[234:237], v204 offset:55296
	ds_read_b128 v[238:241], v204 offset:56320
	global_load_lds_dwordx4 v164, s[98:99]
	s_add_i32 m0, s35, 0x2000
	s_add_u32 s22, s22, 0x20080
	v_lshl_add_u64 v[182:183], v[242:243], 0, s[4:5]
	s_addc_u32 s23, s23, 0
	s_add_i32 s35, s46, s27
	global_load_lds_dwordx4 v[182:183], off
	s_mov_b32 m0, s35
	s_nop 0
	global_load_lds_dwordx4 v164, s[22:23]
	s_add_i32 m0, s35, 0x2000
	s_nop 0
	global_load_lds_dwordx4 v168, s[22:23]
	v_lshl_add_u64 v[182:183], v[244:245], 0, s[4:5]
	s_mov_b32 m0, s53
	s_nop 0
	global_load_lds_dwordx4 v[182:183], off
	v_lshl_add_u64 v[182:183], v[246:247], 0, s[4:5]
	s_mov_b32 m0, s54
	s_nop 0
	global_load_lds_dwordx4 v[182:183], off
	s_waitcnt vmcnt(8)
	s_waitcnt lgkmcnt(0)
	s_barrier
	s_waitcnt lgkmcnt(0)
	v_mfma_f32_16x16x32_bf16 v[78:81], v[50:53], v[210:213], v[78:81]
	v_mfma_f32_16x16x32_bf16 v[74:77], v[66:69], v[210:213], v[74:77]
	v_mfma_f32_16x16x32_bf16 v[62:65], v[50:53], v[218:221], v[62:65]
	v_mfma_f32_16x16x32_bf16 v[58:61], v[66:69], v[218:221], v[58:61]
	v_mfma_f32_16x16x32_bf16 v[30:33], v[50:53], v[226:229], v[30:33]
	v_mfma_f32_16x16x32_bf16 v[26:29], v[66:69], v[226:229], v[26:29]
	v_mfma_f32_16x16x32_bf16 v[14:17], v[50:53], v[234:237], v[14:17]
	v_mfma_f32_16x16x32_bf16 v[10:13], v[66:69], v[234:237], v[10:13]
	v_mfma_f32_16x16x32_bf16 v[78:81], v[54:57], v[214:217], v[78:81]
	v_mfma_f32_16x16x32_bf16 v[74:77], v[70:73], v[214:217], v[74:77]
	v_mfma_f32_16x16x32_bf16 v[62:65], v[54:57], v[222:225], v[62:65]
	v_mfma_f32_16x16x32_bf16 v[58:61], v[70:73], v[222:225], v[58:61]
	v_mfma_f32_16x16x32_bf16 v[30:33], v[54:57], v[230:233], v[30:33]
	v_mfma_f32_16x16x32_bf16 v[26:29], v[70:73], v[230:233], v[26:29]
	v_mfma_f32_16x16x32_bf16 v[14:17], v[54:57], v[238:241], v[14:17]
	v_mfma_f32_16x16x32_bf16 v[10:13], v[70:73], v[238:241], v[10:13]
	v_mfma_f32_16x16x32_bf16 v[34:37], v[98:101], v[210:213], v[34:37]
	v_mfma_f32_16x16x32_bf16 v[70:73], v[102:105], v[214:217], v[34:37]
	v_mfma_f32_16x16x32_bf16 v[34:37], v[106:109], v[210:213], v[38:41]
	v_mfma_f32_16x16x32_bf16 v[66:69], v[110:113], v[214:217], v[34:37]
	v_mfma_f32_16x16x32_bf16 v[34:37], v[98:101], v[218:221], v[42:45]
	v_mfma_f32_16x16x32_bf16 v[54:57], v[102:105], v[222:225], v[34:37]
	v_mfma_f32_16x16x32_bf16 v[34:37], v[106:109], v[218:221], v[46:49]
	v_mfma_f32_16x16x32_bf16 v[22:25], v[98:101], v[226:229], v[22:25]
	v_mfma_f32_16x16x32_bf16 v[18:21], v[106:109], v[226:229], v[18:21]
	v_mfma_f32_16x16x32_bf16 v[6:9], v[98:101], v[234:237], v[6:9]
	v_mfma_f32_16x16x32_bf16 v[2:5], v[106:109], v[234:237], v[2:5]
	v_mfma_f32_16x16x32_bf16 v[50:53], v[110:113], v[222:225], v[34:37]
	v_mfma_f32_16x16x32_bf16 v[22:25], v[102:105], v[230:233], v[22:25]
	v_mfma_f32_16x16x32_bf16 v[18:21], v[110:113], v[230:233], v[18:21]
	v_mfma_f32_16x16x32_bf16 v[6:9], v[102:105], v[238:241], v[6:9]
	v_mfma_f32_16x16x32_bf16 v[2:5], v[110:113], v[238:241], v[2:5]
	s_barrier
	s_add_i32 s34, s34, 2
	s_add_u32 s24, s24, 0x100
	s_addc_u32 s25, s25, 0
	s_add_u32 s20, s20, 0x100
	s_addc_u32 s21, s21, 0
	s_cmp_lt_u32 s34, 30
; #define PG8_STAGE(bufoff, gbase, voff) do { _Pragma("unroll") for (int _i = 0; _i < 2; ++_i) \
;         __builtin_amdgcn_global_load_lds((const unsigned*)((const char*)(gbase) + (voff)[_i]), (LAS unsigned*)(lds + (bufoff) + ldsw + _i * 8192), 16, 0, 0); } while (0)
; #define PG8_LDA(dst, b, h) do { _Pragma("unroll") for (int m = 0; m < 4; ++m) _Pragma("unroll") for (int k = 0; k < 2; ++k) dst[m][k] = *(const LAS bf16x8*)(lds + PG8_SA(b, h) + aoff + m * 2048 + k * 1024); } while (0)
; #define PG8_LDB(dst, b, h) do { _Pragma("unroll") for (int n = 0; n < 2; ++n) _Pragma("unroll") for (int k = 0; k < 2; ++k) dst[n][k] = *(const LAS bf16x8*)(lds + PG8_SB(b, h) + boff + n * 2048 + k * 1024); } while (0)
; #define PG8_MMA(ai, bj, At, Bt) do { __builtin_amdgcn_s_setprio(1); _Pragma("unroll") for (int m = 0; m < 4; ++m) _Pragma("unroll") for (int n = 0; n < 2; ++n) _Pragma("unroll") for (int k = 0; k < 2; ++k) \
;         acc[ai][bj][m][n] = __builtin_amdgcn_mfma_f32_16x16x32_bf16(Bt[n][k], At[m][k], acc[ai][bj][m][n], 0, 0, 0); __builtin_amdgcn_s_setprio(0); } while (0)
; #define PG8_WAIT_V(n) asm volatile("s_waitcnt vmcnt(" #n ")" ::: "memory")
; #define PG8_WAIT_L(n) asm volatile("s_waitcnt lgkmcnt(" #n ")" ::: "memory")
; template <class Epi, class Sched, bool ALIGN_EPI = false, bool SP2 = false>
; __device__ __forceinline__ void gemm_phase(LAS unsigned char* lds, const Gemm g, const Sched& S, const Epi& E) {
;     ...
;         for (int t = 0; t < nt; t += 2) {
;             const bool last = (t == nt - 2);
;             const char* a1 = cA + (size_t)(t + 1) * kstep;
;             const char* a2 = last ? nA : cA + (size_t)(t + 2) * kstep; const char* b2 = last ? nB : cB + (size_t)(t + 2) * kstep;
;             const char* a3 = a2 + kstep; const char* b3 = b2 + kstep;
;             if (last && has_next) S.a_ready(nxt);
;             if constexpr (SP2) {
;             PG8_LDB(B0, 0, 0); PG8_LDB(B1, 0, 1); PG8_SCHED; PG8_LDA(At, 0, 0); PG8_STAGE(PG8_SA(1, 1), a1 + hstep, voffA);
;             PG8_WAIT_V(8); PG8_WAIT_L(0); PG8_BAR; PG8_MMA(0, 0, At, B0); PG8_MMA(0, 1, At, B1); PG8_BAR; PG8_SCHED;
;             PG8_LDA(At, 0, 1); PG8_STAGE(PG8_SB(0, 0), b2, voffB); PG8_STAGE(PG8_SB(0, 1), b2 + hstepB, voffB); PG8_STAGE(PG8_SA(0, 0), a2, voffA);
;             PG8_WAIT_V(8); PG8_WAIT_L(0); PG8_BAR; PG8_MMA(1, 0, At, B0); PG8_MMA(1, 1, At, B1); PG8_BAR; PG8_SCHED;
.LBB0_2143:
	ds_read_b128 v[34:37], v202
	ds_read_b128 v[38:41], v202 offset:1024
	ds_read_b128 v[42:45], v202 offset:2048
	ds_read_b128 v[46:49], v202 offset:3072
	ds_read_b128 v[98:101], v203
	ds_read_b128 v[102:105], v203 offset:1024
	ds_read_b128 v[106:109], v203 offset:2048
	ds_read_b128 v[110:113], v203 offset:3072
	s_add_u32 s22, s20, 0xfff80080
	s_addc_u32 s23, s21, -1
	s_cmp_eq_u32 s34, 28
	s_cselect_b32 s37, s3, s23
	s_cselect_b32 s36, s13, s22
	s_cselect_b32 s23, s11, s25
	s_cselect_b32 s22, s19, s24
	s_add_i32 m0, s28, 0xc000
	ds_read_b128 v[210:213], v204
	ds_read_b128 v[214:217], v204 offset:1024
	ds_read_b128 v[218:221], v204 offset:2048
	ds_read_b128 v[222:225], v204 offset:3072
	ds_read_b128 v[226:229], v204 offset:4096
	ds_read_b128 v[230:233], v204 offset:5120
	ds_read_b128 v[234:237], v204 offset:6144
	ds_read_b128 v[238:241], v204 offset:7168
	global_load_lds_dwordx4 v174, s[20:21]
	s_add_i32 m0, s28, 0xe000
	s_nop 0
	global_load_lds_dwordx4 v172, s[20:21]
	s_waitcnt vmcnt(8)
	s_waitcnt lgkmcnt(0)
	s_barrier
	s_waitcnt lgkmcnt(0)
	v_mfma_f32_16x16x32_bf16 v[158:161], v[34:37], v[210:213], v[158:161]
	v_mfma_f32_16x16x32_bf16 v[154:157], v[42:45], v[210:213], v[154:157]
	v_mfma_f32_16x16x32_bf16 v[142:145], v[34:37], v[218:221], v[142:145]
	v_mfma_f32_16x16x32_bf16 v[138:141], v[42:45], v[218:221], v[138:141]
	v_mfma_f32_16x16x32_bf16 v[126:129], v[34:37], v[226:229], v[126:129]
	v_mfma_f32_16x16x32_bf16 v[122:125], v[42:45], v[226:229], v[122:125]
	v_mfma_f32_16x16x32_bf16 v[94:97], v[34:37], v[234:237], v[94:97]
	v_mfma_f32_16x16x32_bf16 v[90:93], v[42:45], v[234:237], v[90:93]
	v_mfma_f32_16x16x32_bf16 v[158:161], v[38:41], v[214:217], v[158:161]
	v_mfma_f32_16x16x32_bf16 v[154:157], v[46:49], v[214:217], v[154:157]
	v_mfma_f32_16x16x32_bf16 v[142:145], v[38:41], v[222:225], v[142:145]
	v_mfma_f32_16x16x32_bf16 v[138:141], v[46:49], v[222:225], v[138:141]
	v_mfma_f32_16x16x32_bf16 v[126:129], v[38:41], v[230:233], v[126:129]
	v_mfma_f32_16x16x32_bf16 v[122:125], v[46:49], v[230:233], v[122:125]
	v_mfma_f32_16x16x32_bf16 v[94:97], v[38:41], v[238:241], v[94:97]
	v_mfma_f32_16x16x32_bf16 v[90:93], v[46:49], v[238:241], v[90:93]
	v_mfma_f32_16x16x32_bf16 v[150:153], v[98:101], v[210:213], v[150:153]
	v_mfma_f32_16x16x32_bf16 v[146:149], v[106:109], v[210:213], v[146:149]
	v_mfma_f32_16x16x32_bf16 v[134:137], v[98:101], v[218:221], v[134:137]
	v_mfma_f32_16x16x32_bf16 v[130:133], v[106:109], v[218:221], v[130:133]
	v_mfma_f32_16x16x32_bf16 v[118:121], v[98:101], v[226:229], v[118:121]
	v_mfma_f32_16x16x32_bf16 v[114:117], v[106:109], v[226:229], v[114:117]
	v_mfma_f32_16x16x32_bf16 v[86:89], v[98:101], v[234:237], v[86:89]
	v_mfma_f32_16x16x32_bf16 v[82:85], v[106:109], v[234:237], v[82:85]
	v_mfma_f32_16x16x32_bf16 v[150:153], v[102:105], v[214:217], v[150:153]
	v_mfma_f32_16x16x32_bf16 v[146:149], v[110:113], v[214:217], v[146:149]
	v_mfma_f32_16x16x32_bf16 v[134:137], v[102:105], v[222:225], v[134:137]
	v_mfma_f32_16x16x32_bf16 v[130:133], v[110:113], v[222:225], v[130:133]
	v_mfma_f32_16x16x32_bf16 v[118:121], v[102:105], v[230:233], v[118:121]
	v_mfma_f32_16x16x32_bf16 v[114:117], v[110:113], v[230:233], v[114:117]
	v_mfma_f32_16x16x32_bf16 v[86:89], v[102:105], v[238:241], v[86:89]
	v_mfma_f32_16x16x32_bf16 v[82:85], v[110:113], v[238:241], v[82:85]
	s_barrier
	s_add_i32 s35, s56, s27
	s_mov_b32 m0, s35
	ds_read_b128 v[210:213], v204 offset:16384
	ds_read_b128 v[214:217], v204 offset:17408
	ds_read_b128 v[218:221], v204 offset:18432
	ds_read_b128 v[222:225], v204 offset:19456
	ds_read_b128 v[226:229], v204 offset:20480
	ds_read_b128 v[230:233], v204 offset:21504
	ds_read_b128 v[234:237], v204 offset:22528
	ds_read_b128 v[238:241], v204 offset:23552
	global_load_lds_dwordx4 v164, s[22:23]
	s_add_i32 m0, s35, 0x2000
	s_add_u32 s46, s22, 0x20000
	v_lshl_add_u64 v[242:243], s[22:23], 0, v[168:169]
	s_addc_u32 s47, s23, 0
	s_add_i32 s35, s57, s27
	global_load_lds_dwordx4 v168, s[22:23]
	s_mov_b32 m0, s35
	v_lshl_add_u64 v[246:247], s[36:37], 0, v[166:167]
	global_load_lds_dwordx4 v164, s[46:47]
	s_add_i32 m0, s35, 0x2000
	s_nop 0
	global_load_lds_dwordx4 v168, s[46:47]
	v_lshl_add_u64 v[244:245], s[36:37], 0, v[162:163]
	s_mov_b32 m0, s28
	s_nop 0
	global_load_lds_dwordx4 v162, s[36:37]
	s_mov_b32 m0, s29
	s_nop 0
	global_load_lds_dwordx4 v166, s[36:37]
	s_waitcnt vmcnt(8)
	s_waitcnt lgkmcnt(0)
	s_barrier
	s_waitcnt lgkmcnt(0)
	v_mfma_f32_16x16x32_bf16 v[78:81], v[34:37], v[210:213], v[78:81]
	v_mfma_f32_16x16x32_bf16 v[74:77], v[42:45], v[210:213], v[74:77]
	v_mfma_f32_16x16x32_bf16 v[62:65], v[34:37], v[218:221], v[62:65]
	v_mfma_f32_16x16x32_bf16 v[58:61], v[42:45], v[218:221], v[58:61]
	v_mfma_f32_16x16x32_bf16 v[30:33], v[34:37], v[226:229], v[30:33]
	v_mfma_f32_16x16x32_bf16 v[26:29], v[42:45], v[226:229], v[26:29]
	v_mfma_f32_16x16x32_bf16 v[14:17], v[34:37], v[234:237], v[14:17]
	v_mfma_f32_16x16x32_bf16 v[10:13], v[42:45], v[234:237], v[10:13]
	v_mfma_f32_16x16x32_bf16 v[78:81], v[38:41], v[214:217], v[78:81]
	v_mfma_f32_16x16x32_bf16 v[74:77], v[46:49], v[214:217], v[74:77]
	v_mfma_f32_16x16x32_bf16 v[62:65], v[38:41], v[222:225], v[62:65]
	v_mfma_f32_16x16x32_bf16 v[58:61], v[46:49], v[222:225], v[58:61]
	v_mfma_f32_16x16x32_bf16 v[30:33], v[38:41], v[230:233], v[30:33]
	v_mfma_f32_16x16x32_bf16 v[26:29], v[46:49], v[230:233], v[26:29]
	v_mfma_f32_16x16x32_bf16 v[14:17], v[38:41], v[238:241], v[14:17]
	v_mfma_f32_16x16x32_bf16 v[10:13], v[46:49], v[238:241], v[10:13]
	v_mfma_f32_16x16x32_bf16 v[22:25], v[98:101], v[226:229], v[22:25]
	v_mfma_f32_16x16x32_bf16 v[18:21], v[106:109], v[226:229], v[18:21]
	v_mfma_f32_16x16x32_bf16 v[6:9], v[98:101], v[234:237], v[6:9]
	v_mfma_f32_16x16x32_bf16 v[2:5], v[106:109], v[234:237], v[2:5]
	v_mfma_f32_16x16x32_bf16 v[34:37], v[98:101], v[210:213], v[70:73]
	v_mfma_f32_16x16x32_bf16 v[38:41], v[106:109], v[210:213], v[66:69]
	v_mfma_f32_16x16x32_bf16 v[42:45], v[98:101], v[218:221], v[54:57]
	v_mfma_f32_16x16x32_bf16 v[46:49], v[106:109], v[218:221], v[50:53]
	v_mfma_f32_16x16x32_bf16 v[22:25], v[102:105], v[230:233], v[22:25]
	v_mfma_f32_16x16x32_bf16 v[18:21], v[110:113], v[230:233], v[18:21]
	v_mfma_f32_16x16x32_bf16 v[6:9], v[102:105], v[238:241], v[6:9]
	v_mfma_f32_16x16x32_bf16 v[2:5], v[110:113], v[238:241], v[2:5]
	v_mfma_f32_16x16x32_bf16 v[34:37], v[102:105], v[214:217], v[34:37]
	v_mfma_f32_16x16x32_bf16 v[38:41], v[110:113], v[214:217], v[38:41]
	v_mfma_f32_16x16x32_bf16 v[42:45], v[102:105], v[222:225], v[42:45]
	v_mfma_f32_16x16x32_bf16 v[46:49], v[110:113], v[222:225], v[46:49]
	s_barrier
; #define PG8_STAGE(bufoff, gbase, voff) do { _Pragma("unroll") for (int _i = 0; _i < 2; ++_i) \
;         __builtin_amdgcn_global_load_lds((const unsigned*)((const char*)(gbase) + (voff)[_i]), (LAS unsigned*)(lds + (bufoff) + ldsw + _i * 8192), 16, 0, 0); } while (0)
; #define PG8_LDA(dst, b, h) do { _Pragma("unroll") for (int m = 0; m < 4; ++m) _Pragma("unroll") for (int k = 0; k < 2; ++k) dst[m][k] = *(const LAS bf16x8*)(lds + PG8_SA(b, h) + aoff + m * 2048 + k * 1024); } while (0)
; #define PG8_LDB(dst, b, h) do { _Pragma("unroll") for (int n = 0; n < 2; ++n) _Pragma("unroll") for (int k = 0; k < 2; ++k) dst[n][k] = *(const LAS bf16x8*)(lds + PG8_SB(b, h) + boff + n * 2048 + k * 1024); } while (0)
; #define PG8_MMA(ai, bj, At, Bt) do { __builtin_amdgcn_s_setprio(1); _Pragma("unroll") for (int m = 0; m < 4; ++m) _Pragma("unroll") for (int n = 0; n < 2; ++n) _Pragma("unroll") for (int k = 0; k < 2; ++k) \
;         acc[ai][bj][m][n] = __builtin_amdgcn_mfma_f32_16x16x32_bf16(Bt[n][k], At[m][k], acc[ai][bj][m][n], 0, 0, 0); __builtin_amdgcn_s_setprio(0); } while (0)
; #define PG8_WAIT_V(n) asm volatile("s_waitcnt vmcnt(" #n ")" ::: "memory")
; #define PG8_WAIT_L(n) asm volatile("s_waitcnt lgkmcnt(" #n ")" ::: "memory")
; #define PG8_BAR __builtin_amdgcn_s_barrier()
; #define PG8_SCHED __builtin_amdgcn_sched_barrier(0)
; template <class Epi, class Sched, bool ALIGN_EPI = false, bool SP2 = false>
; __device__ __forceinline__ void gemm_phase(LAS unsigned char* lds, const Gemm g, const Sched& S, const Epi& E) {
;     ...
;         for (int t = 0; t < nt; t += 2) {
;     ...
;             PG8_LDB(B0, 1, 0); PG8_LDB(B1, 1, 1); PG8_SCHED; PG8_LDA(At, 1, 0); PG8_STAGE(PG8_SA(0, 1), a2 + hstep, voffA);
;             PG8_WAIT_V(8); PG8_WAIT_L(0); PG8_BAR; PG8_MMA(0, 0, At, B0); PG8_MMA(0, 1, At, B1); PG8_BAR; PG8_SCHED;
;             PG8_LDA(At, 1, 1); PG8_STAGE(PG8_SB(1, 0), b3, voffB); PG8_STAGE(PG8_SB(1, 1), b3 + hstepB, voffB); PG8_STAGE(PG8_SA(1, 0), a3, voffA);
;             PG8_WAIT_V(8); PG8_WAIT_L(0); PG8_BAR; PG8_MMA(1, 0, At, B0); PG8_MMA(1, 1, At, B1); PG8_BAR; PG8_SCHED;
	s_add_i32 s35, 0, 0x18000
	s_add_i32 s46, 0, 0x1c000
	v_add_u32_e32 v70, s35, v185
	v_add_u32_e32 v110, s46, v185
	ds_read_b128 v[50:53], v70
	ds_read_b128 v[54:57], v70 offset:1024
	ds_read_b128 v[66:69], v70 offset:2048
	ds_read_b128 v[70:73], v70 offset:3072
	ds_read_b128 v[98:101], v110
	ds_read_b128 v[102:105], v110 offset:1024
	ds_read_b128 v[106:109], v110 offset:2048
	ds_read_b128 v[110:113], v110 offset:3072
	s_add_u32 s36, s36, 0x80000
	s_addc_u32 s37, s37, 0
	s_mov_b32 m0, s30
	ds_read_b128 v[210:213], v204 offset:32768
	ds_read_b128 v[214:217], v204 offset:33792
	ds_read_b128 v[218:221], v204 offset:34816
	ds_read_b128 v[222:225], v204 offset:35840
	ds_read_b128 v[226:229], v204 offset:36864
	ds_read_b128 v[230:233], v204 offset:37888
	ds_read_b128 v[234:237], v204 offset:38912
	ds_read_b128 v[238:241], v204 offset:39936
	global_load_lds_dwordx4 v162, s[36:37]
	s_mov_b32 m0, s31
	s_nop 0
	global_load_lds_dwordx4 v166, s[36:37]
	s_waitcnt vmcnt(8)
	s_waitcnt lgkmcnt(0)
	s_barrier
	s_waitcnt lgkmcnt(0)
	v_mfma_f32_16x16x32_bf16 v[158:161], v[50:53], v[210:213], v[158:161]
	v_mfma_f32_16x16x32_bf16 v[154:157], v[66:69], v[210:213], v[154:157]
	v_mfma_f32_16x16x32_bf16 v[142:145], v[50:53], v[218:221], v[142:145]
	v_mfma_f32_16x16x32_bf16 v[138:141], v[66:69], v[218:221], v[138:141]
	v_mfma_f32_16x16x32_bf16 v[126:129], v[50:53], v[226:229], v[126:129]
	v_mfma_f32_16x16x32_bf16 v[122:125], v[66:69], v[226:229], v[122:125]
	v_mfma_f32_16x16x32_bf16 v[94:97], v[50:53], v[234:237], v[94:97]
	v_mfma_f32_16x16x32_bf16 v[90:93], v[66:69], v[234:237], v[90:93]
	v_mfma_f32_16x16x32_bf16 v[158:161], v[54:57], v[214:217], v[158:161]
	v_mfma_f32_16x16x32_bf16 v[154:157], v[70:73], v[214:217], v[154:157]
	v_mfma_f32_16x16x32_bf16 v[142:145], v[54:57], v[222:225], v[142:145]
	v_mfma_f32_16x16x32_bf16 v[138:141], v[70:73], v[222:225], v[138:141]
	v_mfma_f32_16x16x32_bf16 v[126:129], v[54:57], v[230:233], v[126:129]
	v_mfma_f32_16x16x32_bf16 v[122:125], v[70:73], v[230:233], v[122:125]
	v_mfma_f32_16x16x32_bf16 v[94:97], v[54:57], v[238:241], v[94:97]
	v_mfma_f32_16x16x32_bf16 v[90:93], v[70:73], v[238:241], v[90:93]
	v_mfma_f32_16x16x32_bf16 v[150:153], v[98:101], v[210:213], v[150:153]
	v_mfma_f32_16x16x32_bf16 v[146:149], v[106:109], v[210:213], v[146:149]
	v_mfma_f32_16x16x32_bf16 v[134:137], v[98:101], v[218:221], v[134:137]
	v_mfma_f32_16x16x32_bf16 v[130:133], v[106:109], v[218:221], v[130:133]
	v_mfma_f32_16x16x32_bf16 v[118:121], v[98:101], v[226:229], v[118:121]
	v_mfma_f32_16x16x32_bf16 v[114:117], v[106:109], v[226:229], v[114:117]
	v_mfma_f32_16x16x32_bf16 v[86:89], v[98:101], v[234:237], v[86:89]
	v_mfma_f32_16x16x32_bf16 v[82:85], v[106:109], v[234:237], v[82:85]
	v_mfma_f32_16x16x32_bf16 v[150:153], v[102:105], v[214:217], v[150:153]
	v_mfma_f32_16x16x32_bf16 v[146:149], v[110:113], v[214:217], v[146:149]
	v_mfma_f32_16x16x32_bf16 v[134:137], v[102:105], v[222:225], v[134:137]
	v_mfma_f32_16x16x32_bf16 v[130:133], v[110:113], v[222:225], v[130:133]
	v_mfma_f32_16x16x32_bf16 v[118:121], v[102:105], v[230:233], v[118:121]
	v_mfma_f32_16x16x32_bf16 v[114:117], v[110:113], v[230:233], v[114:117]
	v_mfma_f32_16x16x32_bf16 v[86:89], v[102:105], v[238:241], v[86:89]
	v_mfma_f32_16x16x32_bf16 v[82:85], v[110:113], v[238:241], v[82:85]
	s_barrier
	s_add_u32 s98, s22, 0x80
	s_addc_u32 s99, s23, 0
	s_add_i32 s35, s35, s27
	s_mov_b32 m0, s35
	ds_read_b128 v[210:213], v204 offset:49152
	ds_read_b128 v[214:217], v204 offset:50176
	ds_read_b128 v[218:221], v204 offset:51200
	ds_read_b128 v[222:225], v204 offset:52224
	ds_read_b128 v[226:229], v204 offset:53248
	ds_read_b128 v[230:233], v204 offset:54272
	ds_read_b128 v[234:237], v204 offset:55296
	ds_read_b128 v[238:241], v204 offset:56320
	global_load_lds_dwordx4 v164, s[98:99]
	s_add_i32 m0, s35, 0x2000
	s_add_u32 s22, s22, 0x20080
	v_lshl_add_u64 v[182:183], v[242:243], 0, s[4:5]
	s_addc_u32 s23, s23, 0
	s_add_i32 s35, s46, s27
	global_load_lds_dwordx4 v[182:183], off
	s_mov_b32 m0, s35
	s_nop 0
	global_load_lds_dwordx4 v164, s[22:23]
	s_add_i32 m0, s35, 0x2000
	s_nop 0
	global_load_lds_dwordx4 v168, s[22:23]
	v_lshl_add_u64 v[182:183], v[244:245], 0, s[4:5]
	s_mov_b32 m0, s53
	s_nop 0
	global_load_lds_dwordx4 v[182:183], off
	v_lshl_add_u64 v[182:183], v[246:247], 0, s[4:5]
	s_mov_b32 m0, s54
	s_nop 0
	global_load_lds_dwordx4 v[182:183], off
	s_waitcnt vmcnt(8)
	s_waitcnt lgkmcnt(0)
	s_barrier
	s_waitcnt lgkmcnt(0)
	v_mfma_f32_16x16x32_bf16 v[78:81], v[50:53], v[210:213], v[78:81]
	v_mfma_f32_16x16x32_bf16 v[74:77], v[66:69], v[210:213], v[74:77]
	v_mfma_f32_16x16x32_bf16 v[62:65], v[50:53], v[218:221], v[62:65]
	v_mfma_f32_16x16x32_bf16 v[58:61], v[66:69], v[218:221], v[58:61]
	v_mfma_f32_16x16x32_bf16 v[30:33], v[50:53], v[226:229], v[30:33]
	v_mfma_f32_16x16x32_bf16 v[26:29], v[66:69], v[226:229], v[26:29]
	v_mfma_f32_16x16x32_bf16 v[14:17], v[50:53], v[234:237], v[14:17]
	v_mfma_f32_16x16x32_bf16 v[10:13], v[66:69], v[234:237], v[10:13]
	v_mfma_f32_16x16x32_bf16 v[78:81], v[54:57], v[214:217], v[78:81]
	v_mfma_f32_16x16x32_bf16 v[74:77], v[70:73], v[214:217], v[74:77]
	v_mfma_f32_16x16x32_bf16 v[62:65], v[54:57], v[222:225], v[62:65]
	v_mfma_f32_16x16x32_bf16 v[58:61], v[70:73], v[222:225], v[58:61]
	v_mfma_f32_16x16x32_bf16 v[30:33], v[54:57], v[230:233], v[30:33]
	v_mfma_f32_16x16x32_bf16 v[26:29], v[70:73], v[230:233], v[26:29]
	v_mfma_f32_16x16x32_bf16 v[14:17], v[54:57], v[238:241], v[14:17]
	v_mfma_f32_16x16x32_bf16 v[10:13], v[70:73], v[238:241], v[10:13]
	v_mfma_f32_16x16x32_bf16 v[34:37], v[98:101], v[210:213], v[34:37]
	v_mfma_f32_16x16x32_bf16 v[70:73], v[102:105], v[214:217], v[34:37]
	v_mfma_f32_16x16x32_bf16 v[34:37], v[106:109], v[210:213], v[38:41]
	v_mfma_f32_16x16x32_bf16 v[66:69], v[110:113], v[214:217], v[34:37]
	v_mfma_f32_16x16x32_bf16 v[34:37], v[98:101], v[218:221], v[42:45]
	v_mfma_f32_16x16x32_bf16 v[54:57], v[102:105], v[222:225], v[34:37]
	v_mfma_f32_16x16x32_bf16 v[34:37], v[106:109], v[218:221], v[46:49]
	v_mfma_f32_16x16x32_bf16 v[22:25], v[98:101], v[226:229], v[22:25]
	v_mfma_f32_16x16x32_bf16 v[18:21], v[106:109], v[226:229], v[18:21]
	v_mfma_f32_16x16x32_bf16 v[6:9], v[98:101], v[234:237], v[6:9]
	v_mfma_f32_16x16x32_bf16 v[2:5], v[106:109], v[234:237], v[2:5]
	v_mfma_f32_16x16x32_bf16 v[50:53], v[110:113], v[222:225], v[34:37]
	v_mfma_f32_16x16x32_bf16 v[22:25], v[102:105], v[230:233], v[22:25]
	v_mfma_f32_16x16x32_bf16 v[18:21], v[110:113], v[230:233], v[18:21]
	v_mfma_f32_16x16x32_bf16 v[6:9], v[102:105], v[238:241], v[6:9]
	v_mfma_f32_16x16x32_bf16 v[2:5], v[110:113], v[238:241], v[2:5]
	s_barrier
	s_add_i32 s34, s34, 2
	s_add_u32 s24, s24, 0x100
	s_addc_u32 s25, s25, 0
	s_add_u32 s20, s20, 0x100
	s_addc_u32 s21, s21, 0
	s_cmp_lt_u32 s34, 30
	s_cbranch_scc1 .LBB0_2143
	s_setprio 0
	s_andn2_b64 vcc, exec, s[8:9]
	s_cbranch_vccnz .LBB0_2146
	s_barrier

; #define PG8_STAGE(bufoff, gbase, voff) do { _Pragma("unroll") for (int _i = 0; _i < 2; ++_i) \
;         __builtin_amdgcn_global_load_lds((const unsigned*)((const char*)(gbase) + (voff)[_i]), (LAS unsigned*)(lds + (bufoff) + ldsw + _i * 8192), 16, 0, 0); } while (0)
; #define PG8_LDA(dst, b, h) do { _Pragma("unroll") for (int m = 0; m < 4; ++m) _Pragma("unroll") for (int k = 0; k < 2; ++k) dst[m][k] = *(const LAS bf16x8*)(lds + PG8_SA(b, h) + aoff + m * 2048 + k * 1024); } while (0)
; #define PG8_LDB(dst, b, h) do { _Pragma("unroll") for (int n = 0; n < 2; ++n) _Pragma("unroll") for (int k = 0; k < 2; ++k) dst[n][k] = *(const LAS bf16x8*)(lds + PG8_SB(b, h) + boff + n * 2048 + k * 1024); } while (0)
; #define PG8_MMA(ai, bj, At, Bt) do { __builtin_amdgcn_s_setprio(1); _Pragma("unroll") for (int m = 0; m < 4; ++m) _Pragma("unroll") for (int n = 0; n < 2; ++n) _Pragma("unroll") for (int k = 0; k < 2; ++k) \
;         acc[ai][bj][m][n] = __builtin_amdgcn_mfma_f32_16x16x32_bf16(Bt[n][k], At[m][k], acc[ai][bj][m][n], 0, 0, 0); __builtin_amdgcn_s_setprio(0); } while (0)
; #define PG8_WAIT_V(n) asm volatile("s_waitcnt vmcnt(" #n ")" ::: "memory")
; #define PG8_WAIT_L(n) asm volatile("s_waitcnt lgkmcnt(" #n ")" ::: "memory")
; template <class Epi, class Sched, bool ALIGN_EPI = false, bool SP2 = false>
; __device__ __forceinline__ void gemm_phase(LAS unsigned char* lds, const Gemm g, const Sched& S, const Epi& E) {
;     ...
;         for (int t = 0; t < nt; t += 2) {
;             const bool last = (t == nt - 2);
;             const char* a1 = cA + (size_t)(t + 1) * kstep;
;             const char* a2 = last ? nA : cA + (size_t)(t + 2) * kstep; const char* b2 = last ? nB : cB + (size_t)(t + 2) * kstep;
;             const char* a3 = a2 + kstep; const char* b3 = b2 + kstep;
;             if (last && has_next) S.a_ready(nxt);
;             if constexpr (SP2) {
;             PG8_LDB(B0, 0, 0); PG8_LDB(B1, 0, 1); PG8_SCHED; PG8_LDA(At, 0, 0); PG8_STAGE(PG8_SA(1, 1), a1 + hstep, voffA);
;             PG8_WAIT_V(8); PG8_WAIT_L(0); PG8_BAR; PG8_MMA(0, 0, At, B0); PG8_MMA(0, 1, At, B1); PG8_BAR; PG8_SCHED;
;             PG8_LDA(At, 0, 1); PG8_STAGE(PG8_SB(0, 0), b2, voffB); PG8_STAGE(PG8_SB(0, 1), b2 + hstepB, voffB); PG8_STAGE(PG8_SA(0, 0), a2, voffA);
;             PG8_WAIT_V(8); PG8_WAIT_L(0); PG8_BAR; PG8_MMA(1, 0, At, B0); PG8_MMA(1, 1, At, B1); PG8_BAR; PG8_SCHED;
.Lprio_2766:
	ds_read_b128 v[50:53], v196
	ds_read_b128 v[54:57], v196 offset:1024
	ds_read_b128 v[138:141], v196 offset:2048
	ds_read_b128 v[142:145], v196 offset:3072
	ds_read_b128 v[146:149], v197
	ds_read_b128 v[150:153], v197 offset:1024
	ds_read_b128 v[174:177], v197 offset:2048
	ds_read_b128 v[178:181], v197 offset:3072
	s_add_u32 s24, s22, 0xfff80080
	s_addc_u32 s25, s23, -1
	s_cmp_eq_u32 s55, 28
	s_cselect_b32 s35, s3, s25
	s_cselect_b32 s34, s15, s24
	s_cselect_b32 s25, s13, s54
	s_cselect_b32 s24, s21, s53
	s_add_i32 m0, s28, 0xc000
	ds_read_b128 v[182:185], v198
	ds_read_b128 v[186:189], v198 offset:1024
	ds_read_b128 v[202:205], v198 offset:2048
	ds_read_b128 v[206:209], v198 offset:3072
	ds_read_b128 v[210:213], v198 offset:4096
	ds_read_b128 v[214:217], v198 offset:5120
	ds_read_b128 v[218:221], v198 offset:6144
	ds_read_b128 v[222:225], v198 offset:7168
	global_load_lds_dwordx4 v168, s[22:23]
	s_add_i32 m0, s28, 0xe000
	s_nop 0
	global_load_lds_dwordx4 v166, s[22:23]
	s_waitcnt lgkmcnt(0)
	s_barrier
	s_waitcnt lgkmcnt(0)
	v_mfma_f32_16x16x32_bf16 v[134:137], v[50:53], v[182:185], 0
	v_mfma_f32_16x16x32_bf16 v[130:133], v[138:141], v[182:185], 0
	v_mfma_f32_16x16x32_bf16 v[118:121], v[50:53], v[202:205], 0
	v_mfma_f32_16x16x32_bf16 v[114:117], v[138:141], v[202:205], 0
	v_mfma_f32_16x16x32_bf16 v[102:105], v[50:53], v[210:213], 0
	v_mfma_f32_16x16x32_bf16 v[98:101], v[138:141], v[210:213], 0
	v_mfma_f32_16x16x32_bf16 v[86:89], v[50:53], v[218:221], 0
	v_mfma_f32_16x16x32_bf16 v[82:85], v[138:141], v[218:221], 0
	v_mfma_f32_16x16x32_bf16 v[134:137], v[54:57], v[186:189], v[134:137]
	v_mfma_f32_16x16x32_bf16 v[130:133], v[142:145], v[186:189], v[130:133]
	v_mfma_f32_16x16x32_bf16 v[118:121], v[54:57], v[206:209], v[118:121]
	v_mfma_f32_16x16x32_bf16 v[114:117], v[142:145], v[206:209], v[114:117]
	v_mfma_f32_16x16x32_bf16 v[102:105], v[54:57], v[214:217], v[102:105]
	v_mfma_f32_16x16x32_bf16 v[98:101], v[142:145], v[214:217], v[98:101]
	v_mfma_f32_16x16x32_bf16 v[86:89], v[54:57], v[222:225], v[86:89]
	v_mfma_f32_16x16x32_bf16 v[82:85], v[142:145], v[222:225], v[82:85]
	v_mfma_f32_16x16x32_bf16 v[126:129], v[146:149], v[182:185], 0
	v_mfma_f32_16x16x32_bf16 v[122:125], v[174:177], v[182:185], 0
	v_mfma_f32_16x16x32_bf16 v[110:113], v[146:149], v[202:205], 0
	v_mfma_f32_16x16x32_bf16 v[106:109], v[174:177], v[202:205], 0
	v_mfma_f32_16x16x32_bf16 v[94:97], v[146:149], v[210:213], 0
	v_mfma_f32_16x16x32_bf16 v[90:93], v[174:177], v[210:213], 0
	v_mfma_f32_16x16x32_bf16 v[78:81], v[146:149], v[218:221], 0
	v_mfma_f32_16x16x32_bf16 v[74:77], v[174:177], v[218:221], 0
	v_mfma_f32_16x16x32_bf16 v[126:129], v[150:153], v[186:189], v[126:129]
	v_mfma_f32_16x16x32_bf16 v[122:125], v[178:181], v[186:189], v[122:125]
	v_mfma_f32_16x16x32_bf16 v[110:113], v[150:153], v[206:209], v[110:113]
	v_mfma_f32_16x16x32_bf16 v[106:109], v[178:181], v[206:209], v[106:109]
	v_mfma_f32_16x16x32_bf16 v[94:97], v[150:153], v[214:217], v[94:97]
	v_mfma_f32_16x16x32_bf16 v[90:93], v[178:181], v[214:217], v[90:93]
	v_mfma_f32_16x16x32_bf16 v[78:81], v[150:153], v[222:225], v[78:81]
	v_mfma_f32_16x16x32_bf16 v[74:77], v[178:181], v[222:225], v[74:77]
	s_barrier
	s_add_i32 s56, s51, s27
	s_mov_b32 m0, s56
	ds_read_b128 v[182:185], v198 offset:16384
	ds_read_b128 v[186:189], v198 offset:17408
	ds_read_b128 v[202:205], v198 offset:18432
	ds_read_b128 v[206:209], v198 offset:19456
	ds_read_b128 v[210:213], v198 offset:20480
	ds_read_b128 v[214:217], v198 offset:21504
	ds_read_b128 v[218:221], v198 offset:22528
	ds_read_b128 v[222:225], v198 offset:23552
	global_load_lds_dwordx4 v156, s[24:25]
	s_add_i32 m0, s56, 0x2000
	s_add_u32 s56, s24, 0x20000
	v_lshl_add_u64 v[226:227], s[24:25], 0, v[160:161]
	s_addc_u32 s57, s25, 0
	s_add_i32 s58, s52, s27
	global_load_lds_dwordx4 v160, s[24:25]
	s_mov_b32 m0, s58
	v_lshl_add_u64 v[230:231], s[34:35], 0, v[158:159]
	global_load_lds_dwordx4 v156, s[56:57]
	s_add_i32 m0, s58, 0x2000
	s_nop 0
	global_load_lds_dwordx4 v160, s[56:57]
	v_lshl_add_u64 v[228:229], s[34:35], 0, v[154:155]
	s_mov_b32 m0, s28
	s_nop 0
	global_load_lds_dwordx4 v154, s[34:35]
	s_mov_b32 m0, s29
	s_nop 0
	global_load_lds_dwordx4 v158, s[34:35]
	s_waitcnt lgkmcnt(0)
	s_barrier
	s_waitcnt lgkmcnt(0)
	v_mfma_f32_16x16x32_bf16 v[70:73], v[50:53], v[182:185], 0
	v_mfma_f32_16x16x32_bf16 v[66:69], v[138:141], v[182:185], 0
	v_mfma_f32_16x16x32_bf16 v[46:49], v[50:53], v[202:205], 0
	v_mfma_f32_16x16x32_bf16 v[42:45], v[138:141], v[202:205], 0
	v_mfma_f32_16x16x32_bf16 v[30:33], v[50:53], v[210:213], 0
	v_mfma_f32_16x16x32_bf16 v[26:29], v[138:141], v[210:213], 0
	v_mfma_f32_16x16x32_bf16 v[14:17], v[50:53], v[218:221], 0
	v_mfma_f32_16x16x32_bf16 v[10:13], v[138:141], v[218:221], 0
	v_mfma_f32_16x16x32_bf16 v[70:73], v[54:57], v[186:189], v[70:73]
	v_mfma_f32_16x16x32_bf16 v[66:69], v[142:145], v[186:189], v[66:69]
	v_mfma_f32_16x16x32_bf16 v[46:49], v[54:57], v[206:209], v[46:49]
	v_mfma_f32_16x16x32_bf16 v[42:45], v[142:145], v[206:209], v[42:45]
	v_mfma_f32_16x16x32_bf16 v[30:33], v[54:57], v[214:217], v[30:33]
	v_mfma_f32_16x16x32_bf16 v[26:29], v[142:145], v[214:217], v[26:29]
	v_mfma_f32_16x16x32_bf16 v[14:17], v[54:57], v[222:225], v[14:17]
	v_mfma_f32_16x16x32_bf16 v[10:13], v[142:145], v[222:225], v[10:13]
	v_mfma_f32_16x16x32_bf16 v[38:41], v[146:149], v[202:205], 0
	v_mfma_f32_16x16x32_bf16 v[34:37], v[174:177], v[202:205], 0
	v_mfma_f32_16x16x32_bf16 v[22:25], v[146:149], v[210:213], 0
	v_mfma_f32_16x16x32_bf16 v[18:21], v[174:177], v[210:213], 0
	v_mfma_f32_16x16x32_bf16 v[6:9], v[146:149], v[218:221], 0
	v_mfma_f32_16x16x32_bf16 v[2:5], v[174:177], v[218:221], 0
	v_mfma_f32_16x16x32_bf16 v[50:53], v[146:149], v[182:185], 0
	v_mfma_f32_16x16x32_bf16 v[54:57], v[174:177], v[182:185], 0
	v_mfma_f32_16x16x32_bf16 v[38:41], v[150:153], v[206:209], v[38:41]
	v_mfma_f32_16x16x32_bf16 v[34:37], v[178:181], v[206:209], v[34:37]
	v_mfma_f32_16x16x32_bf16 v[22:25], v[150:153], v[214:217], v[22:25]
	v_mfma_f32_16x16x32_bf16 v[18:21], v[178:181], v[214:217], v[18:21]
	v_mfma_f32_16x16x32_bf16 v[6:9], v[150:153], v[222:225], v[6:9]
	v_mfma_f32_16x16x32_bf16 v[2:5], v[178:181], v[222:225], v[2:5]
	v_mfma_f32_16x16x32_bf16 v[50:53], v[150:153], v[186:189], v[50:53]
	v_mfma_f32_16x16x32_bf16 v[54:57], v[178:181], v[186:189], v[54:57]
	s_barrier
; #define PG8_STAGE(bufoff, gbase, voff) do { _Pragma("unroll") for (int _i = 0; _i < 2; ++_i) \
;         __builtin_amdgcn_global_load_lds((const unsigned*)((const char*)(gbase) + (voff)[_i]), (LAS unsigned*)(lds + (bufoff) + ldsw + _i * 8192), 16, 0, 0); } while (0)
; #define PG8_LDA(dst, b, h) do { _Pragma("unroll") for (int m = 0; m < 4; ++m) _Pragma("unroll") for (int k = 0; k < 2; ++k) dst[m][k] = *(const LAS bf16x8*)(lds + PG8_SA(b, h) + aoff + m * 2048 + k * 1024); } while (0)
; #define PG8_LDB(dst, b, h) do { _Pragma("unroll") for (int n = 0; n < 2; ++n) _Pragma("unroll") for (int k = 0; k < 2; ++k) dst[n][k] = *(const LAS bf16x8*)(lds + PG8_SB(b, h) + boff + n * 2048 + k * 1024); } while (0)
; #define PG8_MMA(ai, bj, At, Bt) do { __builtin_amdgcn_s_setprio(1); _Pragma("unroll") for (int m = 0; m < 4; ++m) _Pragma("unroll") for (int n = 0; n < 2; ++n) _Pragma("unroll") for (int k = 0; k < 2; ++k) \
;         acc[ai][bj][m][n] = __builtin_amdgcn_mfma_f32_16x16x32_bf16(Bt[n][k], At[m][k], acc[ai][bj][m][n], 0, 0, 0); __builtin_amdgcn_s_setprio(0); } while (0)
; #define PG8_WAIT_V(n) asm volatile("s_waitcnt vmcnt(" #n ")" ::: "memory")
; #define PG8_WAIT_L(n) asm volatile("s_waitcnt lgkmcnt(" #n ")" ::: "memory")
; #define PG8_BAR __builtin_amdgcn_s_barrier()
; #define PG8_SCHED __builtin_amdgcn_sched_barrier(0)
; template <class Epi, class Sched, bool ALIGN_EPI = false, bool SP2 = false>
; __device__ __forceinline__ void gemm_phase(LAS unsigned char* lds, const Gemm g, const Sched& S, const Epi& E) {
;     ...
;             PG8_LDB(B0, 1, 0); PG8_LDB(B1, 1, 1); PG8_SCHED; PG8_LDA(At, 1, 0); PG8_STAGE(PG8_SA(0, 1), a2 + hstep, voffA);
;             PG8_WAIT_V(8); PG8_WAIT_L(0); PG8_BAR; PG8_MMA(0, 0, At, B0); PG8_MMA(0, 1, At, B1); PG8_BAR; PG8_SCHED;
;             PG8_LDA(At, 1, 1); PG8_STAGE(PG8_SB(1, 0), b3, voffB); PG8_STAGE(PG8_SB(1, 1), b3 + hstepB, voffB); PG8_STAGE(PG8_SA(1, 0), a3, voffA);
;             PG8_WAIT_V(8); PG8_WAIT_L(0); PG8_BAR; PG8_MMA(1, 0, At, B0); PG8_MMA(1, 1, At, B1); PG8_BAR; PG8_SCHED;
	s_add_i32 s56, 0, 0x18000
	s_add_i32 s57, 0, 0x1c000
	v_add_u32_e32 v142, s56, v1
	v_add_u32_e32 v162, s57, v1
	ds_read_b128 v[58:61], v142
	ds_read_b128 v[62:65], v142 offset:1024
	ds_read_b128 v[138:141], v142 offset:2048
	ds_read_b128 v[142:145], v142 offset:3072
	ds_read_b128 v[146:149], v162
	ds_read_b128 v[150:153], v162 offset:1024
	ds_read_b128 v[174:177], v162 offset:2048
	ds_read_b128 v[178:181], v162 offset:3072
	s_add_u32 s34, s34, 0x80000
	s_addc_u32 s35, s35, 0
	s_mov_b32 m0, s30
	ds_read_b128 v[182:185], v198 offset:32768
	ds_read_b128 v[186:189], v198 offset:33792
	ds_read_b128 v[202:205], v198 offset:34816
	ds_read_b128 v[206:209], v198 offset:35840
	ds_read_b128 v[210:213], v198 offset:36864
	ds_read_b128 v[214:217], v198 offset:37888
	ds_read_b128 v[218:221], v198 offset:38912
	ds_read_b128 v[222:225], v198 offset:39936
	global_load_lds_dwordx4 v154, s[34:35]
	s_mov_b32 m0, s31
	s_nop 0
	global_load_lds_dwordx4 v158, s[34:35]
	s_waitcnt vmcnt(8)
	s_waitcnt lgkmcnt(0)
	s_barrier
	s_waitcnt lgkmcnt(0)
	v_mfma_f32_16x16x32_bf16 v[134:137], v[58:61], v[182:185], v[134:137]
	v_mfma_f32_16x16x32_bf16 v[130:133], v[138:141], v[182:185], v[130:133]
	v_mfma_f32_16x16x32_bf16 v[118:121], v[58:61], v[202:205], v[118:121]
	v_mfma_f32_16x16x32_bf16 v[114:117], v[138:141], v[202:205], v[114:117]
	v_mfma_f32_16x16x32_bf16 v[102:105], v[58:61], v[210:213], v[102:105]
	v_mfma_f32_16x16x32_bf16 v[98:101], v[138:141], v[210:213], v[98:101]
	v_mfma_f32_16x16x32_bf16 v[86:89], v[58:61], v[218:221], v[86:89]
	v_mfma_f32_16x16x32_bf16 v[82:85], v[138:141], v[218:221], v[82:85]
	v_mfma_f32_16x16x32_bf16 v[134:137], v[62:65], v[186:189], v[134:137]
	v_mfma_f32_16x16x32_bf16 v[130:133], v[142:145], v[186:189], v[130:133]
	v_mfma_f32_16x16x32_bf16 v[118:121], v[62:65], v[206:209], v[118:121]
	v_mfma_f32_16x16x32_bf16 v[114:117], v[142:145], v[206:209], v[114:117]
	v_mfma_f32_16x16x32_bf16 v[102:105], v[62:65], v[214:217], v[102:105]
	v_mfma_f32_16x16x32_bf16 v[98:101], v[142:145], v[214:217], v[98:101]
	v_mfma_f32_16x16x32_bf16 v[86:89], v[62:65], v[222:225], v[86:89]
	v_mfma_f32_16x16x32_bf16 v[82:85], v[142:145], v[222:225], v[82:85]
	v_mfma_f32_16x16x32_bf16 v[126:129], v[146:149], v[182:185], v[126:129]
	v_mfma_f32_16x16x32_bf16 v[122:125], v[174:177], v[182:185], v[122:125]
	v_mfma_f32_16x16x32_bf16 v[110:113], v[146:149], v[202:205], v[110:113]
	v_mfma_f32_16x16x32_bf16 v[106:109], v[174:177], v[202:205], v[106:109]
	v_mfma_f32_16x16x32_bf16 v[94:97], v[146:149], v[210:213], v[94:97]
	v_mfma_f32_16x16x32_bf16 v[90:93], v[174:177], v[210:213], v[90:93]
	v_mfma_f32_16x16x32_bf16 v[78:81], v[146:149], v[218:221], v[78:81]
	v_mfma_f32_16x16x32_bf16 v[74:77], v[174:177], v[218:221], v[74:77]
	v_mfma_f32_16x16x32_bf16 v[126:129], v[150:153], v[186:189], v[126:129]
	v_mfma_f32_16x16x32_bf16 v[122:125], v[178:181], v[186:189], v[122:125]
	v_mfma_f32_16x16x32_bf16 v[110:113], v[150:153], v[206:209], v[110:113]
	v_mfma_f32_16x16x32_bf16 v[106:109], v[178:181], v[206:209], v[106:109]
	v_mfma_f32_16x16x32_bf16 v[94:97], v[150:153], v[214:217], v[94:97]
	v_mfma_f32_16x16x32_bf16 v[90:93], v[178:181], v[214:217], v[90:93]
	v_mfma_f32_16x16x32_bf16 v[78:81], v[150:153], v[222:225], v[78:81]
	v_mfma_f32_16x16x32_bf16 v[74:77], v[178:181], v[222:225], v[74:77]
	s_barrier
	s_add_u32 s98, s24, 0x80
	s_addc_u32 s99, s25, 0
	s_add_i32 s34, s56, s27
	s_mov_b32 m0, s34
	ds_read_b128 v[182:185], v198 offset:49152
	ds_read_b128 v[186:189], v198 offset:50176
	ds_read_b128 v[202:205], v198 offset:51200
	ds_read_b128 v[206:209], v198 offset:52224
	ds_read_b128 v[210:213], v198 offset:53248
	ds_read_b128 v[214:217], v198 offset:54272
	ds_read_b128 v[218:221], v198 offset:55296
	ds_read_b128 v[222:225], v198 offset:56320
	global_load_lds_dwordx4 v156, s[98:99]
	s_add_i32 m0, s34, 0x2000
	s_add_u32 s24, s24, 0x20080
	v_lshl_add_u64 v[190:191], v[226:227], 0, s[8:9]
	s_addc_u32 s25, s25, 0
	s_add_i32 s34, s57, s27
	global_load_lds_dwordx4 v[190:191], off
	s_mov_b32 m0, s34
	s_nop 0
	global_load_lds_dwordx4 v156, s[24:25]
	s_add_i32 m0, s34, 0x2000
	s_nop 0
	global_load_lds_dwordx4 v160, s[24:25]
	v_lshl_add_u64 v[190:191], v[228:229], 0, s[8:9]
	s_mov_b32 m0, s48
	s_nop 0
	global_load_lds_dwordx4 v[190:191], off
	v_lshl_add_u64 v[190:191], v[230:231], 0, s[8:9]
	s_mov_b32 m0, s49
	s_nop 0
	global_load_lds_dwordx4 v[190:191], off
	s_waitcnt vmcnt(8)
	s_waitcnt lgkmcnt(0)
	s_barrier
	s_waitcnt lgkmcnt(0)
	v_mfma_f32_16x16x32_bf16 v[70:73], v[58:61], v[182:185], v[70:73]
	v_mfma_f32_16x16x32_bf16 v[66:69], v[138:141], v[182:185], v[66:69]
	v_mfma_f32_16x16x32_bf16 v[46:49], v[58:61], v[202:205], v[46:49]
	v_mfma_f32_16x16x32_bf16 v[42:45], v[138:141], v[202:205], v[42:45]
	v_mfma_f32_16x16x32_bf16 v[30:33], v[58:61], v[210:213], v[30:33]
	v_mfma_f32_16x16x32_bf16 v[26:29], v[138:141], v[210:213], v[26:29]
	v_mfma_f32_16x16x32_bf16 v[14:17], v[58:61], v[218:221], v[14:17]
	v_mfma_f32_16x16x32_bf16 v[10:13], v[138:141], v[218:221], v[10:13]
	v_mfma_f32_16x16x32_bf16 v[70:73], v[62:65], v[186:189], v[70:73]
	v_mfma_f32_16x16x32_bf16 v[66:69], v[142:145], v[186:189], v[66:69]
	v_mfma_f32_16x16x32_bf16 v[46:49], v[62:65], v[206:209], v[46:49]
	v_mfma_f32_16x16x32_bf16 v[42:45], v[142:145], v[206:209], v[42:45]
	v_mfma_f32_16x16x32_bf16 v[30:33], v[62:65], v[214:217], v[30:33]
	v_mfma_f32_16x16x32_bf16 v[26:29], v[142:145], v[214:217], v[26:29]
	v_mfma_f32_16x16x32_bf16 v[14:17], v[62:65], v[222:225], v[14:17]
	v_mfma_f32_16x16x32_bf16 v[10:13], v[142:145], v[222:225], v[10:13]
	v_mfma_f32_16x16x32_bf16 v[50:53], v[146:149], v[182:185], v[50:53]
	v_mfma_f32_16x16x32_bf16 v[62:65], v[150:153], v[186:189], v[50:53]
	v_mfma_f32_16x16x32_bf16 v[50:53], v[174:177], v[182:185], v[54:57]
	v_mfma_f32_16x16x32_bf16 v[38:41], v[146:149], v[202:205], v[38:41]
	v_mfma_f32_16x16x32_bf16 v[34:37], v[174:177], v[202:205], v[34:37]
	v_mfma_f32_16x16x32_bf16 v[22:25], v[146:149], v[210:213], v[22:25]
	v_mfma_f32_16x16x32_bf16 v[18:21], v[174:177], v[210:213], v[18:21]
	v_mfma_f32_16x16x32_bf16 v[6:9], v[146:149], v[218:221], v[6:9]
	v_mfma_f32_16x16x32_bf16 v[2:5], v[174:177], v[218:221], v[2:5]
	v_mfma_f32_16x16x32_bf16 v[58:61], v[178:181], v[186:189], v[50:53]
	v_mfma_f32_16x16x32_bf16 v[38:41], v[150:153], v[206:209], v[38:41]
	v_mfma_f32_16x16x32_bf16 v[34:37], v[178:181], v[206:209], v[34:37]
	v_mfma_f32_16x16x32_bf16 v[22:25], v[150:153], v[214:217], v[22:25]
	v_mfma_f32_16x16x32_bf16 v[18:21], v[178:181], v[214:217], v[18:21]
	v_mfma_f32_16x16x32_bf16 v[6:9], v[150:153], v[222:225], v[6:9]
	v_mfma_f32_16x16x32_bf16 v[2:5], v[178:181], v[222:225], v[2:5]
	s_barrier
	s_add_i32 s55, s55, 2
	s_add_u32 s53, s53, 0x100
	s_addc_u32 s54, s54, 0
	s_add_u32 s22, s22, 0x100
	s_addc_u32 s23, s23, 0
	s_cmp_lt_u32 s55, 30
; #define PG8_STAGE(bufoff, gbase, voff) do { _Pragma("unroll") for (int _i = 0; _i < 2; ++_i) \
;         __builtin_amdgcn_global_load_lds((const unsigned*)((const char*)(gbase) + (voff)[_i]), (LAS unsigned*)(lds + (bufoff) + ldsw + _i * 8192), 16, 0, 0); } while (0)
; #define PG8_LDA(dst, b, h) do { _Pragma("unroll") for (int m = 0; m < 4; ++m) _Pragma("unroll") for (int k = 0; k < 2; ++k) dst[m][k] = *(const LAS bf16x8*)(lds + PG8_SA(b, h) + aoff + m * 2048 + k * 1024); } while (0)
; #define PG8_LDB(dst, b, h) do { _Pragma("unroll") for (int n = 0; n < 2; ++n) _Pragma("unroll") for (int k = 0; k < 2; ++k) dst[n][k] = *(const LAS bf16x8*)(lds + PG8_SB(b, h) + boff + n * 2048 + k * 1024); } while (0)
; #define PG8_MMA(ai, bj, At, Bt) do { __builtin_amdgcn_s_setprio(1); _Pragma("unroll") for (int m = 0; m < 4; ++m) _Pragma("unroll") for (int n = 0; n < 2; ++n) _Pragma("unroll") for (int k = 0; k < 2; ++k) \
;         acc[ai][bj][m][n] = __builtin_amdgcn_mfma_f32_16x16x32_bf16(Bt[n][k], At[m][k], acc[ai][bj][m][n], 0, 0, 0); __builtin_amdgcn_s_setprio(0); } while (0)
; #define PG8_WAIT_V(n) asm volatile("s_waitcnt vmcnt(" #n ")" ::: "memory")
; #define PG8_WAIT_L(n) asm volatile("s_waitcnt lgkmcnt(" #n ")" ::: "memory")
; template <class Epi, class Sched, bool ALIGN_EPI = false, bool SP2 = false>
; __device__ __forceinline__ void gemm_phase(LAS unsigned char* lds, const Gemm g, const Sched& S, const Epi& E) {
;     ...
;         for (int t = 0; t < nt; t += 2) {
;             const bool last = (t == nt - 2);
;             const char* a1 = cA + (size_t)(t + 1) * kstep;
;             const char* a2 = last ? nA : cA + (size_t)(t + 2) * kstep; const char* b2 = last ? nB : cB + (size_t)(t + 2) * kstep;
;             const char* a3 = a2 + kstep; const char* b3 = b2 + kstep;
;             if (last && has_next) S.a_ready(nxt);
;             if constexpr (SP2) {
;             PG8_LDB(B0, 0, 0); PG8_LDB(B1, 0, 1); PG8_SCHED; PG8_LDA(At, 0, 0); PG8_STAGE(PG8_SA(1, 1), a1 + hstep, voffA);
;             PG8_WAIT_V(8); PG8_WAIT_L(0); PG8_BAR; PG8_MMA(0, 0, At, B0); PG8_MMA(0, 1, At, B1); PG8_BAR; PG8_SCHED;
;             PG8_LDA(At, 0, 1); PG8_STAGE(PG8_SB(0, 0), b2, voffB); PG8_STAGE(PG8_SB(0, 1), b2 + hstepB, voffB); PG8_STAGE(PG8_SA(0, 0), a2, voffA);
;             PG8_WAIT_V(8); PG8_WAIT_L(0); PG8_BAR; PG8_MMA(1, 0, At, B0); PG8_MMA(1, 1, At, B1); PG8_BAR; PG8_SCHED;
.LBB0_2766:
	ds_read_b128 v[50:53], v196
	ds_read_b128 v[54:57], v196 offset:1024
	ds_read_b128 v[138:141], v196 offset:2048
	ds_read_b128 v[142:145], v196 offset:3072
	ds_read_b128 v[146:149], v197
	ds_read_b128 v[150:153], v197 offset:1024
	ds_read_b128 v[174:177], v197 offset:2048
	ds_read_b128 v[178:181], v197 offset:3072
	s_add_u32 s24, s22, 0xfff80080
	s_addc_u32 s25, s23, -1
	s_cmp_eq_u32 s55, 28
	s_cselect_b32 s35, s3, s25
	s_cselect_b32 s34, s15, s24
	s_cselect_b32 s25, s13, s54
	s_cselect_b32 s24, s21, s53
	s_add_i32 m0, s28, 0xc000
	ds_read_b128 v[182:185], v198
	ds_read_b128 v[186:189], v198 offset:1024
	ds_read_b128 v[202:205], v198 offset:2048
	ds_read_b128 v[206:209], v198 offset:3072
	ds_read_b128 v[210:213], v198 offset:4096
	ds_read_b128 v[214:217], v198 offset:5120
	ds_read_b128 v[218:221], v198 offset:6144
	ds_read_b128 v[222:225], v198 offset:7168
	global_load_lds_dwordx4 v168, s[22:23]
	s_add_i32 m0, s28, 0xe000
	s_nop 0
	global_load_lds_dwordx4 v166, s[22:23]
	s_waitcnt vmcnt(8)
	s_waitcnt lgkmcnt(0)
	s_barrier
	s_waitcnt lgkmcnt(0)
	v_mfma_f32_16x16x32_bf16 v[134:137], v[50:53], v[182:185], v[134:137]
	v_mfma_f32_16x16x32_bf16 v[130:133], v[138:141], v[182:185], v[130:133]
	v_mfma_f32_16x16x32_bf16 v[118:121], v[50:53], v[202:205], v[118:121]
	v_mfma_f32_16x16x32_bf16 v[114:117], v[138:141], v[202:205], v[114:117]
	v_mfma_f32_16x16x32_bf16 v[102:105], v[50:53], v[210:213], v[102:105]
	v_mfma_f32_16x16x32_bf16 v[98:101], v[138:141], v[210:213], v[98:101]
	v_mfma_f32_16x16x32_bf16 v[86:89], v[50:53], v[218:221], v[86:89]
	v_mfma_f32_16x16x32_bf16 v[82:85], v[138:141], v[218:221], v[82:85]
	v_mfma_f32_16x16x32_bf16 v[134:137], v[54:57], v[186:189], v[134:137]
	v_mfma_f32_16x16x32_bf16 v[130:133], v[142:145], v[186:189], v[130:133]
	v_mfma_f32_16x16x32_bf16 v[118:121], v[54:57], v[206:209], v[118:121]
	v_mfma_f32_16x16x32_bf16 v[114:117], v[142:145], v[206:209], v[114:117]
	v_mfma_f32_16x16x32_bf16 v[102:105], v[54:57], v[214:217], v[102:105]
	v_mfma_f32_16x16x32_bf16 v[98:101], v[142:145], v[214:217], v[98:101]
	v_mfma_f32_16x16x32_bf16 v[86:89], v[54:57], v[222:225], v[86:89]
	v_mfma_f32_16x16x32_bf16 v[82:85], v[142:145], v[222:225], v[82:85]
	v_mfma_f32_16x16x32_bf16 v[126:129], v[146:149], v[182:185], v[126:129]
	v_mfma_f32_16x16x32_bf16 v[122:125], v[174:177], v[182:185], v[122:125]
	v_mfma_f32_16x16x32_bf16 v[110:113], v[146:149], v[202:205], v[110:113]
	v_mfma_f32_16x16x32_bf16 v[106:109], v[174:177], v[202:205], v[106:109]
	v_mfma_f32_16x16x32_bf16 v[94:97], v[146:149], v[210:213], v[94:97]
	v_mfma_f32_16x16x32_bf16 v[90:93], v[174:177], v[210:213], v[90:93]
	v_mfma_f32_16x16x32_bf16 v[78:81], v[146:149], v[218:221], v[78:81]
	v_mfma_f32_16x16x32_bf16 v[74:77], v[174:177], v[218:221], v[74:77]
	v_mfma_f32_16x16x32_bf16 v[126:129], v[150:153], v[186:189], v[126:129]
	v_mfma_f32_16x16x32_bf16 v[122:125], v[178:181], v[186:189], v[122:125]
	v_mfma_f32_16x16x32_bf16 v[110:113], v[150:153], v[206:209], v[110:113]
	v_mfma_f32_16x16x32_bf16 v[106:109], v[178:181], v[206:209], v[106:109]
	v_mfma_f32_16x16x32_bf16 v[94:97], v[150:153], v[214:217], v[94:97]
	v_mfma_f32_16x16x32_bf16 v[90:93], v[178:181], v[214:217], v[90:93]
	v_mfma_f32_16x16x32_bf16 v[78:81], v[150:153], v[222:225], v[78:81]
	v_mfma_f32_16x16x32_bf16 v[74:77], v[178:181], v[222:225], v[74:77]
	s_barrier
	s_add_i32 s56, s51, s27
	s_mov_b32 m0, s56
	ds_read_b128 v[182:185], v198 offset:16384
	ds_read_b128 v[186:189], v198 offset:17408
	ds_read_b128 v[202:205], v198 offset:18432
	ds_read_b128 v[206:209], v198 offset:19456
	ds_read_b128 v[210:213], v198 offset:20480
	ds_read_b128 v[214:217], v198 offset:21504
	ds_read_b128 v[218:221], v198 offset:22528
	ds_read_b128 v[222:225], v198 offset:23552
	global_load_lds_dwordx4 v156, s[24:25]
	s_add_i32 m0, s56, 0x2000
	s_add_u32 s56, s24, 0x20000
	v_lshl_add_u64 v[226:227], s[24:25], 0, v[160:161]
	s_addc_u32 s57, s25, 0
	s_add_i32 s58, s52, s27
	global_load_lds_dwordx4 v160, s[24:25]
	s_mov_b32 m0, s58
	v_lshl_add_u64 v[230:231], s[34:35], 0, v[158:159]
	global_load_lds_dwordx4 v156, s[56:57]
	s_add_i32 m0, s58, 0x2000
	s_nop 0
	global_load_lds_dwordx4 v160, s[56:57]
	v_lshl_add_u64 v[228:229], s[34:35], 0, v[154:155]
	s_mov_b32 m0, s28
	s_nop 0
	global_load_lds_dwordx4 v154, s[34:35]
	s_mov_b32 m0, s29
	s_nop 0
	global_load_lds_dwordx4 v158, s[34:35]
	s_waitcnt vmcnt(8)
	s_waitcnt lgkmcnt(0)
	s_barrier
	s_waitcnt lgkmcnt(0)
	v_mfma_f32_16x16x32_bf16 v[70:73], v[50:53], v[182:185], v[70:73]
	v_mfma_f32_16x16x32_bf16 v[66:69], v[138:141], v[182:185], v[66:69]
	v_mfma_f32_16x16x32_bf16 v[46:49], v[50:53], v[202:205], v[46:49]
	v_mfma_f32_16x16x32_bf16 v[42:45], v[138:141], v[202:205], v[42:45]
	v_mfma_f32_16x16x32_bf16 v[30:33], v[50:53], v[210:213], v[30:33]
	v_mfma_f32_16x16x32_bf16 v[26:29], v[138:141], v[210:213], v[26:29]
	v_mfma_f32_16x16x32_bf16 v[14:17], v[50:53], v[218:221], v[14:17]
	v_mfma_f32_16x16x32_bf16 v[10:13], v[138:141], v[218:221], v[10:13]
	v_mfma_f32_16x16x32_bf16 v[70:73], v[54:57], v[186:189], v[70:73]
	v_mfma_f32_16x16x32_bf16 v[66:69], v[142:145], v[186:189], v[66:69]
	v_mfma_f32_16x16x32_bf16 v[46:49], v[54:57], v[206:209], v[46:49]
	v_mfma_f32_16x16x32_bf16 v[42:45], v[142:145], v[206:209], v[42:45]
	v_mfma_f32_16x16x32_bf16 v[30:33], v[54:57], v[214:217], v[30:33]
	v_mfma_f32_16x16x32_bf16 v[26:29], v[142:145], v[214:217], v[26:29]
	v_mfma_f32_16x16x32_bf16 v[14:17], v[54:57], v[222:225], v[14:17]
	v_mfma_f32_16x16x32_bf16 v[10:13], v[142:145], v[222:225], v[10:13]
	v_mfma_f32_16x16x32_bf16 v[38:41], v[146:149], v[202:205], v[38:41]
	v_mfma_f32_16x16x32_bf16 v[34:37], v[174:177], v[202:205], v[34:37]
	v_mfma_f32_16x16x32_bf16 v[22:25], v[146:149], v[210:213], v[22:25]
	v_mfma_f32_16x16x32_bf16 v[18:21], v[174:177], v[210:213], v[18:21]
	v_mfma_f32_16x16x32_bf16 v[6:9], v[146:149], v[218:221], v[6:9]
	v_mfma_f32_16x16x32_bf16 v[2:5], v[174:177], v[218:221], v[2:5]
	v_mfma_f32_16x16x32_bf16 v[50:53], v[146:149], v[182:185], v[62:65]
	v_mfma_f32_16x16x32_bf16 v[54:57], v[174:177], v[182:185], v[58:61]
	v_mfma_f32_16x16x32_bf16 v[38:41], v[150:153], v[206:209], v[38:41]
	v_mfma_f32_16x16x32_bf16 v[34:37], v[178:181], v[206:209], v[34:37]
	v_mfma_f32_16x16x32_bf16 v[22:25], v[150:153], v[214:217], v[22:25]
	v_mfma_f32_16x16x32_bf16 v[18:21], v[178:181], v[214:217], v[18:21]
	v_mfma_f32_16x16x32_bf16 v[6:9], v[150:153], v[222:225], v[6:9]
	v_mfma_f32_16x16x32_bf16 v[2:5], v[178:181], v[222:225], v[2:5]
	v_mfma_f32_16x16x32_bf16 v[50:53], v[150:153], v[186:189], v[50:53]
	v_mfma_f32_16x16x32_bf16 v[54:57], v[178:181], v[186:189], v[54:57]
	s_barrier
; #define PG8_STAGE(bufoff, gbase, voff) do { _Pragma("unroll") for (int _i = 0; _i < 2; ++_i) \
;         __builtin_amdgcn_global_load_lds((const unsigned*)((const char*)(gbase) + (voff)[_i]), (LAS unsigned*)(lds + (bufoff) + ldsw + _i * 8192), 16, 0, 0); } while (0)
; #define PG8_LDA(dst, b, h) do { _Pragma("unroll") for (int m = 0; m < 4; ++m) _Pragma("unroll") for (int k = 0; k < 2; ++k) dst[m][k] = *(const LAS bf16x8*)(lds + PG8_SA(b, h) + aoff + m * 2048 + k * 1024); } while (0)
; #define PG8_LDB(dst, b, h) do { _Pragma("unroll") for (int n = 0; n < 2; ++n) _Pragma("unroll") for (int k = 0; k < 2; ++k) dst[n][k] = *(const LAS bf16x8*)(lds + PG8_SB(b, h) + boff + n * 2048 + k * 1024); } while (0)
; #define PG8_MMA(ai, bj, At, Bt) do { __builtin_amdgcn_s_setprio(1); _Pragma("unroll") for (int m = 0; m < 4; ++m) _Pragma("unroll") for (int n = 0; n < 2; ++n) _Pragma("unroll") for (int k = 0; k < 2; ++k) \
;         acc[ai][bj][m][n] = __builtin_amdgcn_mfma_f32_16x16x32_bf16(Bt[n][k], At[m][k], acc[ai][bj][m][n], 0, 0, 0); __builtin_amdgcn_s_setprio(0); } while (0)
; #define PG8_WAIT_V(n) asm volatile("s_waitcnt vmcnt(" #n ")" ::: "memory")
; #define PG8_WAIT_L(n) asm volatile("s_waitcnt lgkmcnt(" #n ")" ::: "memory")
; #define PG8_BAR __builtin_amdgcn_s_barrier()
; #define PG8_SCHED __builtin_amdgcn_sched_barrier(0)
; template <class Epi, class Sched, bool ALIGN_EPI = false, bool SP2 = false>
; __device__ __forceinline__ void gemm_phase(LAS unsigned char* lds, const Gemm g, const Sched& S, const Epi& E) {
;     ...
;         for (int t = 0; t < nt; t += 2) {
;     ...
;             PG8_LDB(B0, 1, 0); PG8_LDB(B1, 1, 1); PG8_SCHED; PG8_LDA(At, 1, 0); PG8_STAGE(PG8_SA(0, 1), a2 + hstep, voffA);
;             PG8_WAIT_V(8); PG8_WAIT_L(0); PG8_BAR; PG8_MMA(0, 0, At, B0); PG8_MMA(0, 1, At, B1); PG8_BAR; PG8_SCHED;
;             PG8_LDA(At, 1, 1); PG8_STAGE(PG8_SB(1, 0), b3, voffB); PG8_STAGE(PG8_SB(1, 1), b3 + hstepB, voffB); PG8_STAGE(PG8_SA(1, 0), a3, voffA);
;             PG8_WAIT_V(8); PG8_WAIT_L(0); PG8_BAR; PG8_MMA(1, 0, At, B0); PG8_MMA(1, 1, At, B1); PG8_BAR; PG8_SCHED;
	s_add_i32 s56, 0, 0x18000
	s_add_i32 s57, 0, 0x1c000
	v_add_u32_e32 v142, s56, v1
	v_add_u32_e32 v162, s57, v1
	ds_read_b128 v[58:61], v142
	ds_read_b128 v[62:65], v142 offset:1024
	ds_read_b128 v[138:141], v142 offset:2048
	ds_read_b128 v[142:145], v142 offset:3072
	ds_read_b128 v[146:149], v162
	ds_read_b128 v[150:153], v162 offset:1024
	ds_read_b128 v[174:177], v162 offset:2048
	ds_read_b128 v[178:181], v162 offset:3072
	s_add_u32 s34, s34, 0x80000
	s_addc_u32 s35, s35, 0
	s_mov_b32 m0, s30
	ds_read_b128 v[182:185], v198 offset:32768
	ds_read_b128 v[186:189], v198 offset:33792
	ds_read_b128 v[202:205], v198 offset:34816
	ds_read_b128 v[206:209], v198 offset:35840
	ds_read_b128 v[210:213], v198 offset:36864
	ds_read_b128 v[214:217], v198 offset:37888
	ds_read_b128 v[218:221], v198 offset:38912
	ds_read_b128 v[222:225], v198 offset:39936
	global_load_lds_dwordx4 v154, s[34:35]
	s_mov_b32 m0, s31
	s_nop 0
	global_load_lds_dwordx4 v158, s[34:35]
	s_waitcnt vmcnt(8)
	s_waitcnt lgkmcnt(0)
	s_barrier
	s_waitcnt lgkmcnt(0)
	v_mfma_f32_16x16x32_bf16 v[134:137], v[58:61], v[182:185], v[134:137]
	v_mfma_f32_16x16x32_bf16 v[130:133], v[138:141], v[182:185], v[130:133]
	v_mfma_f32_16x16x32_bf16 v[118:121], v[58:61], v[202:205], v[118:121]
	v_mfma_f32_16x16x32_bf16 v[114:117], v[138:141], v[202:205], v[114:117]
	v_mfma_f32_16x16x32_bf16 v[102:105], v[58:61], v[210:213], v[102:105]
	v_mfma_f32_16x16x32_bf16 v[98:101], v[138:141], v[210:213], v[98:101]
	v_mfma_f32_16x16x32_bf16 v[86:89], v[58:61], v[218:221], v[86:89]
	v_mfma_f32_16x16x32_bf16 v[82:85], v[138:141], v[218:221], v[82:85]
	v_mfma_f32_16x16x32_bf16 v[134:137], v[62:65], v[186:189], v[134:137]
	v_mfma_f32_16x16x32_bf16 v[130:133], v[142:145], v[186:189], v[130:133]
	v_mfma_f32_16x16x32_bf16 v[118:121], v[62:65], v[206:209], v[118:121]
	v_mfma_f32_16x16x32_bf16 v[114:117], v[142:145], v[206:209], v[114:117]
	v_mfma_f32_16x16x32_bf16 v[102:105], v[62:65], v[214:217], v[102:105]
	v_mfma_f32_16x16x32_bf16 v[98:101], v[142:145], v[214:217], v[98:101]
	v_mfma_f32_16x16x32_bf16 v[86:89], v[62:65], v[222:225], v[86:89]
	v_mfma_f32_16x16x32_bf16 v[82:85], v[142:145], v[222:225], v[82:85]
	v_mfma_f32_16x16x32_bf16 v[126:129], v[146:149], v[182:185], v[126:129]
	v_mfma_f32_16x16x32_bf16 v[122:125], v[174:177], v[182:185], v[122:125]
	v_mfma_f32_16x16x32_bf16 v[110:113], v[146:149], v[202:205], v[110:113]
	v_mfma_f32_16x16x32_bf16 v[106:109], v[174:177], v[202:205], v[106:109]
	v_mfma_f32_16x16x32_bf16 v[94:97], v[146:149], v[210:213], v[94:97]
	v_mfma_f32_16x16x32_bf16 v[90:93], v[174:177], v[210:213], v[90:93]
	v_mfma_f32_16x16x32_bf16 v[78:81], v[146:149], v[218:221], v[78:81]
	v_mfma_f32_16x16x32_bf16 v[74:77], v[174:177], v[218:221], v[74:77]
	v_mfma_f32_16x16x32_bf16 v[126:129], v[150:153], v[186:189], v[126:129]
	v_mfma_f32_16x16x32_bf16 v[122:125], v[178:181], v[186:189], v[122:125]
	v_mfma_f32_16x16x32_bf16 v[110:113], v[150:153], v[206:209], v[110:113]
	v_mfma_f32_16x16x32_bf16 v[106:109], v[178:181], v[206:209], v[106:109]
	v_mfma_f32_16x16x32_bf16 v[94:97], v[150:153], v[214:217], v[94:97]
	v_mfma_f32_16x16x32_bf16 v[90:93], v[178:181], v[214:217], v[90:93]
	v_mfma_f32_16x16x32_bf16 v[78:81], v[150:153], v[222:225], v[78:81]
	v_mfma_f32_16x16x32_bf16 v[74:77], v[178:181], v[222:225], v[74:77]
	s_barrier
	s_add_u32 s98, s24, 0x80
	s_addc_u32 s99, s25, 0
	s_add_i32 s34, s56, s27
	s_mov_b32 m0, s34
	ds_read_b128 v[182:185], v198 offset:49152
	ds_read_b128 v[186:189], v198 offset:50176
	ds_read_b128 v[202:205], v198 offset:51200
	ds_read_b128 v[206:209], v198 offset:52224
	ds_read_b128 v[210:213], v198 offset:53248
	ds_read_b128 v[214:217], v198 offset:54272
	ds_read_b128 v[218:221], v198 offset:55296
	ds_read_b128 v[222:225], v198 offset:56320
	global_load_lds_dwordx4 v156, s[98:99]
	s_add_i32 m0, s34, 0x2000
	s_add_u32 s24, s24, 0x20080
	v_lshl_add_u64 v[190:191], v[226:227], 0, s[8:9]
	s_addc_u32 s25, s25, 0
	s_add_i32 s34, s57, s27
	global_load_lds_dwordx4 v[190:191], off
	s_mov_b32 m0, s34
	s_nop 0
	global_load_lds_dwordx4 v156, s[24:25]
	s_add_i32 m0, s34, 0x2000
	s_nop 0
	global_load_lds_dwordx4 v160, s[24:25]
	v_lshl_add_u64 v[190:191], v[228:229], 0, s[8:9]
	s_mov_b32 m0, s48
	s_nop 0
	global_load_lds_dwordx4 v[190:191], off
	v_lshl_add_u64 v[190:191], v[230:231], 0, s[8:9]
	s_mov_b32 m0, s49
	s_nop 0
	global_load_lds_dwordx4 v[190:191], off
	s_waitcnt vmcnt(8)
	s_waitcnt lgkmcnt(0)
	s_barrier
	s_waitcnt lgkmcnt(0)
	v_mfma_f32_16x16x32_bf16 v[70:73], v[58:61], v[182:185], v[70:73]
	v_mfma_f32_16x16x32_bf16 v[66:69], v[138:141], v[182:185], v[66:69]
	v_mfma_f32_16x16x32_bf16 v[46:49], v[58:61], v[202:205], v[46:49]
	v_mfma_f32_16x16x32_bf16 v[42:45], v[138:141], v[202:205], v[42:45]
	v_mfma_f32_16x16x32_bf16 v[30:33], v[58:61], v[210:213], v[30:33]
	v_mfma_f32_16x16x32_bf16 v[26:29], v[138:141], v[210:213], v[26:29]
	v_mfma_f32_16x16x32_bf16 v[14:17], v[58:61], v[218:221], v[14:17]
	v_mfma_f32_16x16x32_bf16 v[10:13], v[138:141], v[218:221], v[10:13]
	v_mfma_f32_16x16x32_bf16 v[70:73], v[62:65], v[186:189], v[70:73]
	v_mfma_f32_16x16x32_bf16 v[66:69], v[142:145], v[186:189], v[66:69]
	v_mfma_f32_16x16x32_bf16 v[46:49], v[62:65], v[206:209], v[46:49]
	v_mfma_f32_16x16x32_bf16 v[42:45], v[142:145], v[206:209], v[42:45]
	v_mfma_f32_16x16x32_bf16 v[30:33], v[62:65], v[214:217], v[30:33]
	v_mfma_f32_16x16x32_bf16 v[26:29], v[142:145], v[214:217], v[26:29]
	v_mfma_f32_16x16x32_bf16 v[14:17], v[62:65], v[222:225], v[14:17]
	v_mfma_f32_16x16x32_bf16 v[10:13], v[142:145], v[222:225], v[10:13]
	v_mfma_f32_16x16x32_bf16 v[50:53], v[146:149], v[182:185], v[50:53]
	v_mfma_f32_16x16x32_bf16 v[62:65], v[150:153], v[186:189], v[50:53]
	v_mfma_f32_16x16x32_bf16 v[50:53], v[174:177], v[182:185], v[54:57]
	v_mfma_f32_16x16x32_bf16 v[38:41], v[146:149], v[202:205], v[38:41]
	v_mfma_f32_16x16x32_bf16 v[34:37], v[174:177], v[202:205], v[34:37]
	v_mfma_f32_16x16x32_bf16 v[22:25], v[146:149], v[210:213], v[22:25]
	v_mfma_f32_16x16x32_bf16 v[18:21], v[174:177], v[210:213], v[18:21]
	v_mfma_f32_16x16x32_bf16 v[6:9], v[146:149], v[218:221], v[6:9]
	v_mfma_f32_16x16x32_bf16 v[2:5], v[174:177], v[218:221], v[2:5]
	v_mfma_f32_16x16x32_bf16 v[58:61], v[178:181], v[186:189], v[50:53]
	v_mfma_f32_16x16x32_bf16 v[38:41], v[150:153], v[206:209], v[38:41]
	v_mfma_f32_16x16x32_bf16 v[34:37], v[178:181], v[206:209], v[34:37]
	v_mfma_f32_16x16x32_bf16 v[22:25], v[150:153], v[214:217], v[22:25]
	v_mfma_f32_16x16x32_bf16 v[18:21], v[178:181], v[214:217], v[18:21]
	v_mfma_f32_16x16x32_bf16 v[6:9], v[150:153], v[222:225], v[6:9]
	v_mfma_f32_16x16x32_bf16 v[2:5], v[178:181], v[222:225], v[2:5]
	s_barrier
	s_add_i32 s55, s55, 2
	s_add_u32 s53, s53, 0x100
	s_addc_u32 s54, s54, 0
	s_add_u32 s22, s22, 0x100
	s_addc_u32 s23, s23, 0
	s_cmp_lt_u32 s55, 30
	s_cbranch_scc1 .LBB0_2766
	s_setprio 0
	s_andn2_b64 vcc, exec, s[10:11]
	s_cbranch_vccnz .LBB0_2769
	s_barrier

; #define PG8_STAGE(bufoff, gbase, voff) do { _Pragma("unroll") for (int _i = 0; _i < 2; ++_i) \
;         __builtin_amdgcn_global_load_lds((const unsigned*)((const char*)(gbase) + (voff)[_i]), (LAS unsigned*)(lds + (bufoff) + ldsw + _i * 8192), 16, 0, 0); } while (0)
; #define PG8_LDA(dst, b, h) do { _Pragma("unroll") for (int m = 0; m < 4; ++m) _Pragma("unroll") for (int k = 0; k < 2; ++k) dst[m][k] = *(const LAS bf16x8*)(lds + PG8_SA(b, h) + aoff + m * 2048 + k * 1024); } while (0)
; #define PG8_LDB(dst, b, h) do { _Pragma("unroll") for (int n = 0; n < 2; ++n) _Pragma("unroll") for (int k = 0; k < 2; ++k) dst[n][k] = *(const LAS bf16x8*)(lds + PG8_SB(b, h) + boff + n * 2048 + k * 1024); } while (0)
; #define PG8_MMA(ai, bj, At, Bt) do { __builtin_amdgcn_s_setprio(1); _Pragma("unroll") for (int m = 0; m < 4; ++m) _Pragma("unroll") for (int n = 0; n < 2; ++n) _Pragma("unroll") for (int k = 0; k < 2; ++k) \
;         acc[ai][bj][m][n] = __builtin_amdgcn_mfma_f32_16x16x32_bf16(Bt[n][k], At[m][k], acc[ai][bj][m][n], 0, 0, 0); __builtin_amdgcn_s_setprio(0); } while (0)
; #define PG8_WAIT_V(n) asm volatile("s_waitcnt vmcnt(" #n ")" ::: "memory")
; #define PG8_WAIT_L(n) asm volatile("s_waitcnt lgkmcnt(" #n ")" ::: "memory")
; template <class Epi, class Sched, bool ALIGN_EPI = false, bool SP2 = false>
; __device__ __forceinline__ void gemm_phase(LAS unsigned char* lds, const Gemm g, const Sched& S, const Epi& E) {
;     ...
;         for (int t = 0; t < nt; t += 2) {
;             const bool last = (t == nt - 2);
;             const char* a1 = cA + (size_t)(t + 1) * kstep;
;             const char* a2 = last ? nA : cA + (size_t)(t + 2) * kstep; const char* b2 = last ? nB : cB + (size_t)(t + 2) * kstep;
;             const char* a3 = a2 + kstep; const char* b3 = b2 + kstep;
;             if (last && has_next) S.a_ready(nxt);
;             if constexpr (SP2) {
;             PG8_LDB(B0, 0, 0); PG8_LDB(B1, 0, 1); PG8_SCHED; PG8_LDA(At, 0, 0); PG8_STAGE(PG8_SA(1, 1), a1 + hstep, voffA);
;             PG8_WAIT_V(8); PG8_WAIT_L(0); PG8_BAR; PG8_MMA(0, 0, At, B0); PG8_MMA(0, 1, At, B1); PG8_BAR; PG8_SCHED;
;             PG8_LDA(At, 0, 1); PG8_STAGE(PG8_SB(0, 0), b2, voffB); PG8_STAGE(PG8_SB(0, 1), b2 + hstepB, voffB); PG8_STAGE(PG8_SA(0, 0), a2, voffA);
;             PG8_WAIT_V(8); PG8_WAIT_L(0); PG8_BAR; PG8_MMA(1, 0, At, B0); PG8_MMA(1, 1, At, B1); PG8_BAR; PG8_SCHED;
.Lprio_2916:
	ds_read_b128 v[66:69], v173
	ds_read_b128 v[70:73], v173 offset:1024
	ds_read_b128 v[74:77], v173 offset:2048
	ds_read_b128 v[78:81], v173 offset:3072
	ds_read_b128 v[162:165], v174
	ds_read_b128 v[180:183], v174 offset:1024
	ds_read_b128 v[184:187], v174 offset:2048
	ds_read_b128 v[188:191], v174 offset:3072
	s_add_u32 s20, s18, 0xfff80080
	s_addc_u32 s21, s19, -1
	s_cmp_eq_u32 s50, 28
	s_cselect_b32 s23, s13, s21
	s_cselect_b32 s22, s46, s20
	s_cselect_b32 s21, s11, s49
	s_cselect_b32 s20, s47, s48
	s_add_i32 m0, s28, 0xc000
	ds_read_b128 v[192:195], v175
	ds_read_b128 v[196:199], v175 offset:1024
	ds_read_b128 v[200:203], v175 offset:2048
	ds_read_b128 v[204:207], v175 offset:3072
	ds_read_b128 v[208:211], v175 offset:4096
	ds_read_b128 v[212:215], v175 offset:5120
	ds_read_b128 v[216:219], v175 offset:6144
	ds_read_b128 v[220:223], v175 offset:7168
	global_load_lds_dwordx4 v156, s[18:19]
	s_add_i32 m0, s28, 0xe000
	s_nop 0
	global_load_lds_dwordx4 v154, s[18:19]
	s_waitcnt lgkmcnt(0)
	s_barrier
	s_waitcnt lgkmcnt(0)
	v_mfma_f32_16x16x32_bf16 v[142:145], v[66:69], v[192:195], 0
	v_mfma_f32_16x16x32_bf16 v[138:141], v[74:77], v[192:195], 0
	v_mfma_f32_16x16x32_bf16 v[126:129], v[66:69], v[200:203], 0
	v_mfma_f32_16x16x32_bf16 v[122:125], v[74:77], v[200:203], 0
	v_mfma_f32_16x16x32_bf16 v[110:113], v[66:69], v[208:211], 0
	v_mfma_f32_16x16x32_bf16 v[106:109], v[74:77], v[208:211], 0
	v_mfma_f32_16x16x32_bf16 v[94:97], v[66:69], v[216:219], 0
	v_mfma_f32_16x16x32_bf16 v[90:93], v[74:77], v[216:219], 0
	v_mfma_f32_16x16x32_bf16 v[142:145], v[70:73], v[196:199], v[142:145]
	v_mfma_f32_16x16x32_bf16 v[138:141], v[78:81], v[196:199], v[138:141]
	v_mfma_f32_16x16x32_bf16 v[126:129], v[70:73], v[204:207], v[126:129]
	v_mfma_f32_16x16x32_bf16 v[122:125], v[78:81], v[204:207], v[122:125]
	v_mfma_f32_16x16x32_bf16 v[110:113], v[70:73], v[212:215], v[110:113]
	v_mfma_f32_16x16x32_bf16 v[106:109], v[78:81], v[212:215], v[106:109]
	v_mfma_f32_16x16x32_bf16 v[94:97], v[70:73], v[220:223], v[94:97]
	v_mfma_f32_16x16x32_bf16 v[90:93], v[78:81], v[220:223], v[90:93]
	v_mfma_f32_16x16x32_bf16 v[134:137], v[162:165], v[192:195], 0
	v_mfma_f32_16x16x32_bf16 v[130:133], v[184:187], v[192:195], 0
	v_mfma_f32_16x16x32_bf16 v[118:121], v[162:165], v[200:203], 0
	v_mfma_f32_16x16x32_bf16 v[114:117], v[184:187], v[200:203], 0
	v_mfma_f32_16x16x32_bf16 v[102:105], v[162:165], v[208:211], 0
	v_mfma_f32_16x16x32_bf16 v[98:101], v[184:187], v[208:211], 0
	v_mfma_f32_16x16x32_bf16 v[86:89], v[162:165], v[216:219], 0
	v_mfma_f32_16x16x32_bf16 v[82:85], v[184:187], v[216:219], 0
	v_mfma_f32_16x16x32_bf16 v[134:137], v[180:183], v[196:199], v[134:137]
	v_mfma_f32_16x16x32_bf16 v[130:133], v[188:191], v[196:199], v[130:133]
	v_mfma_f32_16x16x32_bf16 v[118:121], v[180:183], v[204:207], v[118:121]
	v_mfma_f32_16x16x32_bf16 v[114:117], v[188:191], v[204:207], v[114:117]
	v_mfma_f32_16x16x32_bf16 v[102:105], v[180:183], v[212:215], v[102:105]
	v_mfma_f32_16x16x32_bf16 v[98:101], v[188:191], v[212:215], v[98:101]
	v_mfma_f32_16x16x32_bf16 v[86:89], v[180:183], v[220:223], v[86:89]
	v_mfma_f32_16x16x32_bf16 v[82:85], v[188:191], v[220:223], v[82:85]
	s_barrier
	s_add_i32 s51, s41, s25
	s_mov_b32 m0, s51
	ds_read_b128 v[192:195], v175 offset:16384
	ds_read_b128 v[196:199], v175 offset:17408
	ds_read_b128 v[200:203], v175 offset:18432
	ds_read_b128 v[204:207], v175 offset:19456
	ds_read_b128 v[208:211], v175 offset:20480
	ds_read_b128 v[212:215], v175 offset:21504
	ds_read_b128 v[216:219], v175 offset:22528
	ds_read_b128 v[220:223], v175 offset:23552
	global_load_lds_dwordx4 v150, s[20:21]
	s_add_i32 m0, s51, 0x2000
	s_add_u32 s52, s20, 0x80000
	v_lshl_add_u64 v[224:225], s[20:21], 0, v[146:147]
	s_addc_u32 s53, s21, 0
	s_add_i32 s51, s42, s25
	global_load_lds_dwordx4 v146, s[20:21]
	s_mov_b32 m0, s51
	v_lshl_add_u64 v[228:229], s[22:23], 0, v[148:149]
	global_load_lds_dwordx4 v150, s[52:53]
	s_add_i32 m0, s51, 0x2000
	s_nop 0
	global_load_lds_dwordx4 v146, s[52:53]
	v_lshl_add_u64 v[226:227], s[22:23], 0, v[152:153]
	s_mov_b32 m0, s28
	s_nop 0
	global_load_lds_dwordx4 v152, s[22:23]
	s_mov_b32 m0, s29
	s_nop 0
	global_load_lds_dwordx4 v148, s[22:23]
	s_waitcnt lgkmcnt(0)
	s_barrier
	s_waitcnt lgkmcnt(0)
	v_mfma_f32_16x16x32_bf16 v[62:65], v[66:69], v[192:195], 0
	v_mfma_f32_16x16x32_bf16 v[58:61], v[74:77], v[192:195], 0
	v_mfma_f32_16x16x32_bf16 v[46:49], v[66:69], v[200:203], 0
	v_mfma_f32_16x16x32_bf16 v[42:45], v[74:77], v[200:203], 0
	v_mfma_f32_16x16x32_bf16 v[30:33], v[66:69], v[208:211], 0
	v_mfma_f32_16x16x32_bf16 v[26:29], v[74:77], v[208:211], 0
	v_mfma_f32_16x16x32_bf16 v[14:17], v[66:69], v[216:219], 0
	v_mfma_f32_16x16x32_bf16 v[10:13], v[74:77], v[216:219], 0
	v_mfma_f32_16x16x32_bf16 v[62:65], v[70:73], v[196:199], v[62:65]
	v_mfma_f32_16x16x32_bf16 v[58:61], v[78:81], v[196:199], v[58:61]
	v_mfma_f32_16x16x32_bf16 v[46:49], v[70:73], v[204:207], v[46:49]
	v_mfma_f32_16x16x32_bf16 v[42:45], v[78:81], v[204:207], v[42:45]
	v_mfma_f32_16x16x32_bf16 v[30:33], v[70:73], v[212:215], v[30:33]
	v_mfma_f32_16x16x32_bf16 v[26:29], v[78:81], v[212:215], v[26:29]
	v_mfma_f32_16x16x32_bf16 v[14:17], v[70:73], v[220:223], v[14:17]
	v_mfma_f32_16x16x32_bf16 v[10:13], v[78:81], v[220:223], v[10:13]
	v_mfma_f32_16x16x32_bf16 v[54:57], v[162:165], v[192:195], 0
	v_mfma_f32_16x16x32_bf16 v[50:53], v[184:187], v[192:195], 0
	v_mfma_f32_16x16x32_bf16 v[38:41], v[162:165], v[200:203], 0
	v_mfma_f32_16x16x32_bf16 v[34:37], v[184:187], v[200:203], 0
	v_mfma_f32_16x16x32_bf16 v[22:25], v[162:165], v[208:211], 0
	v_mfma_f32_16x16x32_bf16 v[18:21], v[184:187], v[208:211], 0
	v_mfma_f32_16x16x32_bf16 v[6:9], v[162:165], v[216:219], 0
	v_mfma_f32_16x16x32_bf16 v[2:5], v[184:187], v[216:219], 0
	v_mfma_f32_16x16x32_bf16 v[54:57], v[180:183], v[196:199], v[54:57]
	v_mfma_f32_16x16x32_bf16 v[50:53], v[188:191], v[196:199], v[50:53]
	v_mfma_f32_16x16x32_bf16 v[38:41], v[180:183], v[204:207], v[38:41]
	v_mfma_f32_16x16x32_bf16 v[34:37], v[188:191], v[204:207], v[34:37]
	v_mfma_f32_16x16x32_bf16 v[22:25], v[180:183], v[212:215], v[22:25]
	v_mfma_f32_16x16x32_bf16 v[18:21], v[188:191], v[212:215], v[18:21]
	v_mfma_f32_16x16x32_bf16 v[6:9], v[180:183], v[220:223], v[6:9]
	v_mfma_f32_16x16x32_bf16 v[2:5], v[188:191], v[220:223], v[2:5]
	s_barrier
; #define PG8_STAGE(bufoff, gbase, voff) do { _Pragma("unroll") for (int _i = 0; _i < 2; ++_i) \
;         __builtin_amdgcn_global_load_lds((const unsigned*)((const char*)(gbase) + (voff)[_i]), (LAS unsigned*)(lds + (bufoff) + ldsw + _i * 8192), 16, 0, 0); } while (0)
; #define PG8_LDA(dst, b, h) do { _Pragma("unroll") for (int m = 0; m < 4; ++m) _Pragma("unroll") for (int k = 0; k < 2; ++k) dst[m][k] = *(const LAS bf16x8*)(lds + PG8_SA(b, h) + aoff + m * 2048 + k * 1024); } while (0)
; #define PG8_LDB(dst, b, h) do { _Pragma("unroll") for (int n = 0; n < 2; ++n) _Pragma("unroll") for (int k = 0; k < 2; ++k) dst[n][k] = *(const LAS bf16x8*)(lds + PG8_SB(b, h) + boff + n * 2048 + k * 1024); } while (0)
; #define PG8_MMA(ai, bj, At, Bt) do { __builtin_amdgcn_s_setprio(1); _Pragma("unroll") for (int m = 0; m < 4; ++m) _Pragma("unroll") for (int n = 0; n < 2; ++n) _Pragma("unroll") for (int k = 0; k < 2; ++k) \
;         acc[ai][bj][m][n] = __builtin_amdgcn_mfma_f32_16x16x32_bf16(Bt[n][k], At[m][k], acc[ai][bj][m][n], 0, 0, 0); __builtin_amdgcn_s_setprio(0); } while (0)
; #define PG8_WAIT_V(n) asm volatile("s_waitcnt vmcnt(" #n ")" ::: "memory")
; #define PG8_WAIT_L(n) asm volatile("s_waitcnt lgkmcnt(" #n ")" ::: "memory")
; #define PG8_BAR __builtin_amdgcn_s_barrier()
; #define PG8_SCHED __builtin_amdgcn_sched_barrier(0)
; template <class Epi, class Sched, bool ALIGN_EPI = false, bool SP2 = false>
; __device__ __forceinline__ void gemm_phase(LAS unsigned char* lds, const Gemm g, const Sched& S, const Epi& E) {
;     ...
;         for (int t = 0; t < nt; t += 2) {
;     ...
;             PG8_LDB(B0, 1, 0); PG8_LDB(B1, 1, 1); PG8_SCHED; PG8_LDA(At, 1, 0); PG8_STAGE(PG8_SA(0, 1), a2 + hstep, voffA);
;             PG8_WAIT_V(8); PG8_WAIT_L(0); PG8_BAR; PG8_MMA(0, 0, At, B0); PG8_MMA(0, 1, At, B1); PG8_BAR; PG8_SCHED;
;             PG8_LDA(At, 1, 1); PG8_STAGE(PG8_SB(1, 0), b3, voffB); PG8_STAGE(PG8_SB(1, 1), b3 + hstepB, voffB); PG8_STAGE(PG8_SA(1, 0), a3, voffA);
;             PG8_WAIT_V(8); PG8_WAIT_L(0); PG8_BAR; PG8_MMA(1, 0, At, B0); PG8_MMA(1, 1, At, B1); PG8_BAR; PG8_SCHED;
	s_add_i32 s51, 0, 0x18000
	s_add_i32 s52, 0, 0x1c000
	v_add_u32_e32 v78, s51, v169
	v_add_u32_e32 v168, s52, v169
	ds_read_b128 v[66:69], v78
	ds_read_b128 v[70:73], v78 offset:1024
	ds_read_b128 v[74:77], v78 offset:2048
	ds_read_b128 v[78:81], v78 offset:3072
	ds_read_b128 v[162:165], v168
	ds_read_b128 v[180:183], v168 offset:1024
	ds_read_b128 v[184:187], v168 offset:2048
	ds_read_b128 v[188:191], v168 offset:3072
	s_add_u32 s22, s22, 0x80000
	s_addc_u32 s23, s23, 0
	s_mov_b32 m0, s30
	ds_read_b128 v[192:195], v175 offset:32768
	ds_read_b128 v[196:199], v175 offset:33792
	ds_read_b128 v[200:203], v175 offset:34816
	ds_read_b128 v[204:207], v175 offset:35840
	ds_read_b128 v[208:211], v175 offset:36864
	ds_read_b128 v[212:215], v175 offset:37888
	ds_read_b128 v[216:219], v175 offset:38912
	ds_read_b128 v[220:223], v175 offset:39936
	global_load_lds_dwordx4 v152, s[22:23]
	s_mov_b32 m0, s31
	s_nop 0
	global_load_lds_dwordx4 v148, s[22:23]
	s_waitcnt vmcnt(8)
	s_waitcnt lgkmcnt(0)
	s_barrier
	s_waitcnt lgkmcnt(0)
	v_mfma_f32_16x16x32_bf16 v[142:145], v[66:69], v[192:195], v[142:145]
	v_mfma_f32_16x16x32_bf16 v[138:141], v[74:77], v[192:195], v[138:141]
	v_mfma_f32_16x16x32_bf16 v[126:129], v[66:69], v[200:203], v[126:129]
	v_mfma_f32_16x16x32_bf16 v[122:125], v[74:77], v[200:203], v[122:125]
	v_mfma_f32_16x16x32_bf16 v[110:113], v[66:69], v[208:211], v[110:113]
	v_mfma_f32_16x16x32_bf16 v[106:109], v[74:77], v[208:211], v[106:109]
	v_mfma_f32_16x16x32_bf16 v[94:97], v[66:69], v[216:219], v[94:97]
	v_mfma_f32_16x16x32_bf16 v[90:93], v[74:77], v[216:219], v[90:93]
	v_mfma_f32_16x16x32_bf16 v[142:145], v[70:73], v[196:199], v[142:145]
	v_mfma_f32_16x16x32_bf16 v[138:141], v[78:81], v[196:199], v[138:141]
	v_mfma_f32_16x16x32_bf16 v[126:129], v[70:73], v[204:207], v[126:129]
	v_mfma_f32_16x16x32_bf16 v[122:125], v[78:81], v[204:207], v[122:125]
	v_mfma_f32_16x16x32_bf16 v[110:113], v[70:73], v[212:215], v[110:113]
	v_mfma_f32_16x16x32_bf16 v[106:109], v[78:81], v[212:215], v[106:109]
	v_mfma_f32_16x16x32_bf16 v[94:97], v[70:73], v[220:223], v[94:97]
	v_mfma_f32_16x16x32_bf16 v[90:93], v[78:81], v[220:223], v[90:93]
	v_mfma_f32_16x16x32_bf16 v[134:137], v[162:165], v[192:195], v[134:137]
	v_mfma_f32_16x16x32_bf16 v[130:133], v[184:187], v[192:195], v[130:133]
	v_mfma_f32_16x16x32_bf16 v[118:121], v[162:165], v[200:203], v[118:121]
	v_mfma_f32_16x16x32_bf16 v[114:117], v[184:187], v[200:203], v[114:117]
	v_mfma_f32_16x16x32_bf16 v[102:105], v[162:165], v[208:211], v[102:105]
	v_mfma_f32_16x16x32_bf16 v[98:101], v[184:187], v[208:211], v[98:101]
	v_mfma_f32_16x16x32_bf16 v[86:89], v[162:165], v[216:219], v[86:89]
	v_mfma_f32_16x16x32_bf16 v[82:85], v[184:187], v[216:219], v[82:85]
	v_mfma_f32_16x16x32_bf16 v[134:137], v[180:183], v[196:199], v[134:137]
	v_mfma_f32_16x16x32_bf16 v[130:133], v[188:191], v[196:199], v[130:133]
	v_mfma_f32_16x16x32_bf16 v[118:121], v[180:183], v[204:207], v[118:121]
	v_mfma_f32_16x16x32_bf16 v[114:117], v[188:191], v[204:207], v[114:117]
	v_mfma_f32_16x16x32_bf16 v[102:105], v[180:183], v[212:215], v[102:105]
	v_mfma_f32_16x16x32_bf16 v[98:101], v[188:191], v[212:215], v[98:101]
	v_mfma_f32_16x16x32_bf16 v[86:89], v[180:183], v[220:223], v[86:89]
	v_mfma_f32_16x16x32_bf16 v[82:85], v[188:191], v[220:223], v[82:85]
	s_barrier
	s_add_u32 s98, s20, 0x80
	s_addc_u32 s99, s21, 0
	s_add_i32 s22, s51, s25
	s_mov_b32 m0, s22
	ds_read_b128 v[192:195], v175 offset:49152
	ds_read_b128 v[196:199], v175 offset:50176
	ds_read_b128 v[200:203], v175 offset:51200
	ds_read_b128 v[204:207], v175 offset:52224
	ds_read_b128 v[208:211], v175 offset:53248
	ds_read_b128 v[212:215], v175 offset:54272
	ds_read_b128 v[216:219], v175 offset:55296
	ds_read_b128 v[220:223], v175 offset:56320
	global_load_lds_dwordx4 v150, s[98:99]
	s_add_i32 m0, s22, 0x2000
	s_add_u32 s20, s20, 0x80080
	v_lshl_add_u64 v[166:167], v[224:225], 0, s[6:7]
	s_addc_u32 s21, s21, 0
	s_add_i32 s22, s52, s25
	global_load_lds_dwordx4 v[166:167], off
	s_mov_b32 m0, s22
	s_nop 0
	global_load_lds_dwordx4 v150, s[20:21]
	s_add_i32 m0, s22, 0x2000
	s_nop 0
	global_load_lds_dwordx4 v146, s[20:21]
	v_lshl_add_u64 v[166:167], v[226:227], 0, s[6:7]
	s_mov_b32 m0, s39
	s_nop 0
	global_load_lds_dwordx4 v[166:167], off
	v_lshl_add_u64 v[166:167], v[228:229], 0, s[6:7]
	s_mov_b32 m0, s40
	s_nop 0
	global_load_lds_dwordx4 v[166:167], off
	s_waitcnt vmcnt(8)
	s_waitcnt lgkmcnt(0)
	s_barrier
	s_waitcnt lgkmcnt(0)
	v_mfma_f32_16x16x32_bf16 v[62:65], v[66:69], v[192:195], v[62:65]
	v_mfma_f32_16x16x32_bf16 v[58:61], v[74:77], v[192:195], v[58:61]
	v_mfma_f32_16x16x32_bf16 v[46:49], v[66:69], v[200:203], v[46:49]
	v_mfma_f32_16x16x32_bf16 v[42:45], v[74:77], v[200:203], v[42:45]
	v_mfma_f32_16x16x32_bf16 v[30:33], v[66:69], v[208:211], v[30:33]
	v_mfma_f32_16x16x32_bf16 v[26:29], v[74:77], v[208:211], v[26:29]
	v_mfma_f32_16x16x32_bf16 v[14:17], v[66:69], v[216:219], v[14:17]
	v_mfma_f32_16x16x32_bf16 v[10:13], v[74:77], v[216:219], v[10:13]
	v_mfma_f32_16x16x32_bf16 v[62:65], v[70:73], v[196:199], v[62:65]
	v_mfma_f32_16x16x32_bf16 v[58:61], v[78:81], v[196:199], v[58:61]
	v_mfma_f32_16x16x32_bf16 v[46:49], v[70:73], v[204:207], v[46:49]
	v_mfma_f32_16x16x32_bf16 v[42:45], v[78:81], v[204:207], v[42:45]
	v_mfma_f32_16x16x32_bf16 v[30:33], v[70:73], v[212:215], v[30:33]
	v_mfma_f32_16x16x32_bf16 v[26:29], v[78:81], v[212:215], v[26:29]
	v_mfma_f32_16x16x32_bf16 v[14:17], v[70:73], v[220:223], v[14:17]
	v_mfma_f32_16x16x32_bf16 v[10:13], v[78:81], v[220:223], v[10:13]
	v_mfma_f32_16x16x32_bf16 v[54:57], v[162:165], v[192:195], v[54:57]
	v_mfma_f32_16x16x32_bf16 v[50:53], v[184:187], v[192:195], v[50:53]
	v_mfma_f32_16x16x32_bf16 v[38:41], v[162:165], v[200:203], v[38:41]
	v_mfma_f32_16x16x32_bf16 v[34:37], v[184:187], v[200:203], v[34:37]
	v_mfma_f32_16x16x32_bf16 v[22:25], v[162:165], v[208:211], v[22:25]
	v_mfma_f32_16x16x32_bf16 v[18:21], v[184:187], v[208:211], v[18:21]
	v_mfma_f32_16x16x32_bf16 v[6:9], v[162:165], v[216:219], v[6:9]
	v_mfma_f32_16x16x32_bf16 v[2:5], v[184:187], v[216:219], v[2:5]
	v_mfma_f32_16x16x32_bf16 v[54:57], v[180:183], v[196:199], v[54:57]
	v_mfma_f32_16x16x32_bf16 v[50:53], v[188:191], v[196:199], v[50:53]
	v_mfma_f32_16x16x32_bf16 v[38:41], v[180:183], v[204:207], v[38:41]
	v_mfma_f32_16x16x32_bf16 v[34:37], v[188:191], v[204:207], v[34:37]
	v_mfma_f32_16x16x32_bf16 v[22:25], v[180:183], v[212:215], v[22:25]
	v_mfma_f32_16x16x32_bf16 v[18:21], v[188:191], v[212:215], v[18:21]
	v_mfma_f32_16x16x32_bf16 v[6:9], v[180:183], v[220:223], v[6:9]
	v_mfma_f32_16x16x32_bf16 v[2:5], v[188:191], v[220:223], v[2:5]
	s_barrier
	s_add_i32 s50, s50, 2
	s_add_u32 s48, s48, 0x100
	s_addc_u32 s49, s49, 0
	s_add_u32 s18, s18, 0x100
	s_addc_u32 s19, s19, 0
	s_cmp_lt_u32 s50, 30
; #define PG8_STAGE(bufoff, gbase, voff) do { _Pragma("unroll") for (int _i = 0; _i < 2; ++_i) \
;         __builtin_amdgcn_global_load_lds((const unsigned*)((const char*)(gbase) + (voff)[_i]), (LAS unsigned*)(lds + (bufoff) + ldsw + _i * 8192), 16, 0, 0); } while (0)
; #define PG8_LDA(dst, b, h) do { _Pragma("unroll") for (int m = 0; m < 4; ++m) _Pragma("unroll") for (int k = 0; k < 2; ++k) dst[m][k] = *(const LAS bf16x8*)(lds + PG8_SA(b, h) + aoff + m * 2048 + k * 1024); } while (0)
; #define PG8_LDB(dst, b, h) do { _Pragma("unroll") for (int n = 0; n < 2; ++n) _Pragma("unroll") for (int k = 0; k < 2; ++k) dst[n][k] = *(const LAS bf16x8*)(lds + PG8_SB(b, h) + boff + n * 2048 + k * 1024); } while (0)
; #define PG8_MMA(ai, bj, At, Bt) do { __builtin_amdgcn_s_setprio(1); _Pragma("unroll") for (int m = 0; m < 4; ++m) _Pragma("unroll") for (int n = 0; n < 2; ++n) _Pragma("unroll") for (int k = 0; k < 2; ++k) \
;         acc[ai][bj][m][n] = __builtin_amdgcn_mfma_f32_16x16x32_bf16(Bt[n][k], At[m][k], acc[ai][bj][m][n], 0, 0, 0); __builtin_amdgcn_s_setprio(0); } while (0)
; #define PG8_WAIT_V(n) asm volatile("s_waitcnt vmcnt(" #n ")" ::: "memory")
; #define PG8_WAIT_L(n) asm volatile("s_waitcnt lgkmcnt(" #n ")" ::: "memory")
; #define PG8_BAR __builtin_amdgcn_s_barrier()
; template <class Epi, class Sched, bool ALIGN_EPI = false, bool SP2 = false>
; __device__ __forceinline__ void gemm_phase(LAS unsigned char* lds, const Gemm g, const Sched& S, const Epi& E) {
;     ...
;             const bool last = (t == nt - 2);
;             const char* a1 = cA + (size_t)(t + 1) * kstep;
;             const char* a2 = last ? nA : cA + (size_t)(t + 2) * kstep; const char* b2 = last ? nB : cB + (size_t)(t + 2) * kstep;
;             const char* a3 = a2 + kstep; const char* b3 = b2 + kstep;
;             if (last && has_next) S.a_ready(nxt);
;             if constexpr (SP2) {
;             PG8_LDB(B0, 0, 0); PG8_LDB(B1, 0, 1); PG8_SCHED; PG8_LDA(At, 0, 0); PG8_STAGE(PG8_SA(1, 1), a1 + hstep, voffA);
;             PG8_WAIT_V(8); PG8_WAIT_L(0); PG8_BAR; PG8_MMA(0, 0, At, B0); PG8_MMA(0, 1, At, B1); PG8_BAR; PG8_SCHED;
;             PG8_LDA(At, 0, 1); PG8_STAGE(PG8_SB(0, 0), b2, voffB); PG8_STAGE(PG8_SB(0, 1), b2 + hstepB, voffB); PG8_STAGE(PG8_SA(0, 0), a2, voffA);
;             PG8_WAIT_V(8); PG8_WAIT_L(0); PG8_BAR; PG8_MMA(1, 0, At, B0); PG8_MMA(1, 1, At, B1); PG8_BAR; PG8_SCHED;
.LBB0_2916:
	ds_read_b128 v[66:69], v173
	ds_read_b128 v[70:73], v173 offset:1024
	ds_read_b128 v[74:77], v173 offset:2048
	ds_read_b128 v[78:81], v173 offset:3072
	ds_read_b128 v[162:165], v174
	ds_read_b128 v[180:183], v174 offset:1024
	ds_read_b128 v[184:187], v174 offset:2048
	ds_read_b128 v[188:191], v174 offset:3072
	s_add_u32 s20, s18, 0xfff80080
	s_addc_u32 s21, s19, -1
	s_cmp_eq_u32 s50, 28
	s_cselect_b32 s23, s13, s21
	s_cselect_b32 s22, s46, s20
	s_cselect_b32 s21, s11, s49
	s_cselect_b32 s20, s47, s48
	s_add_i32 m0, s28, 0xc000
	ds_read_b128 v[192:195], v175
	ds_read_b128 v[196:199], v175 offset:1024
	ds_read_b128 v[200:203], v175 offset:2048
	ds_read_b128 v[204:207], v175 offset:3072
	ds_read_b128 v[208:211], v175 offset:4096
	ds_read_b128 v[212:215], v175 offset:5120
	ds_read_b128 v[216:219], v175 offset:6144
	ds_read_b128 v[220:223], v175 offset:7168
	global_load_lds_dwordx4 v156, s[18:19]
	s_add_i32 m0, s28, 0xe000
	s_nop 0
	global_load_lds_dwordx4 v154, s[18:19]
	s_waitcnt vmcnt(8)
	s_waitcnt lgkmcnt(0)
	s_barrier
	s_waitcnt lgkmcnt(0)
	v_mfma_f32_16x16x32_bf16 v[142:145], v[66:69], v[192:195], v[142:145]
	v_mfma_f32_16x16x32_bf16 v[138:141], v[74:77], v[192:195], v[138:141]
	v_mfma_f32_16x16x32_bf16 v[126:129], v[66:69], v[200:203], v[126:129]
	v_mfma_f32_16x16x32_bf16 v[122:125], v[74:77], v[200:203], v[122:125]
	v_mfma_f32_16x16x32_bf16 v[110:113], v[66:69], v[208:211], v[110:113]
	v_mfma_f32_16x16x32_bf16 v[106:109], v[74:77], v[208:211], v[106:109]
	v_mfma_f32_16x16x32_bf16 v[94:97], v[66:69], v[216:219], v[94:97]
	v_mfma_f32_16x16x32_bf16 v[90:93], v[74:77], v[216:219], v[90:93]
	v_mfma_f32_16x16x32_bf16 v[142:145], v[70:73], v[196:199], v[142:145]
	v_mfma_f32_16x16x32_bf16 v[138:141], v[78:81], v[196:199], v[138:141]
	v_mfma_f32_16x16x32_bf16 v[126:129], v[70:73], v[204:207], v[126:129]
	v_mfma_f32_16x16x32_bf16 v[122:125], v[78:81], v[204:207], v[122:125]
	v_mfma_f32_16x16x32_bf16 v[110:113], v[70:73], v[212:215], v[110:113]
	v_mfma_f32_16x16x32_bf16 v[106:109], v[78:81], v[212:215], v[106:109]
	v_mfma_f32_16x16x32_bf16 v[94:97], v[70:73], v[220:223], v[94:97]
	v_mfma_f32_16x16x32_bf16 v[90:93], v[78:81], v[220:223], v[90:93]
	v_mfma_f32_16x16x32_bf16 v[134:137], v[162:165], v[192:195], v[134:137]
	v_mfma_f32_16x16x32_bf16 v[130:133], v[184:187], v[192:195], v[130:133]
	v_mfma_f32_16x16x32_bf16 v[118:121], v[162:165], v[200:203], v[118:121]
	v_mfma_f32_16x16x32_bf16 v[114:117], v[184:187], v[200:203], v[114:117]
	v_mfma_f32_16x16x32_bf16 v[102:105], v[162:165], v[208:211], v[102:105]
	v_mfma_f32_16x16x32_bf16 v[98:101], v[184:187], v[208:211], v[98:101]
	v_mfma_f32_16x16x32_bf16 v[86:89], v[162:165], v[216:219], v[86:89]
	v_mfma_f32_16x16x32_bf16 v[82:85], v[184:187], v[216:219], v[82:85]
	v_mfma_f32_16x16x32_bf16 v[134:137], v[180:183], v[196:199], v[134:137]
	v_mfma_f32_16x16x32_bf16 v[130:133], v[188:191], v[196:199], v[130:133]
	v_mfma_f32_16x16x32_bf16 v[118:121], v[180:183], v[204:207], v[118:121]
	v_mfma_f32_16x16x32_bf16 v[114:117], v[188:191], v[204:207], v[114:117]
	v_mfma_f32_16x16x32_bf16 v[102:105], v[180:183], v[212:215], v[102:105]
	v_mfma_f32_16x16x32_bf16 v[98:101], v[188:191], v[212:215], v[98:101]
	v_mfma_f32_16x16x32_bf16 v[86:89], v[180:183], v[220:223], v[86:89]
	v_mfma_f32_16x16x32_bf16 v[82:85], v[188:191], v[220:223], v[82:85]
	s_barrier
	s_add_i32 s51, s41, s25
	s_mov_b32 m0, s51
	ds_read_b128 v[192:195], v175 offset:16384
	ds_read_b128 v[196:199], v175 offset:17408
	ds_read_b128 v[200:203], v175 offset:18432
	ds_read_b128 v[204:207], v175 offset:19456
	ds_read_b128 v[208:211], v175 offset:20480
	ds_read_b128 v[212:215], v175 offset:21504
	ds_read_b128 v[216:219], v175 offset:22528
	ds_read_b128 v[220:223], v175 offset:23552
	global_load_lds_dwordx4 v150, s[20:21]
	s_add_i32 m0, s51, 0x2000
	s_add_u32 s52, s20, 0x80000
	v_lshl_add_u64 v[224:225], s[20:21], 0, v[146:147]
	s_addc_u32 s53, s21, 0
	s_add_i32 s51, s42, s25
	global_load_lds_dwordx4 v146, s[20:21]
	s_mov_b32 m0, s51
	v_lshl_add_u64 v[228:229], s[22:23], 0, v[148:149]
	global_load_lds_dwordx4 v150, s[52:53]
	s_add_i32 m0, s51, 0x2000
	s_nop 0
	global_load_lds_dwordx4 v146, s[52:53]
	v_lshl_add_u64 v[226:227], s[22:23], 0, v[152:153]
	s_mov_b32 m0, s28
	s_nop 0
	global_load_lds_dwordx4 v152, s[22:23]
	s_mov_b32 m0, s29
	s_nop 0
	global_load_lds_dwordx4 v148, s[22:23]
	s_waitcnt vmcnt(8)
	s_waitcnt lgkmcnt(0)
	s_barrier
	s_waitcnt lgkmcnt(0)
	v_mfma_f32_16x16x32_bf16 v[62:65], v[66:69], v[192:195], v[62:65]
	v_mfma_f32_16x16x32_bf16 v[58:61], v[74:77], v[192:195], v[58:61]
	v_mfma_f32_16x16x32_bf16 v[46:49], v[66:69], v[200:203], v[46:49]
	v_mfma_f32_16x16x32_bf16 v[42:45], v[74:77], v[200:203], v[42:45]
	v_mfma_f32_16x16x32_bf16 v[30:33], v[66:69], v[208:211], v[30:33]
	v_mfma_f32_16x16x32_bf16 v[26:29], v[74:77], v[208:211], v[26:29]
	v_mfma_f32_16x16x32_bf16 v[14:17], v[66:69], v[216:219], v[14:17]
	v_mfma_f32_16x16x32_bf16 v[10:13], v[74:77], v[216:219], v[10:13]
	v_mfma_f32_16x16x32_bf16 v[62:65], v[70:73], v[196:199], v[62:65]
	v_mfma_f32_16x16x32_bf16 v[58:61], v[78:81], v[196:199], v[58:61]
	v_mfma_f32_16x16x32_bf16 v[46:49], v[70:73], v[204:207], v[46:49]
	v_mfma_f32_16x16x32_bf16 v[42:45], v[78:81], v[204:207], v[42:45]
	v_mfma_f32_16x16x32_bf16 v[30:33], v[70:73], v[212:215], v[30:33]
	v_mfma_f32_16x16x32_bf16 v[26:29], v[78:81], v[212:215], v[26:29]
	v_mfma_f32_16x16x32_bf16 v[14:17], v[70:73], v[220:223], v[14:17]
	v_mfma_f32_16x16x32_bf16 v[10:13], v[78:81], v[220:223], v[10:13]
	v_mfma_f32_16x16x32_bf16 v[54:57], v[162:165], v[192:195], v[54:57]
	v_mfma_f32_16x16x32_bf16 v[50:53], v[184:187], v[192:195], v[50:53]
	v_mfma_f32_16x16x32_bf16 v[38:41], v[162:165], v[200:203], v[38:41]
	v_mfma_f32_16x16x32_bf16 v[34:37], v[184:187], v[200:203], v[34:37]
	v_mfma_f32_16x16x32_bf16 v[22:25], v[162:165], v[208:211], v[22:25]
	v_mfma_f32_16x16x32_bf16 v[18:21], v[184:187], v[208:211], v[18:21]
	v_mfma_f32_16x16x32_bf16 v[6:9], v[162:165], v[216:219], v[6:9]
	v_mfma_f32_16x16x32_bf16 v[2:5], v[184:187], v[216:219], v[2:5]
	v_mfma_f32_16x16x32_bf16 v[54:57], v[180:183], v[196:199], v[54:57]
	v_mfma_f32_16x16x32_bf16 v[50:53], v[188:191], v[196:199], v[50:53]
	v_mfma_f32_16x16x32_bf16 v[38:41], v[180:183], v[204:207], v[38:41]
	v_mfma_f32_16x16x32_bf16 v[34:37], v[188:191], v[204:207], v[34:37]
	v_mfma_f32_16x16x32_bf16 v[22:25], v[180:183], v[212:215], v[22:25]
	v_mfma_f32_16x16x32_bf16 v[18:21], v[188:191], v[212:215], v[18:21]
	v_mfma_f32_16x16x32_bf16 v[6:9], v[180:183], v[220:223], v[6:9]
	v_mfma_f32_16x16x32_bf16 v[2:5], v[188:191], v[220:223], v[2:5]
	s_barrier
; #define PG8_STAGE(bufoff, gbase, voff) do { _Pragma("unroll") for (int _i = 0; _i < 2; ++_i) \
;         __builtin_amdgcn_global_load_lds((const unsigned*)((const char*)(gbase) + (voff)[_i]), (LAS unsigned*)(lds + (bufoff) + ldsw + _i * 8192), 16, 0, 0); } while (0)
; #define PG8_LDA(dst, b, h) do { _Pragma("unroll") for (int m = 0; m < 4; ++m) _Pragma("unroll") for (int k = 0; k < 2; ++k) dst[m][k] = *(const LAS bf16x8*)(lds + PG8_SA(b, h) + aoff + m * 2048 + k * 1024); } while (0)
; #define PG8_LDB(dst, b, h) do { _Pragma("unroll") for (int n = 0; n < 2; ++n) _Pragma("unroll") for (int k = 0; k < 2; ++k) dst[n][k] = *(const LAS bf16x8*)(lds + PG8_SB(b, h) + boff + n * 2048 + k * 1024); } while (0)
; #define PG8_MMA(ai, bj, At, Bt) do { __builtin_amdgcn_s_setprio(1); _Pragma("unroll") for (int m = 0; m < 4; ++m) _Pragma("unroll") for (int n = 0; n < 2; ++n) _Pragma("unroll") for (int k = 0; k < 2; ++k) \
;         acc[ai][bj][m][n] = __builtin_amdgcn_mfma_f32_16x16x32_bf16(Bt[n][k], At[m][k], acc[ai][bj][m][n], 0, 0, 0); __builtin_amdgcn_s_setprio(0); } while (0)
; #define PG8_WAIT_V(n) asm volatile("s_waitcnt vmcnt(" #n ")" ::: "memory")
; #define PG8_WAIT_L(n) asm volatile("s_waitcnt lgkmcnt(" #n ")" ::: "memory")
; #define PG8_BAR __builtin_amdgcn_s_barrier()
; #define PG8_SCHED __builtin_amdgcn_sched_barrier(0)
; template <class Epi, class Sched, bool ALIGN_EPI = false, bool SP2 = false>
; __device__ __forceinline__ void gemm_phase(LAS unsigned char* lds, const Gemm g, const Sched& S, const Epi& E) {
;     ...
;             PG8_LDB(B0, 1, 0); PG8_LDB(B1, 1, 1); PG8_SCHED; PG8_LDA(At, 1, 0); PG8_STAGE(PG8_SA(0, 1), a2 + hstep, voffA);
;             PG8_WAIT_V(8); PG8_WAIT_L(0); PG8_BAR; PG8_MMA(0, 0, At, B0); PG8_MMA(0, 1, At, B1); PG8_BAR; PG8_SCHED;
;             PG8_LDA(At, 1, 1); PG8_STAGE(PG8_SB(1, 0), b3, voffB); PG8_STAGE(PG8_SB(1, 1), b3 + hstepB, voffB); PG8_STAGE(PG8_SA(1, 0), a3, voffA);
;             PG8_WAIT_V(8); PG8_WAIT_L(0); PG8_BAR; PG8_MMA(1, 0, At, B0); PG8_MMA(1, 1, At, B1); PG8_BAR; PG8_SCHED;
	s_add_i32 s51, 0, 0x18000
	s_add_i32 s52, 0, 0x1c000
	v_add_u32_e32 v78, s51, v169
	v_add_u32_e32 v168, s52, v169
	ds_read_b128 v[66:69], v78
	ds_read_b128 v[70:73], v78 offset:1024
	ds_read_b128 v[74:77], v78 offset:2048
	ds_read_b128 v[78:81], v78 offset:3072
	ds_read_b128 v[162:165], v168
	ds_read_b128 v[180:183], v168 offset:1024
	ds_read_b128 v[184:187], v168 offset:2048
	ds_read_b128 v[188:191], v168 offset:3072
	s_add_u32 s22, s22, 0x80000
	s_addc_u32 s23, s23, 0
	s_mov_b32 m0, s30
	ds_read_b128 v[192:195], v175 offset:32768
	ds_read_b128 v[196:199], v175 offset:33792
	ds_read_b128 v[200:203], v175 offset:34816
	ds_read_b128 v[204:207], v175 offset:35840
	ds_read_b128 v[208:211], v175 offset:36864
	ds_read_b128 v[212:215], v175 offset:37888
	ds_read_b128 v[216:219], v175 offset:38912
	ds_read_b128 v[220:223], v175 offset:39936
	global_load_lds_dwordx4 v152, s[22:23]
	s_mov_b32 m0, s31
	s_nop 0
	global_load_lds_dwordx4 v148, s[22:23]
	s_waitcnt vmcnt(8)
	s_waitcnt lgkmcnt(0)
	s_barrier
	s_waitcnt lgkmcnt(0)
	v_mfma_f32_16x16x32_bf16 v[142:145], v[66:69], v[192:195], v[142:145]
	v_mfma_f32_16x16x32_bf16 v[138:141], v[74:77], v[192:195], v[138:141]
	v_mfma_f32_16x16x32_bf16 v[126:129], v[66:69], v[200:203], v[126:129]
	v_mfma_f32_16x16x32_bf16 v[122:125], v[74:77], v[200:203], v[122:125]
	v_mfma_f32_16x16x32_bf16 v[110:113], v[66:69], v[208:211], v[110:113]
	v_mfma_f32_16x16x32_bf16 v[106:109], v[74:77], v[208:211], v[106:109]
	v_mfma_f32_16x16x32_bf16 v[94:97], v[66:69], v[216:219], v[94:97]
	v_mfma_f32_16x16x32_bf16 v[90:93], v[74:77], v[216:219], v[90:93]
	v_mfma_f32_16x16x32_bf16 v[142:145], v[70:73], v[196:199], v[142:145]
	v_mfma_f32_16x16x32_bf16 v[138:141], v[78:81], v[196:199], v[138:141]
	v_mfma_f32_16x16x32_bf16 v[126:129], v[70:73], v[204:207], v[126:129]
	v_mfma_f32_16x16x32_bf16 v[122:125], v[78:81], v[204:207], v[122:125]
	v_mfma_f32_16x16x32_bf16 v[110:113], v[70:73], v[212:215], v[110:113]
	v_mfma_f32_16x16x32_bf16 v[106:109], v[78:81], v[212:215], v[106:109]
	v_mfma_f32_16x16x32_bf16 v[94:97], v[70:73], v[220:223], v[94:97]
	v_mfma_f32_16x16x32_bf16 v[90:93], v[78:81], v[220:223], v[90:93]
	v_mfma_f32_16x16x32_bf16 v[134:137], v[162:165], v[192:195], v[134:137]
	v_mfma_f32_16x16x32_bf16 v[130:133], v[184:187], v[192:195], v[130:133]
	v_mfma_f32_16x16x32_bf16 v[118:121], v[162:165], v[200:203], v[118:121]
	v_mfma_f32_16x16x32_bf16 v[114:117], v[184:187], v[200:203], v[114:117]
	v_mfma_f32_16x16x32_bf16 v[102:105], v[162:165], v[208:211], v[102:105]
	v_mfma_f32_16x16x32_bf16 v[98:101], v[184:187], v[208:211], v[98:101]
	v_mfma_f32_16x16x32_bf16 v[86:89], v[162:165], v[216:219], v[86:89]
	v_mfma_f32_16x16x32_bf16 v[82:85], v[184:187], v[216:219], v[82:85]
	v_mfma_f32_16x16x32_bf16 v[134:137], v[180:183], v[196:199], v[134:137]
	v_mfma_f32_16x16x32_bf16 v[130:133], v[188:191], v[196:199], v[130:133]
	v_mfma_f32_16x16x32_bf16 v[118:121], v[180:183], v[204:207], v[118:121]
	v_mfma_f32_16x16x32_bf16 v[114:117], v[188:191], v[204:207], v[114:117]
	v_mfma_f32_16x16x32_bf16 v[102:105], v[180:183], v[212:215], v[102:105]
	v_mfma_f32_16x16x32_bf16 v[98:101], v[188:191], v[212:215], v[98:101]
	v_mfma_f32_16x16x32_bf16 v[86:89], v[180:183], v[220:223], v[86:89]
	v_mfma_f32_16x16x32_bf16 v[82:85], v[188:191], v[220:223], v[82:85]
	s_barrier
	s_add_u32 s98, s20, 0x80
	s_addc_u32 s99, s21, 0
	s_add_i32 s22, s51, s25
	s_mov_b32 m0, s22
	ds_read_b128 v[192:195], v175 offset:49152
	ds_read_b128 v[196:199], v175 offset:50176
	ds_read_b128 v[200:203], v175 offset:51200
	ds_read_b128 v[204:207], v175 offset:52224
	ds_read_b128 v[208:211], v175 offset:53248
	ds_read_b128 v[212:215], v175 offset:54272
	ds_read_b128 v[216:219], v175 offset:55296
	ds_read_b128 v[220:223], v175 offset:56320
	global_load_lds_dwordx4 v150, s[98:99]
	s_add_i32 m0, s22, 0x2000
	s_add_u32 s20, s20, 0x80080
	v_lshl_add_u64 v[166:167], v[224:225], 0, s[6:7]
	s_addc_u32 s21, s21, 0
	s_add_i32 s22, s52, s25
	global_load_lds_dwordx4 v[166:167], off
	s_mov_b32 m0, s22
	s_nop 0
	global_load_lds_dwordx4 v150, s[20:21]
	s_add_i32 m0, s22, 0x2000
	s_nop 0
	global_load_lds_dwordx4 v146, s[20:21]
	v_lshl_add_u64 v[166:167], v[226:227], 0, s[6:7]
	s_mov_b32 m0, s39
	s_nop 0
	global_load_lds_dwordx4 v[166:167], off
	v_lshl_add_u64 v[166:167], v[228:229], 0, s[6:7]
	s_mov_b32 m0, s40
	s_nop 0
	global_load_lds_dwordx4 v[166:167], off
	s_waitcnt vmcnt(8)
	s_waitcnt lgkmcnt(0)
	s_barrier
	s_waitcnt lgkmcnt(0)
	v_mfma_f32_16x16x32_bf16 v[62:65], v[66:69], v[192:195], v[62:65]
	v_mfma_f32_16x16x32_bf16 v[58:61], v[74:77], v[192:195], v[58:61]
	v_mfma_f32_16x16x32_bf16 v[46:49], v[66:69], v[200:203], v[46:49]
	v_mfma_f32_16x16x32_bf16 v[42:45], v[74:77], v[200:203], v[42:45]
	v_mfma_f32_16x16x32_bf16 v[30:33], v[66:69], v[208:211], v[30:33]
	v_mfma_f32_16x16x32_bf16 v[26:29], v[74:77], v[208:211], v[26:29]
	v_mfma_f32_16x16x32_bf16 v[14:17], v[66:69], v[216:219], v[14:17]
	v_mfma_f32_16x16x32_bf16 v[10:13], v[74:77], v[216:219], v[10:13]
	v_mfma_f32_16x16x32_bf16 v[62:65], v[70:73], v[196:199], v[62:65]
	v_mfma_f32_16x16x32_bf16 v[58:61], v[78:81], v[196:199], v[58:61]
	v_mfma_f32_16x16x32_bf16 v[46:49], v[70:73], v[204:207], v[46:49]
	v_mfma_f32_16x16x32_bf16 v[42:45], v[78:81], v[204:207], v[42:45]
	v_mfma_f32_16x16x32_bf16 v[30:33], v[70:73], v[212:215], v[30:33]
	v_mfma_f32_16x16x32_bf16 v[26:29], v[78:81], v[212:215], v[26:29]
	v_mfma_f32_16x16x32_bf16 v[14:17], v[70:73], v[220:223], v[14:17]
	v_mfma_f32_16x16x32_bf16 v[10:13], v[78:81], v[220:223], v[10:13]
	v_mfma_f32_16x16x32_bf16 v[54:57], v[162:165], v[192:195], v[54:57]
	v_mfma_f32_16x16x32_bf16 v[50:53], v[184:187], v[192:195], v[50:53]
	v_mfma_f32_16x16x32_bf16 v[38:41], v[162:165], v[200:203], v[38:41]
	v_mfma_f32_16x16x32_bf16 v[34:37], v[184:187], v[200:203], v[34:37]
	v_mfma_f32_16x16x32_bf16 v[22:25], v[162:165], v[208:211], v[22:25]
	v_mfma_f32_16x16x32_bf16 v[18:21], v[184:187], v[208:211], v[18:21]
	v_mfma_f32_16x16x32_bf16 v[6:9], v[162:165], v[216:219], v[6:9]
	v_mfma_f32_16x16x32_bf16 v[2:5], v[184:187], v[216:219], v[2:5]
	v_mfma_f32_16x16x32_bf16 v[54:57], v[180:183], v[196:199], v[54:57]
	v_mfma_f32_16x16x32_bf16 v[50:53], v[188:191], v[196:199], v[50:53]
	v_mfma_f32_16x16x32_bf16 v[38:41], v[180:183], v[204:207], v[38:41]
	v_mfma_f32_16x16x32_bf16 v[34:37], v[188:191], v[204:207], v[34:37]
	v_mfma_f32_16x16x32_bf16 v[22:25], v[180:183], v[212:215], v[22:25]
	v_mfma_f32_16x16x32_bf16 v[18:21], v[188:191], v[212:215], v[18:21]
	v_mfma_f32_16x16x32_bf16 v[6:9], v[180:183], v[220:223], v[6:9]
	v_mfma_f32_16x16x32_bf16 v[2:5], v[188:191], v[220:223], v[2:5]
	s_barrier
	s_add_i32 s50, s50, 2
	s_add_u32 s48, s48, 0x100
	s_addc_u32 s49, s49, 0
	s_add_u32 s18, s18, 0x100
	s_addc_u32 s19, s19, 0
	s_cmp_lt_u32 s50, 30
	s_cbranch_scc1 .LBB0_2916
	s_setprio 0
	s_andn2_b64 vcc, exec, s[8:9]
	s_cbranch_vccnz .LBB0_2919
	s_barrier

; #define PG8_STAGE(bufoff, gbase, voff) do { _Pragma("unroll") for (int _i = 0; _i < 2; ++_i) \
;         __builtin_amdgcn_global_load_lds((const unsigned*)((const char*)(gbase) + (voff)[_i]), (LAS unsigned*)(lds + (bufoff) + ldsw + _i * 8192), 16, 0, 0); } while (0)
; #define PG8_LDA(dst, b, h) do { _Pragma("unroll") for (int m = 0; m < 4; ++m) _Pragma("unroll") for (int k = 0; k < 2; ++k) dst[m][k] = *(const LAS bf16x8*)(lds + PG8_SA(b, h) + aoff + m * 2048 + k * 1024); } while (0)
; #define PG8_LDB(dst, b, h) do { _Pragma("unroll") for (int n = 0; n < 2; ++n) _Pragma("unroll") for (int k = 0; k < 2; ++k) dst[n][k] = *(const LAS bf16x8*)(lds + PG8_SB(b, h) + boff + n * 2048 + k * 1024); } while (0)
; #define PG8_MMA(ai, bj, At, Bt) do { __builtin_amdgcn_s_setprio(1); _Pragma("unroll") for (int m = 0; m < 4; ++m) _Pragma("unroll") for (int n = 0; n < 2; ++n) _Pragma("unroll") for (int k = 0; k < 2; ++k) \
;         acc[ai][bj][m][n] = __builtin_amdgcn_mfma_f32_16x16x32_bf16(Bt[n][k], At[m][k], acc[ai][bj][m][n], 0, 0, 0); __builtin_amdgcn_s_setprio(0); } while (0)
; #define PG8_WAIT_V(n) asm volatile("s_waitcnt vmcnt(" #n ")" ::: "memory")
; #define PG8_WAIT_L(n) asm volatile("s_waitcnt lgkmcnt(" #n ")" ::: "memory")
; #define PG8_BAR __builtin_amdgcn_s_barrier()
; template <class Epi, class Sched, bool ALIGN_EPI = false, bool SP2 = false>
; __device__ __forceinline__ void gemm_phase(LAS unsigned char* lds, const Gemm g, const Sched& S, const Epi& E) {
;     ...
;             const bool last = (t == nt - 2);
;             const char* a1 = cA + (size_t)(t + 1) * kstep;
;             const char* a2 = last ? nA : cA + (size_t)(t + 2) * kstep; const char* b2 = last ? nB : cB + (size_t)(t + 2) * kstep;
;             const char* a3 = a2 + kstep; const char* b3 = b2 + kstep;
;             if (last && has_next) S.a_ready(nxt);
;             if constexpr (SP2) {
;             PG8_LDB(B0, 0, 0); PG8_LDB(B1, 0, 1); PG8_SCHED; PG8_LDA(At, 0, 0); PG8_STAGE(PG8_SA(1, 1), a1 + hstep, voffA);
;             PG8_WAIT_V(8); PG8_WAIT_L(0); PG8_BAR; PG8_MMA(0, 0, At, B0); PG8_MMA(0, 1, At, B1); PG8_BAR; PG8_SCHED;
;             PG8_LDA(At, 0, 1); PG8_STAGE(PG8_SB(0, 0), b2, voffB); PG8_STAGE(PG8_SB(0, 1), b2 + hstepB, voffB); PG8_STAGE(PG8_SA(0, 0), a2, voffA);
;             PG8_WAIT_V(8); PG8_WAIT_L(0); PG8_BAR; PG8_MMA(1, 0, At, B0); PG8_MMA(1, 1, At, B1); PG8_BAR; PG8_SCHED;
.Lprio_3002:
	ds_read_b128 v[152:155], v147
	ds_read_b128 v[156:159], v147 offset:1024
	ds_read_b128 v[160:163], v147 offset:2048
	ds_read_b128 v[164:167], v147 offset:3072
	ds_read_b128 v[168:171], v148
	ds_read_b128 v[172:175], v148 offset:1024
	ds_read_b128 v[176:179], v148 offset:2048
	ds_read_b128 v[180:183], v148 offset:3072
	s_add_u32 s16, s14, 0x100
	s_addc_u32 s17, s15, 0
	s_cmpk_eq_i32 s40, 0x54
	s_cselect_b32 s21, s11, s17
	s_cselect_b32 s20, s10, s16
	s_cselect_b32 s19, s3, s39
	s_cselect_b32 s18, s2, s13
	v_lshl_add_u64 v[216:217], s[14:15], 0, v[138:139]
	s_add_i32 m0, s24, 0xc000
	ds_read_b128 v[184:187], v149
	ds_read_b128 v[188:191], v149 offset:1024
	ds_read_b128 v[192:195], v149 offset:2048
	ds_read_b128 v[196:199], v149 offset:3072
	ds_read_b128 v[200:203], v149 offset:4096
	ds_read_b128 v[204:207], v149 offset:5120
	ds_read_b128 v[208:211], v149 offset:6144
	ds_read_b128 v[212:215], v149 offset:7168
	global_load_lds_dwordx4 v[216:217], off
	v_lshl_add_u64 v[216:217], s[14:15], 0, v[136:137]
	s_add_i32 m0, s24, 0xe000
	s_nop 0
	global_load_lds_dwordx4 v[216:217], off
	s_waitcnt lgkmcnt(0)
	s_barrier
	s_waitcnt lgkmcnt(0)
	v_mfma_f32_16x16x32_bf16 v[124:127], v[152:155], v[184:187], 0
	v_mfma_f32_16x16x32_bf16 v[120:123], v[160:163], v[184:187], 0
	v_mfma_f32_16x16x32_bf16 v[112:115], v[152:155], v[192:195], 0
	v_mfma_f32_16x16x32_bf16 v[104:107], v[160:163], v[192:195], 0
	v_mfma_f32_16x16x32_bf16 v[92:95], v[152:155], v[200:203], 0
	v_mfma_f32_16x16x32_bf16 v[88:91], v[160:163], v[200:203], 0
	v_mfma_f32_16x16x32_bf16 v[76:79], v[152:155], v[208:211], 0
	v_mfma_f32_16x16x32_bf16 v[72:75], v[160:163], v[208:211], 0
	v_mfma_f32_16x16x32_bf16 v[124:127], v[156:159], v[188:191], v[124:127]
	v_mfma_f32_16x16x32_bf16 v[120:123], v[164:167], v[188:191], v[120:123]
	v_mfma_f32_16x16x32_bf16 v[112:115], v[156:159], v[196:199], v[112:115]
	v_mfma_f32_16x16x32_bf16 v[104:107], v[164:167], v[196:199], v[104:107]
	v_mfma_f32_16x16x32_bf16 v[92:95], v[156:159], v[204:207], v[92:95]
	v_mfma_f32_16x16x32_bf16 v[88:91], v[164:167], v[204:207], v[88:91]
	v_mfma_f32_16x16x32_bf16 v[76:79], v[156:159], v[212:215], v[76:79]
	v_mfma_f32_16x16x32_bf16 v[72:75], v[164:167], v[212:215], v[72:75]
	v_mfma_f32_16x16x32_bf16 v[116:119], v[168:171], v[184:187], 0
	v_mfma_f32_16x16x32_bf16 v[108:111], v[176:179], v[184:187], 0
	v_mfma_f32_16x16x32_bf16 v[100:103], v[168:171], v[192:195], 0
	v_mfma_f32_16x16x32_bf16 v[96:99], v[176:179], v[192:195], 0
	v_mfma_f32_16x16x32_bf16 v[84:87], v[168:171], v[200:203], 0
	v_mfma_f32_16x16x32_bf16 v[80:83], v[176:179], v[200:203], 0
	v_mfma_f32_16x16x32_bf16 v[68:71], v[168:171], v[208:211], 0
	v_mfma_f32_16x16x32_bf16 v[64:67], v[176:179], v[208:211], 0
	v_mfma_f32_16x16x32_bf16 v[116:119], v[172:175], v[188:191], v[116:119]
	v_mfma_f32_16x16x32_bf16 v[108:111], v[180:183], v[188:191], v[108:111]
	v_mfma_f32_16x16x32_bf16 v[100:103], v[172:175], v[196:199], v[100:103]
	v_mfma_f32_16x16x32_bf16 v[96:99], v[180:183], v[196:199], v[96:99]
	v_mfma_f32_16x16x32_bf16 v[84:87], v[172:175], v[204:207], v[84:87]
	v_mfma_f32_16x16x32_bf16 v[80:83], v[180:183], v[204:207], v[80:83]
	v_mfma_f32_16x16x32_bf16 v[68:71], v[172:175], v[212:215], v[68:71]
	v_mfma_f32_16x16x32_bf16 v[64:67], v[180:183], v[212:215], v[64:67]
	s_barrier
	s_add_i32 s14, s34, s23
	s_mov_b32 m0, s14
	ds_read_b128 v[184:187], v149 offset:16384
	ds_read_b128 v[188:191], v149 offset:17408
	ds_read_b128 v[192:195], v149 offset:18432
	ds_read_b128 v[196:199], v149 offset:19456
	ds_read_b128 v[200:203], v149 offset:20480
	ds_read_b128 v[204:207], v149 offset:21504
	ds_read_b128 v[208:211], v149 offset:22528
	ds_read_b128 v[212:215], v149 offset:23552
	global_load_lds_dwordx4 v130, s[18:19]
	s_add_i32 m0, s14, 0x2000
	s_add_u32 s14, s18, 0x58000
	v_lshl_add_u64 v[218:219], s[18:19], 0, v[134:135]
	s_addc_u32 s15, s19, 0
	s_add_i32 s41, s35, s23
	global_load_lds_dwordx4 v134, s[18:19]
	s_mov_b32 m0, s41
	global_load_lds_dwordx4 v130, s[14:15]
	s_add_i32 m0, s41, 0x2000
	s_nop 0
	global_load_lds_dwordx4 v134, s[14:15]
	s_mov_b32 m0, s24
	s_nop 0
	global_load_lds_dwordx4 v128, s[20:21]
	s_mov_b32 m0, s25
	s_nop 0
	global_load_lds_dwordx4 v132, s[20:21]
	s_waitcnt lgkmcnt(0)
	s_barrier
	s_waitcnt lgkmcnt(0)
	v_mfma_f32_16x16x32_bf16 v[60:63], v[152:155], v[184:187], 0
	v_mfma_f32_16x16x32_bf16 v[56:59], v[160:163], v[184:187], 0
	v_mfma_f32_16x16x32_bf16 v[44:47], v[152:155], v[192:195], 0
	v_mfma_f32_16x16x32_bf16 v[40:43], v[160:163], v[192:195], 0
	v_mfma_f32_16x16x32_bf16 v[28:31], v[152:155], v[200:203], 0
	v_mfma_f32_16x16x32_bf16 v[24:27], v[160:163], v[200:203], 0
	v_mfma_f32_16x16x32_bf16 v[12:15], v[152:155], v[208:211], 0
	v_mfma_f32_16x16x32_bf16 v[8:11], v[160:163], v[208:211], 0
	v_mfma_f32_16x16x32_bf16 v[60:63], v[156:159], v[188:191], v[60:63]
	v_mfma_f32_16x16x32_bf16 v[56:59], v[164:167], v[188:191], v[56:59]
	v_mfma_f32_16x16x32_bf16 v[44:47], v[156:159], v[196:199], v[44:47]
	v_mfma_f32_16x16x32_bf16 v[40:43], v[164:167], v[196:199], v[40:43]
	v_mfma_f32_16x16x32_bf16 v[28:31], v[156:159], v[204:207], v[28:31]
	v_mfma_f32_16x16x32_bf16 v[24:27], v[164:167], v[204:207], v[24:27]
	v_mfma_f32_16x16x32_bf16 v[12:15], v[156:159], v[212:215], v[12:15]
	v_mfma_f32_16x16x32_bf16 v[8:11], v[164:167], v[212:215], v[8:11]
	v_mfma_f32_16x16x32_bf16 v[52:55], v[168:171], v[184:187], 0
	v_mfma_f32_16x16x32_bf16 v[48:51], v[176:179], v[184:187], 0
	v_mfma_f32_16x16x32_bf16 v[36:39], v[168:171], v[192:195], 0
	v_mfma_f32_16x16x32_bf16 v[32:35], v[176:179], v[192:195], 0
	v_mfma_f32_16x16x32_bf16 v[20:23], v[168:171], v[200:203], 0
	v_mfma_f32_16x16x32_bf16 v[16:19], v[176:179], v[200:203], 0
	v_mfma_f32_16x16x32_bf16 v[4:7], v[168:171], v[208:211], 0
	v_mfma_f32_16x16x32_bf16 v[0:3], v[176:179], v[208:211], 0
	v_mfma_f32_16x16x32_bf16 v[52:55], v[172:175], v[188:191], v[52:55]
	v_mfma_f32_16x16x32_bf16 v[48:51], v[180:183], v[188:191], v[48:51]
	v_mfma_f32_16x16x32_bf16 v[36:39], v[172:175], v[196:199], v[36:39]
	v_mfma_f32_16x16x32_bf16 v[32:35], v[180:183], v[196:199], v[32:35]
	v_mfma_f32_16x16x32_bf16 v[20:23], v[172:175], v[204:207], v[20:23]
	v_mfma_f32_16x16x32_bf16 v[16:19], v[180:183], v[204:207], v[16:19]
	v_mfma_f32_16x16x32_bf16 v[4:7], v[172:175], v[212:215], v[4:7]
	v_mfma_f32_16x16x32_bf16 v[0:3], v[180:183], v[212:215], v[0:3]
	s_barrier
; #define PG8_STAGE(bufoff, gbase, voff) do { _Pragma("unroll") for (int _i = 0; _i < 2; ++_i) \
;         __builtin_amdgcn_global_load_lds((const unsigned*)((const char*)(gbase) + (voff)[_i]), (LAS unsigned*)(lds + (bufoff) + ldsw + _i * 8192), 16, 0, 0); } while (0)
; #define PG8_LDA(dst, b, h) do { _Pragma("unroll") for (int m = 0; m < 4; ++m) _Pragma("unroll") for (int k = 0; k < 2; ++k) dst[m][k] = *(const LAS bf16x8*)(lds + PG8_SA(b, h) + aoff + m * 2048 + k * 1024); } while (0)
; #define PG8_LDB(dst, b, h) do { _Pragma("unroll") for (int n = 0; n < 2; ++n) _Pragma("unroll") for (int k = 0; k < 2; ++k) dst[n][k] = *(const LAS bf16x8*)(lds + PG8_SB(b, h) + boff + n * 2048 + k * 1024); } while (0)
; #define PG8_MMA(ai, bj, At, Bt) do { __builtin_amdgcn_s_setprio(1); _Pragma("unroll") for (int m = 0; m < 4; ++m) _Pragma("unroll") for (int n = 0; n < 2; ++n) _Pragma("unroll") for (int k = 0; k < 2; ++k) \
;         acc[ai][bj][m][n] = __builtin_amdgcn_mfma_f32_16x16x32_bf16(Bt[n][k], At[m][k], acc[ai][bj][m][n], 0, 0, 0); __builtin_amdgcn_s_setprio(0); } while (0)
; #define PG8_WAIT_V(n) asm volatile("s_waitcnt vmcnt(" #n ")" ::: "memory")
; #define PG8_WAIT_L(n) asm volatile("s_waitcnt lgkmcnt(" #n ")" ::: "memory")
; #define PG8_BAR __builtin_amdgcn_s_barrier()
; #define PG8_SCHED __builtin_amdgcn_sched_barrier(0)
; template <class Epi, class Sched, bool ALIGN_EPI = false, bool SP2 = false>
; __device__ __forceinline__ void gemm_phase(LAS unsigned char* lds, const Gemm g, const Sched& S, const Epi& E) {
;     ...
;             PG8_LDB(B0, 1, 0); PG8_LDB(B1, 1, 1); PG8_SCHED; PG8_LDA(At, 1, 0); PG8_STAGE(PG8_SA(0, 1), a2 + hstep, voffA);
;             PG8_WAIT_V(8); PG8_WAIT_L(0); PG8_BAR; PG8_MMA(0, 0, At, B0); PG8_MMA(0, 1, At, B1); PG8_BAR; PG8_SCHED;
;             PG8_LDA(At, 1, 1); PG8_STAGE(PG8_SB(1, 0), b3, voffB); PG8_STAGE(PG8_SB(1, 1), b3 + hstepB, voffB); PG8_STAGE(PG8_SA(1, 0), a3, voffA);
;             PG8_WAIT_V(8); PG8_WAIT_L(0); PG8_BAR; PG8_MMA(1, 0, At, B0); PG8_MMA(1, 1, At, B1); PG8_BAR; PG8_SCHED;
	s_add_i32 s41, 0, 0x18000
	s_add_i32 s42, 0, 0x1c000
	v_add_u32_e32 v164, s41, v144
	v_add_u32_e32 v180, s42, v144
	ds_read_b128 v[152:155], v164
	ds_read_b128 v[156:159], v164 offset:1024
	ds_read_b128 v[160:163], v164 offset:2048
	ds_read_b128 v[164:167], v164 offset:3072
	ds_read_b128 v[168:171], v180
	ds_read_b128 v[172:175], v180 offset:1024
	ds_read_b128 v[176:179], v180 offset:2048
	ds_read_b128 v[180:183], v180 offset:3072
	s_add_u32 s14, s20, 0x160000
	s_addc_u32 s15, s21, 0
	s_mov_b32 m0, s26
	ds_read_b128 v[184:187], v149 offset:32768
	ds_read_b128 v[188:191], v149 offset:33792
	ds_read_b128 v[192:195], v149 offset:34816
	ds_read_b128 v[196:199], v149 offset:35840
	ds_read_b128 v[200:203], v149 offset:36864
	ds_read_b128 v[204:207], v149 offset:37888
	ds_read_b128 v[208:211], v149 offset:38912
	ds_read_b128 v[212:215], v149 offset:39936
	global_load_lds_dwordx4 v128, s[14:15]
	s_mov_b32 m0, s27
	s_nop 0
	global_load_lds_dwordx4 v132, s[14:15]
	s_waitcnt vmcnt(8)
	s_waitcnt lgkmcnt(0)
	s_barrier
	s_waitcnt lgkmcnt(0)
	v_mfma_f32_16x16x32_bf16 v[124:127], v[152:155], v[184:187], v[124:127]
	v_mfma_f32_16x16x32_bf16 v[120:123], v[160:163], v[184:187], v[120:123]
	v_mfma_f32_16x16x32_bf16 v[112:115], v[152:155], v[192:195], v[112:115]
	v_mfma_f32_16x16x32_bf16 v[104:107], v[160:163], v[192:195], v[104:107]
	v_mfma_f32_16x16x32_bf16 v[92:95], v[152:155], v[200:203], v[92:95]
	v_mfma_f32_16x16x32_bf16 v[88:91], v[160:163], v[200:203], v[88:91]
	v_mfma_f32_16x16x32_bf16 v[76:79], v[152:155], v[208:211], v[76:79]
	v_mfma_f32_16x16x32_bf16 v[72:75], v[160:163], v[208:211], v[72:75]
	v_mfma_f32_16x16x32_bf16 v[124:127], v[156:159], v[188:191], v[124:127]
	v_mfma_f32_16x16x32_bf16 v[120:123], v[164:167], v[188:191], v[120:123]
	v_mfma_f32_16x16x32_bf16 v[112:115], v[156:159], v[196:199], v[112:115]
	v_mfma_f32_16x16x32_bf16 v[104:107], v[164:167], v[196:199], v[104:107]
	v_mfma_f32_16x16x32_bf16 v[92:95], v[156:159], v[204:207], v[92:95]
	v_mfma_f32_16x16x32_bf16 v[88:91], v[164:167], v[204:207], v[88:91]
	v_mfma_f32_16x16x32_bf16 v[76:79], v[156:159], v[212:215], v[76:79]
	v_mfma_f32_16x16x32_bf16 v[72:75], v[164:167], v[212:215], v[72:75]
	v_mfma_f32_16x16x32_bf16 v[116:119], v[168:171], v[184:187], v[116:119]
	v_mfma_f32_16x16x32_bf16 v[108:111], v[176:179], v[184:187], v[108:111]
	v_mfma_f32_16x16x32_bf16 v[100:103], v[168:171], v[192:195], v[100:103]
	v_mfma_f32_16x16x32_bf16 v[96:99], v[176:179], v[192:195], v[96:99]
	v_mfma_f32_16x16x32_bf16 v[84:87], v[168:171], v[200:203], v[84:87]
	v_mfma_f32_16x16x32_bf16 v[80:83], v[176:179], v[200:203], v[80:83]
	v_mfma_f32_16x16x32_bf16 v[68:71], v[168:171], v[208:211], v[68:71]
	v_mfma_f32_16x16x32_bf16 v[64:67], v[176:179], v[208:211], v[64:67]
	v_mfma_f32_16x16x32_bf16 v[116:119], v[172:175], v[188:191], v[116:119]
	v_mfma_f32_16x16x32_bf16 v[108:111], v[180:183], v[188:191], v[108:111]
	v_mfma_f32_16x16x32_bf16 v[100:103], v[172:175], v[196:199], v[100:103]
	v_mfma_f32_16x16x32_bf16 v[96:99], v[180:183], v[196:199], v[96:99]
	v_mfma_f32_16x16x32_bf16 v[84:87], v[172:175], v[204:207], v[84:87]
	v_mfma_f32_16x16x32_bf16 v[80:83], v[180:183], v[204:207], v[80:83]
	v_mfma_f32_16x16x32_bf16 v[68:71], v[172:175], v[212:215], v[68:71]
	v_mfma_f32_16x16x32_bf16 v[64:67], v[180:183], v[212:215], v[64:67]
	s_barrier
	s_add_u32 s98, s18, 0x80
	s_addc_u32 s99, s19, 0
	s_add_u32 s100, s20, 0x80
	s_addc_u32 s101, s21, 0
	s_add_i32 s14, s41, s23
	s_mov_b32 m0, s14
	ds_read_b128 v[184:187], v149 offset:49152
	ds_read_b128 v[188:191], v149 offset:50176
	ds_read_b128 v[192:195], v149 offset:51200
	ds_read_b128 v[196:199], v149 offset:52224
	ds_read_b128 v[200:203], v149 offset:53248
	ds_read_b128 v[204:207], v149 offset:54272
	ds_read_b128 v[208:211], v149 offset:55296
	ds_read_b128 v[212:215], v149 offset:56320
	global_load_lds_dwordx4 v130, s[98:99]
	s_add_i32 m0, s14, 0x2000
	s_add_u32 s14, s18, 0x58080
	v_lshl_add_u64 v[216:217], v[218:219], 0, s[6:7]
	s_addc_u32 s15, s19, 0
	s_add_i32 s18, s42, s23
	global_load_lds_dwordx4 v[216:217], off
	s_mov_b32 m0, s18
	s_nop 0
	global_load_lds_dwordx4 v130, s[14:15]
	s_add_i32 m0, s18, 0x2000
	s_nop 0
	global_load_lds_dwordx4 v134, s[14:15]
	s_mov_b32 m0, s31
	s_nop 0
	global_load_lds_dwordx4 v128, s[100:101]
	s_mov_b32 m0, s33
	s_nop 0
	global_load_lds_dwordx4 v132, s[100:101]
	s_waitcnt vmcnt(8)
	s_waitcnt lgkmcnt(0)
	s_barrier
	s_waitcnt lgkmcnt(0)
	v_mfma_f32_16x16x32_bf16 v[60:63], v[152:155], v[184:187], v[60:63]
	v_mfma_f32_16x16x32_bf16 v[56:59], v[160:163], v[184:187], v[56:59]
	v_mfma_f32_16x16x32_bf16 v[44:47], v[152:155], v[192:195], v[44:47]
	v_mfma_f32_16x16x32_bf16 v[40:43], v[160:163], v[192:195], v[40:43]
	v_mfma_f32_16x16x32_bf16 v[28:31], v[152:155], v[200:203], v[28:31]
	v_mfma_f32_16x16x32_bf16 v[24:27], v[160:163], v[200:203], v[24:27]
	v_mfma_f32_16x16x32_bf16 v[12:15], v[152:155], v[208:211], v[12:15]
	v_mfma_f32_16x16x32_bf16 v[8:11], v[160:163], v[208:211], v[8:11]
	v_mfma_f32_16x16x32_bf16 v[60:63], v[156:159], v[188:191], v[60:63]
	v_mfma_f32_16x16x32_bf16 v[56:59], v[164:167], v[188:191], v[56:59]
	v_mfma_f32_16x16x32_bf16 v[44:47], v[156:159], v[196:199], v[44:47]
	v_mfma_f32_16x16x32_bf16 v[40:43], v[164:167], v[196:199], v[40:43]
	v_mfma_f32_16x16x32_bf16 v[28:31], v[156:159], v[204:207], v[28:31]
	v_mfma_f32_16x16x32_bf16 v[24:27], v[164:167], v[204:207], v[24:27]
	v_mfma_f32_16x16x32_bf16 v[12:15], v[156:159], v[212:215], v[12:15]
	v_mfma_f32_16x16x32_bf16 v[8:11], v[164:167], v[212:215], v[8:11]
	v_mfma_f32_16x16x32_bf16 v[52:55], v[168:171], v[184:187], v[52:55]
	v_mfma_f32_16x16x32_bf16 v[48:51], v[176:179], v[184:187], v[48:51]
	v_mfma_f32_16x16x32_bf16 v[36:39], v[168:171], v[192:195], v[36:39]
	v_mfma_f32_16x16x32_bf16 v[32:35], v[176:179], v[192:195], v[32:35]
	v_mfma_f32_16x16x32_bf16 v[20:23], v[168:171], v[200:203], v[20:23]
	v_mfma_f32_16x16x32_bf16 v[16:19], v[176:179], v[200:203], v[16:19]
	v_mfma_f32_16x16x32_bf16 v[4:7], v[168:171], v[208:211], v[4:7]
	v_mfma_f32_16x16x32_bf16 v[0:3], v[176:179], v[208:211], v[0:3]
	v_mfma_f32_16x16x32_bf16 v[52:55], v[172:175], v[188:191], v[52:55]
	v_mfma_f32_16x16x32_bf16 v[48:51], v[180:183], v[188:191], v[48:51]
	v_mfma_f32_16x16x32_bf16 v[36:39], v[172:175], v[196:199], v[36:39]
	v_mfma_f32_16x16x32_bf16 v[32:35], v[180:183], v[196:199], v[32:35]
	v_mfma_f32_16x16x32_bf16 v[20:23], v[172:175], v[204:207], v[20:23]
	v_mfma_f32_16x16x32_bf16 v[16:19], v[180:183], v[204:207], v[16:19]
	v_mfma_f32_16x16x32_bf16 v[4:7], v[172:175], v[212:215], v[4:7]
	v_mfma_f32_16x16x32_bf16 v[0:3], v[180:183], v[212:215], v[0:3]
	s_barrier
	s_add_i32 s40, s40, 2
	s_add_u32 s13, s13, 0x100
	s_addc_u32 s39, s39, 0
	s_cmpk_lt_u32 s40, 0x56
	s_mov_b64 s[14:15], s[16:17]
; #define PG8_STAGE(bufoff, gbase, voff) do { _Pragma("unroll") for (int _i = 0; _i < 2; ++_i) \
;         __builtin_amdgcn_global_load_lds((const unsigned*)((const char*)(gbase) + (voff)[_i]), (LAS unsigned*)(lds + (bufoff) + ldsw + _i * 8192), 16, 0, 0); } while (0)
; #define PG8_LDA(dst, b, h) do { _Pragma("unroll") for (int m = 0; m < 4; ++m) _Pragma("unroll") for (int k = 0; k < 2; ++k) dst[m][k] = *(const LAS bf16x8*)(lds + PG8_SA(b, h) + aoff + m * 2048 + k * 1024); } while (0)
; #define PG8_LDB(dst, b, h) do { _Pragma("unroll") for (int n = 0; n < 2; ++n) _Pragma("unroll") for (int k = 0; k < 2; ++k) dst[n][k] = *(const LAS bf16x8*)(lds + PG8_SB(b, h) + boff + n * 2048 + k * 1024); } while (0)
; #define PG8_MMA(ai, bj, At, Bt) do { __builtin_amdgcn_s_setprio(1); _Pragma("unroll") for (int m = 0; m < 4; ++m) _Pragma("unroll") for (int n = 0; n < 2; ++n) _Pragma("unroll") for (int k = 0; k < 2; ++k) \
;         acc[ai][bj][m][n] = __builtin_amdgcn_mfma_f32_16x16x32_bf16(Bt[n][k], At[m][k], acc[ai][bj][m][n], 0, 0, 0); __builtin_amdgcn_s_setprio(0); } while (0)
; #define PG8_WAIT_V(n) asm volatile("s_waitcnt vmcnt(" #n ")" ::: "memory")
; #define PG8_WAIT_L(n) asm volatile("s_waitcnt lgkmcnt(" #n ")" ::: "memory")
; #define PG8_BAR __builtin_amdgcn_s_barrier()
; template <class Epi, class Sched, bool ALIGN_EPI = false, bool SP2 = false>
; __device__ __forceinline__ void gemm_phase(LAS unsigned char* lds, const Gemm g, const Sched& S, const Epi& E) {
;     ...
;             const bool last = (t == nt - 2);
;             const char* a1 = cA + (size_t)(t + 1) * kstep;
;             const char* a2 = last ? nA : cA + (size_t)(t + 2) * kstep; const char* b2 = last ? nB : cB + (size_t)(t + 2) * kstep;
;             const char* a3 = a2 + kstep; const char* b3 = b2 + kstep;
;             if (last && has_next) S.a_ready(nxt);
;             if constexpr (SP2) {
;             PG8_LDB(B0, 0, 0); PG8_LDB(B1, 0, 1); PG8_SCHED; PG8_LDA(At, 0, 0); PG8_STAGE(PG8_SA(1, 1), a1 + hstep, voffA);
;             PG8_WAIT_V(8); PG8_WAIT_L(0); PG8_BAR; PG8_MMA(0, 0, At, B0); PG8_MMA(0, 1, At, B1); PG8_BAR; PG8_SCHED;
;             PG8_LDA(At, 0, 1); PG8_STAGE(PG8_SB(0, 0), b2, voffB); PG8_STAGE(PG8_SB(0, 1), b2 + hstepB, voffB); PG8_STAGE(PG8_SA(0, 0), a2, voffA);
;             PG8_WAIT_V(8); PG8_WAIT_L(0); PG8_BAR; PG8_MMA(1, 0, At, B0); PG8_MMA(1, 1, At, B1); PG8_BAR; PG8_SCHED;
.LBB0_3002:
	ds_read_b128 v[152:155], v147
	ds_read_b128 v[156:159], v147 offset:1024
	ds_read_b128 v[160:163], v147 offset:2048
	ds_read_b128 v[164:167], v147 offset:3072
	ds_read_b128 v[168:171], v148
	ds_read_b128 v[172:175], v148 offset:1024
	ds_read_b128 v[176:179], v148 offset:2048
	ds_read_b128 v[180:183], v148 offset:3072
	s_add_u32 s16, s14, 0x100
	s_addc_u32 s17, s15, 0
	s_cmpk_eq_i32 s40, 0x54
	s_cselect_b32 s21, s11, s17
	s_cselect_b32 s20, s10, s16
	s_cselect_b32 s19, s3, s39
	s_cselect_b32 s18, s2, s13
	v_lshl_add_u64 v[216:217], s[14:15], 0, v[138:139]
	s_add_i32 m0, s24, 0xc000
	ds_read_b128 v[184:187], v149
	ds_read_b128 v[188:191], v149 offset:1024
	ds_read_b128 v[192:195], v149 offset:2048
	ds_read_b128 v[196:199], v149 offset:3072
	ds_read_b128 v[200:203], v149 offset:4096
	ds_read_b128 v[204:207], v149 offset:5120
	ds_read_b128 v[208:211], v149 offset:6144
	ds_read_b128 v[212:215], v149 offset:7168
	global_load_lds_dwordx4 v[216:217], off
	v_lshl_add_u64 v[216:217], s[14:15], 0, v[136:137]
	s_add_i32 m0, s24, 0xe000
	s_nop 0
	global_load_lds_dwordx4 v[216:217], off
	s_waitcnt vmcnt(8)
	s_waitcnt lgkmcnt(0)
	s_barrier
	s_waitcnt lgkmcnt(0)
	v_mfma_f32_16x16x32_bf16 v[124:127], v[152:155], v[184:187], v[124:127]
	v_mfma_f32_16x16x32_bf16 v[120:123], v[160:163], v[184:187], v[120:123]
	v_mfma_f32_16x16x32_bf16 v[112:115], v[152:155], v[192:195], v[112:115]
	v_mfma_f32_16x16x32_bf16 v[104:107], v[160:163], v[192:195], v[104:107]
	v_mfma_f32_16x16x32_bf16 v[92:95], v[152:155], v[200:203], v[92:95]
	v_mfma_f32_16x16x32_bf16 v[88:91], v[160:163], v[200:203], v[88:91]
	v_mfma_f32_16x16x32_bf16 v[76:79], v[152:155], v[208:211], v[76:79]
	v_mfma_f32_16x16x32_bf16 v[72:75], v[160:163], v[208:211], v[72:75]
	v_mfma_f32_16x16x32_bf16 v[124:127], v[156:159], v[188:191], v[124:127]
	v_mfma_f32_16x16x32_bf16 v[120:123], v[164:167], v[188:191], v[120:123]
	v_mfma_f32_16x16x32_bf16 v[112:115], v[156:159], v[196:199], v[112:115]
	v_mfma_f32_16x16x32_bf16 v[104:107], v[164:167], v[196:199], v[104:107]
	v_mfma_f32_16x16x32_bf16 v[92:95], v[156:159], v[204:207], v[92:95]
	v_mfma_f32_16x16x32_bf16 v[88:91], v[164:167], v[204:207], v[88:91]
	v_mfma_f32_16x16x32_bf16 v[76:79], v[156:159], v[212:215], v[76:79]
	v_mfma_f32_16x16x32_bf16 v[72:75], v[164:167], v[212:215], v[72:75]
	v_mfma_f32_16x16x32_bf16 v[116:119], v[168:171], v[184:187], v[116:119]
	v_mfma_f32_16x16x32_bf16 v[108:111], v[176:179], v[184:187], v[108:111]
	v_mfma_f32_16x16x32_bf16 v[100:103], v[168:171], v[192:195], v[100:103]
	v_mfma_f32_16x16x32_bf16 v[96:99], v[176:179], v[192:195], v[96:99]
	v_mfma_f32_16x16x32_bf16 v[84:87], v[168:171], v[200:203], v[84:87]
	v_mfma_f32_16x16x32_bf16 v[80:83], v[176:179], v[200:203], v[80:83]
	v_mfma_f32_16x16x32_bf16 v[68:71], v[168:171], v[208:211], v[68:71]
	v_mfma_f32_16x16x32_bf16 v[64:67], v[176:179], v[208:211], v[64:67]
	v_mfma_f32_16x16x32_bf16 v[116:119], v[172:175], v[188:191], v[116:119]
	v_mfma_f32_16x16x32_bf16 v[108:111], v[180:183], v[188:191], v[108:111]
	v_mfma_f32_16x16x32_bf16 v[100:103], v[172:175], v[196:199], v[100:103]
	v_mfma_f32_16x16x32_bf16 v[96:99], v[180:183], v[196:199], v[96:99]
	v_mfma_f32_16x16x32_bf16 v[84:87], v[172:175], v[204:207], v[84:87]
	v_mfma_f32_16x16x32_bf16 v[80:83], v[180:183], v[204:207], v[80:83]
	v_mfma_f32_16x16x32_bf16 v[68:71], v[172:175], v[212:215], v[68:71]
	v_mfma_f32_16x16x32_bf16 v[64:67], v[180:183], v[212:215], v[64:67]
	s_barrier
	s_add_i32 s14, s34, s23
	s_mov_b32 m0, s14
	ds_read_b128 v[184:187], v149 offset:16384
	ds_read_b128 v[188:191], v149 offset:17408
	ds_read_b128 v[192:195], v149 offset:18432
	ds_read_b128 v[196:199], v149 offset:19456
	ds_read_b128 v[200:203], v149 offset:20480
	ds_read_b128 v[204:207], v149 offset:21504
	ds_read_b128 v[208:211], v149 offset:22528
	ds_read_b128 v[212:215], v149 offset:23552
	global_load_lds_dwordx4 v130, s[18:19]
	s_add_i32 m0, s14, 0x2000
	s_add_u32 s14, s18, 0x58000
	v_lshl_add_u64 v[218:219], s[18:19], 0, v[134:135]
	s_addc_u32 s15, s19, 0
	s_add_i32 s41, s35, s23
	global_load_lds_dwordx4 v134, s[18:19]
	s_mov_b32 m0, s41
	global_load_lds_dwordx4 v130, s[14:15]
	s_add_i32 m0, s41, 0x2000
	s_nop 0
	global_load_lds_dwordx4 v134, s[14:15]
	s_mov_b32 m0, s24
	s_nop 0
	global_load_lds_dwordx4 v128, s[20:21]
	s_mov_b32 m0, s25
	s_nop 0
	global_load_lds_dwordx4 v132, s[20:21]
	s_waitcnt vmcnt(8)
	s_waitcnt lgkmcnt(0)
	s_barrier
	s_waitcnt lgkmcnt(0)
	v_mfma_f32_16x16x32_bf16 v[60:63], v[152:155], v[184:187], v[60:63]
	v_mfma_f32_16x16x32_bf16 v[56:59], v[160:163], v[184:187], v[56:59]
	v_mfma_f32_16x16x32_bf16 v[44:47], v[152:155], v[192:195], v[44:47]
	v_mfma_f32_16x16x32_bf16 v[40:43], v[160:163], v[192:195], v[40:43]
	v_mfma_f32_16x16x32_bf16 v[28:31], v[152:155], v[200:203], v[28:31]
	v_mfma_f32_16x16x32_bf16 v[24:27], v[160:163], v[200:203], v[24:27]
	v_mfma_f32_16x16x32_bf16 v[12:15], v[152:155], v[208:211], v[12:15]
	v_mfma_f32_16x16x32_bf16 v[8:11], v[160:163], v[208:211], v[8:11]
	v_mfma_f32_16x16x32_bf16 v[60:63], v[156:159], v[188:191], v[60:63]
	v_mfma_f32_16x16x32_bf16 v[56:59], v[164:167], v[188:191], v[56:59]
	v_mfma_f32_16x16x32_bf16 v[44:47], v[156:159], v[196:199], v[44:47]
	v_mfma_f32_16x16x32_bf16 v[40:43], v[164:167], v[196:199], v[40:43]
	v_mfma_f32_16x16x32_bf16 v[28:31], v[156:159], v[204:207], v[28:31]
	v_mfma_f32_16x16x32_bf16 v[24:27], v[164:167], v[204:207], v[24:27]
	v_mfma_f32_16x16x32_bf16 v[12:15], v[156:159], v[212:215], v[12:15]
	v_mfma_f32_16x16x32_bf16 v[8:11], v[164:167], v[212:215], v[8:11]
	v_mfma_f32_16x16x32_bf16 v[52:55], v[168:171], v[184:187], v[52:55]
	v_mfma_f32_16x16x32_bf16 v[48:51], v[176:179], v[184:187], v[48:51]
	v_mfma_f32_16x16x32_bf16 v[36:39], v[168:171], v[192:195], v[36:39]
	v_mfma_f32_16x16x32_bf16 v[32:35], v[176:179], v[192:195], v[32:35]
	v_mfma_f32_16x16x32_bf16 v[20:23], v[168:171], v[200:203], v[20:23]
	v_mfma_f32_16x16x32_bf16 v[16:19], v[176:179], v[200:203], v[16:19]
	v_mfma_f32_16x16x32_bf16 v[4:7], v[168:171], v[208:211], v[4:7]
	v_mfma_f32_16x16x32_bf16 v[0:3], v[176:179], v[208:211], v[0:3]
	v_mfma_f32_16x16x32_bf16 v[52:55], v[172:175], v[188:191], v[52:55]
	v_mfma_f32_16x16x32_bf16 v[48:51], v[180:183], v[188:191], v[48:51]
	v_mfma_f32_16x16x32_bf16 v[36:39], v[172:175], v[196:199], v[36:39]
	v_mfma_f32_16x16x32_bf16 v[32:35], v[180:183], v[196:199], v[32:35]
	v_mfma_f32_16x16x32_bf16 v[20:23], v[172:175], v[204:207], v[20:23]
	v_mfma_f32_16x16x32_bf16 v[16:19], v[180:183], v[204:207], v[16:19]
	v_mfma_f32_16x16x32_bf16 v[4:7], v[172:175], v[212:215], v[4:7]
	v_mfma_f32_16x16x32_bf16 v[0:3], v[180:183], v[212:215], v[0:3]
	s_barrier
; #define PG8_STAGE(bufoff, gbase, voff) do { _Pragma("unroll") for (int _i = 0; _i < 2; ++_i) \
;         __builtin_amdgcn_global_load_lds((const unsigned*)((const char*)(gbase) + (voff)[_i]), (LAS unsigned*)(lds + (bufoff) + ldsw + _i * 8192), 16, 0, 0); } while (0)
; #define PG8_LDA(dst, b, h) do { _Pragma("unroll") for (int m = 0; m < 4; ++m) _Pragma("unroll") for (int k = 0; k < 2; ++k) dst[m][k] = *(const LAS bf16x8*)(lds + PG8_SA(b, h) + aoff + m * 2048 + k * 1024); } while (0)
; #define PG8_LDB(dst, b, h) do { _Pragma("unroll") for (int n = 0; n < 2; ++n) _Pragma("unroll") for (int k = 0; k < 2; ++k) dst[n][k] = *(const LAS bf16x8*)(lds + PG8_SB(b, h) + boff + n * 2048 + k * 1024); } while (0)
; #define PG8_MMA(ai, bj, At, Bt) do { __builtin_amdgcn_s_setprio(1); _Pragma("unroll") for (int m = 0; m < 4; ++m) _Pragma("unroll") for (int n = 0; n < 2; ++n) _Pragma("unroll") for (int k = 0; k < 2; ++k) \
;         acc[ai][bj][m][n] = __builtin_amdgcn_mfma_f32_16x16x32_bf16(Bt[n][k], At[m][k], acc[ai][bj][m][n], 0, 0, 0); __builtin_amdgcn_s_setprio(0); } while (0)
; #define PG8_WAIT_V(n) asm volatile("s_waitcnt vmcnt(" #n ")" ::: "memory")
; #define PG8_WAIT_L(n) asm volatile("s_waitcnt lgkmcnt(" #n ")" ::: "memory")
; #define PG8_BAR __builtin_amdgcn_s_barrier()
; #define PG8_SCHED __builtin_amdgcn_sched_barrier(0)
; template <class Epi, class Sched, bool ALIGN_EPI = false, bool SP2 = false>
; __device__ __forceinline__ void gemm_phase(LAS unsigned char* lds, const Gemm g, const Sched& S, const Epi& E) {
;     ...
;             PG8_LDB(B0, 1, 0); PG8_LDB(B1, 1, 1); PG8_SCHED; PG8_LDA(At, 1, 0); PG8_STAGE(PG8_SA(0, 1), a2 + hstep, voffA);
;             PG8_WAIT_V(8); PG8_WAIT_L(0); PG8_BAR; PG8_MMA(0, 0, At, B0); PG8_MMA(0, 1, At, B1); PG8_BAR; PG8_SCHED;
;             PG8_LDA(At, 1, 1); PG8_STAGE(PG8_SB(1, 0), b3, voffB); PG8_STAGE(PG8_SB(1, 1), b3 + hstepB, voffB); PG8_STAGE(PG8_SA(1, 0), a3, voffA);
;             PG8_WAIT_V(8); PG8_WAIT_L(0); PG8_BAR; PG8_MMA(1, 0, At, B0); PG8_MMA(1, 1, At, B1); PG8_BAR; PG8_SCHED;
	s_add_i32 s41, 0, 0x18000
	s_add_i32 s42, 0, 0x1c000
	v_add_u32_e32 v164, s41, v144
	v_add_u32_e32 v180, s42, v144
	ds_read_b128 v[152:155], v164
	ds_read_b128 v[156:159], v164 offset:1024
	ds_read_b128 v[160:163], v164 offset:2048
	ds_read_b128 v[164:167], v164 offset:3072
	ds_read_b128 v[168:171], v180
	ds_read_b128 v[172:175], v180 offset:1024
	ds_read_b128 v[176:179], v180 offset:2048
	ds_read_b128 v[180:183], v180 offset:3072
	s_add_u32 s14, s20, 0x160000
	s_addc_u32 s15, s21, 0
	s_mov_b32 m0, s26
	ds_read_b128 v[184:187], v149 offset:32768
	ds_read_b128 v[188:191], v149 offset:33792
	ds_read_b128 v[192:195], v149 offset:34816
	ds_read_b128 v[196:199], v149 offset:35840
	ds_read_b128 v[200:203], v149 offset:36864
	ds_read_b128 v[204:207], v149 offset:37888
	ds_read_b128 v[208:211], v149 offset:38912
	ds_read_b128 v[212:215], v149 offset:39936
	global_load_lds_dwordx4 v128, s[14:15]
	s_mov_b32 m0, s27
	s_nop 0
	global_load_lds_dwordx4 v132, s[14:15]
	s_waitcnt vmcnt(8)
	s_waitcnt lgkmcnt(0)
	s_barrier
	s_waitcnt lgkmcnt(0)
	v_mfma_f32_16x16x32_bf16 v[124:127], v[152:155], v[184:187], v[124:127]
	v_mfma_f32_16x16x32_bf16 v[120:123], v[160:163], v[184:187], v[120:123]
	v_mfma_f32_16x16x32_bf16 v[112:115], v[152:155], v[192:195], v[112:115]
	v_mfma_f32_16x16x32_bf16 v[104:107], v[160:163], v[192:195], v[104:107]
	v_mfma_f32_16x16x32_bf16 v[92:95], v[152:155], v[200:203], v[92:95]
	v_mfma_f32_16x16x32_bf16 v[88:91], v[160:163], v[200:203], v[88:91]
	v_mfma_f32_16x16x32_bf16 v[76:79], v[152:155], v[208:211], v[76:79]
	v_mfma_f32_16x16x32_bf16 v[72:75], v[160:163], v[208:211], v[72:75]
	v_mfma_f32_16x16x32_bf16 v[124:127], v[156:159], v[188:191], v[124:127]
	v_mfma_f32_16x16x32_bf16 v[120:123], v[164:167], v[188:191], v[120:123]
	v_mfma_f32_16x16x32_bf16 v[112:115], v[156:159], v[196:199], v[112:115]
	v_mfma_f32_16x16x32_bf16 v[104:107], v[164:167], v[196:199], v[104:107]
	v_mfma_f32_16x16x32_bf16 v[92:95], v[156:159], v[204:207], v[92:95]
	v_mfma_f32_16x16x32_bf16 v[88:91], v[164:167], v[204:207], v[88:91]
	v_mfma_f32_16x16x32_bf16 v[76:79], v[156:159], v[212:215], v[76:79]
	v_mfma_f32_16x16x32_bf16 v[72:75], v[164:167], v[212:215], v[72:75]
	v_mfma_f32_16x16x32_bf16 v[116:119], v[168:171], v[184:187], v[116:119]
	v_mfma_f32_16x16x32_bf16 v[108:111], v[176:179], v[184:187], v[108:111]
	v_mfma_f32_16x16x32_bf16 v[100:103], v[168:171], v[192:195], v[100:103]
	v_mfma_f32_16x16x32_bf16 v[96:99], v[176:179], v[192:195], v[96:99]
	v_mfma_f32_16x16x32_bf16 v[84:87], v[168:171], v[200:203], v[84:87]
	v_mfma_f32_16x16x32_bf16 v[80:83], v[176:179], v[200:203], v[80:83]
	v_mfma_f32_16x16x32_bf16 v[68:71], v[168:171], v[208:211], v[68:71]
	v_mfma_f32_16x16x32_bf16 v[64:67], v[176:179], v[208:211], v[64:67]
	v_mfma_f32_16x16x32_bf16 v[116:119], v[172:175], v[188:191], v[116:119]
	v_mfma_f32_16x16x32_bf16 v[108:111], v[180:183], v[188:191], v[108:111]
	v_mfma_f32_16x16x32_bf16 v[100:103], v[172:175], v[196:199], v[100:103]
	v_mfma_f32_16x16x32_bf16 v[96:99], v[180:183], v[196:199], v[96:99]
	v_mfma_f32_16x16x32_bf16 v[84:87], v[172:175], v[204:207], v[84:87]
	v_mfma_f32_16x16x32_bf16 v[80:83], v[180:183], v[204:207], v[80:83]
	v_mfma_f32_16x16x32_bf16 v[68:71], v[172:175], v[212:215], v[68:71]
	v_mfma_f32_16x16x32_bf16 v[64:67], v[180:183], v[212:215], v[64:67]
	s_barrier
	s_add_u32 s98, s18, 0x80
	s_addc_u32 s99, s19, 0
	s_add_u32 s100, s20, 0x80
	s_addc_u32 s101, s21, 0
	s_add_i32 s14, s41, s23
	s_mov_b32 m0, s14
	ds_read_b128 v[184:187], v149 offset:49152
	ds_read_b128 v[188:191], v149 offset:50176
	ds_read_b128 v[192:195], v149 offset:51200
	ds_read_b128 v[196:199], v149 offset:52224
	ds_read_b128 v[200:203], v149 offset:53248
	ds_read_b128 v[204:207], v149 offset:54272
	ds_read_b128 v[208:211], v149 offset:55296
	ds_read_b128 v[212:215], v149 offset:56320
	global_load_lds_dwordx4 v130, s[98:99]
	s_add_i32 m0, s14, 0x2000
	s_add_u32 s14, s18, 0x58080
	v_lshl_add_u64 v[216:217], v[218:219], 0, s[6:7]
	s_addc_u32 s15, s19, 0
	s_add_i32 s18, s42, s23
	global_load_lds_dwordx4 v[216:217], off
	s_mov_b32 m0, s18
	s_nop 0
	global_load_lds_dwordx4 v130, s[14:15]
	s_add_i32 m0, s18, 0x2000
	s_nop 0
	global_load_lds_dwordx4 v134, s[14:15]
	s_mov_b32 m0, s31
	s_nop 0
	global_load_lds_dwordx4 v128, s[100:101]
	s_mov_b32 m0, s33
	s_nop 0
	global_load_lds_dwordx4 v132, s[100:101]
	s_waitcnt vmcnt(8)
	s_waitcnt lgkmcnt(0)
	s_barrier
	s_waitcnt lgkmcnt(0)
	v_mfma_f32_16x16x32_bf16 v[60:63], v[152:155], v[184:187], v[60:63]
	v_mfma_f32_16x16x32_bf16 v[56:59], v[160:163], v[184:187], v[56:59]
	v_mfma_f32_16x16x32_bf16 v[44:47], v[152:155], v[192:195], v[44:47]
	v_mfma_f32_16x16x32_bf16 v[40:43], v[160:163], v[192:195], v[40:43]
	v_mfma_f32_16x16x32_bf16 v[28:31], v[152:155], v[200:203], v[28:31]
	v_mfma_f32_16x16x32_bf16 v[24:27], v[160:163], v[200:203], v[24:27]
	v_mfma_f32_16x16x32_bf16 v[12:15], v[152:155], v[208:211], v[12:15]
	v_mfma_f32_16x16x32_bf16 v[8:11], v[160:163], v[208:211], v[8:11]
	v_mfma_f32_16x16x32_bf16 v[60:63], v[156:159], v[188:191], v[60:63]
	v_mfma_f32_16x16x32_bf16 v[56:59], v[164:167], v[188:191], v[56:59]
	v_mfma_f32_16x16x32_bf16 v[44:47], v[156:159], v[196:199], v[44:47]
	v_mfma_f32_16x16x32_bf16 v[40:43], v[164:167], v[196:199], v[40:43]
	v_mfma_f32_16x16x32_bf16 v[28:31], v[156:159], v[204:207], v[28:31]
	v_mfma_f32_16x16x32_bf16 v[24:27], v[164:167], v[204:207], v[24:27]
	v_mfma_f32_16x16x32_bf16 v[12:15], v[156:159], v[212:215], v[12:15]
	v_mfma_f32_16x16x32_bf16 v[8:11], v[164:167], v[212:215], v[8:11]
	v_mfma_f32_16x16x32_bf16 v[52:55], v[168:171], v[184:187], v[52:55]
	v_mfma_f32_16x16x32_bf16 v[48:51], v[176:179], v[184:187], v[48:51]
	v_mfma_f32_16x16x32_bf16 v[36:39], v[168:171], v[192:195], v[36:39]
	v_mfma_f32_16x16x32_bf16 v[32:35], v[176:179], v[192:195], v[32:35]
	v_mfma_f32_16x16x32_bf16 v[20:23], v[168:171], v[200:203], v[20:23]
	v_mfma_f32_16x16x32_bf16 v[16:19], v[176:179], v[200:203], v[16:19]
	v_mfma_f32_16x16x32_bf16 v[4:7], v[168:171], v[208:211], v[4:7]
	v_mfma_f32_16x16x32_bf16 v[0:3], v[176:179], v[208:211], v[0:3]
	v_mfma_f32_16x16x32_bf16 v[52:55], v[172:175], v[188:191], v[52:55]
	v_mfma_f32_16x16x32_bf16 v[48:51], v[180:183], v[188:191], v[48:51]
	v_mfma_f32_16x16x32_bf16 v[36:39], v[172:175], v[196:199], v[36:39]
	v_mfma_f32_16x16x32_bf16 v[32:35], v[180:183], v[196:199], v[32:35]
	v_mfma_f32_16x16x32_bf16 v[20:23], v[172:175], v[204:207], v[20:23]
	v_mfma_f32_16x16x32_bf16 v[16:19], v[180:183], v[204:207], v[16:19]
	v_mfma_f32_16x16x32_bf16 v[4:7], v[172:175], v[212:215], v[4:7]
	v_mfma_f32_16x16x32_bf16 v[0:3], v[180:183], v[212:215], v[0:3]
	s_barrier
	s_add_i32 s40, s40, 2
	s_add_u32 s13, s13, 0x100
	s_addc_u32 s39, s39, 0
	s_cmpk_lt_u32 s40, 0x56
	s_mov_b64 s[14:15], s[16:17]
	s_cbranch_scc1 .LBB0_3002
	s_setprio 0
	s_andn2_b64 vcc, exec, s[8:9]
	s_cbranch_vccnz .LBB0_3005
	s_barrier
